# gMLP gelu exponent chain folded to x*(k1+k2*x^2): 2 fewer f32 VALU per gelu (570 sites), on top of NSA selected-step prolog version
# speedup vs baseline: 1.0524x; 1.0024x over previous
.LBB0_595:
	s_or_b64 exec, exec, s[0:1]
	v_mov_b32_e32 v0, v194
	s_waitcnt lgkmcnt(0)
	s_barrier
	v_mov_b32_e32 v129, 0xc0135761
	s_nop 0
	v_readfirstlane_b32 s0, v0
	s_ashr_i32 s2, s0, 8
	v_readlane_b32 s0, v254, 41
	s_add_i32 s10, s2, s0
	v_readlane_b32 s0, v252, 50
	v_readlane_b32 s1, v252, 51
	s_mul_i32 s15, s2, 0x12000
	s_andn2_b64 vcc, exec, s[0:1]
	s_mov_b64 s[0:1], -1
	s_cbranch_vccnz .LBB0_618
	s_cmpk_gt_i32 s10, 0x87f
	s_cbranch_scc1 .LBB0_617
	v_readlane_b32 s0, v254, 51
	s_lshl_b32 s8, s0, 9
	s_mov_b32 s9, s89
	v_readlane_b32 s40, v251, 6
	s_lshl_b64 s[0:1], s[8:9], 2
	v_readlane_b32 s52, v251, 18
	v_readlane_b32 s53, v251, 19
	s_add_u32 s9, s52, s0
	v_readlane_b32 s54, v251, 20
	s_addc_u32 s11, s53, s1
	v_readlane_b32 s55, v251, 21
	s_add_u32 s20, s54, s0
	v_readlane_b32 s0, v254, 42
	s_addc_u32 s21, s55, s1
	s_add_i32 s0, s0, s2
	s_lshl_b32 s75, s0, 5
	s_lshl_b32 s0, s2, 5
	v_readlane_b32 s1, v254, 44
	s_add_i32 s74, s15, 0x10000
	s_add_i32 s76, s1, s0
	s_mov_b32 s77, s10
	v_readlane_b32 s41, v251, 7
	v_readlane_b32 s42, v251, 8
	v_readlane_b32 s43, v251, 9
	v_readlane_b32 s44, v251, 10
	v_readlane_b32 s45, v251, 11
	v_readlane_b32 s46, v251, 12
	v_readlane_b32 s47, v251, 13
	v_readlane_b32 s48, v251, 14
	v_readlane_b32 s49, v251, 15
	v_readlane_b32 s50, v251, 16
	v_readlane_b32 s51, v251, 17
	s_branch .LBB0_599

.LBB0_608:
	v_lshl_add_u64 v[12:13], v[10:11], 0, s[0:1]
	global_load_dwordx4 v[2:5], v[12:13], off offset:1072
	global_load_dwordx4 v[6:9], v[12:13], off offset:1056
	global_load_dwordx4 v[18:21], v[12:13], off offset:1040
	global_load_dwordx4 v[22:25], v[12:13], off offset:1024
	s_add_u32 s0, s0, 0x80
	s_addc_u32 s1, s1, 0
	s_cmpk_lg_i32 s0, 0x200
	s_waitcnt vmcnt(0)
	v_lshlrev_b32_e32 v0, 16, v22
	v_mul_f32_e32 v17, v0, v0
	v_fmamk_f32 v17, v17, 0xbdd2d3e7, v129
	v_mul_f32_e32 v17, v17, v0
	v_exp_f32_e32 v17, v17
	v_and_b32_e32 v38, 0xffff0000, v25
	v_add_f32_e32 v17, 1.0, v17
	v_rcp_f32_e32 v17, v17
	s_nop 0
	v_mul_f32_e32 v27, v17, v0
	v_and_b32_e32 v0, 0xffff0000, v22
	v_mul_f32_e32 v17, v0, v0
	v_fmamk_f32 v17, v17, 0xbdd2d3e7, v129
	v_mul_f32_e32 v17, v17, v0
	v_exp_f32_e32 v17, v17
	v_mul_f32_e32 v26, v27, v27
	v_add_f32_e32 v17, 1.0, v17
	v_rcp_f32_e32 v17, v17
	s_nop 0
	v_mul_f32_e32 v29, v17, v0
	v_lshlrev_b32_e32 v0, 16, v23
	v_mul_f32_e32 v17, v0, v0
	v_fmamk_f32 v17, v17, 0xbdd2d3e7, v129
	v_mul_f32_e32 v17, v17, v0
	v_exp_f32_e32 v17, v17
	v_mul_f32_e32 v28, v29, v29
	v_add_f32_e32 v17, 1.0, v17
	v_rcp_f32_e32 v17, v17
	s_nop 0
	v_mul_f32_e32 v31, v17, v0
	v_and_b32_e32 v0, 0xffff0000, v23
	v_mul_f32_e32 v17, v0, v0
	v_fmamk_f32 v17, v17, 0xbdd2d3e7, v129
	v_mul_f32_e32 v17, v17, v0
	v_exp_f32_e32 v17, v17
	v_mul_f32_e32 v30, v31, v31
	v_add_f32_e32 v17, 1.0, v17
	v_rcp_f32_e32 v17, v17
	s_nop 0
	v_mul_f32_e32 v23, v17, v0
	v_lshlrev_b32_e32 v0, 16, v24
	v_mul_f32_e32 v17, v0, v0
	v_fmamk_f32 v17, v17, 0xbdd2d3e7, v129
	v_mul_f32_e32 v17, v17, v0
	v_exp_f32_e32 v17, v17
	v_mul_f32_e32 v22, v23, v23
	v_pk_add_f32 v[22:23], v[30:31], v[22:23]
	v_add_f32_e32 v17, 1.0, v17
	v_rcp_f32_e32 v17, v17
	s_nop 0
	v_mul_f32_e32 v35, v17, v0
	v_and_b32_e32 v0, 0xffff0000, v24
	v_mul_f32_e32 v17, v0, v0
	v_fmamk_f32 v17, v17, 0xbdd2d3e7, v129
	v_mul_f32_e32 v17, v17, v0
	v_exp_f32_e32 v17, v17
	v_mul_f32_e32 v24, v38, v38
	v_fmamk_f32 v24, v24, 0xbdd2d3e7, v129
	v_mul_f32_e32 v24, v24, v38
	v_add_f32_e32 v17, 1.0, v17
	v_rcp_f32_e32 v17, v17
	v_exp_f32_e32 v24, v24
	v_mul_f32_e32 v37, v17, v0
	v_lshlrev_b32_e32 v0, 16, v25
	v_mul_f32_e32 v17, v0, v0
	v_fmamk_f32 v17, v17, 0xbdd2d3e7, v129
	v_mul_f32_e32 v17, v17, v0
	v_exp_f32_e32 v17, v17
	v_add_f32_e32 v24, 1.0, v24
	v_rcp_f32_e32 v39, v24
	v_pk_add_f32 v[24:25], v[26:27], v[28:29]
	v_add_f32_e32 v17, 1.0, v17
	v_rcp_f32_e32 v17, v17
	v_mul_f32_e32 v34, v35, v35
	v_mul_f32_e32 v36, v37, v37
	v_pk_add_f32 v[14:15], v[14:15], v[24:25]
	v_mul_f32_e32 v25, v39, v38
	v_pk_add_f32 v[14:15], v[14:15], v[22:23]
	v_pk_add_f32 v[22:23], v[34:35], v[36:37]
	v_mul_f32_e32 v24, v25, v25
	v_pk_add_f32 v[14:15], v[14:15], v[22:23]
	v_mul_f32_e32 v23, v17, v0
	v_lshlrev_b32_e32 v0, 16, v18
	v_mul_f32_e32 v17, v0, v0
	v_fmamk_f32 v17, v17, 0xbdd2d3e7, v129
	v_mul_f32_e32 v17, v17, v0
	v_exp_f32_e32 v17, v17
	v_mul_f32_e32 v22, v23, v23
	v_pk_add_f32 v[22:23], v[22:23], v[24:25]
	v_and_b32_e32 v34, 0xffff0000, v21
	v_add_f32_e32 v17, 1.0, v17
	v_rcp_f32_e32 v17, v17
	v_pk_add_f32 v[14:15], v[14:15], v[22:23]
	v_mul_f32_e32 v23, v17, v0
	v_and_b32_e32 v0, 0xffff0000, v18
	v_mul_f32_e32 v17, v0, v0
	v_fmamk_f32 v17, v17, 0xbdd2d3e7, v129
	v_mul_f32_e32 v17, v17, v0
	v_exp_f32_e32 v17, v17
	v_mul_f32_e32 v22, v23, v23
	v_add_f32_e32 v17, 1.0, v17
	v_rcp_f32_e32 v17, v17
	s_nop 0
	v_mul_f32_e32 v25, v17, v0
	v_lshlrev_b32_e32 v0, 16, v19
	v_mul_f32_e32 v17, v0, v0
	v_fmamk_f32 v17, v17, 0xbdd2d3e7, v129
	v_mul_f32_e32 v17, v17, v0
	v_exp_f32_e32 v17, v17
	v_mul_f32_e32 v24, v25, v25
	v_add_f32_e32 v17, 1.0, v17
	v_rcp_f32_e32 v17, v17
	s_nop 0
	v_mul_f32_e32 v27, v17, v0
	v_and_b32_e32 v0, 0xffff0000, v19
	v_mul_f32_e32 v17, v0, v0
	v_fmamk_f32 v17, v17, 0xbdd2d3e7, v129
	v_mul_f32_e32 v17, v17, v0
	v_exp_f32_e32 v17, v17
	v_mul_f32_e32 v26, v27, v27
	v_add_f32_e32 v17, 1.0, v17
	v_rcp_f32_e32 v17, v17
	s_nop 0
	v_mul_f32_e32 v19, v17, v0
	v_lshlrev_b32_e32 v0, 16, v20
	v_mul_f32_e32 v17, v0, v0
	v_fmamk_f32 v17, v17, 0xbdd2d3e7, v129
	v_mul_f32_e32 v17, v17, v0
	v_exp_f32_e32 v17, v17
	v_mul_f32_e32 v18, v19, v19
	v_pk_add_f32 v[18:19], v[26:27], v[18:19]
	v_add_f32_e32 v17, 1.0, v17
	v_rcp_f32_e32 v17, v17
	s_nop 0
	v_mul_f32_e32 v29, v17, v0
	v_and_b32_e32 v0, 0xffff0000, v20
	v_mul_f32_e32 v17, v0, v0
	v_fmamk_f32 v17, v17, 0xbdd2d3e7, v129
	v_mul_f32_e32 v17, v17, v0
	v_exp_f32_e32 v17, v17
	v_mul_f32_e32 v20, v34, v34
	v_fmamk_f32 v20, v20, 0xbdd2d3e7, v129
	v_mul_f32_e32 v20, v20, v34
	v_add_f32_e32 v17, 1.0, v17
	v_rcp_f32_e32 v17, v17
	v_exp_f32_e32 v20, v20
	v_mul_f32_e32 v31, v17, v0
	v_lshlrev_b32_e32 v0, 16, v21
	v_mul_f32_e32 v17, v0, v0
	v_fmamk_f32 v17, v17, 0xbdd2d3e7, v129
	v_mul_f32_e32 v17, v17, v0
	v_exp_f32_e32 v17, v17
	v_add_f32_e32 v20, 1.0, v20
	v_rcp_f32_e32 v35, v20
	v_pk_add_f32 v[20:21], v[22:23], v[24:25]
	v_add_f32_e32 v17, 1.0, v17
	v_rcp_f32_e32 v17, v17
	v_mul_f32_e32 v28, v29, v29
	v_mul_f32_e32 v30, v31, v31
	v_pk_add_f32 v[14:15], v[14:15], v[20:21]
	v_mul_f32_e32 v21, v35, v34
	v_pk_add_f32 v[14:15], v[14:15], v[18:19]
	v_pk_add_f32 v[18:19], v[28:29], v[30:31]
	v_mul_f32_e32 v20, v21, v21
	v_pk_add_f32 v[14:15], v[14:15], v[18:19]
	v_mul_f32_e32 v19, v17, v0
	v_lshlrev_b32_e32 v0, 16, v6
	v_mul_f32_e32 v17, v0, v0
	v_fmamk_f32 v17, v17, 0xbdd2d3e7, v129
	v_mul_f32_e32 v17, v17, v0
	v_exp_f32_e32 v17, v17
	v_mul_f32_e32 v18, v19, v19
	v_pk_add_f32 v[18:19], v[18:19], v[20:21]
	v_and_b32_e32 v28, 0xffff0000, v9
	v_add_f32_e32 v17, 1.0, v17
	v_rcp_f32_e32 v17, v17
	v_pk_add_f32 v[14:15], v[14:15], v[18:19]
	v_mul_f32_e32 v19, v17, v0
	v_and_b32_e32 v0, 0xffff0000, v6
	v_mul_f32_e32 v6, v0, v0
	v_fmamk_f32 v6, v6, 0xbdd2d3e7, v129
	v_mul_f32_e32 v6, v6, v0
	v_exp_f32_e32 v6, v6
	v_mul_f32_e32 v18, v19, v19
	v_add_f32_e32 v6, 1.0, v6
	v_rcp_f32_e32 v6, v6
	s_nop 0
	v_mul_f32_e32 v21, v6, v0
	v_lshlrev_b32_e32 v0, 16, v7
	v_mul_f32_e32 v6, v0, v0
	v_fmamk_f32 v6, v6, 0xbdd2d3e7, v129
	v_mul_f32_e32 v6, v6, v0
	v_exp_f32_e32 v6, v6
	v_mul_f32_e32 v20, v21, v21
	v_add_f32_e32 v6, 1.0, v6
	v_rcp_f32_e32 v6, v6
	s_nop 0
	v_mul_f32_e32 v23, v6, v0
	v_and_b32_e32 v0, 0xffff0000, v7
	v_mul_f32_e32 v6, v0, v0
	v_fmamk_f32 v6, v6, 0xbdd2d3e7, v129
	v_mul_f32_e32 v6, v6, v0
	v_exp_f32_e32 v6, v6
	v_mul_f32_e32 v22, v23, v23
	v_add_f32_e32 v6, 1.0, v6
	v_rcp_f32_e32 v6, v6
	s_nop 0
	v_mul_f32_e32 v7, v6, v0
	v_lshlrev_b32_e32 v0, 16, v8
	v_mul_f32_e32 v17, v0, v0
	v_fmamk_f32 v17, v17, 0xbdd2d3e7, v129
	v_mul_f32_e32 v17, v17, v0
	v_exp_f32_e32 v17, v17
	v_mul_f32_e32 v6, v7, v7
	v_pk_add_f32 v[6:7], v[22:23], v[6:7]
	v_add_f32_e32 v17, 1.0, v17
	v_rcp_f32_e32 v17, v17
	s_nop 0
	v_mul_f32_e32 v25, v17, v0
	v_and_b32_e32 v0, 0xffff0000, v8
	v_mul_f32_e32 v8, v0, v0
	v_fmamk_f32 v8, v8, 0xbdd2d3e7, v129
	v_mul_f32_e32 v8, v8, v0
	v_exp_f32_e32 v8, v8
	v_mul_f32_e32 v24, v25, v25
	v_add_f32_e32 v8, 1.0, v8
	v_rcp_f32_e32 v8, v8
	s_nop 0
	v_mul_f32_e32 v27, v8, v0
	v_lshlrev_b32_e32 v0, 16, v9
	v_mul_f32_e32 v8, v0, v0
	v_fmamk_f32 v8, v8, 0xbdd2d3e7, v129
	v_mul_f32_e32 v8, v8, v0
	v_exp_f32_e32 v8, v8
	v_mul_f32_e32 v26, v27, v27
	v_add_f32_e32 v8, 1.0, v8
	v_rcp_f32_e32 v17, v8
	v_mul_f32_e32 v8, v28, v28
	v_fmamk_f32 v8, v8, 0xbdd2d3e7, v129
	v_mul_f32_e32 v8, v8, v28
	v_exp_f32_e32 v8, v8
	s_nop 0
	v_add_f32_e32 v8, 1.0, v8
	v_rcp_f32_e32 v29, v8
	v_pk_add_f32 v[8:9], v[18:19], v[20:21]
	s_nop 0
	v_pk_add_f32 v[8:9], v[14:15], v[8:9]
	v_mul_f32_e32 v15, v29, v28
	v_pk_add_f32 v[6:7], v[8:9], v[6:7]
	v_pk_add_f32 v[8:9], v[24:25], v[26:27]
	v_mul_f32_e32 v14, v15, v15
	v_pk_add_f32 v[6:7], v[6:7], v[8:9]
	v_mul_f32_e32 v9, v17, v0
	v_mul_f32_e32 v8, v9, v9
	v_pk_add_f32 v[8:9], v[8:9], v[14:15]
	v_lshlrev_b32_e32 v0, 16, v2
	v_pk_add_f32 v[6:7], v[6:7], v[8:9]
	v_mul_f32_e32 v8, v0, v0
	v_fmamk_f32 v8, v8, 0xbdd2d3e7, v129
	v_mul_f32_e32 v8, v8, v0
	v_exp_f32_e32 v8, v8
	v_and_b32_e32 v24, 0xffff0000, v5
	v_add_f32_e32 v8, 1.0, v8
	v_rcp_f32_e32 v8, v8
	s_nop 0
	v_mul_f32_e32 v9, v8, v0
	v_and_b32_e32 v0, 0xffff0000, v2
	v_mul_f32_e32 v2, v0, v0
	v_fmamk_f32 v2, v2, 0xbdd2d3e7, v129
	v_mul_f32_e32 v2, v2, v0
	v_exp_f32_e32 v2, v2
	v_mul_f32_e32 v8, v9, v9
	v_add_f32_e32 v2, 1.0, v2
	v_rcp_f32_e32 v2, v2
	s_nop 0
	v_mul_f32_e32 v15, v2, v0
	v_lshlrev_b32_e32 v0, 16, v3
	v_mul_f32_e32 v2, v0, v0
	v_fmamk_f32 v2, v2, 0xbdd2d3e7, v129
	v_mul_f32_e32 v2, v2, v0
	v_exp_f32_e32 v2, v2
	v_mul_f32_e32 v14, v15, v15
	v_add_f32_e32 v2, 1.0, v2
	v_rcp_f32_e32 v2, v2
	s_nop 0
	v_mul_f32_e32 v19, v2, v0
	v_and_b32_e32 v0, 0xffff0000, v3
	v_mul_f32_e32 v2, v0, v0
	v_fmamk_f32 v2, v2, 0xbdd2d3e7, v129
	v_mul_f32_e32 v2, v2, v0
	v_exp_f32_e32 v2, v2
	v_mul_f32_e32 v18, v19, v19
	v_add_f32_e32 v2, 1.0, v2
	v_rcp_f32_e32 v2, v2
	s_nop 0
	v_mul_f32_e32 v3, v2, v0
	v_lshlrev_b32_e32 v0, 16, v4
	v_mul_f32_e32 v17, v0, v0
	v_fmamk_f32 v17, v17, 0xbdd2d3e7, v129
	v_mul_f32_e32 v17, v17, v0
	v_exp_f32_e32 v17, v17
	v_mul_f32_e32 v2, v3, v3
	v_pk_add_f32 v[2:3], v[18:19], v[2:3]
	v_add_f32_e32 v17, 1.0, v17
	v_rcp_f32_e32 v17, v17
	s_nop 0
	v_mul_f32_e32 v21, v17, v0
	v_and_b32_e32 v0, 0xffff0000, v4
	v_mul_f32_e32 v4, v0, v0
	v_fmamk_f32 v4, v4, 0xbdd2d3e7, v129
	v_mul_f32_e32 v4, v4, v0
	v_exp_f32_e32 v4, v4
	v_mul_f32_e32 v20, v21, v21
	v_add_f32_e32 v4, 1.0, v4
	v_rcp_f32_e32 v4, v4
	s_nop 0
	v_mul_f32_e32 v23, v4, v0
	v_lshlrev_b32_e32 v0, 16, v5
	v_mul_f32_e32 v4, v0, v0
	v_fmamk_f32 v4, v4, 0xbdd2d3e7, v129
	v_mul_f32_e32 v4, v4, v0
	v_exp_f32_e32 v4, v4
	v_mul_f32_e32 v22, v23, v23
	v_add_f32_e32 v4, 1.0, v4
	v_rcp_f32_e32 v17, v4
	v_mul_f32_e32 v4, v24, v24
	v_fmamk_f32 v4, v4, 0xbdd2d3e7, v129
	v_mul_f32_e32 v4, v4, v24
	v_exp_f32_e32 v4, v4
	s_nop 0
	v_add_f32_e32 v4, 1.0, v4
	v_rcp_f32_e32 v25, v4
	v_pk_add_f32 v[4:5], v[8:9], v[14:15]
	s_nop 0
	v_pk_add_f32 v[4:5], v[6:7], v[4:5]
	v_mul_f32_e32 v7, v25, v24
	v_pk_add_f32 v[2:3], v[4:5], v[2:3]
	v_pk_add_f32 v[4:5], v[20:21], v[22:23]
	v_mul_f32_e32 v6, v7, v7
	v_pk_add_f32 v[2:3], v[2:3], v[4:5]
	v_mul_f32_e32 v5, v17, v0
	v_mul_f32_e32 v4, v5, v5
	v_pk_add_f32 v[4:5], v[4:5], v[6:7]
	s_nop 0
	v_pk_add_f32 v[22:23], v[2:3], v[4:5]
	global_load_dwordx4 v[2:5], v[12:13], off offset:1136
	global_load_dwordx4 v[6:9], v[12:13], off offset:1120
	global_load_dwordx4 v[18:21], v[12:13], off offset:1104
	s_nop 0
	global_load_dwordx4 v[12:15], v[12:13], off offset:1088
	s_waitcnt vmcnt(0)
	v_lshlrev_b32_e32 v0, 16, v12
	v_mul_f32_e32 v17, v0, v0
	v_fmamk_f32 v17, v17, 0xbdd2d3e7, v129
	v_mul_f32_e32 v17, v17, v0
	v_exp_f32_e32 v17, v17
	v_and_b32_e32 v36, 0xffff0000, v15
	v_add_f32_e32 v17, 1.0, v17
	v_rcp_f32_e32 v17, v17
	s_nop 0
	v_mul_f32_e32 v25, v17, v0
	v_and_b32_e32 v0, 0xffff0000, v12
	v_mul_f32_e32 v12, v0, v0
	v_fmamk_f32 v12, v12, 0xbdd2d3e7, v129
	v_mul_f32_e32 v12, v12, v0
	v_exp_f32_e32 v12, v12
	v_mul_f32_e32 v24, v25, v25
	v_add_f32_e32 v12, 1.0, v12
	v_rcp_f32_e32 v12, v12
	s_nop 0
	v_mul_f32_e32 v27, v12, v0
	v_lshlrev_b32_e32 v0, 16, v13
	v_mul_f32_e32 v12, v0, v0
	v_fmamk_f32 v12, v12, 0xbdd2d3e7, v129
	v_mul_f32_e32 v12, v12, v0
	v_exp_f32_e32 v12, v12
	v_mul_f32_e32 v26, v27, v27
	v_add_f32_e32 v12, 1.0, v12
	v_rcp_f32_e32 v12, v12
	s_nop 0
	v_mul_f32_e32 v29, v12, v0
	v_and_b32_e32 v0, 0xffff0000, v13
	v_mul_f32_e32 v12, v0, v0
	v_fmamk_f32 v12, v12, 0xbdd2d3e7, v129
	v_mul_f32_e32 v12, v12, v0
	v_exp_f32_e32 v12, v12
	v_mul_f32_e32 v28, v29, v29
	v_add_f32_e32 v12, 1.0, v12
	v_rcp_f32_e32 v12, v12
	s_nop 0
	v_mul_f32_e32 v13, v12, v0
	v_lshlrev_b32_e32 v0, 16, v14
	v_mul_f32_e32 v17, v0, v0
	v_fmamk_f32 v17, v17, 0xbdd2d3e7, v129
	v_mul_f32_e32 v17, v17, v0
	v_exp_f32_e32 v17, v17
	v_mul_f32_e32 v12, v13, v13
	v_pk_add_f32 v[12:13], v[28:29], v[12:13]
	v_add_f32_e32 v17, 1.0, v17
	v_rcp_f32_e32 v17, v17
	s_nop 0
	v_mul_f32_e32 v31, v17, v0
	v_and_b32_e32 v0, 0xffff0000, v14
	v_mul_f32_e32 v14, v0, v0
	v_fmamk_f32 v14, v14, 0xbdd2d3e7, v129
	v_mul_f32_e32 v14, v14, v0
	v_exp_f32_e32 v14, v14
	v_mul_f32_e32 v30, v31, v31
	v_add_f32_e32 v14, 1.0, v14
	v_rcp_f32_e32 v14, v14
	s_nop 0
	v_mul_f32_e32 v35, v14, v0
	v_lshlrev_b32_e32 v0, 16, v15
	v_mul_f32_e32 v14, v0, v0
	v_fmamk_f32 v14, v14, 0xbdd2d3e7, v129
	v_mul_f32_e32 v14, v14, v0
	v_exp_f32_e32 v14, v14
	v_mul_f32_e32 v34, v35, v35
	v_add_f32_e32 v14, 1.0, v14
	v_rcp_f32_e32 v17, v14
	v_mul_f32_e32 v14, v36, v36
	v_fmamk_f32 v14, v14, 0xbdd2d3e7, v129
	v_mul_f32_e32 v14, v14, v36
	v_exp_f32_e32 v14, v14
	s_nop 0
	v_add_f32_e32 v14, 1.0, v14
	v_rcp_f32_e32 v37, v14
	v_pk_add_f32 v[14:15], v[24:25], v[26:27]
	s_nop 0
	v_pk_add_f32 v[14:15], v[22:23], v[14:15]
	v_mul_f32_e32 v23, v37, v36
	v_pk_add_f32 v[12:13], v[14:15], v[12:13]
	v_pk_add_f32 v[14:15], v[30:31], v[34:35]
	v_mul_f32_e32 v22, v23, v23
	v_pk_add_f32 v[12:13], v[12:13], v[14:15]
	v_mul_f32_e32 v15, v17, v0
	v_mul_f32_e32 v14, v15, v15
	v_pk_add_f32 v[14:15], v[14:15], v[22:23]
	v_lshlrev_b32_e32 v0, 16, v18
	v_pk_add_f32 v[12:13], v[12:13], v[14:15]
	v_mul_f32_e32 v14, v0, v0
	v_fmamk_f32 v14, v14, 0xbdd2d3e7, v129
	v_mul_f32_e32 v14, v14, v0
	v_exp_f32_e32 v14, v14
	s_nop 0
	v_add_f32_e32 v14, 1.0, v14
	v_rcp_f32_e32 v14, v14
	s_nop 0
	v_mul_f32_e32 v15, v14, v0
	v_and_b32_e32 v0, 0xffff0000, v18
	v_mul_f32_e32 v14, v0, v0
	v_fmamk_f32 v14, v14, 0xbdd2d3e7, v129
	v_mul_f32_e32 v14, v14, v0
	v_exp_f32_e32 v14, v14
	s_nop 0
	v_add_f32_e32 v14, 1.0, v14
	v_rcp_f32_e32 v14, v14
	s_nop 0
	v_mul_f32_e32 v23, v14, v0
	v_lshlrev_b32_e32 v0, 16, v19
	v_mul_f32_e32 v17, v0, v0
	v_fmamk_f32 v17, v17, 0xbdd2d3e7, v129
	v_mul_f32_e32 v17, v17, v0
	v_exp_f32_e32 v17, v17
	v_mul_f32_e32 v14, v15, v15
	v_mul_f32_e32 v22, v23, v23
	v_pk_add_f32 v[14:15], v[14:15], v[22:23]
	v_add_f32_e32 v17, 1.0, v17
	v_rcp_f32_e32 v17, v17
	v_pk_add_f32 v[12:13], v[12:13], v[14:15]
	v_mul_f32_e32 v25, v17, v0
	v_and_b32_e32 v0, 0xffff0000, v19
	v_mul_f32_e32 v17, v0, v0
	v_fmamk_f32 v17, v17, 0xbdd2d3e7, v129
	v_mul_f32_e32 v17, v17, v0
	v_exp_f32_e32 v17, v17
	v_mul_f32_e32 v24, v25, v25
	v_add_f32_e32 v17, 1.0, v17
	v_rcp_f32_e32 v17, v17
	s_nop 0
	v_mul_f32_e32 v19, v17, v0
	v_lshlrev_b32_e32 v0, 16, v20
	v_mul_f32_e32 v17, v0, v0
	v_fmamk_f32 v17, v17, 0xbdd2d3e7, v129
	v_mul_f32_e32 v17, v17, v0
	v_exp_f32_e32 v17, v17
	v_mul_f32_e32 v18, v19, v19
	v_pk_add_f32 v[14:15], v[24:25], v[18:19]
	v_add_f32_e32 v17, 1.0, v17
	v_rcp_f32_e32 v17, v17
	v_pk_add_f32 v[12:13], v[12:13], v[14:15]
	v_mul_f32_e32 v27, v17, v0
	v_and_b32_e32 v0, 0xffff0000, v20
	v_mul_f32_e32 v17, v0, v0
	v_fmamk_f32 v17, v17, 0xbdd2d3e7, v129
	v_mul_f32_e32 v17, v17, v0
	v_exp_f32_e32 v17, v17
	v_and_b32_e32 v20, 0xffff0000, v21
	v_mul_f32_e32 v26, v27, v27
	v_add_f32_e32 v17, 1.0, v17
	v_rcp_f32_e32 v17, v17
	s_nop 0
	v_mul_f32_e32 v29, v17, v0
	v_lshlrev_b32_e32 v0, 16, v21
	v_mul_f32_e32 v17, v0, v0
	v_mul_f32_e32 v21, v20, v20
	v_fmamk_f32 v17, v17, 0xbdd2d3e7, v129
	v_fmamk_f32 v21, v21, 0xbdd2d3e7, v129
	v_mul_f32_e32 v17, v17, v0
	v_mul_f32_e32 v21, v21, v20
	v_exp_f32_e32 v17, v17
	v_exp_f32_e32 v21, v21
	v_mul_f32_e32 v28, v29, v29
	v_pk_add_f32 v[14:15], v[26:27], v[28:29]
	v_add_f32_e32 v17, 1.0, v17
	v_add_f32_e32 v21, 1.0, v21
	v_rcp_f32_e32 v17, v17
	v_rcp_f32_e32 v21, v21
	v_pk_add_f32 v[12:13], v[12:13], v[14:15]
	v_and_b32_e32 v26, 0xffff0000, v9
	v_mul_f32_e32 v15, v17, v0
	v_mul_f32_e32 v19, v21, v20
	v_mul_f32_e32 v14, v15, v15
	v_mul_f32_e32 v18, v19, v19
	v_pk_add_f32 v[14:15], v[14:15], v[18:19]
	v_lshlrev_b32_e32 v0, 16, v6
	v_pk_add_f32 v[12:13], v[12:13], v[14:15]
	v_mul_f32_e32 v14, v0, v0
	v_fmamk_f32 v14, v14, 0xbdd2d3e7, v129
	v_mul_f32_e32 v14, v14, v0
	v_exp_f32_e32 v14, v14
	s_nop 0
	v_add_f32_e32 v14, 1.0, v14
	v_rcp_f32_e32 v14, v14
	s_nop 0
	v_mul_f32_e32 v15, v14, v0
	v_and_b32_e32 v0, 0xffff0000, v6
	v_mul_f32_e32 v6, v0, v0
	v_fmamk_f32 v6, v6, 0xbdd2d3e7, v129
	v_mul_f32_e32 v6, v6, v0
	v_exp_f32_e32 v6, v6
	v_mul_f32_e32 v14, v15, v15
	v_add_f32_e32 v6, 1.0, v6
	v_rcp_f32_e32 v6, v6
	s_nop 0
	v_mul_f32_e32 v19, v6, v0
	v_lshlrev_b32_e32 v0, 16, v7
	v_mul_f32_e32 v6, v0, v0
	v_fmamk_f32 v6, v6, 0xbdd2d3e7, v129
	v_mul_f32_e32 v6, v6, v0
	v_exp_f32_e32 v6, v6
	v_mul_f32_e32 v18, v19, v19
	v_add_f32_e32 v6, 1.0, v6
	v_rcp_f32_e32 v6, v6
	s_nop 0
	v_mul_f32_e32 v21, v6, v0
	v_and_b32_e32 v0, 0xffff0000, v7
	v_mul_f32_e32 v6, v0, v0
	v_fmamk_f32 v6, v6, 0xbdd2d3e7, v129
	v_mul_f32_e32 v6, v6, v0
	v_exp_f32_e32 v6, v6
	v_mul_f32_e32 v20, v21, v21
	v_add_f32_e32 v6, 1.0, v6
	v_rcp_f32_e32 v6, v6
	s_nop 0
	v_mul_f32_e32 v7, v6, v0
	v_lshlrev_b32_e32 v0, 16, v8
	v_mul_f32_e32 v17, v0, v0
	v_fmamk_f32 v17, v17, 0xbdd2d3e7, v129
	v_mul_f32_e32 v17, v17, v0
	v_exp_f32_e32 v17, v17
	v_mul_f32_e32 v6, v7, v7
	v_pk_add_f32 v[6:7], v[20:21], v[6:7]
	v_add_f32_e32 v17, 1.0, v17
	v_rcp_f32_e32 v17, v17
	s_nop 0
	v_mul_f32_e32 v23, v17, v0
	v_and_b32_e32 v0, 0xffff0000, v8
	v_mul_f32_e32 v8, v0, v0
	v_fmamk_f32 v8, v8, 0xbdd2d3e7, v129
	v_mul_f32_e32 v8, v8, v0
	v_exp_f32_e32 v8, v8
	v_mul_f32_e32 v22, v23, v23
	v_add_f32_e32 v8, 1.0, v8
	v_rcp_f32_e32 v8, v8
	s_nop 0
	v_mul_f32_e32 v25, v8, v0
	v_lshlrev_b32_e32 v0, 16, v9
	v_mul_f32_e32 v8, v0, v0
	v_fmamk_f32 v8, v8, 0xbdd2d3e7, v129
	v_mul_f32_e32 v8, v8, v0
	v_exp_f32_e32 v8, v8
	v_mul_f32_e32 v24, v25, v25
	v_add_f32_e32 v8, 1.0, v8
	v_rcp_f32_e32 v17, v8
	v_mul_f32_e32 v8, v26, v26
	v_fmamk_f32 v8, v8, 0xbdd2d3e7, v129
	v_mul_f32_e32 v8, v8, v26
	v_exp_f32_e32 v8, v8
	s_nop 0
	v_add_f32_e32 v8, 1.0, v8
	v_rcp_f32_e32 v27, v8
	v_pk_add_f32 v[8:9], v[14:15], v[18:19]
	s_nop 0
	v_pk_add_f32 v[8:9], v[12:13], v[8:9]
	v_mul_f32_e32 v13, v27, v26
	v_pk_add_f32 v[6:7], v[8:9], v[6:7]
	v_pk_add_f32 v[8:9], v[22:23], v[24:25]
	v_mul_f32_e32 v12, v13, v13
	v_pk_add_f32 v[6:7], v[6:7], v[8:9]
	v_mul_f32_e32 v9, v17, v0
	v_mul_f32_e32 v8, v9, v9
	v_pk_add_f32 v[8:9], v[8:9], v[12:13]
	v_lshlrev_b32_e32 v0, 16, v2
	v_pk_add_f32 v[6:7], v[6:7], v[8:9]
	v_mul_f32_e32 v8, v0, v0
	v_fmamk_f32 v8, v8, 0xbdd2d3e7, v129
	v_mul_f32_e32 v8, v8, v0
	v_exp_f32_e32 v8, v8
	v_and_b32_e32 v22, 0xffff0000, v5
	v_add_f32_e32 v8, 1.0, v8
	v_rcp_f32_e32 v8, v8
	s_nop 0
	v_mul_f32_e32 v9, v8, v0
	v_and_b32_e32 v0, 0xffff0000, v2
	v_mul_f32_e32 v2, v0, v0
	v_fmamk_f32 v2, v2, 0xbdd2d3e7, v129
	v_mul_f32_e32 v2, v2, v0
	v_exp_f32_e32 v2, v2
	v_mul_f32_e32 v8, v9, v9
	v_add_f32_e32 v2, 1.0, v2
	v_rcp_f32_e32 v2, v2
	s_nop 0
	v_mul_f32_e32 v13, v2, v0
	v_lshlrev_b32_e32 v0, 16, v3
	v_mul_f32_e32 v2, v0, v0
	v_fmamk_f32 v2, v2, 0xbdd2d3e7, v129
	v_mul_f32_e32 v2, v2, v0
	v_exp_f32_e32 v2, v2
	v_mul_f32_e32 v12, v13, v13
	v_add_f32_e32 v2, 1.0, v2
	v_rcp_f32_e32 v2, v2
	s_nop 0
	v_mul_f32_e32 v15, v2, v0
	v_and_b32_e32 v0, 0xffff0000, v3
	v_mul_f32_e32 v2, v0, v0
	v_fmamk_f32 v2, v2, 0xbdd2d3e7, v129
	v_mul_f32_e32 v2, v2, v0
	v_exp_f32_e32 v2, v2
	v_mul_f32_e32 v14, v15, v15
	v_add_f32_e32 v2, 1.0, v2
	v_rcp_f32_e32 v2, v2
	s_nop 0
	v_mul_f32_e32 v3, v2, v0
	v_lshlrev_b32_e32 v0, 16, v4
	v_mul_f32_e32 v17, v0, v0
	v_fmamk_f32 v17, v17, 0xbdd2d3e7, v129
	v_mul_f32_e32 v17, v17, v0
	v_exp_f32_e32 v17, v17
	v_mul_f32_e32 v2, v3, v3
	v_pk_add_f32 v[2:3], v[14:15], v[2:3]
	v_add_f32_e32 v17, 1.0, v17
	v_rcp_f32_e32 v17, v17
	s_nop 0
	v_mul_f32_e32 v19, v17, v0
	v_and_b32_e32 v0, 0xffff0000, v4
	v_mul_f32_e32 v4, v0, v0
	v_fmamk_f32 v4, v4, 0xbdd2d3e7, v129
	v_mul_f32_e32 v4, v4, v0
	v_exp_f32_e32 v4, v4
	v_mul_f32_e32 v18, v19, v19
	v_add_f32_e32 v4, 1.0, v4
	v_rcp_f32_e32 v4, v4
	s_nop 0
	v_mul_f32_e32 v21, v4, v0
	v_lshlrev_b32_e32 v0, 16, v5
	v_mul_f32_e32 v4, v0, v0
	v_fmamk_f32 v4, v4, 0xbdd2d3e7, v129
	v_mul_f32_e32 v4, v4, v0
	v_exp_f32_e32 v4, v4
	v_mul_f32_e32 v20, v21, v21
	v_add_f32_e32 v4, 1.0, v4
	v_rcp_f32_e32 v17, v4
	v_mul_f32_e32 v4, v22, v22
	v_fmamk_f32 v4, v4, 0xbdd2d3e7, v129
	v_mul_f32_e32 v4, v4, v22
	v_exp_f32_e32 v4, v4
	s_nop 0
	v_add_f32_e32 v4, 1.0, v4
	v_rcp_f32_e32 v23, v4
	v_pk_add_f32 v[4:5], v[8:9], v[12:13]
	s_nop 0
	v_pk_add_f32 v[4:5], v[6:7], v[4:5]
	v_mul_f32_e32 v7, v23, v22
	v_pk_add_f32 v[2:3], v[4:5], v[2:3]
	v_pk_add_f32 v[4:5], v[18:19], v[20:21]
	v_mul_f32_e32 v6, v7, v7
	v_pk_add_f32 v[2:3], v[2:3], v[4:5]
	v_mul_f32_e32 v5, v17, v0
	v_mul_f32_e32 v4, v5, v5
	v_pk_add_f32 v[4:5], v[4:5], v[6:7]
	s_nop 0
	v_pk_add_f32 v[14:15], v[2:3], v[4:5]
	s_cbranch_scc1 .LBB0_608
	s_add_i32 s2, s77, 0xffffff80
	s_lshl_b32 s0, s2, 5
	v_readlane_b32 s40, v251, 54
	s_and_b32 s4, s0, 0x7fffff80
	v_readlane_b32 s46, v251, 60
	v_readlane_b32 s47, v251, 61
	v_or_b32_e32 v0, s4, v33
	v_lshlrev_b32_e32 v20, 8, v16
	v_mov_b64_e32 v[2:3], s[46:47]
	v_mad_u64_u32 v[2:3], s[0:1], v0, s3, v[2:3]
	s_lshl_b32 s0, s2, 7
	s_and_b32 s5, s0, 0x180
	s_lshl_b32 s2, s5, 2
	s_add_u32 s0, s9, s2
	s_addc_u32 s1, s11, 0
	s_add_u32 s6, s20, s2
	s_addc_u32 s7, s21, 0
	s_lshl_b32 s88, s5, 1
	v_lshl_add_u64 v[2:3], v[2:3], 0, s[88:89]
	v_lshlrev_b32_e32 v0, 7, v16
	v_lshl_add_u64 v[22:23], v[2:3], 0, v[0:1]
	global_load_dwordx4 v[10:13], v[22:23], off offset:1024
	global_load_dwordx2 v[28:29], v20, s[0:1]
	global_load_dwordx2 v[26:27], v20, s[6:7]
	global_load_dwordx2 v[38:39], v20, s[0:1] offset:16
	global_load_dwordx2 v[42:43], v20, s[0:1] offset:32
	global_load_dwordx2 v[24:25], v20, s[0:1] offset:48
	global_load_dwordx2 v[44:45], v20, s[6:7] offset:16
	global_load_dwordx2 v[46:47], v20, s[6:7] offset:32
	global_load_dwordx2 v[30:31], v20, s[6:7] offset:48
	v_xor_b32_e32 v3, 1, v234
	v_cmp_lt_i32_e32 vcc, v3, v235
	v_lshlrev_b32_e32 v36, 6, v16
	v_mul_u32_u24_e32 v2, 0x4400, v16
	v_lshlrev_b32_e32 v35, 1, v33
	v_cndmask_b32_e32 v3, v234, v3, vcc
	v_add3_u32 v41, s15, v2, v35
	v_or_b32_e32 v2, 1, v36
	v_lshlrev_b32_e32 v4, 2, v3
	v_mul_u32_u24_e32 v5, 0x110, v2
	ds_bpermute_b32 v3, v4, v15
	ds_bpermute_b32 v2, v4, v14
	s_mov_b32 s2, 0x3b000000
	v_add3_u32 v37, s15, v5, v35
	v_or_b32_e32 v78, 7, v36
	v_or_b32_e32 v80, 10, v36
	s_waitcnt lgkmcnt(0)
	v_pk_add_f32 v[2:3], v[14:15], v[2:3]
	v_or_b32_e32 v79, 11, v36
	v_pk_mul_f32 v[18:19], v[2:3], s[2:3] op_sel_hi:[1,0]
	v_readlane_b32 s48, v251, 62
	v_fma_f32 v2, -v19, v19, v18
	v_max_f32_e32 v2, 0, v2
	v_add_f32_e32 v2, 0x358637bd, v2
	v_mul_f32_e32 v3, 0x4b800000, v2
	v_cmp_gt_f32_e32 vcc, s69, v2
	v_readlane_b32 s49, v251, 63
	v_readlane_b32 s50, v252, 0
	v_cndmask_b32_e32 v2, v2, v3, vcc
	v_rsq_f32_e32 v18, v2
	global_load_dwordx4 v[14:17], v[22:23], off offset:1040
	global_load_dwordx4 v[2:5], v[22:23], off offset:1072
	global_load_dwordx4 v[6:9], v[22:23], off offset:1056
	v_readlane_b32 s51, v252, 1
	v_readlane_b32 s52, v252, 2
	v_mul_f32_e32 v40, 0x45800000, v18
	v_cndmask_b32_e32 v40, v18, v40, vcc
	v_readlane_b32 s53, v252, 3
	v_readlane_b32 s54, v252, 4
	v_readlane_b32 s55, v252, 5
	s_or_b32 s12, s5, s8
	v_readlane_b32 s48, v251, 22
	v_readlane_b32 s49, v251, 23
	v_mov_b32_e32 v21, v1
	v_mul_u32_u24_e32 v83, 0x110, v33
	v_add3_u32 v0, s15, v83, v0
	v_or_b32_e32 v100, 31, v36
	v_cmp_gt_u32_e32 vcc, v33, v36
	v_or_b32_e32 v57, 48, v36
	v_and_b32_e32 v34, 15, v50
	s_mov_b32 s13, s89
	v_readlane_b32 s50, v251, 24
	v_readlane_b32 s51, v251, 25
	v_readlane_b32 s41, v251, 55
	v_readlane_b32 s42, v251, 56
	v_readlane_b32 s43, v251, 57
	v_readlane_b32 s44, v251, 58
	v_readlane_b32 s45, v251, 59
	v_readlane_b32 s52, v251, 26
	v_readlane_b32 s53, v251, 27
	v_readlane_b32 s54, v251, 28
	v_readlane_b32 s55, v251, 29
	v_readlane_b32 s56, v251, 30
	v_readlane_b32 s57, v251, 31
	v_readlane_b32 s58, v251, 32
	v_readlane_b32 s59, v251, 33
	v_readlane_b32 s60, v251, 34
	v_readlane_b32 s61, v251, 35
	v_readlane_b32 s62, v251, 36
	v_readlane_b32 s63, v251, 37
	s_waitcnt vmcnt(11)
	v_lshlrev_b32_e32 v48, 16, v11
	v_and_b32_e32 v11, 0xffff0000, v11
	v_mul_f32_e32 v54, v11, v11
	v_fmamk_f32 v54, v54, 0xbdd2d3e7, v129
	v_lshlrev_b32_e32 v18, 16, v10
	v_mul_f32_e32 v54, v54, v11
	v_and_b32_e32 v10, 0xffff0000, v10
	v_mul_f32_e32 v51, v18, v18
	v_mul_f32_e32 v52, v10, v10
	v_fmamk_f32 v51, v51, 0xbdd2d3e7, v129
	v_fmamk_f32 v52, v52, 0xbdd2d3e7, v129
	v_mul_f32_e32 v51, v51, v18
	v_exp_f32_e32 v54, v54
	v_mul_f32_e32 v52, v52, v10
	v_exp_f32_e32 v51, v51
	v_exp_f32_e32 v52, v52
	v_add_f32_e32 v54, 1.0, v54
	v_rcp_f32_e32 v54, v54
	v_lshlrev_b32_e32 v49, 16, v12
	v_mul_f32_e32 v55, v49, v49
	v_add_f32_e32 v51, 1.0, v51
	v_fmamk_f32 v55, v55, 0xbdd2d3e7, v129
	v_add_f32_e32 v52, 1.0, v52
	v_rcp_f32_e32 v51, v51
	v_mul_f32_e32 v55, v55, v49
	v_rcp_f32_e32 v52, v52
	v_fma_f32 v11, v54, v11, -v19
	v_mul_f32_e32 v59, v40, v11
	v_and_b32_e32 v11, 0xffff0000, v12
	v_mul_f32_e32 v12, v11, v11
	v_exp_f32_e32 v55, v55
	v_fma_f32 v18, v51, v18, -v19
	v_fmamk_f32 v12, v12, 0xbdd2d3e7, v129
	v_fma_f32 v10, v52, v10, -v19
	v_mul_f32_e32 v18, v40, v18
	v_mul_f32_e32 v12, v12, v11
	v_mul_f32_e32 v10, v40, v10
	s_waitcnt vmcnt(9)
	v_fma_f32 v18, v28, v18, v26
	v_fmac_f32_e32 v27, v29, v10
	v_cvt_pk_bf16_f32 v10, v18, s0
	v_lshlrev_b32_e32 v26, 16, v13
	v_cvt_pk_bf16_f32 v18, v27, s0
	ds_write_b16 v41, v10 offset:34816
	ds_write_b16 v37, v18 offset:34816
	v_add_f32_e32 v10, 1.0, v55
	v_exp_f32_e32 v12, v12
	v_mul_f32_e32 v27, v26, v26
	v_rcp_f32_e32 v10, v10
	v_fmamk_f32 v27, v27, 0xbdd2d3e7, v129
	v_mul_f32_e32 v27, v27, v26
	v_add_f32_e32 v12, 1.0, v12
	v_fma_f32 v10, v10, v49, -v19
	v_rcp_f32_e32 v12, v12
	v_exp_f32_e32 v27, v27
	v_mul_f32_e32 v10, v40, v10
	s_waitcnt vmcnt(5)
	v_fma_f32 v10, v38, v10, v44
	v_cvt_pk_bf16_f32 v10, v10, s0
	ds_write_b16 v37, v10 offset:35632
	v_fma_f32 v10, v12, v11, -v19
	v_add_f32_e32 v11, 1.0, v27
	v_rcp_f32_e32 v11, v11
	v_mul_f32_e32 v10, v40, v10
	v_fmac_f32_e32 v45, v10, v39
	v_cvt_pk_bf16_f32 v10, v45, s0
	ds_write_b16 v37, v10 offset:35904
	v_fma_f32 v10, v11, v26, -v19
	v_and_b32_e32 v11, 0xffff0000, v13
	v_mul_f32_e32 v12, v11, v11
	v_fmamk_f32 v12, v12, 0xbdd2d3e7, v129
	v_mul_f32_e32 v12, v12, v11
	v_exp_f32_e32 v12, v12
	s_waitcnt vmcnt(2)
	v_lshlrev_b32_e32 v13, 16, v14
	v_mul_f32_e32 v26, v13, v13
	v_fmamk_f32 v26, v26, 0xbdd2d3e7, v129
	v_add_f32_e32 v12, 1.0, v12
	v_rcp_f32_e32 v12, v12
	v_mul_f32_e32 v26, v26, v13
	v_fma_f32 v11, v12, v11, -v19
	v_exp_f32_e32 v26, v26
	v_mul_f32_e32 v44, v40, v11
	v_and_b32_e32 v11, 0xffff0000, v14
	v_mul_f32_e32 v12, v11, v11
	v_fmamk_f32 v12, v12, 0xbdd2d3e7, v129
	v_mul_f32_e32 v12, v12, v11
	v_mul_f32_e32 v45, v40, v10
	v_add_f32_e32 v10, 1.0, v26
	v_rcp_f32_e32 v10, v10
	v_exp_f32_e32 v12, v12
	v_lshlrev_b32_e32 v27, 16, v16
	v_fma_f32 v10, v10, v13, -v19
	v_lshlrev_b32_e32 v13, 16, v15
	v_add_f32_e32 v12, 1.0, v12
	v_mul_f32_e32 v14, v13, v13
	v_rcp_f32_e32 v12, v12
	v_fmamk_f32 v14, v14, 0xbdd2d3e7, v129
	v_mul_f32_e32 v10, v40, v10
	v_mul_f32_e32 v14, v14, v13
	v_fma_f32 v10, v42, v10, v46
	v_cvt_pk_bf16_f32 v10, v10, s0
	v_exp_f32_e32 v14, v14
	ds_write_b16 v37, v10 offset:36720
	v_fma_f32 v10, v12, v11, -v19
	v_mul_f32_e32 v10, v40, v10
	v_fmac_f32_e32 v47, v43, v10
	v_cvt_pk_bf16_f32 v10, v47, s0
	v_and_b32_e32 v15, 0xffff0000, v15
	v_add_f32_e32 v11, 1.0, v14
	ds_write_b16 v37, v10 offset:36992
	v_mul_f32_e32 v10, v15, v15
	v_rcp_f32_e32 v11, v11
	v_fmamk_f32 v10, v10, 0xbdd2d3e7, v129
	v_mul_f32_e32 v10, v10, v15
	v_fma_f32 v14, v11, v13, -v19
	v_exp_f32_e32 v26, v10
	global_load_dwordx2 v[10:11], v20, s[0:1] offset:64
	global_load_dwordx2 v[12:13], v20, s[6:7] offset:64
	v_mul_f32_e32 v28, v27, v27
	v_fmamk_f32 v28, v28, 0xbdd2d3e7, v129
	v_add_f32_e32 v26, 1.0, v26
	v_mul_f32_e32 v28, v28, v27
	v_rcp_f32_e32 v26, v26
	v_exp_f32_e32 v28, v28
	v_fma_f32 v15, v26, v15, -v19
	v_mul_f32_e32 v46, v40, v15
	v_and_b32_e32 v15, 0xffff0000, v16
	v_mul_f32_e32 v16, v15, v15
	v_mul_f32_e32 v47, v40, v14
	v_add_f32_e32 v14, 1.0, v28
	v_fmamk_f32 v16, v16, 0xbdd2d3e7, v129
	v_rcp_f32_e32 v14, v14
	v_mul_f32_e32 v16, v16, v15
	v_exp_f32_e32 v16, v16
	v_fma_f32 v14, v14, v27, -v19
	v_mul_f32_e32 v14, v40, v14
	v_fma_f32 v14, v24, v14, v30
	v_lshlrev_b32_e32 v24, 16, v17
	v_add_f32_e32 v16, 1.0, v16
	v_mul_f32_e32 v26, v24, v24
	v_rcp_f32_e32 v16, v16
	v_fmamk_f32 v26, v26, 0xbdd2d3e7, v129
	v_mul_f32_e32 v26, v26, v24
	v_cvt_pk_bf16_f32 v14, v14, s0
	v_exp_f32_e32 v26, v26
	ds_write_b16 v37, v14 offset:37808
	v_fma_f32 v14, v16, v15, -v19
	v_mul_f32_e32 v14, v40, v14
	v_fmac_f32_e32 v31, v14, v25
	v_cvt_pk_bf16_f32 v14, v31, s0
	v_and_b32_e32 v25, 0xffff0000, v17
	v_add_f32_e32 v15, 1.0, v26
	ds_write_b16 v37, v14 offset:38080
	v_mul_f32_e32 v14, v25, v25
	v_rcp_f32_e32 v15, v15
	v_fmamk_f32 v14, v14, 0xbdd2d3e7, v129
	v_mul_f32_e32 v14, v14, v25
	v_fma_f32 v24, v15, v24, -v19
	v_exp_f32_e32 v26, v14
	global_load_dwordx2 v[14:15], v20, s[0:1] offset:80
	global_load_dwordx2 v[16:17], v20, s[6:7] offset:80
	s_waitcnt vmcnt(4)
	v_lshlrev_b32_e32 v27, 16, v6
	v_mul_f32_e32 v28, v27, v27
	v_fmamk_f32 v28, v28, 0xbdd2d3e7, v129
	v_mul_f32_e32 v28, v28, v27
	v_exp_f32_e32 v28, v28
	v_mul_f32_e32 v55, v40, v24
	v_mul_f32_e32 v53, v48, v48
	v_fmamk_f32 v53, v53, 0xbdd2d3e7, v129
	v_add_f32_e32 v24, 1.0, v28
	v_rcp_f32_e32 v24, v24
	v_and_b32_e32 v6, 0xffff0000, v6
	v_mul_f32_e32 v53, v53, v48
	v_fma_f32 v24, v24, v27, -v19
	v_mul_f32_e32 v31, v40, v24
	v_mul_f32_e32 v24, v6, v6
	v_fmamk_f32 v24, v24, 0xbdd2d3e7, v129
	v_mul_f32_e32 v24, v24, v6
	v_exp_f32_e32 v53, v53
	v_exp_f32_e32 v41, v24
	v_add_f32_e32 v53, 1.0, v53
	v_add_f32_e32 v26, 1.0, v26
	v_rcp_f32_e32 v53, v53
	v_rcp_f32_e32 v26, v26
	s_waitcnt vmcnt(2)
	v_fma_f32 v10, v10, v31, v12
	v_lshlrev_b32_e32 v31, 16, v7
	v_add_f32_e32 v12, 1.0, v41
	v_mul_f32_e32 v41, v31, v31
	v_fmamk_f32 v41, v41, 0xbdd2d3e7, v129
	v_mul_f32_e32 v41, v41, v31
	v_fma_f32 v48, v53, v48, -v19
	v_fma_f32 v25, v26, v25, -v19
	v_mul_f32_e32 v65, v40, v48
	v_mul_f32_e32 v54, v40, v25
	global_load_dwordx2 v[24:25], v20, s[0:1] offset:96
	global_load_dwordx2 v[28:29], v20, s[0:1] offset:112
	global_load_dwordx2 v[26:27], v20, s[6:7] offset:96
	global_load_dwordx2 v[48:49], v20, s[6:7] offset:112
	v_exp_f32_e32 v41, v41
	v_rcp_f32_e32 v12, v12
	v_cvt_pk_bf16_f32 v10, v10, s0
	ds_write_b16 v37, v10 offset:38896
	v_add_f32_e32 v10, 1.0, v41
	v_fma_f32 v6, v12, v6, -v19
	v_rcp_f32_e32 v10, v10
	v_mul_f32_e32 v6, v40, v6
	v_fmac_f32_e32 v13, v11, v6
	v_cvt_pk_bf16_f32 v6, v13, s0
	v_and_b32_e32 v7, 0xffff0000, v7
	ds_write_b16 v37, v6 offset:39168
	v_fma_f32 v6, v10, v31, -v19
	v_mul_f32_e32 v10, v7, v7
	v_fmamk_f32 v10, v10, 0xbdd2d3e7, v129
	v_mul_f32_e32 v10, v10, v7
	v_exp_f32_e32 v10, v10
	v_lshlrev_b32_e32 v11, 16, v8
	v_mul_f32_e32 v12, v11, v11
	v_fmamk_f32 v12, v12, 0xbdd2d3e7, v129
	v_mul_f32_e32 v12, v12, v11
	v_add_f32_e32 v10, 1.0, v10
	v_rcp_f32_e32 v10, v10
	v_exp_f32_e32 v12, v12
	v_mul_f32_e32 v53, v40, v6
	v_fma_f32 v7, v10, v7, -v19
	v_mul_f32_e32 v52, v40, v7
	v_and_b32_e32 v7, 0xffff0000, v8
	v_add_f32_e32 v6, 1.0, v12
	v_mul_f32_e32 v8, v7, v7
	v_rcp_f32_e32 v6, v6
	v_fmamk_f32 v8, v8, 0xbdd2d3e7, v129
	v_mul_f32_e32 v8, v8, v7
	v_lshlrev_b32_e32 v10, 16, v9
	v_fma_f32 v6, v6, v11, -v19
	v_exp_f32_e32 v8, v8
	v_mul_f32_e32 v11, v10, v10
	v_fmamk_f32 v11, v11, 0xbdd2d3e7, v129
	v_mul_f32_e32 v11, v11, v10
	v_add_f32_e32 v8, 1.0, v8
	v_rcp_f32_e32 v8, v8
	v_exp_f32_e32 v11, v11
	v_mul_f32_e32 v6, v40, v6
	s_waitcnt vmcnt(4)
	v_fma_f32 v6, v14, v6, v16
	v_cvt_pk_bf16_f32 v6, v6, s0
	ds_write_b16 v37, v6 offset:39984
	v_fma_f32 v6, v8, v7, -v19
	v_add_f32_e32 v7, 1.0, v11
	v_rcp_f32_e32 v7, v7
	v_mul_f32_e32 v6, v40, v6
	v_fmac_f32_e32 v17, v6, v15
	v_cvt_pk_bf16_f32 v6, v17, s0
	ds_write_b16 v37, v6 offset:40256
	v_fma_f32 v6, v7, v10, -v19
	v_and_b32_e32 v7, 0xffff0000, v9
	v_lshlrev_b32_e32 v9, 16, v2
	v_mul_f32_e32 v10, v9, v9
	v_fmamk_f32 v10, v10, 0xbdd2d3e7, v129
	v_mul_f32_e32 v8, v7, v7
	v_mul_f32_e32 v10, v10, v9
	v_fmamk_f32 v8, v8, 0xbdd2d3e7, v129
	v_mul_f32_e32 v8, v8, v7
	v_exp_f32_e32 v10, v10
	v_exp_f32_e32 v8, v8
	v_mul_f32_e32 v58, v40, v6
	v_add_f32_e32 v6, 1.0, v10
	global_load_dwordx4 v[10:13], v[22:23], off offset:1104
	global_load_dwordx4 v[14:17], v[22:23], off offset:1088
	v_add_f32_e32 v8, 1.0, v8
	v_rcp_f32_e32 v8, v8
	v_and_b32_e32 v2, 0xffff0000, v2
	v_rcp_f32_e32 v6, v6
	v_or_b32_e32 v18, 4, v36
	v_fma_f32 v7, v8, v7, -v19
	v_mul_f32_e32 v56, v40, v7
	v_mul_f32_e32 v7, v2, v2
	v_fmamk_f32 v7, v7, 0xbdd2d3e7, v129
	v_mul_f32_e32 v7, v7, v2
	v_exp_f32_e32 v7, v7
	v_lshlrev_b32_e32 v8, 16, v3
	v_fma_f32 v6, v6, v9, -v19
	v_mul_f32_e32 v9, v8, v8
	v_add_f32_e32 v7, 1.0, v7
	v_rcp_f32_e32 v7, v7
	v_fmamk_f32 v9, v9, 0xbdd2d3e7, v129
	v_mul_f32_e32 v9, v9, v8
	v_fma_f32 v2, v7, v2, -v19
	v_mul_f32_e32 v6, v40, v6
	v_mul_f32_e32 v2, v40, v2
	s_waitcnt vmcnt(3)
	v_fma_f32 v6, v24, v6, v26
	v_exp_f32_e32 v9, v9
	v_fmac_f32_e32 v27, v25, v2
	v_cvt_pk_bf16_f32 v6, v6, s0
	v_cvt_pk_bf16_f32 v2, v27, s0
	ds_write_b16 v37, v6 offset:41072
	ds_write_b16 v37, v2 offset:41344
	global_load_dwordx2 v[24:25], v20, s[0:1] offset:128
	global_load_dwordx2 v[26:27], v20, s[6:7] offset:128
	v_add_f32_e32 v6, 1.0, v9
	v_rcp_f32_e32 v6, v6
	v_and_b32_e32 v3, 0xffff0000, v3
	v_lshlrev_b32_e32 v7, 16, v4
	v_or_b32_e32 v38, 8, v36
	v_fma_f32 v2, v6, v8, -v19
	v_mul_f32_e32 v6, v3, v3
	v_fmamk_f32 v6, v6, 0xbdd2d3e7, v129
	v_mul_f32_e32 v6, v6, v3
	v_exp_f32_e32 v6, v6
	v_mul_f32_e32 v8, v7, v7
	v_fmamk_f32 v8, v8, 0xbdd2d3e7, v129
	v_mul_f32_e32 v8, v8, v7
	v_add_f32_e32 v6, 1.0, v6
	v_rcp_f32_e32 v6, v6
	v_exp_f32_e32 v8, v8
	v_mul_f32_e32 v64, v40, v2
	v_fma_f32 v3, v6, v3, -v19
	v_mul_f32_e32 v63, v40, v3
	v_and_b32_e32 v3, 0xffff0000, v4
	v_add_f32_e32 v2, 1.0, v8
	v_mul_f32_e32 v4, v3, v3
	v_rcp_f32_e32 v2, v2
	v_fmamk_f32 v4, v4, 0xbdd2d3e7, v129
	v_mul_f32_e32 v4, v4, v3
	v_fma_f32 v2, v2, v7, -v19
	v_exp_f32_e32 v4, v4
	v_mul_f32_e32 v2, v40, v2
	s_waitcnt vmcnt(4)
	v_fma_f32 v2, v28, v2, v48
	v_cvt_pk_bf16_f32 v2, v2, s0
	ds_write_b16 v37, v2 offset:42160
	v_add_f32_e32 v2, 1.0, v4
	v_lshlrev_b32_e32 v4, 16, v5
	v_mul_f32_e32 v6, v4, v4
	v_fmamk_f32 v6, v6, 0xbdd2d3e7, v129
	v_rcp_f32_e32 v2, v2
	v_mul_f32_e32 v6, v6, v4
	v_exp_f32_e32 v6, v6
	v_fma_f32 v2, v2, v3, -v19
	v_mul_f32_e32 v2, v40, v2
	v_fmac_f32_e32 v49, v2, v29
	v_add_f32_e32 v2, 1.0, v6
	v_cvt_pk_bf16_f32 v6, v49, s0
	ds_write_b16 v37, v6 offset:42432
	global_load_dwordx2 v[60:61], v20, s[0:1] offset:144
	global_load_dwordx2 v[66:67], v20, s[6:7] offset:144
	v_and_b32_e32 v3, 0xffff0000, v5
	v_mul_f32_e32 v5, v3, v3
	v_fmamk_f32 v5, v5, 0xbdd2d3e7, v129
	v_mul_f32_e32 v5, v5, v3
	v_rcp_f32_e32 v2, v2
	v_exp_f32_e32 v5, v5
	s_waitcnt vmcnt(4)
	v_lshlrev_b32_e32 v28, 16, v14
	v_and_b32_e32 v14, 0xffff0000, v14
	v_fma_f32 v2, v2, v4, -v19
	v_add_f32_e32 v4, 1.0, v5
	v_mul_f32_e32 v5, v28, v28
	v_fmamk_f32 v5, v5, 0xbdd2d3e7, v129
	v_mul_f32_e32 v5, v5, v28
	v_rcp_f32_e32 v4, v4
	v_exp_f32_e32 v5, v5
	v_mul_f32_e32 v69, v40, v2
	v_fma_f32 v2, v4, v3, -v19
	v_mul_f32_e32 v68, v40, v2
	v_add_f32_e32 v2, 1.0, v5
	v_rcp_f32_e32 v29, v2
	global_load_dwordx4 v[2:5], v[22:23], off offset:1136
	global_load_dwordx4 v[6:9], v[22:23], off offset:1120
	v_or_b32_e32 v39, 12, v36
	v_or_b32_e32 v30, 16, v36
	v_fma_f32 v22, v29, v28, -v19
	v_mul_f32_e32 v48, v40, v22
	v_mul_f32_e32 v22, v14, v14
	v_fmamk_f32 v22, v22, 0xbdd2d3e7, v129
	v_mul_f32_e32 v22, v22, v14
	v_exp_f32_e32 v49, v22
	global_load_dwordx2 v[74:75], v20, s[0:1] offset:160
	global_load_dwordx2 v[22:23], v20, s[0:1] offset:176
	global_load_dwordx2 v[76:77], v20, s[6:7] offset:160
	global_load_dwordx2 v[28:29], v20, s[6:7] offset:176
	s_waitcnt vmcnt(8)
	v_fma_f32 v24, v24, v48, v26
	v_lshlrev_b32_e32 v48, 16, v15
	v_add_f32_e32 v26, 1.0, v49
	v_mul_f32_e32 v49, v48, v48
	v_fmamk_f32 v49, v49, 0xbdd2d3e7, v129
	v_mul_f32_e32 v49, v49, v48
	v_exp_f32_e32 v49, v49
	v_rcp_f32_e32 v26, v26
	v_cvt_pk_bf16_f32 v24, v24, s0
	ds_write_b16 v37, v24 offset:43248
	v_add_f32_e32 v24, 1.0, v49
	v_fma_f32 v14, v26, v14, -v19
	v_rcp_f32_e32 v24, v24
	v_mul_f32_e32 v14, v40, v14
	v_fmac_f32_e32 v27, v25, v14
	v_cvt_pk_bf16_f32 v14, v27, s0
	v_and_b32_e32 v15, 0xffff0000, v15
	ds_write_b16 v37, v14 offset:43520
	v_fma_f32 v14, v24, v48, -v19
	v_mul_f32_e32 v24, v15, v15
	v_fmamk_f32 v24, v24, 0xbdd2d3e7, v129
	v_mul_f32_e32 v24, v24, v15
	v_exp_f32_e32 v24, v24
	v_lshlrev_b32_e32 v25, 16, v16
	v_mul_f32_e32 v26, v25, v25
	v_fmamk_f32 v26, v26, 0xbdd2d3e7, v129
	v_mul_f32_e32 v26, v26, v25
	v_add_f32_e32 v24, 1.0, v24
	v_rcp_f32_e32 v24, v24
	v_exp_f32_e32 v26, v26
	v_mul_f32_e32 v73, v40, v14
	v_fma_f32 v15, v24, v15, -v19
	v_mul_f32_e32 v72, v40, v15
	v_and_b32_e32 v15, 0xffff0000, v16
	v_add_f32_e32 v14, 1.0, v26
	v_mul_f32_e32 v16, v15, v15
	v_rcp_f32_e32 v14, v14
	v_fmamk_f32 v16, v16, 0xbdd2d3e7, v129
	v_mul_f32_e32 v16, v16, v15
	v_lshlrev_b32_e32 v24, 16, v17
	v_fma_f32 v14, v14, v25, -v19
	v_exp_f32_e32 v16, v16
	v_mul_f32_e32 v25, v24, v24
	v_fmamk_f32 v25, v25, 0xbdd2d3e7, v129
	v_mul_f32_e32 v25, v25, v24
	v_add_f32_e32 v16, 1.0, v16
	v_rcp_f32_e32 v16, v16
	v_exp_f32_e32 v25, v25
	v_mul_f32_e32 v14, v40, v14
	s_waitcnt vmcnt(6)
	v_fma_f32 v14, v60, v14, v66
	v_cvt_pk_bf16_f32 v14, v14, s0
	ds_write_b16 v37, v14 offset:44336
	v_fma_f32 v14, v16, v15, -v19
	v_add_f32_e32 v15, 1.0, v25
	v_rcp_f32_e32 v15, v15
	v_mul_f32_e32 v14, v40, v14
	v_fmac_f32_e32 v67, v14, v61
	v_cvt_pk_bf16_f32 v14, v67, s0
	ds_write_b16 v37, v14 offset:44608
	v_fma_f32 v14, v15, v24, -v19
	v_and_b32_e32 v15, 0xffff0000, v17
	v_mul_f32_e32 v16, v15, v15
	v_fmamk_f32 v16, v16, 0xbdd2d3e7, v129
	v_mul_f32_e32 v16, v16, v15
	v_exp_f32_e32 v16, v16
	v_lshlrev_b32_e32 v17, 16, v10
	v_mul_f32_e32 v24, v17, v17
	v_fmamk_f32 v24, v24, 0xbdd2d3e7, v129
	v_mul_f32_e32 v24, v24, v17
	v_add_f32_e32 v16, 1.0, v16
	v_rcp_f32_e32 v16, v16
	v_exp_f32_e32 v24, v24
	v_and_b32_e32 v10, 0xffff0000, v10
	v_mul_f32_e32 v71, v40, v14
	v_fma_f32 v15, v16, v15, -v19
	v_add_f32_e32 v14, 1.0, v24
	v_mul_f32_e32 v70, v40, v15
	v_mul_f32_e32 v15, v10, v10
	v_rcp_f32_e32 v14, v14
	v_fmamk_f32 v15, v15, 0xbdd2d3e7, v129
	v_mul_f32_e32 v15, v15, v10
	v_fma_f32 v14, v14, v17, -v19
	v_exp_f32_e32 v15, v15
	v_mul_f32_e32 v14, v40, v14
	s_waitcnt vmcnt(1)
	v_fma_f32 v14, v74, v14, v76
	v_cvt_pk_bf16_f32 v14, v14, s0
	ds_write_b16 v37, v14 offset:45424
	v_add_f32_e32 v14, 1.0, v15
	v_lshlrev_b32_e32 v15, 16, v11
	v_rcp_f32_e32 v14, v14
	v_mul_f32_e32 v16, v15, v15
	v_fmamk_f32 v16, v16, 0xbdd2d3e7, v129
	v_mul_f32_e32 v16, v16, v15
	v_and_b32_e32 v11, 0xffff0000, v11
	v_fma_f32 v10, v14, v10, -v19
	v_mul_f32_e32 v14, v11, v11
	v_exp_f32_e32 v16, v16
	v_fmamk_f32 v14, v14, 0xbdd2d3e7, v129
	v_mul_f32_e32 v14, v14, v11
	v_mul_f32_e32 v10, v40, v10
	v_fmac_f32_e32 v77, v75, v10
	v_add_f32_e32 v10, 1.0, v16
	v_exp_f32_e32 v14, v14
	v_rcp_f32_e32 v10, v10
	v_cvt_pk_bf16_f32 v16, v77, s0
	ds_write_b16 v37, v16 offset:45696
	v_add_f32_e32 v14, 1.0, v14
	v_fma_f32 v10, v10, v15, -v19
	v_rcp_f32_e32 v14, v14
	v_lshlrev_b32_e32 v15, 16, v12
	v_mul_f32_e32 v16, v15, v15
	v_fmamk_f32 v16, v16, 0xbdd2d3e7, v129
	v_mul_f32_e32 v16, v16, v15
	v_mul_f32_e32 v67, v40, v10
	v_fma_f32 v10, v14, v11, -v19
	v_and_b32_e32 v11, 0xffff0000, v12
	v_mul_f32_e32 v12, v11, v11
	v_exp_f32_e32 v16, v16
	v_fmamk_f32 v12, v12, 0xbdd2d3e7, v129
	v_mul_f32_e32 v12, v12, v11
	v_mul_f32_e32 v66, v40, v10
	v_add_f32_e32 v10, 1.0, v16
	v_exp_f32_e32 v12, v12
	v_rcp_f32_e32 v10, v10
	v_or_b32_e32 v76, 2, v36
	v_lshlrev_b32_e32 v14, 2, v76
	v_add_f32_e32 v12, 1.0, v12
	v_fma_f32 v10, v10, v15, -v19
	v_rcp_f32_e32 v12, v12
	v_mul_f32_e32 v10, v40, v10
	s_waitcnt vmcnt(0)
	v_fma_f32 v10, v22, v10, v28
	v_cvt_pk_bf16_f32 v10, v10, s0
	ds_write_b16 v37, v10 offset:46512
	v_fma_f32 v10, v12, v11, -v19
	v_lshlrev_b32_e32 v11, 16, v13
	v_mul_f32_e32 v12, v11, v11
	v_fmamk_f32 v12, v12, 0xbdd2d3e7, v129
	v_mul_f32_e32 v12, v12, v11
	v_exp_f32_e32 v12, v12
	v_mul_f32_e32 v10, v40, v10
	v_fmac_f32_e32 v29, v10, v23
	v_cvt_pk_bf16_f32 v10, v29, s0
	global_load_dword v15, v14, s[0:1]
	s_nop 0
	global_load_dword v14, v14, s[6:7]
	ds_write_b16 v37, v10 offset:46784
	v_add_f32_e32 v10, 1.0, v12
	v_rcp_f32_e32 v10, v10
	v_or_b32_e32 v77, 3, v36
	v_lshlrev_b32_e32 v12, 2, v77
	global_load_dword v16, v12, s[0:1]
	global_load_dword v17, v12, s[6:7]
	v_fma_f32 v10, v10, v11, -v19
	v_and_b32_e32 v11, 0xffff0000, v13
	v_mul_f32_e32 v12, v11, v11
	v_fmamk_f32 v12, v12, 0xbdd2d3e7, v129
	v_mul_f32_e32 v12, v12, v11
	v_lshlrev_b32_e32 v13, 16, v6
	v_exp_f32_e32 v12, v12
	v_mul_f32_e32 v22, v13, v13
	v_fmamk_f32 v22, v22, 0xbdd2d3e7, v129
	v_mul_f32_e32 v22, v22, v13
	v_add_f32_e32 v12, 1.0, v12
	v_exp_f32_e32 v22, v22
	v_rcp_f32_e32 v12, v12
	v_mul_f32_e32 v75, v40, v10
	v_and_b32_e32 v6, 0xffff0000, v6
	v_add_f32_e32 v10, 1.0, v22
	v_fma_f32 v11, v12, v11, -v19
	v_rcp_f32_e32 v10, v10
	v_mul_f32_e32 v74, v40, v11
	v_mul_f32_e32 v11, v6, v6
	v_fmamk_f32 v11, v11, 0xbdd2d3e7, v129
	v_mul_f32_e32 v11, v11, v6
	v_fma_f32 v10, v10, v13, -v19
	v_exp_f32_e32 v22, v11
	v_mul_f32_e32 v81, v40, v10
	global_load_dwordx2 v[10:11], v20, s[0:1] offset:192
	global_load_dwordx2 v[12:13], v20, s[6:7] offset:192
	v_lshlrev_b32_e32 v23, 16, v7
	v_mul_f32_e32 v24, v23, v23
	v_and_b32_e32 v7, 0xffff0000, v7
	v_fmamk_f32 v24, v24, 0xbdd2d3e7, v129
	v_mul_f32_e32 v25, v7, v7
	v_mul_f32_e32 v24, v24, v23
	v_fmamk_f32 v25, v25, 0xbdd2d3e7, v129
	v_mul_f32_e32 v25, v25, v7
	v_add_f32_e32 v22, 1.0, v22
	v_rcp_f32_e32 v22, v22
	v_exp_f32_e32 v24, v24
	v_exp_f32_e32 v25, v25
	v_fma_f32 v6, v22, v6, -v19
	v_add_f32_e32 v22, 1.0, v24
	v_rcp_f32_e32 v22, v22
	v_add_f32_e32 v24, 1.0, v25
	v_rcp_f32_e32 v24, v24
	v_mul_f32_e32 v82, v40, v6
	v_fma_f32 v6, v22, v23, -v19
	v_mul_f32_e32 v62, v40, v6
	v_fma_f32 v6, v24, v7, -v19
	v_lshlrev_b32_e32 v90, 16, v8
	v_mul_f32_e32 v61, v40, v6
	v_or_b32_e32 v6, s12, v33
	v_lshlrev_b32_e32 v6, 7, v6
	v_mov_b32_e32 v7, v1
	v_lshl_add_u64 v[6:7], v[6:7], 2, s[48:49]
	v_lshl_add_u64 v[6:7], v[6:7], 0, v[20:21]
	v_and_b32_e32 v8, 0xffff0000, v8
	v_mul_f32_e32 v97, v8, v8
	v_fmamk_f32 v97, v97, 0xbdd2d3e7, v129
	v_mul_f32_e32 v97, v97, v8
	v_exp_f32_e32 v97, v97
	v_and_b32_e32 v98, 0xffff0000, v9
	v_and_b32_e32 v104, 0xffff0000, v5
	s_waitcnt vmcnt(4)
	v_fmac_f32_e32 v14, v15, v65
	v_mul_u32_u24_e32 v15, 0x110, v76
	v_cvt_pk_bf16_f32 v14, v14, s0
	v_add3_u32 v15, s15, v15, v35
	v_or_b32_e32 v65, 6, v36
	ds_write_b16 v15, v14 offset:34816
	v_lshlrev_b32_e32 v14, 2, v65
	global_load_dword v84, v14, s[0:1]
	global_load_dword v85, v14, s[6:7]
	s_waitcnt vmcnt(4)
	v_fmac_f32_e32 v17, v16, v59
	v_lshlrev_b32_e32 v14, 2, v78
	v_mul_u32_u24_e32 v15, 0x110, v77
	global_load_dword v86, v14, s[0:1]
	global_load_dword v87, v14, s[6:7]
	v_cvt_pk_bf16_f32 v14, v17, s0
	v_add3_u32 v15, s15, v15, v35
	ds_write_b16 v15, v14 offset:34816
	v_lshlrev_b32_e32 v14, 2, v80
	global_load_dwordx2 v[22:23], v20, s[0:1] offset:208
	global_load_dwordx2 v[24:25], v20, s[6:7] offset:208
	global_load_dword v88, v14, s[0:1]
	global_load_dword v89, v14, s[6:7]
	v_lshlrev_b32_e32 v14, 2, v79
	global_load_dword v91, v14, s[0:1]
	global_load_dword v92, v14, s[6:7]
	v_mul_f32_e32 v14, v90, v90
	v_fmamk_f32 v14, v14, 0xbdd2d3e7, v129
	v_mul_f32_e32 v14, v14, v90
	v_or_b32_e32 v59, 14, v36
	v_lshlrev_b32_e32 v15, 2, v59
	global_load_dword v93, v15, s[0:1]
	global_load_dword v94, v15, s[6:7]
	v_exp_f32_e32 v95, v14
	global_load_dwordx2 v[14:15], v20, s[0:1] offset:224
	global_load_dwordx2 v[16:17], v20, s[0:1] offset:240
	global_load_dwordx2 v[26:27], v20, s[6:7] offset:224
	s_nop 0
	global_load_dwordx2 v[20:21], v20, s[6:7] offset:240
	v_or_b32_e32 v31, 20, v36
	v_or_b32_e32 v41, 24, v36
	v_or_b32_e32 v42, 28, v36
	v_or_b32_e32 v43, 32, v36
	v_or_b32_e32 v48, 36, v36
	v_or_b32_e32 v49, 40, v36
	v_or_b32_e32 v51, 44, v36
	v_or_b32_e32 v60, 52, v36
	s_waitcnt vmcnt(16)
	v_fma_f32 v10, v10, v81, v12
	v_cvt_pk_bf16_f32 v12, v10, s0
	v_or_b32_e32 v10, 15, v36
	v_add_f32_e32 v81, 1.0, v95
	v_lshlrev_b32_e32 v95, 2, v10
	global_load_dword v96, v95, s[0:1]
	s_nop 0
	global_load_dword v95, v95, s[6:7]
	v_rcp_f32_e32 v81, v81
	ds_write_b16 v37, v12 offset:47600
	v_fmac_f32_e32 v13, v11, v82
	v_cvt_pk_bf16_f32 v11, v13, s0
	v_fma_f32 v12, v81, v90, -v19
	v_lshlrev_b32_e32 v90, 16, v9
	v_add_f32_e32 v81, 1.0, v97
	v_mul_f32_e32 v97, v90, v90
	v_fmamk_f32 v97, v97, 0xbdd2d3e7, v129
	v_mul_f32_e32 v97, v97, v90
	v_rcp_f32_e32 v81, v81
	v_exp_f32_e32 v97, v97
	v_mul_f32_e32 v12, v40, v12
	v_mul_u32_u24_e32 v13, 0x110, v80
	v_fma_f32 v8, v81, v8, -v19
	v_add_f32_e32 v81, 1.0, v97
	v_rcp_f32_e32 v81, v81
	v_mul_f32_e32 v99, v40, v8
	v_add3_u32 v13, s15, v13, v35
	v_mul_f32_e32 v9, v98, v98
	v_fma_f32 v8, v81, v90, -v19
	v_mul_u32_u24_e32 v81, 0x110, v65
	v_add3_u32 v81, s15, v81, v35
	v_fmamk_f32 v9, v9, 0xbdd2d3e7, v129
	v_mul_f32_e32 v9, v9, v98
	v_exp_f32_e32 v9, v9
	v_or_b32_e32 v90, 26, v36
	v_or_b32_e32 v29, 56, v36
	v_or_b32_e32 v28, 60, v36
	v_add_f32_e32 v9, 1.0, v9
	v_rcp_f32_e32 v97, v9
	v_mul_f32_e32 v9, v40, v8
	v_fma_f32 v8, v97, v98, -v19
	v_or_b32_e32 v97, 30, v36
	v_mul_f32_e32 v8, v40, v8
	s_waitcnt vmcnt(16)
	v_fmac_f32_e32 v85, v45, v84
	v_cvt_pk_bf16_f32 v45, v85, s0
	ds_write_b16 v81, v45 offset:34816
	v_mul_u32_u24_e32 v45, 0x110, v78
	s_waitcnt vmcnt(14)
	v_fmac_f32_e32 v87, v44, v86
	v_cvt_pk_bf16_f32 v44, v87, s0
	v_add3_u32 v45, s15, v45, v35
	ds_write_b16 v45, v44 offset:34816
	ds_write_b16 v37, v11 offset:47872
	s_waitcnt vmcnt(12)
	v_fma_f32 v11, v22, v12, v24
	s_waitcnt vmcnt(10)
	v_fmac_f32_e32 v89, v88, v47
	v_cvt_pk_bf16_f32 v12, v89, s0
	ds_write_b16 v13, v12 offset:34816
	s_waitcnt vmcnt(8)
	v_fmac_f32_e32 v92, v91, v46
	v_mul_u32_u24_e32 v13, 0x110, v79
	v_cvt_pk_bf16_f32 v12, v92, s0
	v_add3_u32 v13, s15, v13, v35
	v_cvt_pk_bf16_f32 v11, v11, s0
	ds_write_b16 v13, v12 offset:34816
	ds_write_b16 v37, v11 offset:48688
	v_lshlrev_b32_e32 v13, 16, v2
	v_mul_f32_e32 v22, v13, v13
	v_fmamk_f32 v22, v22, 0xbdd2d3e7, v129
	v_mul_f32_e32 v22, v22, v13
	v_exp_f32_e32 v22, v22
	v_fmac_f32_e32 v25, v99, v23
	v_cvt_pk_bf16_f32 v11, v25, s0
	s_waitcnt vmcnt(6)
	v_fmac_f32_e32 v94, v55, v93
	v_mul_u32_u24_e32 v12, 0x110, v59
	ds_write_b16 v37, v11 offset:48960
	v_cvt_pk_bf16_f32 v11, v94, s0
	v_add3_u32 v12, s15, v12, v35
	ds_write_b16 v12, v11 offset:34816
	v_add_f32_e32 v12, 1.0, v22
	v_rcp_f32_e32 v12, v12
	s_waitcnt vmcnt(0)
	v_fmac_f32_e32 v95, v54, v96
	v_mul_u32_u24_e32 v22, 0x110, v10
	v_cvt_pk_bf16_f32 v11, v95, s0
	v_add3_u32 v22, s15, v22, v35
	v_and_b32_e32 v2, 0xffff0000, v2
	ds_write_b16 v22, v11 offset:34816
	v_fma_f32 v11, v12, v13, -v19
	v_mul_f32_e32 v12, v2, v2
	v_lshlrev_b32_e32 v13, 16, v3
	v_fmamk_f32 v12, v12, 0xbdd2d3e7, v129
	v_mul_f32_e32 v22, v13, v13
	v_mul_f32_e32 v12, v12, v2
	v_fmamk_f32 v22, v22, 0xbdd2d3e7, v129
	v_mul_f32_e32 v22, v22, v13
	v_exp_f32_e32 v12, v12
	v_exp_f32_e32 v22, v22
	v_mul_f32_e32 v11, v40, v11
	v_add_f32_e32 v12, 1.0, v12
	v_fma_f32 v11, v14, v11, v26
	v_rcp_f32_e32 v12, v12
	v_add_f32_e32 v14, 1.0, v22
	v_rcp_f32_e32 v14, v14
	v_and_b32_e32 v3, 0xffff0000, v3
	v_fma_f32 v2, v12, v2, -v19
	v_mul_f32_e32 v12, v40, v2
	v_fma_f32 v2, v14, v13, -v19
	v_mul_f32_e32 v13, v3, v3
	v_fmamk_f32 v13, v13, 0xbdd2d3e7, v129
	v_mul_f32_e32 v13, v13, v3
	v_or_b32_e32 v81, 18, v36
	v_or_b32_e32 v86, 19, v36
	v_lshlrev_b32_e32 v14, 2, v81
	v_lshlrev_b32_e32 v22, 2, v86
	global_load_dword v26, v14, s[0:1]
	s_nop 0
	global_load_dword v14, v14, s[6:7]
	s_nop 0
	global_load_dword v54, v22, s[0:1]
	global_load_dword v55, v22, s[6:7]
	v_lshlrev_b32_e32 v22, 16, v4
	v_exp_f32_e32 v13, v13
	v_mul_f32_e32 v23, v22, v22
	v_fmamk_f32 v23, v23, 0xbdd2d3e7, v129
	v_mul_f32_e32 v23, v23, v22
	v_add_f32_e32 v13, 1.0, v13
	v_rcp_f32_e32 v13, v13
	v_exp_f32_e32 v23, v23
	v_or_b32_e32 v87, 22, v36
	v_lshlrev_b32_e32 v24, 2, v87
	v_fma_f32 v3, v13, v3, -v19
	v_add_f32_e32 v13, 1.0, v23
	global_load_dword v82, v24, s[0:1]
	global_load_dword v83, v24, s[6:7]
	v_or_b32_e32 v88, 23, v36
	v_rcp_f32_e32 v13, v13
	v_and_b32_e32 v4, 0xffff0000, v4
	v_lshlrev_b32_e32 v24, 2, v88
	v_mul_f32_e32 v23, v4, v4
	global_load_dword v84, v24, s[0:1]
	global_load_dword v85, v24, s[6:7]
	v_fmamk_f32 v23, v23, 0xbdd2d3e7, v129
	v_mul_f32_e32 v23, v23, v4
	v_fma_f32 v13, v13, v22, -v19
	v_lshlrev_b32_e32 v22, 2, v90
	global_load_dword v91, v22, s[0:1]
	global_load_dword v92, v22, s[6:7]
	v_or_b32_e32 v93, 27, v36
	v_exp_f32_e32 v23, v23
	v_lshlrev_b32_e32 v22, 2, v93
	global_load_dword v94, v22, s[0:1]
	global_load_dword v95, v22, s[6:7]
	v_lshlrev_b32_e32 v96, 16, v5
	v_lshlrev_b32_e32 v22, 2, v97
	global_load_dword v98, v22, s[0:1]
	global_load_dword v99, v22, s[6:7]
	v_mul_f32_e32 v22, 0x3d372713, v96
	v_mul_f32_e32 v89, v40, v13
	v_add_f32_e32 v13, 1.0, v23
	v_lshlrev_b32_e32 v23, 2, v100
	v_mul_f32_e32 v22, v22, v96
	global_load_dword v101, v23, s[0:1]
	global_load_dword v102, v23, s[6:7]
	v_fma_f32 v22, v22, v96, v96
	v_mul_f32_e32 v22, 0xbfcc422a, v22
	v_mul_f32_e32 v103, 0x3fb8aa3b, v22
	global_load_dwordx4 v[22:25], v[6:7], off offset:16
	global_load_dwordx4 v[44:47], v[6:7], off
	v_rcp_f32_e32 v13, v13
	v_exp_f32_e32 v103, v103
	v_mul_f32_e32 v5, v104, v104
	v_fmamk_f32 v5, v5, 0xbdd2d3e7, v129
	v_mul_f32_e32 v5, v5, v104
	v_fma_f32 v4, v13, v4, -v19
	v_add_f32_e32 v13, 1.0, v103
	v_rcp_f32_e32 v13, v13
	v_exp_f32_e32 v5, v5
	v_mul_f32_e32 v105, v40, v4
	v_cvt_pk_bf16_f32 v11, v11, s0
	v_fma_f32 v4, v13, v96, -v19
	v_add_f32_e32 v5, 1.0, v5
	v_rcp_f32_e32 v103, v5
	v_fmac_f32_e32 v27, v15, v12
	v_mul_f32_e32 v5, v40, v4
	v_fma_f32 v16, v16, v89, v20
	v_fma_f32 v4, v103, v104, -v19
	v_mul_u32_u24_e32 v19, 0x110, v87
	v_add3_u32 v19, s15, v19, v35
	v_cvt_pk_bf16_f32 v16, v16, s0
	v_fmac_f32_e32 v21, v105, v17
	v_mul_f32_e32 v2, v40, v2
	v_mul_f32_e32 v3, v40, v3
	v_mul_f32_e32 v4, v40, v4
	v_mul_u32_u24_e32 v17, 0x110, v90
	v_add3_u32 v17, s15, v17, v35
	s_waitcnt vmcnt(16)
	v_fmac_f32_e32 v14, v26, v53
	v_cvt_pk_bf16_f32 v13, v14, s0
	v_mul_u32_u24_e32 v14, 0x110, v81
	v_add3_u32 v14, s15, v14, v35
	ds_write_b16 v14, v13 offset:34816
	s_waitcnt vmcnt(14)
	v_fmac_f32_e32 v55, v54, v52
	v_mul_u32_u24_e32 v14, 0x110, v86
	v_cvt_pk_bf16_f32 v13, v55, s0
	v_add3_u32 v14, s15, v14, v35
	ds_write_b16 v14, v13 offset:34816
	ds_write_b16 v37, v11 offset:49776
	v_cvt_pk_bf16_f32 v11, v27, s0
	ds_write_b16 v37, v11 offset:50048
	global_load_dwordx4 v[12:15], v[6:7], off offset:48
	global_load_dwordx4 v[52:55], v[6:7], off offset:32
	s_waitcnt vmcnt(14)
	v_fmac_f32_e32 v83, v58, v82
	v_cvt_pk_bf16_f32 v11, v83, s0
	ds_write_b16 v19, v11 offset:34816
	v_mul_u32_u24_e32 v19, 0x110, v88
	v_add3_u32 v19, s15, v19, v35
	v_or_b32_e32 v58, 35, v36
	s_waitcnt vmcnt(12)
	v_fmac_f32_e32 v85, v56, v84
	v_cvt_pk_bf16_f32 v11, v85, s0
	v_or_b32_e32 v56, 34, v36
	ds_write_b16 v19, v11 offset:34816
	v_lshlrev_b32_e32 v11, 2, v56
	v_lshlrev_b32_e32 v19, 2, v58
	global_load_dword v40, v11, s[0:1]
	s_nop 0
	global_load_dword v11, v11, s[6:7]
	s_nop 0
	global_load_dword v89, v19, s[0:1]
	global_load_dword v96, v19, s[6:7]
	ds_write_b16 v37, v16 offset:50864
	v_cvt_pk_bf16_f32 v16, v21, s0
	s_waitcnt vmcnt(14)
	v_fmac_f32_e32 v92, v91, v64
	ds_write_b16 v37, v16 offset:51136
	v_cvt_pk_bf16_f32 v16, v92, s0
	ds_write_b16 v17, v16 offset:34816
	s_waitcnt vmcnt(12)
	v_fmac_f32_e32 v95, v94, v63
	v_mul_u32_u24_e32 v17, 0x110, v93
	v_cvt_pk_bf16_f32 v16, v95, s0
	v_add3_u32 v17, s15, v17, v35
	ds_write_b16 v17, v16 offset:34816
	s_waitcnt vmcnt(10)
	v_fmac_f32_e32 v99, v69, v98
	v_mul_u32_u24_e32 v17, 0x110, v97
	v_cvt_pk_bf16_f32 v16, v99, s0
	v_add3_u32 v17, s15, v17, v35
	ds_write_b16 v17, v16 offset:34816
	s_waitcnt vmcnt(8)
	v_fmac_f32_e32 v102, v68, v101
	v_mul_u32_u24_e32 v17, 0x110, v100
	v_cvt_pk_bf16_f32 v16, v102, s0
	v_add3_u32 v17, s15, v17, v35
	ds_write_b16 v17, v16 offset:34816
	s_waitcnt vmcnt(6)
	v_cndmask_b32_e32 v16, 0, v45, vcc
	v_cmp_le_u32_e32 vcc, v36, v33
	v_or_b32_e32 v37, 38, v36
	v_or_b32_e32 v68, 39, v36
	v_cndmask_b32_e32 v17, 0, v44, vcc
	v_cvt_pk_bf16_f32 v16, v17, v16
	v_lshlrev_b32_e32 v17, 2, v37
	global_load_dword v63, v17, s[0:1]
	global_load_dword v64, v17, s[6:7]
	v_lshlrev_b32_e32 v19, 2, v68
	global_load_dword v69, v19, s[0:1]
	global_load_dword v91, v19, s[6:7]
	v_cvt_pk_bf16_f32 v17, v46, v47
	v_cmp_le_u32_e32 vcc, v76, v33
	global_load_dwordx4 v[44:47], v[6:7], off offset:80
	global_load_dwordx4 v[82:85], v[6:7], off offset:64
	v_cndmask_b32_e32 v19, 0, v17, vcc
	v_lshrrev_b32_e32 v17, 16, v17
	v_cmp_le_u32_e32 vcc, v77, v33
	v_or_b32_e32 v76, 43, v36
	s_waitcnt vmcnt(8)
	v_fmac_f32_e32 v11, v40, v73
	v_cndmask_b32_e32 v17, 0, v17, vcc
	v_cmp_gt_u32_e32 vcc, v33, v18
	v_perm_b32 v17, v17, v19, s19
	v_cvt_pk_bf16_f32 v11, v11, s0
	v_cndmask_b32_e32 v19, 0, v23, vcc
	v_cmp_le_u32_e32 vcc, v18, v33
	s_waitcnt vmcnt(6)
	v_fmac_f32_e32 v96, v89, v72
	v_or_b32_e32 v89, 47, v36
	v_cndmask_b32_e32 v18, 0, v22, vcc
	v_cvt_pk_bf16_f32 v18, v18, v19
	v_cvt_pk_bf16_f32 v19, v24, v25
	v_cmp_le_u32_e32 vcc, v65, v33
	v_or_b32_e32 v65, 42, v36
	s_waitcnt vmcnt(4)
	v_fmac_f32_e32 v64, v71, v63
	v_cndmask_b32_e32 v20, 0, v19, vcc
	v_lshrrev_b32_e32 v19, 16, v19
	v_cmp_le_u32_e32 vcc, v78, v33
	s_waitcnt vmcnt(2)
	v_fmac_f32_e32 v91, v70, v69
	v_cndmask_b32_e32 v19, 0, v19, vcc
	v_perm_b32 v19, v19, v20, s19
	ds_write_b128 v0, v[16:19]
	global_load_dwordx4 v[20:23], v[6:7], off offset:112
	global_load_dwordx4 v[24:27], v[6:7], off offset:96
	v_cmp_gt_u32_e32 vcc, v33, v38
	v_lshlrev_b32_e32 v19, 2, v76
	s_nop 0
	v_cndmask_b32_e32 v16, 0, v53, vcc
	v_cmp_le_u32_e32 vcc, v38, v33
	s_nop 1
	v_cndmask_b32_e32 v17, 0, v52, vcc
	v_cvt_pk_bf16_f32 v16, v17, v16
	v_cvt_pk_bf16_f32 v17, v54, v55
	v_cmp_le_u32_e32 vcc, v80, v33
	s_nop 1
	v_cndmask_b32_e32 v18, 0, v17, vcc
	v_lshrrev_b32_e32 v17, 16, v17
	v_cmp_le_u32_e32 vcc, v79, v33
	s_nop 1
	v_cndmask_b32_e32 v17, 0, v17, vcc
	v_perm_b32 v17, v17, v18, s19
	v_mul_u32_u24_e32 v18, 0x110, v56
	v_add3_u32 v18, s15, v18, v35
	ds_write_b16 v18, v11 offset:34816
	v_lshlrev_b32_e32 v18, 2, v65
	global_load_dword v72, v18, s[0:1]
	global_load_dword v73, v18, s[6:7]
	v_mul_u32_u24_e32 v18, 0x110, v58
	v_cvt_pk_bf16_f32 v11, v96, s0
	v_add3_u32 v18, s15, v18, v35
	v_cmp_gt_u32_e32 vcc, v33, v39
	global_load_dword v77, v19, s[0:1]
	global_load_dword v78, v19, s[6:7]
	ds_write_b16 v18, v11 offset:34816
	v_cndmask_b32_e32 v11, 0, v13, vcc
	v_cmp_le_u32_e32 vcc, v39, v33
	s_waitcnt vmcnt(2)
	v_fmac_f32_e32 v73, v72, v67
	v_cndmask_b32_e32 v12, 0, v12, vcc
	v_cvt_pk_bf16_f32 v18, v12, v11
	v_cvt_pk_bf16_f32 v11, v14, v15
	v_cmp_le_u32_e32 vcc, v59, v33
	v_or_b32_e32 v59, 46, v36
	s_waitcnt vmcnt(0)
	v_fmac_f32_e32 v78, v77, v66
	v_cndmask_b32_e32 v12, 0, v11, vcc
	v_lshrrev_b32_e32 v11, 16, v11
	v_cmp_le_u32_e32 vcc, v10, v33
	s_nop 1
	v_cndmask_b32_e32 v10, 0, v11, vcc
	v_perm_b32 v19, v10, v12, s19
	v_lshlrev_b32_e32 v10, 2, v59
	global_load_dword v79, v10, s[0:1]
	global_load_dword v80, v10, s[6:7]
	ds_write_b128 v0, v[16:19] offset:16
	v_lshlrev_b32_e32 v10, 2, v89
	v_mul_u32_u24_e32 v11, 0x110, v37
	global_load_dword v92, v10, s[0:1]
	global_load_dword v94, v10, s[6:7]
	v_cvt_pk_bf16_f32 v10, v64, s0
	v_add3_u32 v11, s15, v11, v35
	ds_write_b16 v11, v10 offset:34816
	global_load_dwordx4 v[10:13], v[6:7], off offset:144
	global_load_dwordx4 v[14:17], v[6:7], off offset:128
	v_mul_u32_u24_e32 v19, 0x110, v68
	v_cvt_pk_bf16_f32 v18, v91, s0
	v_add3_u32 v19, s15, v19, v35
	v_cmp_gt_u32_e32 vcc, v33, v30
	ds_write_b16 v19, v18 offset:34816
	s_waitcnt vmcnt(4)
	v_fmac_f32_e32 v80, v75, v79
	v_cndmask_b32_e32 v18, 0, v83, vcc
	v_cmp_le_u32_e32 vcc, v30, v33
	v_and_or_b32 v83, v32, 64, v34
	s_waitcnt vmcnt(2)
	v_fmac_f32_e32 v94, v74, v92
	v_cndmask_b32_e32 v19, 0, v82, vcc
	v_cvt_pk_bf16_f32 v52, v19, v18
	v_cvt_pk_bf16_f32 v18, v84, v85
	v_cmp_le_u32_e32 vcc, v81, v33
	s_nop 1
	v_cndmask_b32_e32 v19, 0, v18, vcc
	v_lshrrev_b32_e32 v18, 16, v18
	v_cmp_le_u32_e32 vcc, v86, v33
	s_nop 1
	v_cndmask_b32_e32 v18, 0, v18, vcc
	v_cmp_gt_u32_e32 vcc, v33, v31
	v_perm_b32 v53, v18, v19, s19
	s_nop 0
	v_cndmask_b32_e32 v18, 0, v45, vcc
	v_cmp_le_u32_e32 vcc, v31, v33
	v_mul_u32_u24_e32 v31, 0x110, v65
	v_add3_u32 v31, s15, v31, v35
	v_cndmask_b32_e32 v19, 0, v44, vcc
	v_cvt_pk_bf16_f32 v54, v19, v18
	v_cvt_pk_bf16_f32 v18, v46, v47
	v_cmp_le_u32_e32 vcc, v87, v33
	s_nop 1
	v_cndmask_b32_e32 v19, 0, v18, vcc
	v_lshrrev_b32_e32 v18, 16, v18
	v_cmp_le_u32_e32 vcc, v88, v33
	s_nop 1
	v_cndmask_b32_e32 v18, 0, v18, vcc
	v_cmp_gt_u32_e32 vcc, v33, v41
	v_perm_b32 v55, v18, v19, s19
	ds_write_b128 v0, v[52:55] offset:32
	v_cndmask_b32_e32 v18, 0, v25, vcc
	v_cmp_le_u32_e32 vcc, v41, v33
	s_nop 1
	v_cndmask_b32_e32 v19, 0, v24, vcc
	v_cvt_pk_bf16_f32 v18, v19, v18
	v_cvt_pk_bf16_f32 v19, v26, v27
	global_load_dwordx4 v[24:27], v[6:7], off offset:176
	global_load_dwordx4 v[38:41], v[6:7], off offset:160
	v_cmp_le_u32_e32 vcc, v90, v33
	s_nop 1
	v_cndmask_b32_e32 v30, 0, v19, vcc
	v_lshrrev_b32_e32 v19, 16, v19
	v_cmp_le_u32_e32 vcc, v93, v33
	s_nop 1
	v_cndmask_b32_e32 v19, 0, v19, vcc
	v_cmp_gt_u32_e32 vcc, v33, v42
	v_perm_b32 v19, v19, v30, s19
	v_cvt_pk_bf16_f32 v30, v73, s0
	v_cndmask_b32_e32 v21, 0, v21, vcc
	v_cmp_le_u32_e32 vcc, v42, v33
	ds_write_b16 v31, v30 offset:34816
	v_mul_u32_u24_e32 v31, 0x110, v76
	v_cndmask_b32_e32 v20, 0, v20, vcc
	v_cvt_pk_bf16_f32 v20, v20, v21
	v_cvt_pk_bf16_f32 v21, v22, v23
	v_cmp_le_u32_e32 vcc, v97, v33
	v_cvt_pk_bf16_f32 v30, v78, s0
	v_add3_u32 v31, s15, v31, v35
	v_cndmask_b32_e32 v22, 0, v21, vcc
	v_lshrrev_b32_e32 v21, 16, v21
	v_cmp_le_u32_e32 vcc, v100, v33
	ds_write_b16 v31, v30 offset:34816
	v_mul_u32_u24_e32 v23, 0x110, v89
	v_cndmask_b32_e32 v21, 0, v21, vcc
	v_perm_b32 v21, v21, v22, s19
	ds_write_b128 v0, v[18:21] offset:48
	v_mul_u32_u24_e32 v19, 0x110, v59
	v_cvt_pk_bf16_f32 v18, v80, s0
	v_add3_u32 v19, s15, v19, v35
	v_cmp_gt_u32_e32 vcc, v33, v43
	ds_write_b16 v19, v18 offset:34816
	v_cvt_pk_bf16_f32 v22, v94, s0
	v_add3_u32 v23, s15, v23, v35
	s_waitcnt vmcnt(2)
	v_cndmask_b32_e32 v15, 0, v15, vcc
	v_cmp_le_u32_e32 vcc, v43, v33
	global_load_dwordx4 v[18:21], v[6:7], off offset:208
	global_load_dwordx4 v[44:47], v[6:7], off offset:192
	ds_write_b16 v23, v22 offset:34816
	v_cndmask_b32_e32 v14, 0, v14, vcc
	v_or_b32_e32 v23, 50, v36
	v_cvt_pk_bf16_f32 v14, v14, v15
	v_cvt_pk_bf16_f32 v15, v16, v17
	v_or_b32_e32 v22, 51, v36
	v_lshlrev_b32_e32 v17, 2, v23
	v_cmp_le_u32_e32 vcc, v56, v33
	global_load_dword v30, v17, s[0:1]
	global_load_dword v31, v17, s[6:7]
	v_lshlrev_b32_e32 v17, 2, v22
	v_cndmask_b32_e32 v16, 0, v15, vcc
	v_lshrrev_b32_e32 v15, 16, v15
	global_load_dword v42, v17, s[0:1]
	global_load_dword v43, v17, s[6:7]
	v_cmp_le_u32_e32 vcc, v58, v33
	v_or_b32_e32 v56, 58, v36
	s_waitcnt vmcnt(2)
	v_fmac_f32_e32 v31, v30, v62
	v_cndmask_b32_e32 v15, 0, v15, vcc
	v_cmp_gt_u32_e32 vcc, v33, v48
	v_perm_b32 v15, v15, v16, s19
	s_waitcnt vmcnt(0)
	v_fmac_f32_e32 v43, v42, v61
	v_cndmask_b32_e32 v11, 0, v11, vcc
	v_cmp_le_u32_e32 vcc, v48, v33
	v_or_b32_e32 v48, 54, v36
	s_nop 0
	v_cndmask_b32_e32 v10, 0, v10, vcc
	v_cvt_pk_bf16_f32 v16, v10, v11
	v_cvt_pk_bf16_f32 v10, v12, v13
	v_cmp_le_u32_e32 vcc, v37, v33
	v_or_b32_e32 v37, 55, v36
	s_nop 0
	v_cndmask_b32_e32 v11, 0, v10, vcc
	v_lshrrev_b32_e32 v10, 16, v10
	v_cmp_le_u32_e32 vcc, v68, v33
	s_nop 1
	v_cndmask_b32_e32 v10, 0, v10, vcc
	v_perm_b32 v17, v10, v11, s19
	v_lshlrev_b32_e32 v10, 2, v48
	global_load_dword v52, v10, s[0:1]
	global_load_dword v53, v10, s[6:7]
	v_lshlrev_b32_e32 v10, 2, v37
	global_load_dword v54, v10, s[0:1]
	global_load_dword v55, v10, s[6:7]
	v_cmp_gt_u32_e32 vcc, v33, v49
	ds_write_b128 v0, v[14:17] offset:64
	s_waitcnt vmcnt(2)
	v_fmac_f32_e32 v53, v9, v52
	v_cndmask_b32_e32 v10, 0, v39, vcc
	v_cmp_le_u32_e32 vcc, v49, v33
	v_or_b32_e32 v49, 59, v36
	v_cvt_pk_bf16_f32 v9, v53, s0
	v_cndmask_b32_e32 v11, 0, v38, vcc
	v_cvt_pk_bf16_f32 v10, v11, v10
	v_cvt_pk_bf16_f32 v11, v40, v41
	v_cmp_le_u32_e32 vcc, v65, v33
	global_load_dwordx4 v[14:17], v[6:7], off offset:240
	global_load_dwordx4 v[38:41], v[6:7], off offset:224
	v_cndmask_b32_e32 v12, 0, v11, vcc
	v_lshrrev_b32_e32 v11, 16, v11
	v_cmp_le_u32_e32 vcc, v76, v33
	s_waitcnt vmcnt(2)
	v_fmac_f32_e32 v55, v8, v54
	v_cndmask_b32_e32 v6, 0, v11, vcc
	v_perm_b32 v11, v6, v12, s19
	v_lshlrev_b32_e32 v6, 2, v56
	global_load_dword v58, v6, s[0:1]
	global_load_dword v63, v6, s[6:7]
	v_lshlrev_b32_e32 v6, 2, v49
	v_cmp_gt_u32_e32 vcc, v33, v51
	global_load_dword v64, v6, s[0:1]
	global_load_dword v65, v6, s[6:7]
	v_cndmask_b32_e32 v6, 0, v25, vcc
	v_cmp_le_u32_e32 vcc, v51, v33
	s_waitcnt vmcnt(2)
	v_fmac_f32_e32 v63, v58, v2
	v_cndmask_b32_e32 v7, 0, v24, vcc
	v_cvt_pk_bf16_f32 v12, v7, v6
	v_cvt_pk_bf16_f32 v6, v26, v27
	v_cmp_le_u32_e32 vcc, v59, v33
	v_mul_u32_u24_e32 v26, 0x110, v22
	v_cvt_pk_bf16_f32 v27, v31, s0
	v_cndmask_b32_e32 v7, 0, v6, vcc
	v_lshrrev_b32_e32 v6, 16, v6
	v_cmp_le_u32_e32 vcc, v89, v33
	v_add3_u32 v26, s15, v26, v35
	v_cvt_pk_bf16_f32 v2, v63, s0
	v_cndmask_b32_e32 v6, 0, v6, vcc
	v_perm_b32 v13, v6, v7, s19
	ds_write_b128 v0, v[10:13] offset:80
	v_or_b32_e32 v11, 62, v36
	v_or_b32_e32 v10, 63, v36
	v_lshlrev_b32_e32 v7, 2, v11
	global_load_dword v12, v7, s[0:1]
	global_load_dword v13, v7, s[6:7]
	v_lshlrev_b32_e32 v7, 2, v10
	global_load_dword v24, v7, s[0:1]
	global_load_dword v25, v7, s[6:7]
	v_cmp_gt_u32_e32 vcc, v33, v57
	s_waitcnt vmcnt(4)
	v_fmac_f32_e32 v65, v64, v3
	s_waitcnt vmcnt(2)
	v_fmac_f32_e32 v13, v5, v12
	v_cndmask_b32_e32 v6, 0, v45, vcc
	v_cmp_le_u32_e32 vcc, v57, v33
	v_cvt_pk_bf16_f32 v5, v13, s0
	s_waitcnt vmcnt(0)
	v_fmac_f32_e32 v25, v4, v24
	v_cndmask_b32_e32 v7, 0, v44, vcc
	v_cvt_pk_bf16_f32 v6, v7, v6
	v_mul_u32_u24_e32 v7, 0x110, v23
	v_add3_u32 v7, s15, v7, v35
	ds_write_b16 v7, v27 offset:34816
	v_cvt_pk_bf16_f32 v7, v43, s0
	ds_write_b16 v26, v7 offset:34816
	v_cvt_pk_bf16_f32 v7, v46, v47
	v_cmp_le_u32_e32 vcc, v23, v33
	s_nop 1
	v_cndmask_b32_e32 v23, 0, v7, vcc
	v_lshrrev_b32_e32 v7, 16, v7
	v_cmp_le_u32_e32 vcc, v22, v33
	s_nop 1
	v_cndmask_b32_e32 v7, 0, v7, vcc
	v_perm_b32 v7, v7, v23, s19
	v_cmp_gt_u32_e32 vcc, v33, v60
	ds_write_b64 v0, v[6:7] offset:96
	s_nop 0
	v_cndmask_b32_e32 v6, 0, v19, vcc
	v_cmp_le_u32_e32 vcc, v60, v33
	s_nop 1
	v_cndmask_b32_e32 v7, 0, v18, vcc
	v_cvt_pk_bf16_f32 v6, v7, v6
	v_mul_u32_u24_e32 v7, 0x110, v48
	v_add3_u32 v7, s15, v7, v35
	v_mul_u32_u24_e32 v18, 0x110, v37
	v_add3_u32 v18, s15, v18, v35
	ds_write_b16 v7, v9 offset:34816
	v_cvt_pk_bf16_f32 v7, v55, s0
	ds_write_b16 v18, v7 offset:34816
	v_cvt_pk_bf16_f32 v7, v20, v21
	v_cmp_le_u32_e32 vcc, v48, v33
	s_nop 1
	v_cndmask_b32_e32 v8, 0, v7, vcc
	v_lshrrev_b32_e32 v7, 16, v7
	v_cmp_le_u32_e32 vcc, v37, v33
	s_nop 1
	v_cndmask_b32_e32 v7, 0, v7, vcc
	v_perm_b32 v7, v7, v8, s19
	v_cmp_gt_u32_e32 vcc, v33, v29
	ds_write_b64 v0, v[6:7] offset:104
	v_mul_u32_u24_e32 v8, 0x110, v49
	v_cndmask_b32_e32 v6, 0, v39, vcc
	v_cmp_le_u32_e32 vcc, v29, v33
	v_add3_u32 v8, s15, v8, v35
	s_nop 0
	v_cndmask_b32_e32 v7, 0, v38, vcc
	v_cvt_pk_bf16_f32 v6, v7, v6
	v_mul_u32_u24_e32 v7, 0x110, v56
	v_add3_u32 v7, s15, v7, v35
	ds_write_b16 v7, v2 offset:34816
	v_cvt_pk_bf16_f32 v2, v65, s0
	ds_write_b16 v8, v2 offset:34816
	v_cvt_pk_bf16_f32 v2, v40, v41
	v_cmp_le_u32_e32 vcc, v56, v33
	s_nop 1
	v_cndmask_b32_e32 v3, 0, v2, vcc
	v_lshrrev_b32_e32 v2, 16, v2
	v_cmp_le_u32_e32 vcc, v49, v33
	s_nop 1
	v_cndmask_b32_e32 v2, 0, v2, vcc
	v_cmp_gt_u32_e32 vcc, v33, v28
	v_perm_b32 v7, v2, v3, s19
	ds_write_b64 v0, v[6:7] offset:112
	v_cndmask_b32_e32 v2, 0, v15, vcc
	v_cmp_le_u32_e32 vcc, v28, v33
	v_mul_u32_u24_e32 v6, 0x110, v10
	v_add3_u32 v6, s15, v6, v35
	v_cndmask_b32_e32 v3, 0, v14, vcc
	v_cvt_pk_bf16_f32 v2, v3, v2
	v_mul_u32_u24_e32 v3, 0x110, v11
	v_add3_u32 v3, s15, v3, v35
	ds_write_b16 v3, v5 offset:34816
	v_cvt_pk_bf16_f32 v3, v25, s0
	ds_write_b16 v6, v3 offset:34816
	v_cvt_pk_bf16_f32 v3, v16, v17
	v_cmp_le_u32_e32 vcc, v11, v33
	v_mul_u32_u24_e32 v7, 0x88, v83
	s_add_u32 s0, s46, s88
	v_cndmask_b32_e32 v4, 0, v3, vcc
	v_lshrrev_b32_e32 v3, 16, v3
	v_cmp_le_u32_e32 vcc, v10, v33
	s_addc_u32 s1, s47, 0
	s_nop 0
	v_cndmask_b32_e32 v3, 0, v3, vcc
	v_perm_b32 v3, v3, v4, s19
	ds_write_b64 v0, v[2:3] offset:120
	v_bfe_u32 v0, v50, 4, 2
	v_and_b32_e32 v2, 0x4f, v50
	v_lshl_add_u32 v6, v0, 4, s15
	v_mul_u32_u24_e32 v2, 0x88, v2
	v_lshl_add_u32 v51, v2, 1, v6
	s_waitcnt lgkmcnt(0)
	s_barrier
	ds_read_b128 v[2:5], v51 offset:34816
	ds_read_b128 v[72:75], v51 offset:34880
	ds_read_b128 v[14:17], v51 offset:39168
	ds_read_b128 v[76:79], v51 offset:39232
	ds_read_b128 v[22:25], v51 offset:43520
	ds_read_b128 v[84:87], v51 offset:43584
	ds_read_b128 v[30:33], v51 offset:47872
	ds_read_b128 v[88:91], v51 offset:47936
	v_lshl_add_u32 v82, v7, 1, v6
	ds_read_b128 v[6:9], v82
	ds_read_b128 v[34:37], v82 offset:4352
	ds_read_b128 v[52:55], v82 offset:8704
	ds_read_b128 v[68:71], v82 offset:13056
	s_waitcnt lgkmcnt(3)
	v_mfma_f32_16x16x32_bf16 v[10:13], v[2:5], v[6:9], 0
	v_and_b32_e32 v50, 64, v50
	v_mfma_f32_16x16x32_bf16 v[18:21], v[14:17], v[6:9], 0
	v_mfma_f32_16x16x32_bf16 v[26:29], v[22:25], v[6:9], 0
	v_mfma_f32_16x16x32_bf16 v[6:9], v[30:33], v[6:9], 0
	s_waitcnt lgkmcnt(2)
	v_mfma_f32_16x16x32_bf16 v[38:41], v[2:5], v[34:37], 0
	v_mfma_f32_16x16x32_bf16 v[42:45], v[14:17], v[34:37], 0
	v_mfma_f32_16x16x32_bf16 v[46:49], v[22:25], v[34:37], 0
	v_mfma_f32_16x16x32_bf16 v[34:37], v[30:33], v[34:37], 0
	s_waitcnt lgkmcnt(1)
	v_mfma_f32_16x16x32_bf16 v[56:59], v[2:5], v[52:55], 0
	v_mfma_f32_16x16x32_bf16 v[60:63], v[14:17], v[52:55], 0
	v_mfma_f32_16x16x32_bf16 v[64:67], v[22:25], v[52:55], 0
	v_mfma_f32_16x16x32_bf16 v[52:55], v[30:33], v[52:55], 0
	s_waitcnt lgkmcnt(0)
	v_mfma_f32_16x16x32_bf16 v[2:5], v[2:5], v[68:71], 0
	v_mfma_f32_16x16x32_bf16 v[14:17], v[14:17], v[68:71], 0
	v_mfma_f32_16x16x32_bf16 v[22:25], v[22:25], v[68:71], 0
	v_mfma_f32_16x16x32_bf16 v[30:33], v[30:33], v[68:71], 0
	ds_read_b128 v[68:71], v82 offset:64
	s_waitcnt lgkmcnt(0)
	v_mfma_f32_16x16x32_bf16 v[10:13], v[72:75], v[68:71], v[10:13]
	v_mfma_f32_16x16x32_bf16 v[18:21], v[76:79], v[68:71], v[18:21]
	v_mfma_f32_16x16x32_bf16 v[26:29], v[84:87], v[68:71], v[26:29]
	v_mfma_f32_16x16x32_bf16 v[6:9], v[88:91], v[68:71], v[6:9]
	ds_read_b128 v[68:71], v82 offset:4416
	s_waitcnt lgkmcnt(0)
	v_mfma_f32_16x16x32_bf16 v[38:41], v[72:75], v[68:71], v[38:41]
	v_mfma_f32_16x16x32_bf16 v[42:45], v[76:79], v[68:71], v[42:45]
	v_mfma_f32_16x16x32_bf16 v[46:49], v[84:87], v[68:71], v[46:49]
	v_mfma_f32_16x16x32_bf16 v[34:37], v[88:91], v[68:71], v[34:37]
	ds_read_b128 v[68:71], v82 offset:8768
	s_waitcnt lgkmcnt(0)
	v_mfma_f32_16x16x32_bf16 v[92:95], v[76:79], v[68:71], v[60:63]
	s_nop 2
	ds_read_b128 v[60:63], v82 offset:13120
	v_mfma_f32_16x16x32_bf16 v[56:59], v[72:75], v[68:71], v[56:59]
	v_mfma_f32_16x16x32_bf16 v[96:99], v[84:87], v[68:71], v[64:67]
	v_mfma_f32_16x16x32_bf16 v[52:55], v[88:91], v[68:71], v[52:55]
	s_nop 1
	ds_read_b128 v[66:69], v51 offset:34944
	s_waitcnt lgkmcnt(1)
	v_mfma_f32_16x16x32_bf16 v[2:5], v[72:75], v[60:63], v[2:5]
	v_mfma_f32_16x16x32_bf16 v[70:73], v[88:91], v[60:63], v[30:33]
	ds_read_b128 v[88:91], v51 offset:48000
	s_nop 1
	ds_read_b128 v[30:33], v82 offset:128
	v_mfma_f32_16x16x32_bf16 v[14:17], v[76:79], v[60:63], v[14:17]
	s_waitcnt lgkmcnt(0)
	v_mfma_f32_16x16x32_bf16 v[74:77], v[66:69], v[30:33], v[10:13]
	s_nop 2
	ds_read_b128 v[10:13], v51 offset:39296
	v_mfma_f32_16x16x32_bf16 v[100:103], v[88:91], v[30:33], v[6:9]
	s_nop 2
	ds_read_b128 v[6:9], v82 offset:4480
	s_waitcnt lgkmcnt(1)
	v_mfma_f32_16x16x32_bf16 v[78:81], v[10:13], v[30:33], v[18:21]
	s_nop 2
	ds_read_b128 v[18:21], v51 offset:43648
	v_mfma_f32_16x16x32_bf16 v[22:25], v[84:87], v[60:63], v[22:25]
	s_waitcnt lgkmcnt(1)
	v_mfma_f32_16x16x32_bf16 v[104:107], v[66:69], v[6:9], v[38:41]
	v_mfma_f32_16x16x32_bf16 v[108:111], v[10:13], v[6:9], v[42:45]
	s_waitcnt lgkmcnt(0)
	v_mfma_f32_16x16x32_bf16 v[112:115], v[18:21], v[6:9], v[46:49]
	v_mfma_f32_16x16x32_bf16 v[62:65], v[88:91], v[6:9], v[34:37]
	ds_read_b128 v[6:9], v82 offset:8832
	s_waitcnt lgkmcnt(0)
	v_mfma_f32_16x16x32_bf16 v[42:45], v[88:91], v[6:9], v[52:55]
	s_nop 2
	ds_read_b128 v[52:55], v82 offset:13184
	v_mfma_f32_16x16x32_bf16 v[84:87], v[18:21], v[30:33], v[26:29]
	ds_read_b128 v[30:33], v51 offset:35008
	v_mfma_f32_16x16x32_bf16 v[46:49], v[18:21], v[6:9], v[96:99]
	s_waitcnt lgkmcnt(1)
	v_mfma_f32_16x16x32_bf16 v[26:29], v[66:69], v[52:55], v[2:5]
	v_mfma_f32_16x16x32_bf16 v[2:5], v[18:21], v[52:55], v[22:25]
	ds_read_b128 v[18:21], v51 offset:39360
	v_mfma_f32_16x16x32_bf16 v[38:41], v[66:69], v[6:9], v[56:59]
	v_mfma_f32_16x16x32_bf16 v[34:37], v[10:13], v[6:9], v[92:95]
	v_mfma_f32_16x16x32_bf16 v[6:9], v[10:13], v[52:55], v[14:17]
	v_mfma_f32_16x16x32_bf16 v[10:13], v[88:91], v[52:55], v[70:73]
	ds_read_b128 v[52:55], v82 offset:192
	ds_read_b128 v[22:25], v51 offset:43712
	ds_read_b128 v[14:17], v51 offset:48064
	v_lshlrev_b32_e32 v70, 3, v0
	v_lshlrev_b32_e32 v0, 1, v50
	v_lshl_add_u64 v[50:51], s[0:1], 0, v[0:1]
	v_mov_b32_e32 v71, v1
	s_waitcnt lgkmcnt(2)
	v_mfma_f32_16x16x32_bf16 v[88:91], v[30:33], v[52:55], v[74:77]
	ds_read_b128 v[96:99], v82 offset:4544
	v_mfma_f32_16x16x32_bf16 v[92:95], v[18:21], v[52:55], v[78:81]
	s_nop 0
	v_lshl_add_u64 v[74:75], v[50:51], 0, v[70:71]
	s_nop 0
	v_or_b32_e32 v81, s4, v83
	v_mad_u64_u32 v[72:73], s[0:1], v81, s3, v[74:75]
	global_load_dwordx2 v[116:117], v[72:73], off
	s_lshl_b64 s[0:1], s[12:13], 2
	s_add_u32 s0, s50, s0
	s_addc_u32 s1, s51, s1
	v_lshlrev_b32_e32 v80, 2, v83
	s_waitcnt lgkmcnt(0)
	v_mfma_f32_16x16x32_bf16 v[58:61], v[30:33], v[96:99], v[104:107]
	v_or_b32_e32 v83, 16, v81
	v_mad_u64_u32 v[78:79], s[4:5], v83, s3, v[74:75]
	s_nop 0
	global_load_dword v106, v80, s[0:1]
	v_mfma_f32_16x16x32_bf16 v[66:69], v[14:17], v[52:55], v[100:103]
	s_waitcnt vmcnt(0)
	v_add_f32_e32 v92, v92, v106
	s_nop 0
	global_load_dwordx2 v[100:101], v[72:73], off offset:32
	global_load_dwordx2 v[102:103], v[72:73], off offset:64
	global_load_dwordx2 v[104:105], v[72:73], off offset:96
	v_lshlrev_b32_e32 v72, 16, v116
	v_mul_f32_e32 v73, v72, v72
	v_and_b32_e32 v107, 0xffff0000, v116
	v_fmamk_f32 v73, v73, 0xbdd2d3e7, v129
	v_mul_f32_e32 v76, v107, v107
	v_mul_f32_e32 v73, v73, v72
	v_fmamk_f32 v76, v76, 0xbdd2d3e7, v129
	v_mul_f32_e32 v76, v76, v107
	v_exp_f32_e32 v73, v73
	v_mfma_f32_16x16x32_bf16 v[84:87], v[22:25], v[52:55], v[84:87]
	v_add_f32_e32 v67, v67, v106
	v_add_f32_e32 v73, 1.0, v73
	v_rcp_f32_e32 v73, v73
	v_mfma_f32_16x16x32_bf16 v[54:57], v[18:21], v[96:99], v[108:111]
	v_add_f32_e32 v66, v66, v106
	s_nop 2
	v_add_f32_e32 v85, v85, v106
	v_mul_f32_e32 v72, v73, v72
	v_exp_f32_e32 v108, v76
	v_add_f32_e32 v73, v88, v106
	v_mul_f32_e32 v72, v72, v73
	v_add_f32_e32 v88, v89, v106
	v_add_f32_e32 v108, 1.0, v108
	v_rcp_f32_e32 v108, v108
	v_lshlrev_b32_e32 v89, 16, v117
	v_add_f32_e32 v84, v84, v106
	v_add_f32_e32 v86, v86, v106
	v_mul_f32_e32 v73, v108, v107
	v_mul_f32_e32 v73, v73, v88
	v_mul_f32_e32 v88, v89, v89
	v_and_b32_e32 v107, 0xffff0000, v117
	v_fmamk_f32 v88, v88, 0xbdd2d3e7, v129
	v_mul_f32_e32 v108, v107, v107
	v_mul_f32_e32 v88, v88, v89
	v_fmamk_f32 v108, v108, 0xbdd2d3e7, v129
	v_mul_f32_e32 v108, v108, v107
	v_exp_f32_e32 v88, v88
	v_exp_f32_e32 v108, v108
	v_add_f32_e32 v87, v87, v106
	v_add_f32_e32 v88, 1.0, v88
	v_rcp_f32_e32 v109, v88
	v_cvt_pk_bf16_f32 v88, v72, v73
	v_add_f32_e32 v72, 1.0, v108
	v_rcp_f32_e32 v72, v72
	v_mul_f32_e32 v73, v109, v89
	v_add_f32_e32 v89, v90, v106
	v_mul_f32_e32 v73, v73, v89
	v_mul_f32_e32 v72, v72, v107
	v_add_f32_e32 v89, v91, v106
	v_mul_f32_e32 v72, v72, v89
	v_cvt_pk_bf16_f32 v89, v73, v72
	v_mov_b64_e32 v[72:73], s[46:47]
	v_mad_u64_u32 v[90:91], s[4:5], v81, s3, v[72:73]
	v_lshl_add_u64 v[90:91], v[90:91], 0, s[88:89]
	v_lshl_add_u64 v[90:91], v[90:91], 0, v[0:1]
	v_lshl_add_u64 v[90:91], v[90:91], 0, v[70:71]
	global_store_dwordx2 v[90:91], v[88:89], off
	global_load_dwordx2 v[76:77], v[78:79], off
	v_add_f32_e32 v68, v68, v106
	v_add_f32_e32 v69, v69, v106
	v_mfma_f32_16x16x32_bf16 v[50:53], v[22:25], v[96:99], v[112:115]
	s_waitcnt vmcnt(4)
	v_lshlrev_b32_e32 v107, 16, v100
	v_mul_f32_e32 v108, v107, v107
	v_and_b32_e32 v100, 0xffff0000, v100
	v_fmamk_f32 v108, v108, 0xbdd2d3e7, v129
	v_mul_f32_e32 v109, v100, v100
	v_mul_f32_e32 v108, v108, v107
	v_fmamk_f32 v109, v109, 0xbdd2d3e7, v129
	v_mul_f32_e32 v109, v109, v100
	v_exp_f32_e32 v108, v108
	v_exp_f32_e32 v109, v109
	v_mfma_f32_16x16x32_bf16 v[62:65], v[14:17], v[96:99], v[62:65]
	v_add_f32_e32 v108, 1.0, v108
	v_rcp_f32_e32 v108, v108
	v_add_f32_e32 v88, 1.0, v109
	v_rcp_f32_e32 v88, v88
	v_mul_f32_e32 v89, v108, v107
	v_mul_f32_e32 v89, v89, v92
	v_mul_f32_e32 v88, v88, v100
	v_add_f32_e32 v92, v93, v106
	v_mul_f32_e32 v88, v88, v92
	v_lshlrev_b32_e32 v92, 16, v101
	v_mul_f32_e32 v93, v92, v92
	v_and_b32_e32 v100, 0xffff0000, v101
	v_fmamk_f32 v93, v93, 0xbdd2d3e7, v129
	v_mul_f32_e32 v101, v100, v100
	v_mul_f32_e32 v93, v93, v92
	v_fmamk_f32 v101, v101, 0xbdd2d3e7, v129
	v_mul_f32_e32 v101, v101, v100
	v_exp_f32_e32 v93, v93
	v_exp_f32_e32 v101, v101
	v_cvt_pk_bf16_f32 v88, v89, v88
	v_add_f32_e32 v93, 1.0, v93
	v_rcp_f32_e32 v93, v93
	v_add_f32_e32 v89, 1.0, v101
	v_rcp_f32_e32 v89, v89
	v_mul_f32_e32 v92, v93, v92
	v_add_f32_e32 v93, v94, v106
	v_mul_f32_e32 v92, v92, v93
	v_mul_f32_e32 v89, v89, v100
	v_add_f32_e32 v93, v95, v106
	v_mul_f32_e32 v89, v89, v93
	s_waitcnt vmcnt(3)
	v_and_b32_e32 v94, 0xffff0000, v102
	v_cvt_pk_bf16_f32 v89, v92, v89
	v_lshlrev_b32_e32 v92, 16, v102
	v_mul_f32_e32 v95, v94, v94
	v_mul_f32_e32 v93, v92, v92
	v_fmamk_f32 v95, v95, 0xbdd2d3e7, v129
	v_fmamk_f32 v93, v93, 0xbdd2d3e7, v129
	v_mul_f32_e32 v95, v95, v94
	v_mul_f32_e32 v93, v93, v92
	v_exp_f32_e32 v95, v95
	v_exp_f32_e32 v93, v93
	global_store_dwordx2 v[90:91], v[88:89], off offset:32
	v_add_f32_e32 v88, 1.0, v95
	v_add_f32_e32 v93, 1.0, v93
	v_rcp_f32_e32 v88, v88
	v_rcp_f32_e32 v93, v93
	v_mul_f32_e32 v88, v88, v94
	v_mul_f32_e32 v89, v93, v92
	v_mul_f32_e32 v85, v88, v85
	v_lshlrev_b32_e32 v88, 16, v103
	v_and_b32_e32 v92, 0xffff0000, v103
	v_mul_f32_e32 v84, v89, v84
	v_mul_f32_e32 v89, v88, v88
	v_mul_f32_e32 v93, v92, v92
	v_fmamk_f32 v89, v89, 0xbdd2d3e7, v129
	v_fmamk_f32 v93, v93, 0xbdd2d3e7, v129
	v_mul_f32_e32 v89, v89, v88
	v_mul_f32_e32 v93, v93, v92
	v_exp_f32_e32 v89, v89
	v_exp_f32_e32 v93, v93
	v_cvt_pk_bf16_f32 v84, v84, v85
	v_add_f32_e32 v89, 1.0, v89
	v_add_f32_e32 v85, 1.0, v93
	v_rcp_f32_e32 v89, v89
	v_rcp_f32_e32 v85, v85
	v_mul_f32_e32 v88, v89, v88
	v_mul_f32_e32 v85, v85, v92
	v_mul_f32_e32 v86, v88, v86
	v_mul_f32_e32 v85, v85, v87
	s_waitcnt vmcnt(3)
	v_and_b32_e32 v88, 0xffff0000, v104
	v_cvt_pk_bf16_f32 v85, v86, v85
	v_lshlrev_b32_e32 v86, 16, v104
	v_mul_f32_e32 v89, v88, v88
	v_mul_f32_e32 v87, v86, v86
	v_fmamk_f32 v89, v89, 0xbdd2d3e7, v129
	v_fmamk_f32 v87, v87, 0xbdd2d3e7, v129
	v_mul_f32_e32 v89, v89, v88
	v_mul_f32_e32 v87, v87, v86
	v_exp_f32_e32 v89, v89
	v_exp_f32_e32 v87, v87
	global_store_dwordx2 v[90:91], v[84:85], off offset:64
	v_add_f32_e32 v84, 1.0, v89
	v_add_f32_e32 v87, 1.0, v87
	v_rcp_f32_e32 v84, v84
	v_rcp_f32_e32 v87, v87
	v_mul_f32_e32 v84, v84, v88
	v_mul_f32_e32 v85, v87, v86
	v_mul_f32_e32 v67, v84, v67
	v_lshlrev_b32_e32 v84, 16, v105
	v_and_b32_e32 v86, 0xffff0000, v105
	v_mul_f32_e32 v66, v85, v66
	v_mul_f32_e32 v85, v84, v84
	v_mul_f32_e32 v87, v86, v86
	v_fmamk_f32 v85, v85, 0xbdd2d3e7, v129
	v_fmamk_f32 v87, v87, 0xbdd2d3e7, v129
	v_mul_f32_e32 v85, v85, v84
	v_mul_f32_e32 v87, v87, v86
	v_exp_f32_e32 v85, v85
	v_exp_f32_e32 v87, v87
	v_cvt_pk_bf16_f32 v66, v66, v67
	v_add_f32_e32 v85, 1.0, v85
	v_add_f32_e32 v67, 1.0, v87
	v_rcp_f32_e32 v85, v85
	v_rcp_f32_e32 v67, v67
	v_mul_f32_e32 v84, v85, v84
	v_mul_f32_e32 v67, v67, v86
	v_mul_f32_e32 v68, v68, v84
	v_mul_f32_e32 v67, v69, v67
	v_cvt_pk_bf16_f32 v67, v68, v67
	global_store_dwordx2 v[90:91], v[66:67], off offset:96
	global_load_dword v84, v80, s[0:1] offset:64
	ds_read_b128 v[86:89], v82 offset:8896
	global_load_dwordx2 v[90:91], v[78:79], off offset:32
	global_load_dwordx2 v[92:93], v[78:79], off offset:64
	global_load_dwordx2 v[94:95], v[78:79], off offset:96
	s_waitcnt vmcnt(7)
	v_lshlrev_b32_e32 v79, 16, v76
	v_and_b32_e32 v76, 0xffff0000, v76
	v_mul_f32_e32 v67, v76, v76
	v_mul_f32_e32 v66, v79, v79
	v_fmamk_f32 v67, v67, 0xbdd2d3e7, v129
	v_fmamk_f32 v66, v66, 0xbdd2d3e7, v129
	v_mul_f32_e32 v67, v67, v76
	v_mul_f32_e32 v66, v66, v79
	v_exp_f32_e32 v85, v67
	v_exp_f32_e32 v66, v66
	v_or_b32_e32 v78, 32, v81
	v_mad_u64_u32 v[68:69], s[4:5], v78, s3, v[74:75]
	v_add_f32_e32 v85, 1.0, v85
	v_add_f32_e32 v66, 1.0, v66
	v_rcp_f32_e32 v85, v85
	v_rcp_f32_e32 v96, v66
	global_load_dwordx2 v[66:67], v[68:69], off
	s_waitcnt lgkmcnt(0)
	v_mfma_f32_16x16x32_bf16 v[38:41], v[30:33], v[86:89], v[38:41]
	v_mul_f32_e32 v76, v85, v76
	v_mul_f32_e32 v79, v96, v79
	s_waitcnt vmcnt(4)
	v_add_f32_e32 v59, v59, v84
	v_add_f32_e32 v58, v58, v84
	v_mul_f32_e32 v59, v76, v59
	v_lshlrev_b32_e32 v76, 16, v77
	v_and_b32_e32 v77, 0xffff0000, v77
	v_mul_f32_e32 v58, v79, v58
	v_mul_f32_e32 v79, v76, v76
	v_mul_f32_e32 v85, v77, v77
	v_fmamk_f32 v79, v79, 0xbdd2d3e7, v129
	v_fmamk_f32 v85, v85, 0xbdd2d3e7, v129
	v_mul_f32_e32 v79, v79, v76
	v_mul_f32_e32 v85, v85, v77
	v_exp_f32_e32 v79, v79
	v_exp_f32_e32 v85, v85
	v_cvt_pk_bf16_f32 v58, v58, v59
	v_add_f32_e32 v60, v60, v84
	v_add_f32_e32 v79, 1.0, v79
	v_add_f32_e32 v59, 1.0, v85
	v_rcp_f32_e32 v79, v79
	v_rcp_f32_e32 v59, v59
	v_add_f32_e32 v61, v61, v84
	v_add_f32_e32 v55, v55, v84
	v_mul_f32_e32 v76, v79, v76
	v_mul_f32_e32 v59, v59, v77
	v_mul_f32_e32 v60, v76, v60
	v_mul_f32_e32 v59, v59, v61
	s_waitcnt vmcnt(3)
	v_and_b32_e32 v79, 0xffff0000, v90
	v_cvt_pk_bf16_f32 v59, v60, v59
	v_mad_u64_u32 v[60:61], s[4:5], v83, s3, v[72:73]
	v_lshlrev_b32_e32 v76, 16, v90
	v_mul_f32_e32 v83, v79, v79
	v_mul_f32_e32 v77, v76, v76
	v_fmamk_f32 v83, v83, 0xbdd2d3e7, v129
	v_fmamk_f32 v77, v77, 0xbdd2d3e7, v129
	v_mul_f32_e32 v83, v83, v79
	v_mul_f32_e32 v77, v77, v76
	v_exp_f32_e32 v83, v83
	v_lshl_add_u64 v[60:61], v[60:61], 0, s[88:89]
	v_exp_f32_e32 v77, v77
	v_lshl_add_u64 v[60:61], v[60:61], 0, v[0:1]
	v_lshl_add_u64 v[60:61], v[60:61], 0, v[70:71]
	global_store_dwordx2 v[60:61], v[58:59], off
	v_add_f32_e32 v58, 1.0, v83
	v_add_f32_e32 v77, 1.0, v77
	v_rcp_f32_e32 v58, v58
	v_rcp_f32_e32 v77, v77
	v_add_f32_e32 v54, v54, v84
	v_add_f32_e32 v56, v56, v84
	v_mul_f32_e32 v58, v58, v79
	v_mul_f32_e32 v59, v77, v76
	v_mul_f32_e32 v55, v58, v55
	v_lshlrev_b32_e32 v58, 16, v91
	v_and_b32_e32 v76, 0xffff0000, v91
	v_mul_f32_e32 v54, v59, v54
	v_mul_f32_e32 v59, v58, v58
	v_mul_f32_e32 v77, v76, v76
	v_fmamk_f32 v59, v59, 0xbdd2d3e7, v129
	v_fmamk_f32 v77, v77, 0xbdd2d3e7, v129
	v_mul_f32_e32 v59, v59, v58
	v_mul_f32_e32 v77, v77, v76
	v_exp_f32_e32 v59, v59
	v_exp_f32_e32 v77, v77
	v_cvt_pk_bf16_f32 v54, v54, v55
	v_add_f32_e32 v57, v57, v84
	v_add_f32_e32 v59, 1.0, v59
	v_add_f32_e32 v55, 1.0, v77
	v_rcp_f32_e32 v59, v59
	v_rcp_f32_e32 v55, v55
	v_add_f32_e32 v51, v51, v84
	v_add_f32_e32 v50, v50, v84
	v_mul_f32_e32 v58, v59, v58
	v_mul_f32_e32 v55, v55, v76
	v_mul_f32_e32 v56, v58, v56
	v_mul_f32_e32 v55, v55, v57
	s_waitcnt vmcnt(3)
	v_and_b32_e32 v58, 0xffff0000, v92
	v_cvt_pk_bf16_f32 v55, v56, v55
	v_lshlrev_b32_e32 v56, 16, v92
	v_mul_f32_e32 v59, v58, v58
	v_mul_f32_e32 v57, v56, v56
	v_fmamk_f32 v59, v59, 0xbdd2d3e7, v129
	v_fmamk_f32 v57, v57, 0xbdd2d3e7, v129
	v_mul_f32_e32 v59, v59, v58
	v_mul_f32_e32 v57, v57, v56
	v_exp_f32_e32 v59, v59
	v_exp_f32_e32 v57, v57
	global_store_dwordx2 v[60:61], v[54:55], off offset:32
	v_add_f32_e32 v52, v52, v84
	v_add_f32_e32 v54, 1.0, v59
	v_add_f32_e32 v57, 1.0, v57
	v_rcp_f32_e32 v54, v54
	v_rcp_f32_e32 v57, v57
	v_add_f32_e32 v53, v53, v84
	v_mfma_f32_16x16x32_bf16 v[34:37], v[18:21], v[86:89], v[34:37]
	v_mul_f32_e32 v54, v54, v58
	v_mul_f32_e32 v55, v57, v56
	v_mul_f32_e32 v51, v54, v51
	v_lshlrev_b32_e32 v54, 16, v93
	v_and_b32_e32 v56, 0xffff0000, v93
	v_mul_f32_e32 v50, v55, v50
	v_mul_f32_e32 v55, v54, v54
	v_mul_f32_e32 v57, v56, v56
	v_fmamk_f32 v55, v55, 0xbdd2d3e7, v129
	v_fmamk_f32 v57, v57, 0xbdd2d3e7, v129
	v_mul_f32_e32 v55, v55, v54
	v_mul_f32_e32 v57, v57, v56
	v_exp_f32_e32 v55, v55
	v_exp_f32_e32 v57, v57
	v_cvt_pk_bf16_f32 v50, v50, v51
	v_mfma_f32_16x16x32_bf16 v[46:49], v[22:25], v[86:89], v[46:49]
	v_add_f32_e32 v55, 1.0, v55
	v_add_f32_e32 v51, 1.0, v57
	v_rcp_f32_e32 v55, v55
	v_rcp_f32_e32 v51, v51
	v_mfma_f32_16x16x32_bf16 v[42:45], v[14:17], v[86:89], v[42:45]
	v_or_b32_e32 v57, 48, v81
	v_mul_f32_e32 v54, v55, v54
	v_mul_f32_e32 v51, v51, v56
	v_mul_f32_e32 v52, v54, v52
	v_mul_f32_e32 v51, v51, v53
	v_cvt_pk_bf16_f32 v51, v52, v51
	s_waitcnt vmcnt(3)
	v_lshlrev_b32_e32 v52, 16, v94
	v_mul_f32_e32 v53, v52, v52
	v_and_b32_e32 v54, 0xffff0000, v94
	v_fmamk_f32 v53, v53, 0xbdd2d3e7, v129
	v_mul_f32_e32 v55, v54, v54
	v_mul_f32_e32 v53, v53, v52
	v_fmamk_f32 v55, v55, 0xbdd2d3e7, v129
	v_mul_f32_e32 v55, v55, v54
	v_exp_f32_e32 v53, v53
	v_exp_f32_e32 v55, v55
	global_store_dwordx2 v[60:61], v[50:51], off offset:64
	v_add_f32_e32 v53, 1.0, v53
	v_rcp_f32_e32 v53, v53
	v_add_f32_e32 v50, 1.0, v55
	v_rcp_f32_e32 v50, v50
	v_mul_f32_e32 v51, v53, v52
	v_add_f32_e32 v52, v62, v84
	v_mul_f32_e32 v51, v51, v52
	v_mul_f32_e32 v50, v50, v54
	v_add_f32_e32 v52, v63, v84
	v_mul_f32_e32 v50, v50, v52
	v_lshlrev_b32_e32 v52, 16, v95
	v_mul_f32_e32 v53, v52, v52
	v_and_b32_e32 v54, 0xffff0000, v95
	v_fmamk_f32 v53, v53, 0xbdd2d3e7, v129
	v_mul_f32_e32 v55, v54, v54
	v_mul_f32_e32 v53, v53, v52
	v_fmamk_f32 v55, v55, 0xbdd2d3e7, v129
	v_mul_f32_e32 v55, v55, v54
	v_exp_f32_e32 v53, v53
	v_exp_f32_e32 v55, v55
	v_cvt_pk_bf16_f32 v50, v51, v50
	v_add_f32_e32 v53, 1.0, v53
	v_rcp_f32_e32 v53, v53
	v_add_f32_e32 v51, 1.0, v55
	v_rcp_f32_e32 v51, v51
	v_mul_f32_e32 v52, v53, v52
	v_add_f32_e32 v53, v64, v84
	v_mul_f32_e32 v52, v52, v53
	v_mul_f32_e32 v51, v51, v54
	v_add_f32_e32 v53, v65, v84
	v_mul_f32_e32 v51, v51, v53
	v_cvt_pk_bf16_f32 v51, v52, v51
	global_store_dwordx2 v[60:61], v[50:51], off offset:96
	global_load_dword v56, v80, s[0:1] offset:128
	global_load_dwordx2 v[54:55], v[68:69], off offset:32
	ds_read_b128 v[50:53], v82 offset:13248
	global_load_dwordx2 v[58:59], v[68:69], off offset:64
	global_load_dwordx2 v[60:61], v[68:69], off offset:96
	s_waitcnt vmcnt(8)
	v_lshlrev_b32_e32 v62, 16, v66
	s_waitcnt lgkmcnt(0)
	v_mfma_f32_16x16x32_bf16 v[26:29], v[30:33], v[50:53], v[26:29]
	v_mul_f32_e32 v30, v62, v62
	v_and_b32_e32 v63, 0xffff0000, v66
	v_fmamk_f32 v30, v30, 0xbdd2d3e7, v129
	v_mul_f32_e32 v31, v63, v63
	v_mul_f32_e32 v30, v30, v62
	v_fmamk_f32 v31, v31, 0xbdd2d3e7, v129
	v_mul_f32_e32 v31, v31, v63
	v_exp_f32_e32 v30, v30
	v_exp_f32_e32 v64, v31
	v_mad_u64_u32 v[32:33], s[4:5], v57, s3, v[74:75]
	v_add_f32_e32 v30, 1.0, v30
	v_rcp_f32_e32 v65, v30
	v_add_f32_e32 v64, 1.0, v64
	v_rcp_f32_e32 v64, v64
	global_load_dwordx2 v[30:31], v[32:33], off
	v_mul_f32_e32 v62, v65, v62
	v_mfma_f32_16x16x32_bf16 v[6:9], v[18:21], v[50:53], v[6:9]
	global_load_dwordx2 v[18:19], v[32:33], off offset:32
	s_waitcnt vmcnt(5)
	v_add_f32_e32 v38, v38, v56
	v_mul_f32_e32 v38, v62, v38
	v_mul_f32_e32 v62, v64, v63
	v_add_f32_e32 v39, v39, v56
	v_mul_f32_e32 v39, v62, v39
	v_lshlrev_b32_e32 v62, 16, v67
	v_mul_f32_e32 v63, v62, v62
	v_fmamk_f32 v63, v63, 0xbdd2d3e7, v129
	v_and_b32_e32 v64, 0xffff0000, v67
	v_mul_f32_e32 v63, v63, v62
	v_mul_f32_e32 v65, v64, v64
	v_fmamk_f32 v65, v65, 0xbdd2d3e7, v129
	v_mul_f32_e32 v65, v65, v64
	v_exp_f32_e32 v63, v63
	v_exp_f32_e32 v65, v65
	v_add_f32_e32 v63, 1.0, v63
	v_rcp_f32_e32 v63, v63
	v_cvt_pk_bf16_f32 v38, v38, v39
	v_add_f32_e32 v39, 1.0, v65
	v_rcp_f32_e32 v39, v39
	v_mul_f32_e32 v62, v63, v62
	v_add_f32_e32 v40, v40, v56
	v_mul_f32_e32 v40, v62, v40
	s_waitcnt vmcnt(4)
	v_lshlrev_b32_e32 v62, 16, v54
	v_and_b32_e32 v54, 0xffff0000, v54
	v_mul_f32_e32 v39, v39, v64
	v_mul_f32_e32 v64, v54, v54
	v_mul_f32_e32 v63, v62, v62
	v_fmamk_f32 v64, v64, 0xbdd2d3e7, v129
	v_fmamk_f32 v63, v63, 0xbdd2d3e7, v129
	v_mul_f32_e32 v64, v64, v54
	v_add_f32_e32 v41, v41, v56
	v_mul_f32_e32 v63, v63, v62
	v_mul_f32_e32 v39, v39, v41
	v_cvt_pk_bf16_f32 v39, v40, v39
	v_mad_u64_u32 v[40:41], s[4:5], v78, s3, v[72:73]
	v_exp_f32_e32 v64, v64
	v_lshl_add_u64 v[40:41], v[40:41], 0, s[88:89]
	v_exp_f32_e32 v63, v63
	v_lshl_add_u64 v[40:41], v[40:41], 0, v[0:1]
	v_lshl_add_u64 v[40:41], v[40:41], 0, v[70:71]
	global_store_dwordx2 v[40:41], v[38:39], off
	v_add_f32_e32 v38, 1.0, v64
	v_add_f32_e32 v63, 1.0, v63
	v_rcp_f32_e32 v38, v38
	v_rcp_f32_e32 v63, v63
	v_add_f32_e32 v35, v35, v56
	v_add_f32_e32 v34, v34, v56
	v_mul_f32_e32 v38, v38, v54
	v_mul_f32_e32 v39, v63, v62
	v_mul_f32_e32 v35, v38, v35
	v_lshlrev_b32_e32 v38, 16, v55
	v_and_b32_e32 v54, 0xffff0000, v55
	v_mul_f32_e32 v34, v39, v34
	v_mul_f32_e32 v39, v38, v38
	v_mul_f32_e32 v55, v54, v54
	v_fmamk_f32 v39, v39, 0xbdd2d3e7, v129
	v_fmamk_f32 v55, v55, 0xbdd2d3e7, v129
	v_mul_f32_e32 v39, v39, v38
	v_mul_f32_e32 v55, v55, v54
	v_exp_f32_e32 v39, v39
	v_exp_f32_e32 v55, v55
	v_cvt_pk_bf16_f32 v34, v34, v35
	v_add_f32_e32 v36, v36, v56
	v_add_f32_e32 v39, 1.0, v39
	v_add_f32_e32 v35, 1.0, v55
	v_rcp_f32_e32 v39, v39
	v_rcp_f32_e32 v35, v35
	v_add_f32_e32 v37, v37, v56
	v_mfma_f32_16x16x32_bf16 v[2:5], v[22:25], v[50:53], v[2:5]
	v_mul_f32_e32 v38, v39, v38
	v_mul_f32_e32 v35, v35, v54
	v_mul_f32_e32 v36, v38, v36
	v_mul_f32_e32 v35, v35, v37
	v_cvt_pk_bf16_f32 v35, v36, v35
	s_waitcnt vmcnt(4)
	v_lshlrev_b32_e32 v36, 16, v58
	v_mul_f32_e32 v37, v36, v36
	v_and_b32_e32 v38, 0xffff0000, v58
	v_fmamk_f32 v37, v37, 0xbdd2d3e7, v129
	v_mul_f32_e32 v39, v38, v38
	v_mul_f32_e32 v37, v37, v36
	v_fmamk_f32 v39, v39, 0xbdd2d3e7, v129
	v_mul_f32_e32 v39, v39, v38
	v_exp_f32_e32 v37, v37
	v_exp_f32_e32 v39, v39
	global_store_dwordx2 v[40:41], v[34:35], off offset:32
	v_add_f32_e32 v37, 1.0, v37
	v_rcp_f32_e32 v37, v37
	v_add_f32_e32 v34, 1.0, v39
	v_rcp_f32_e32 v34, v34
	s_waitcnt vmcnt(3)
	v_lshlrev_b32_e32 v24, 16, v30
	v_mul_f32_e32 v35, v37, v36
	v_add_f32_e32 v36, v46, v56
	v_mul_f32_e32 v35, v35, v36
	v_mul_f32_e32 v34, v34, v38
	v_add_f32_e32 v36, v47, v56
	v_mul_f32_e32 v34, v34, v36
	v_lshlrev_b32_e32 v36, 16, v59
	v_mul_f32_e32 v37, v36, v36
	v_and_b32_e32 v38, 0xffff0000, v59
	v_fmamk_f32 v37, v37, 0xbdd2d3e7, v129
	v_mul_f32_e32 v39, v38, v38
	v_mul_f32_e32 v37, v37, v36
	v_fmamk_f32 v39, v39, 0xbdd2d3e7, v129
	v_mul_f32_e32 v39, v39, v38
	v_exp_f32_e32 v37, v37
	v_exp_f32_e32 v39, v39
	v_cvt_pk_bf16_f32 v34, v35, v34
	v_add_f32_e32 v37, 1.0, v37
	v_rcp_f32_e32 v37, v37
	v_add_f32_e32 v35, 1.0, v39
	v_rcp_f32_e32 v35, v35
	v_mul_f32_e32 v25, 0x3d372713, v24
	v_mul_f32_e32 v36, v37, v36
	v_add_f32_e32 v37, v48, v56
	v_mul_f32_e32 v36, v36, v37
	v_mul_f32_e32 v35, v35, v38
	v_add_f32_e32 v37, v49, v56
	v_mul_f32_e32 v35, v35, v37
	v_cvt_pk_bf16_f32 v35, v36, v35
	v_lshlrev_b32_e32 v36, 16, v60
	v_mul_f32_e32 v37, v36, v36
	v_and_b32_e32 v38, 0xffff0000, v60
	v_fmamk_f32 v37, v37, 0xbdd2d3e7, v129
	v_mul_f32_e32 v39, v38, v38
	v_mul_f32_e32 v37, v37, v36
	v_fmamk_f32 v39, v39, 0xbdd2d3e7, v129
	v_mul_f32_e32 v39, v39, v38
	v_exp_f32_e32 v37, v37
	v_exp_f32_e32 v39, v39
	global_store_dwordx2 v[40:41], v[34:35], off offset:64
	v_add_f32_e32 v37, 1.0, v37
	v_rcp_f32_e32 v37, v37
	v_add_f32_e32 v34, 1.0, v39
	v_rcp_f32_e32 v34, v34
	v_and_b32_e32 v30, 0xffff0000, v30
	v_mul_f32_e32 v35, v37, v36
	v_add_f32_e32 v36, v42, v56
	v_mul_f32_e32 v35, v35, v36
	v_mul_f32_e32 v34, v34, v38
	v_add_f32_e32 v36, v43, v56
	v_mul_f32_e32 v34, v34, v36
	v_lshlrev_b32_e32 v36, 16, v61
	v_mul_f32_e32 v37, v36, v36
	v_and_b32_e32 v38, 0xffff0000, v61
	v_fmamk_f32 v37, v37, 0xbdd2d3e7, v129
	v_mul_f32_e32 v39, v38, v38
	v_mul_f32_e32 v37, v37, v36
	v_fmamk_f32 v39, v39, 0xbdd2d3e7, v129
	v_mul_f32_e32 v39, v39, v38
	v_exp_f32_e32 v37, v37
	v_exp_f32_e32 v39, v39
	v_cvt_pk_bf16_f32 v34, v35, v34
	v_add_f32_e32 v37, 1.0, v37
	v_rcp_f32_e32 v37, v37
	v_add_f32_e32 v35, 1.0, v39
	v_rcp_f32_e32 v35, v35
	v_mul_f32_e32 v25, v25, v24
	v_mul_f32_e32 v36, v37, v36
	v_add_f32_e32 v37, v44, v56
	v_mul_f32_e32 v36, v36, v37
	v_mul_f32_e32 v35, v35, v38
	v_add_f32_e32 v37, v45, v56
	v_mul_f32_e32 v35, v35, v37
	v_cvt_pk_bf16_f32 v35, v36, v35
	global_store_dwordx2 v[40:41], v[34:35], off offset:96
	global_load_dword v34, v80, s[0:1] offset:192
	s_nop 0
	global_load_dwordx2 v[20:21], v[32:33], off offset:64
	global_load_dwordx2 v[22:23], v[32:33], off offset:96
	v_mul_f32_e32 v32, v30, v30
	v_fma_f32 v25, v25, v24, v24
	v_fmamk_f32 v32, v32, 0xbdd2d3e7, v129
	v_mul_f32_e32 v25, 0xbfcc422a, v25
	v_mul_f32_e32 v32, v32, v30
	v_mul_f32_e32 v25, 0x3fb8aa3b, v25
	v_exp_f32_e32 v25, v25
	v_exp_f32_e32 v32, v32
	v_mfma_f32_16x16x32_bf16 v[10:13], v[14:17], v[50:53], v[10:13]
	v_add_f32_e32 v25, 1.0, v25
	v_rcp_f32_e32 v25, v25
	v_add_f32_e32 v14, 1.0, v32
	v_rcp_f32_e32 v14, v14
	v_mul_f32_e32 v15, v25, v24
	v_and_b32_e32 v24, 0xffff0000, v31
	v_mul_f32_e32 v14, v14, v30
	v_mul_f32_e32 v25, v24, v24
	v_fmamk_f32 v25, v25, 0xbdd2d3e7, v129
	v_mul_f32_e32 v25, v25, v24
	v_exp_f32_e32 v25, v25
	s_waitcnt vmcnt(2)
	v_add_f32_e32 v16, v26, v34
	v_mul_f32_e32 v15, v15, v16
	v_add_f32_e32 v16, v27, v34
	v_mul_f32_e32 v14, v14, v16
	v_lshlrev_b32_e32 v16, 16, v31
	v_mul_f32_e32 v17, v16, v16
	v_fmamk_f32 v17, v17, 0xbdd2d3e7, v129
	v_mul_f32_e32 v17, v17, v16
	v_exp_f32_e32 v17, v17
	v_cvt_pk_bf16_f32 v14, v15, v14
	v_add_f32_e32 v15, 1.0, v25
	v_rcp_f32_e32 v15, v15
	v_add_f32_e32 v17, 1.0, v17
	v_rcp_f32_e32 v17, v17
	v_add_f32_e32 v6, v6, v34
	v_mul_f32_e32 v15, v15, v24
	v_add_f32_e32 v7, v7, v34
	v_mul_f32_e32 v16, v17, v16
	v_add_f32_e32 v17, v28, v34
	v_mul_f32_e32 v16, v16, v17
	v_add_f32_e32 v17, v29, v34
	v_mul_f32_e32 v15, v15, v17
	v_cvt_pk_bf16_f32 v15, v16, v15
	v_mad_u64_u32 v[16:17], s[0:1], v57, s3, v[72:73]
	v_lshl_add_u64 v[16:17], v[16:17], 0, s[88:89]
	v_lshl_add_u64 v[16:17], v[16:17], 0, v[0:1]
	v_lshlrev_b32_e32 v0, 16, v18
	v_mul_f32_e32 v24, v0, v0
	v_and_b32_e32 v18, 0xffff0000, v18
	v_fmamk_f32 v24, v24, 0xbdd2d3e7, v129
	v_mul_f32_e32 v25, v18, v18
	v_mul_f32_e32 v24, v24, v0
	v_fmamk_f32 v25, v25, 0xbdd2d3e7, v129
	v_mul_f32_e32 v25, v25, v18
	v_exp_f32_e32 v24, v24
	v_exp_f32_e32 v25, v25
	v_lshl_add_u64 v[16:17], v[16:17], 0, v[70:71]
	v_add_f32_e32 v24, 1.0, v24
	v_rcp_f32_e32 v24, v24
	global_store_dwordx2 v[16:17], v[14:15], off
	v_add_f32_e32 v14, 1.0, v25
	v_rcp_f32_e32 v14, v14
	v_mul_f32_e32 v0, v24, v0
	v_mul_f32_e32 v0, v0, v6
	v_and_b32_e32 v15, 0xffff0000, v19
	v_mul_f32_e32 v6, v14, v18
	v_mul_f32_e32 v6, v6, v7
	v_lshlrev_b32_e32 v7, 16, v19
	v_mul_f32_e32 v14, v7, v7
	v_fmamk_f32 v14, v14, 0xbdd2d3e7, v129
	v_mul_f32_e32 v18, v15, v15
	v_mul_f32_e32 v14, v14, v7
	v_fmamk_f32 v18, v18, 0xbdd2d3e7, v129
	v_mul_f32_e32 v18, v18, v15
	v_exp_f32_e32 v14, v14
	v_exp_f32_e32 v18, v18
	v_cvt_pk_bf16_f32 v6, v0, v6
	v_add_f32_e32 v14, 1.0, v14
	v_rcp_f32_e32 v14, v14
	v_add_f32_e32 v0, 1.0, v18
	v_rcp_f32_e32 v0, v0
	v_add_f32_e32 v8, v8, v34
	v_mul_f32_e32 v7, v14, v7
	v_mul_f32_e32 v7, v7, v8
	v_mul_f32_e32 v0, v0, v15
	v_add_f32_e32 v8, v9, v34
	v_mul_f32_e32 v0, v0, v8
	v_cvt_pk_bf16_f32 v7, v7, v0
	s_waitcnt vmcnt(2)
	v_lshlrev_b32_e32 v0, 16, v20
	v_mul_f32_e32 v8, v0, v0
	v_and_b32_e32 v9, 0xffff0000, v20
	v_fmamk_f32 v8, v8, 0xbdd2d3e7, v129
	v_mul_f32_e32 v14, v9, v9
	v_mul_f32_e32 v8, v8, v0
	v_fmamk_f32 v14, v14, 0xbdd2d3e7, v129
	v_mul_f32_e32 v14, v14, v9
	v_exp_f32_e32 v8, v8
	v_exp_f32_e32 v14, v14
	global_store_dwordx2 v[16:17], v[6:7], off offset:32
	v_add_f32_e32 v8, 1.0, v8
	v_rcp_f32_e32 v8, v8
	v_add_f32_e32 v6, 1.0, v14
	v_rcp_f32_e32 v6, v6
	v_add_f32_e32 v2, v2, v34
	v_mul_f32_e32 v0, v8, v0
	v_mul_f32_e32 v0, v0, v2
	v_mul_f32_e32 v2, v6, v9
	v_add_f32_e32 v3, v3, v34
	v_mul_f32_e32 v2, v2, v3
	v_lshlrev_b32_e32 v3, 16, v21
	v_mul_f32_e32 v6, v3, v3
	v_and_b32_e32 v7, 0xffff0000, v21
	v_fmamk_f32 v6, v6, 0xbdd2d3e7, v129
	v_mul_f32_e32 v8, v7, v7
	v_mul_f32_e32 v6, v6, v3
	v_fmamk_f32 v8, v8, 0xbdd2d3e7, v129
	v_mul_f32_e32 v8, v8, v7
	v_exp_f32_e32 v6, v6
	v_exp_f32_e32 v8, v8
	v_cvt_pk_bf16_f32 v2, v0, v2
	v_add_f32_e32 v6, 1.0, v6
	v_rcp_f32_e32 v6, v6
	v_add_f32_e32 v0, 1.0, v8
	v_rcp_f32_e32 v0, v0
	v_add_f32_e32 v4, v4, v34
	v_mul_f32_e32 v3, v6, v3
	v_mul_f32_e32 v3, v3, v4
	v_mul_f32_e32 v0, v0, v7
	v_add_f32_e32 v4, v5, v34
	v_mul_f32_e32 v0, v0, v4
	v_cvt_pk_bf16_f32 v3, v3, v0
	s_waitcnt vmcnt(2)
	v_lshlrev_b32_e32 v0, 16, v22
	v_mul_f32_e32 v4, v0, v0
	v_and_b32_e32 v5, 0xffff0000, v22
	v_fmamk_f32 v4, v4, 0xbdd2d3e7, v129
	v_mul_f32_e32 v6, v5, v5
	v_mul_f32_e32 v4, v4, v0
	v_fmamk_f32 v6, v6, 0xbdd2d3e7, v129
	v_mul_f32_e32 v6, v6, v5
	v_exp_f32_e32 v4, v4
	v_exp_f32_e32 v6, v6
	global_store_dwordx2 v[16:17], v[2:3], off offset:64
	v_add_f32_e32 v4, 1.0, v4
	v_rcp_f32_e32 v4, v4
	v_add_f32_e32 v2, 1.0, v6
	v_rcp_f32_e32 v2, v2
	v_add_f32_e32 v3, v10, v34
	v_mul_f32_e32 v0, v4, v0
	v_mul_f32_e32 v0, v0, v3
	v_mul_f32_e32 v2, v2, v5
	v_add_f32_e32 v3, v11, v34
	v_mul_f32_e32 v2, v2, v3
	v_lshlrev_b32_e32 v3, 16, v23
	v_mul_f32_e32 v4, v3, v3
	v_and_b32_e32 v5, 0xffff0000, v23
	v_fmamk_f32 v4, v4, 0xbdd2d3e7, v129
	v_mul_f32_e32 v6, v5, v5
	v_mul_f32_e32 v4, v4, v3
	v_fmamk_f32 v6, v6, 0xbdd2d3e7, v129
	v_mul_f32_e32 v6, v6, v5
	v_exp_f32_e32 v4, v4
	v_exp_f32_e32 v6, v6
	v_cvt_pk_bf16_f32 v2, v0, v2
	v_add_f32_e32 v4, 1.0, v4
	v_rcp_f32_e32 v4, v4
	v_add_f32_e32 v0, 1.0, v6
	v_rcp_f32_e32 v0, v0
	v_mul_f32_e32 v3, v4, v3
	v_add_f32_e32 v4, v12, v34
	v_mul_f32_e32 v3, v3, v4
	v_mul_f32_e32 v0, v0, v5
	v_add_f32_e32 v4, v13, v34
	v_mul_f32_e32 v0, v0, v4
	v_cvt_pk_bf16_f32 v3, v3, v0
	global_store_dwordx2 v[16:17], v[2:3], off offset:96
	s_barrier

.LBB0_621:
	v_lshl_add_u64 v[16:17], v[12:13], 0, s[0:1]
	global_load_dwordx4 v[2:5], v[16:17], off offset:1072
	global_load_dwordx4 v[6:9], v[16:17], off offset:1056
	global_load_dwordx4 v[20:23], v[16:17], off offset:1040
	global_load_dwordx4 v[24:27], v[16:17], off offset:1024
	s_add_u32 s0, s0, 0x80
	s_addc_u32 s1, s1, 0
	s_cmpk_lg_i32 s0, 0x200
	s_waitcnt vmcnt(0)
	v_lshlrev_b32_e32 v0, 16, v24
	v_mul_f32_e32 v19, v0, v0
	v_fmamk_f32 v19, v19, 0xbdd2d3e7, v129
	v_mul_f32_e32 v19, v19, v0
	v_exp_f32_e32 v19, v19
	v_and_b32_e32 v40, 0xffff0000, v27
	v_add_f32_e32 v19, 1.0, v19
	v_rcp_f32_e32 v19, v19
	s_nop 0
	v_mul_f32_e32 v29, v19, v0
	v_and_b32_e32 v0, 0xffff0000, v24
	v_mul_f32_e32 v19, v0, v0
	v_fmamk_f32 v19, v19, 0xbdd2d3e7, v129
	v_mul_f32_e32 v19, v19, v0
	v_exp_f32_e32 v19, v19
	v_mul_f32_e32 v28, v29, v29
	v_add_f32_e32 v19, 1.0, v19
	v_rcp_f32_e32 v19, v19
	s_nop 0
	v_mul_f32_e32 v33, v19, v0
	v_lshlrev_b32_e32 v0, 16, v25
	v_mul_f32_e32 v19, v0, v0
	v_fmamk_f32 v19, v19, 0xbdd2d3e7, v129
	v_mul_f32_e32 v19, v19, v0
	v_exp_f32_e32 v19, v19
	v_mul_f32_e32 v32, v33, v33
	v_add_f32_e32 v19, 1.0, v19
	v_rcp_f32_e32 v19, v19
	s_nop 0
	v_mul_f32_e32 v35, v19, v0
	v_and_b32_e32 v0, 0xffff0000, v25
	v_mul_f32_e32 v19, v0, v0
	v_fmamk_f32 v19, v19, 0xbdd2d3e7, v129
	v_mul_f32_e32 v19, v19, v0
	v_exp_f32_e32 v19, v19
	v_mul_f32_e32 v34, v35, v35
	v_add_f32_e32 v19, 1.0, v19
	v_rcp_f32_e32 v19, v19
	s_nop 0
	v_mul_f32_e32 v25, v19, v0
	v_lshlrev_b32_e32 v0, 16, v26
	v_mul_f32_e32 v19, v0, v0
	v_fmamk_f32 v19, v19, 0xbdd2d3e7, v129
	v_mul_f32_e32 v19, v19, v0
	v_exp_f32_e32 v19, v19
	v_mul_f32_e32 v24, v25, v25
	v_pk_add_f32 v[24:25], v[34:35], v[24:25]
	v_add_f32_e32 v19, 1.0, v19
	v_rcp_f32_e32 v19, v19
	s_nop 0
	v_mul_f32_e32 v37, v19, v0
	v_and_b32_e32 v0, 0xffff0000, v26
	v_mul_f32_e32 v19, v0, v0
	v_fmamk_f32 v19, v19, 0xbdd2d3e7, v129
	v_mul_f32_e32 v19, v19, v0
	v_exp_f32_e32 v19, v19
	v_mul_f32_e32 v26, v40, v40
	v_fmamk_f32 v26, v26, 0xbdd2d3e7, v129
	v_mul_f32_e32 v26, v26, v40
	v_add_f32_e32 v19, 1.0, v19
	v_rcp_f32_e32 v19, v19
	v_exp_f32_e32 v26, v26
	v_mul_f32_e32 v39, v19, v0
	v_lshlrev_b32_e32 v0, 16, v27
	v_mul_f32_e32 v19, v0, v0
	v_fmamk_f32 v19, v19, 0xbdd2d3e7, v129
	v_mul_f32_e32 v19, v19, v0
	v_exp_f32_e32 v19, v19
	v_add_f32_e32 v26, 1.0, v26
	v_rcp_f32_e32 v41, v26
	v_pk_add_f32 v[26:27], v[28:29], v[32:33]
	v_add_f32_e32 v19, 1.0, v19
	v_rcp_f32_e32 v19, v19
	v_mul_f32_e32 v36, v37, v37
	v_mul_f32_e32 v38, v39, v39
	v_pk_add_f32 v[14:15], v[14:15], v[26:27]
	v_mul_f32_e32 v27, v41, v40
	v_pk_add_f32 v[14:15], v[14:15], v[24:25]
	v_pk_add_f32 v[24:25], v[36:37], v[38:39]
	v_mul_f32_e32 v26, v27, v27
	v_pk_add_f32 v[14:15], v[14:15], v[24:25]
	v_mul_f32_e32 v25, v19, v0
	v_lshlrev_b32_e32 v0, 16, v20
	v_mul_f32_e32 v19, v0, v0
	v_fmamk_f32 v19, v19, 0xbdd2d3e7, v129
	v_mul_f32_e32 v19, v19, v0
	v_exp_f32_e32 v19, v19
	v_mul_f32_e32 v24, v25, v25
	v_pk_add_f32 v[24:25], v[24:25], v[26:27]
	v_and_b32_e32 v36, 0xffff0000, v23
	v_add_f32_e32 v19, 1.0, v19
	v_rcp_f32_e32 v19, v19
	v_pk_add_f32 v[14:15], v[14:15], v[24:25]
	v_mul_f32_e32 v25, v19, v0
	v_and_b32_e32 v0, 0xffff0000, v20
	v_mul_f32_e32 v19, v0, v0
	v_fmamk_f32 v19, v19, 0xbdd2d3e7, v129
	v_mul_f32_e32 v19, v19, v0
	v_exp_f32_e32 v19, v19
	v_mul_f32_e32 v24, v25, v25
	v_add_f32_e32 v19, 1.0, v19
	v_rcp_f32_e32 v19, v19
	s_nop 0
	v_mul_f32_e32 v27, v19, v0
	v_lshlrev_b32_e32 v0, 16, v21
	v_mul_f32_e32 v19, v0, v0
	v_fmamk_f32 v19, v19, 0xbdd2d3e7, v129
	v_mul_f32_e32 v19, v19, v0
	v_exp_f32_e32 v19, v19
	v_mul_f32_e32 v26, v27, v27
	v_add_f32_e32 v19, 1.0, v19
	v_rcp_f32_e32 v19, v19
	s_nop 0
	v_mul_f32_e32 v29, v19, v0
	v_and_b32_e32 v0, 0xffff0000, v21
	v_mul_f32_e32 v19, v0, v0
	v_fmamk_f32 v19, v19, 0xbdd2d3e7, v129
	v_mul_f32_e32 v19, v19, v0
	v_exp_f32_e32 v19, v19
	v_mul_f32_e32 v28, v29, v29
	v_add_f32_e32 v19, 1.0, v19
	v_rcp_f32_e32 v19, v19
	s_nop 0
	v_mul_f32_e32 v21, v19, v0
	v_lshlrev_b32_e32 v0, 16, v22
	v_mul_f32_e32 v19, v0, v0
	v_fmamk_f32 v19, v19, 0xbdd2d3e7, v129
	v_mul_f32_e32 v19, v19, v0
	v_exp_f32_e32 v19, v19
	v_mul_f32_e32 v20, v21, v21
	v_pk_add_f32 v[20:21], v[28:29], v[20:21]
	v_add_f32_e32 v19, 1.0, v19
	v_rcp_f32_e32 v19, v19
	s_nop 0
	v_mul_f32_e32 v33, v19, v0
	v_and_b32_e32 v0, 0xffff0000, v22
	v_mul_f32_e32 v19, v0, v0
	v_fmamk_f32 v19, v19, 0xbdd2d3e7, v129
	v_mul_f32_e32 v19, v19, v0
	v_exp_f32_e32 v19, v19
	v_mul_f32_e32 v22, v36, v36
	v_fmamk_f32 v22, v22, 0xbdd2d3e7, v129
	v_mul_f32_e32 v22, v22, v36
	v_add_f32_e32 v19, 1.0, v19
	v_rcp_f32_e32 v19, v19
	v_exp_f32_e32 v22, v22
	v_mul_f32_e32 v35, v19, v0
	v_lshlrev_b32_e32 v0, 16, v23
	v_mul_f32_e32 v19, v0, v0
	v_fmamk_f32 v19, v19, 0xbdd2d3e7, v129
	v_mul_f32_e32 v19, v19, v0
	v_exp_f32_e32 v19, v19
	v_add_f32_e32 v22, 1.0, v22
	v_rcp_f32_e32 v37, v22
	v_pk_add_f32 v[22:23], v[24:25], v[26:27]
	v_add_f32_e32 v19, 1.0, v19
	v_rcp_f32_e32 v19, v19
	v_mul_f32_e32 v32, v33, v33
	v_mul_f32_e32 v34, v35, v35
	v_pk_add_f32 v[14:15], v[14:15], v[22:23]
	v_mul_f32_e32 v23, v37, v36
	v_pk_add_f32 v[14:15], v[14:15], v[20:21]
	v_pk_add_f32 v[20:21], v[32:33], v[34:35]
	v_mul_f32_e32 v22, v23, v23
	v_pk_add_f32 v[14:15], v[14:15], v[20:21]
	v_mul_f32_e32 v21, v19, v0
	v_lshlrev_b32_e32 v0, 16, v6
	v_mul_f32_e32 v19, v0, v0
	v_fmamk_f32 v19, v19, 0xbdd2d3e7, v129
	v_mul_f32_e32 v19, v19, v0
	v_exp_f32_e32 v19, v19
	v_mul_f32_e32 v20, v21, v21
	v_pk_add_f32 v[20:21], v[20:21], v[22:23]
	v_and_b32_e32 v32, 0xffff0000, v9
	v_add_f32_e32 v19, 1.0, v19
	v_rcp_f32_e32 v19, v19
	v_pk_add_f32 v[14:15], v[14:15], v[20:21]
	v_mul_f32_e32 v21, v19, v0
	v_and_b32_e32 v0, 0xffff0000, v6
	v_mul_f32_e32 v6, v0, v0
	v_fmamk_f32 v6, v6, 0xbdd2d3e7, v129
	v_mul_f32_e32 v6, v6, v0
	v_exp_f32_e32 v6, v6
	v_mul_f32_e32 v20, v21, v21
	v_add_f32_e32 v6, 1.0, v6
	v_rcp_f32_e32 v6, v6
	s_nop 0
	v_mul_f32_e32 v23, v6, v0
	v_lshlrev_b32_e32 v0, 16, v7
	v_mul_f32_e32 v6, v0, v0
	v_fmamk_f32 v6, v6, 0xbdd2d3e7, v129
	v_mul_f32_e32 v6, v6, v0
	v_exp_f32_e32 v6, v6
	v_mul_f32_e32 v22, v23, v23
	v_add_f32_e32 v6, 1.0, v6
	v_rcp_f32_e32 v6, v6
	s_nop 0
	v_mul_f32_e32 v25, v6, v0
	v_and_b32_e32 v0, 0xffff0000, v7
	v_mul_f32_e32 v6, v0, v0
	v_fmamk_f32 v6, v6, 0xbdd2d3e7, v129
	v_mul_f32_e32 v6, v6, v0
	v_exp_f32_e32 v6, v6
	v_mul_f32_e32 v24, v25, v25
	v_add_f32_e32 v6, 1.0, v6
	v_rcp_f32_e32 v6, v6
	s_nop 0
	v_mul_f32_e32 v7, v6, v0
	v_lshlrev_b32_e32 v0, 16, v8
	v_mul_f32_e32 v19, v0, v0
	v_fmamk_f32 v19, v19, 0xbdd2d3e7, v129
	v_mul_f32_e32 v19, v19, v0
	v_exp_f32_e32 v19, v19
	v_mul_f32_e32 v6, v7, v7
	v_pk_add_f32 v[6:7], v[24:25], v[6:7]
	v_add_f32_e32 v19, 1.0, v19
	v_rcp_f32_e32 v19, v19
	s_nop 0
	v_mul_f32_e32 v27, v19, v0
	v_and_b32_e32 v0, 0xffff0000, v8
	v_mul_f32_e32 v8, v0, v0
	v_fmamk_f32 v8, v8, 0xbdd2d3e7, v129
	v_mul_f32_e32 v8, v8, v0
	v_exp_f32_e32 v8, v8
	v_mul_f32_e32 v26, v27, v27
	v_add_f32_e32 v8, 1.0, v8
	v_rcp_f32_e32 v8, v8
	s_nop 0
	v_mul_f32_e32 v29, v8, v0
	v_lshlrev_b32_e32 v0, 16, v9
	v_mul_f32_e32 v8, v0, v0
	v_fmamk_f32 v8, v8, 0xbdd2d3e7, v129
	v_mul_f32_e32 v8, v8, v0
	v_exp_f32_e32 v8, v8
	v_mul_f32_e32 v28, v29, v29
	v_add_f32_e32 v8, 1.0, v8
	v_rcp_f32_e32 v19, v8
	v_mul_f32_e32 v8, v32, v32
	v_fmamk_f32 v8, v8, 0xbdd2d3e7, v129
	v_mul_f32_e32 v8, v8, v32
	v_exp_f32_e32 v8, v8
	s_nop 0
	v_add_f32_e32 v8, 1.0, v8
	v_rcp_f32_e32 v33, v8
	v_pk_add_f32 v[8:9], v[20:21], v[22:23]
	s_nop 0
	v_pk_add_f32 v[8:9], v[14:15], v[8:9]
	v_mul_f32_e32 v15, v33, v32
	v_pk_add_f32 v[6:7], v[8:9], v[6:7]
	v_pk_add_f32 v[8:9], v[26:27], v[28:29]
	v_mul_f32_e32 v14, v15, v15
	v_pk_add_f32 v[6:7], v[6:7], v[8:9]
	v_mul_f32_e32 v9, v19, v0
	v_mul_f32_e32 v8, v9, v9
	v_pk_add_f32 v[8:9], v[8:9], v[14:15]
	v_lshlrev_b32_e32 v0, 16, v2
	v_pk_add_f32 v[6:7], v[6:7], v[8:9]
	v_mul_f32_e32 v8, v0, v0
	v_fmamk_f32 v8, v8, 0xbdd2d3e7, v129
	v_mul_f32_e32 v8, v8, v0
	v_exp_f32_e32 v8, v8
	v_and_b32_e32 v26, 0xffff0000, v5
	v_add_f32_e32 v8, 1.0, v8
	v_rcp_f32_e32 v8, v8
	s_nop 0
	v_mul_f32_e32 v9, v8, v0
	v_and_b32_e32 v0, 0xffff0000, v2
	v_mul_f32_e32 v2, v0, v0
	v_fmamk_f32 v2, v2, 0xbdd2d3e7, v129
	v_mul_f32_e32 v2, v2, v0
	v_exp_f32_e32 v2, v2
	v_mul_f32_e32 v8, v9, v9
	v_add_f32_e32 v2, 1.0, v2
	v_rcp_f32_e32 v2, v2
	s_nop 0
	v_mul_f32_e32 v15, v2, v0
	v_lshlrev_b32_e32 v0, 16, v3
	v_mul_f32_e32 v2, v0, v0
	v_fmamk_f32 v2, v2, 0xbdd2d3e7, v129
	v_mul_f32_e32 v2, v2, v0
	v_exp_f32_e32 v2, v2
	v_mul_f32_e32 v14, v15, v15
	v_add_f32_e32 v2, 1.0, v2
	v_rcp_f32_e32 v2, v2
	s_nop 0
	v_mul_f32_e32 v21, v2, v0
	v_and_b32_e32 v0, 0xffff0000, v3
	v_mul_f32_e32 v2, v0, v0
	v_fmamk_f32 v2, v2, 0xbdd2d3e7, v129
	v_mul_f32_e32 v2, v2, v0
	v_exp_f32_e32 v2, v2
	v_mul_f32_e32 v20, v21, v21
	v_add_f32_e32 v2, 1.0, v2
	v_rcp_f32_e32 v2, v2
	s_nop 0
	v_mul_f32_e32 v3, v2, v0
	v_lshlrev_b32_e32 v0, 16, v4
	v_mul_f32_e32 v19, v0, v0
	v_fmamk_f32 v19, v19, 0xbdd2d3e7, v129
	v_mul_f32_e32 v19, v19, v0
	v_exp_f32_e32 v19, v19
	v_mul_f32_e32 v2, v3, v3
	v_pk_add_f32 v[2:3], v[20:21], v[2:3]
	v_add_f32_e32 v19, 1.0, v19
	v_rcp_f32_e32 v19, v19
	s_nop 0
	v_mul_f32_e32 v23, v19, v0
	v_and_b32_e32 v0, 0xffff0000, v4
	v_mul_f32_e32 v4, v0, v0
	v_fmamk_f32 v4, v4, 0xbdd2d3e7, v129
	v_mul_f32_e32 v4, v4, v0
	v_exp_f32_e32 v4, v4
	v_mul_f32_e32 v22, v23, v23
	v_add_f32_e32 v4, 1.0, v4
	v_rcp_f32_e32 v4, v4
	s_nop 0
	v_mul_f32_e32 v25, v4, v0
	v_lshlrev_b32_e32 v0, 16, v5
	v_mul_f32_e32 v4, v0, v0
	v_fmamk_f32 v4, v4, 0xbdd2d3e7, v129
	v_mul_f32_e32 v4, v4, v0
	v_exp_f32_e32 v4, v4
	v_mul_f32_e32 v24, v25, v25
	v_add_f32_e32 v4, 1.0, v4
	v_rcp_f32_e32 v19, v4
	v_mul_f32_e32 v4, v26, v26
	v_fmamk_f32 v4, v4, 0xbdd2d3e7, v129
	v_mul_f32_e32 v4, v4, v26
	v_exp_f32_e32 v4, v4
	s_nop 0
	v_add_f32_e32 v4, 1.0, v4
	v_rcp_f32_e32 v27, v4
	v_pk_add_f32 v[4:5], v[8:9], v[14:15]
	s_nop 0
	v_pk_add_f32 v[4:5], v[6:7], v[4:5]
	v_mul_f32_e32 v7, v27, v26
	v_pk_add_f32 v[2:3], v[4:5], v[2:3]
	v_pk_add_f32 v[4:5], v[22:23], v[24:25]
	v_mul_f32_e32 v6, v7, v7
	v_pk_add_f32 v[2:3], v[2:3], v[4:5]
	v_mul_f32_e32 v5, v19, v0
	v_mul_f32_e32 v4, v5, v5
	v_pk_add_f32 v[4:5], v[4:5], v[6:7]
	s_nop 0
	v_pk_add_f32 v[24:25], v[2:3], v[4:5]
	global_load_dwordx4 v[2:5], v[16:17], off offset:1136
	global_load_dwordx4 v[6:9], v[16:17], off offset:1120
	global_load_dwordx4 v[20:23], v[16:17], off offset:1104
	s_nop 0
	global_load_dwordx4 v[14:17], v[16:17], off offset:1088
	s_waitcnt vmcnt(0)
	v_lshlrev_b32_e32 v0, 16, v14
	v_mul_f32_e32 v19, v0, v0
	v_fmamk_f32 v19, v19, 0xbdd2d3e7, v129
	v_mul_f32_e32 v19, v19, v0
	v_exp_f32_e32 v19, v19
	v_and_b32_e32 v38, 0xffff0000, v17
	v_add_f32_e32 v19, 1.0, v19
	v_rcp_f32_e32 v19, v19
	s_nop 0
	v_mul_f32_e32 v27, v19, v0
	v_and_b32_e32 v0, 0xffff0000, v14
	v_mul_f32_e32 v14, v0, v0
	v_fmamk_f32 v14, v14, 0xbdd2d3e7, v129
	v_mul_f32_e32 v14, v14, v0
	v_exp_f32_e32 v14, v14
	v_mul_f32_e32 v26, v27, v27
	v_add_f32_e32 v14, 1.0, v14
	v_rcp_f32_e32 v14, v14
	s_nop 0
	v_mul_f32_e32 v29, v14, v0
	v_lshlrev_b32_e32 v0, 16, v15
	v_mul_f32_e32 v14, v0, v0
	v_fmamk_f32 v14, v14, 0xbdd2d3e7, v129
	v_mul_f32_e32 v14, v14, v0
	v_exp_f32_e32 v14, v14
	v_mul_f32_e32 v28, v29, v29
	v_add_f32_e32 v14, 1.0, v14
	v_rcp_f32_e32 v14, v14
	s_nop 0
	v_mul_f32_e32 v33, v14, v0
	v_and_b32_e32 v0, 0xffff0000, v15
	v_mul_f32_e32 v14, v0, v0
	v_fmamk_f32 v14, v14, 0xbdd2d3e7, v129
	v_mul_f32_e32 v14, v14, v0
	v_exp_f32_e32 v14, v14
	v_mul_f32_e32 v32, v33, v33
	v_add_f32_e32 v14, 1.0, v14
	v_rcp_f32_e32 v14, v14
	s_nop 0
	v_mul_f32_e32 v15, v14, v0
	v_lshlrev_b32_e32 v0, 16, v16
	v_mul_f32_e32 v19, v0, v0
	v_fmamk_f32 v19, v19, 0xbdd2d3e7, v129
	v_mul_f32_e32 v19, v19, v0
	v_exp_f32_e32 v19, v19
	v_mul_f32_e32 v14, v15, v15
	v_pk_add_f32 v[14:15], v[32:33], v[14:15]
	v_add_f32_e32 v19, 1.0, v19
	v_rcp_f32_e32 v19, v19
	s_nop 0
	v_mul_f32_e32 v35, v19, v0
	v_and_b32_e32 v0, 0xffff0000, v16
	v_mul_f32_e32 v16, v0, v0
	v_fmamk_f32 v16, v16, 0xbdd2d3e7, v129
	v_mul_f32_e32 v16, v16, v0
	v_exp_f32_e32 v16, v16
	v_mul_f32_e32 v34, v35, v35
	v_add_f32_e32 v16, 1.0, v16
	v_rcp_f32_e32 v16, v16
	s_nop 0
	v_mul_f32_e32 v37, v16, v0
	v_lshlrev_b32_e32 v0, 16, v17
	v_mul_f32_e32 v16, v0, v0
	v_fmamk_f32 v16, v16, 0xbdd2d3e7, v129
	v_mul_f32_e32 v16, v16, v0
	v_exp_f32_e32 v16, v16
	v_mul_f32_e32 v36, v37, v37
	v_add_f32_e32 v16, 1.0, v16
	v_rcp_f32_e32 v19, v16
	v_mul_f32_e32 v16, v38, v38
	v_fmamk_f32 v16, v16, 0xbdd2d3e7, v129
	v_mul_f32_e32 v16, v16, v38
	v_exp_f32_e32 v16, v16
	s_nop 0
	v_add_f32_e32 v16, 1.0, v16
	v_rcp_f32_e32 v39, v16
	v_pk_add_f32 v[16:17], v[26:27], v[28:29]
	s_nop 0
	v_pk_add_f32 v[16:17], v[24:25], v[16:17]
	v_mul_f32_e32 v25, v39, v38
	v_pk_add_f32 v[14:15], v[16:17], v[14:15]
	v_pk_add_f32 v[16:17], v[34:35], v[36:37]
	v_mul_f32_e32 v24, v25, v25
	v_pk_add_f32 v[14:15], v[14:15], v[16:17]
	v_mul_f32_e32 v17, v19, v0
	v_mul_f32_e32 v16, v17, v17
	v_pk_add_f32 v[16:17], v[16:17], v[24:25]
	v_lshlrev_b32_e32 v0, 16, v20
	v_pk_add_f32 v[14:15], v[14:15], v[16:17]
	v_mul_f32_e32 v16, v0, v0
	v_fmamk_f32 v16, v16, 0xbdd2d3e7, v129
	v_mul_f32_e32 v16, v16, v0
	v_exp_f32_e32 v16, v16
	s_nop 0
	v_add_f32_e32 v16, 1.0, v16
	v_rcp_f32_e32 v16, v16
	s_nop 0
	v_mul_f32_e32 v17, v16, v0
	v_and_b32_e32 v0, 0xffff0000, v20
	v_mul_f32_e32 v16, v0, v0
	v_fmamk_f32 v16, v16, 0xbdd2d3e7, v129
	v_mul_f32_e32 v16, v16, v0
	v_exp_f32_e32 v16, v16
	s_nop 0
	v_add_f32_e32 v16, 1.0, v16
	v_rcp_f32_e32 v16, v16
	s_nop 0
	v_mul_f32_e32 v25, v16, v0
	v_lshlrev_b32_e32 v0, 16, v21
	v_mul_f32_e32 v19, v0, v0
	v_fmamk_f32 v19, v19, 0xbdd2d3e7, v129
	v_mul_f32_e32 v19, v19, v0
	v_exp_f32_e32 v19, v19
	v_mul_f32_e32 v16, v17, v17
	v_mul_f32_e32 v24, v25, v25
	v_pk_add_f32 v[16:17], v[16:17], v[24:25]
	v_add_f32_e32 v19, 1.0, v19
	v_rcp_f32_e32 v19, v19
	v_pk_add_f32 v[14:15], v[14:15], v[16:17]
	v_mul_f32_e32 v27, v19, v0
	v_and_b32_e32 v0, 0xffff0000, v21
	v_mul_f32_e32 v19, v0, v0
	v_fmamk_f32 v19, v19, 0xbdd2d3e7, v129
	v_mul_f32_e32 v19, v19, v0
	v_exp_f32_e32 v19, v19
	v_mul_f32_e32 v26, v27, v27
	v_add_f32_e32 v19, 1.0, v19
	v_rcp_f32_e32 v19, v19
	s_nop 0
	v_mul_f32_e32 v21, v19, v0
	v_lshlrev_b32_e32 v0, 16, v22
	v_mul_f32_e32 v19, v0, v0
	v_fmamk_f32 v19, v19, 0xbdd2d3e7, v129
	v_mul_f32_e32 v19, v19, v0
	v_exp_f32_e32 v19, v19
	v_mul_f32_e32 v20, v21, v21
	v_pk_add_f32 v[16:17], v[26:27], v[20:21]
	v_add_f32_e32 v19, 1.0, v19
	v_rcp_f32_e32 v19, v19
	v_pk_add_f32 v[14:15], v[14:15], v[16:17]
	v_mul_f32_e32 v29, v19, v0
	v_and_b32_e32 v0, 0xffff0000, v22
	v_mul_f32_e32 v19, v0, v0
	v_fmamk_f32 v19, v19, 0xbdd2d3e7, v129
	v_mul_f32_e32 v19, v19, v0
	v_exp_f32_e32 v19, v19
	v_and_b32_e32 v22, 0xffff0000, v23
	v_mul_f32_e32 v28, v29, v29
	v_add_f32_e32 v19, 1.0, v19
	v_rcp_f32_e32 v19, v19
	s_nop 0
	v_mul_f32_e32 v33, v19, v0
	v_lshlrev_b32_e32 v0, 16, v23
	v_mul_f32_e32 v19, v0, v0
	v_mul_f32_e32 v23, v22, v22
	v_fmamk_f32 v19, v19, 0xbdd2d3e7, v129
	v_fmamk_f32 v23, v23, 0xbdd2d3e7, v129
	v_mul_f32_e32 v19, v19, v0
	v_mul_f32_e32 v23, v23, v22
	v_exp_f32_e32 v19, v19
	v_exp_f32_e32 v23, v23
	v_mul_f32_e32 v32, v33, v33
	v_pk_add_f32 v[16:17], v[28:29], v[32:33]
	v_add_f32_e32 v19, 1.0, v19
	v_add_f32_e32 v23, 1.0, v23
	v_rcp_f32_e32 v19, v19
	v_rcp_f32_e32 v23, v23
	v_pk_add_f32 v[14:15], v[14:15], v[16:17]
	v_and_b32_e32 v28, 0xffff0000, v9
	v_mul_f32_e32 v17, v19, v0
	v_mul_f32_e32 v21, v23, v22
	v_mul_f32_e32 v16, v17, v17
	v_mul_f32_e32 v20, v21, v21
	v_pk_add_f32 v[16:17], v[16:17], v[20:21]
	v_lshlrev_b32_e32 v0, 16, v6
	v_pk_add_f32 v[14:15], v[14:15], v[16:17]
	v_mul_f32_e32 v16, v0, v0
	v_fmamk_f32 v16, v16, 0xbdd2d3e7, v129
	v_mul_f32_e32 v16, v16, v0
	v_exp_f32_e32 v16, v16
	s_nop 0
	v_add_f32_e32 v16, 1.0, v16
	v_rcp_f32_e32 v16, v16
	s_nop 0
	v_mul_f32_e32 v17, v16, v0
	v_and_b32_e32 v0, 0xffff0000, v6
	v_mul_f32_e32 v6, v0, v0
	v_fmamk_f32 v6, v6, 0xbdd2d3e7, v129
	v_mul_f32_e32 v6, v6, v0
	v_exp_f32_e32 v6, v6
	v_mul_f32_e32 v16, v17, v17
	v_add_f32_e32 v6, 1.0, v6
	v_rcp_f32_e32 v6, v6
	s_nop 0
	v_mul_f32_e32 v21, v6, v0
	v_lshlrev_b32_e32 v0, 16, v7
	v_mul_f32_e32 v6, v0, v0
	v_fmamk_f32 v6, v6, 0xbdd2d3e7, v129
	v_mul_f32_e32 v6, v6, v0
	v_exp_f32_e32 v6, v6
	v_mul_f32_e32 v20, v21, v21
	v_add_f32_e32 v6, 1.0, v6
	v_rcp_f32_e32 v6, v6
	s_nop 0
	v_mul_f32_e32 v23, v6, v0
	v_and_b32_e32 v0, 0xffff0000, v7
	v_mul_f32_e32 v6, v0, v0
	v_fmamk_f32 v6, v6, 0xbdd2d3e7, v129
	v_mul_f32_e32 v6, v6, v0
	v_exp_f32_e32 v6, v6
	v_mul_f32_e32 v22, v23, v23
	v_add_f32_e32 v6, 1.0, v6
	v_rcp_f32_e32 v6, v6
	s_nop 0
	v_mul_f32_e32 v7, v6, v0
	v_lshlrev_b32_e32 v0, 16, v8
	v_mul_f32_e32 v19, v0, v0
	v_fmamk_f32 v19, v19, 0xbdd2d3e7, v129
	v_mul_f32_e32 v19, v19, v0
	v_exp_f32_e32 v19, v19
	v_mul_f32_e32 v6, v7, v7
	v_pk_add_f32 v[6:7], v[22:23], v[6:7]
	v_add_f32_e32 v19, 1.0, v19
	v_rcp_f32_e32 v19, v19
	s_nop 0
	v_mul_f32_e32 v25, v19, v0
	v_and_b32_e32 v0, 0xffff0000, v8
	v_mul_f32_e32 v8, v0, v0
	v_fmamk_f32 v8, v8, 0xbdd2d3e7, v129
	v_mul_f32_e32 v8, v8, v0
	v_exp_f32_e32 v8, v8
	v_mul_f32_e32 v24, v25, v25
	v_add_f32_e32 v8, 1.0, v8
	v_rcp_f32_e32 v8, v8
	s_nop 0
	v_mul_f32_e32 v27, v8, v0
	v_lshlrev_b32_e32 v0, 16, v9
	v_mul_f32_e32 v8, v0, v0
	v_fmamk_f32 v8, v8, 0xbdd2d3e7, v129
	v_mul_f32_e32 v8, v8, v0
	v_exp_f32_e32 v8, v8
	v_mul_f32_e32 v26, v27, v27
	v_add_f32_e32 v8, 1.0, v8
	v_rcp_f32_e32 v19, v8
	v_mul_f32_e32 v8, v28, v28
	v_fmamk_f32 v8, v8, 0xbdd2d3e7, v129
	v_mul_f32_e32 v8, v8, v28
	v_exp_f32_e32 v8, v8
	s_nop 0
	v_add_f32_e32 v8, 1.0, v8
	v_rcp_f32_e32 v29, v8
	v_pk_add_f32 v[8:9], v[16:17], v[20:21]
	s_nop 0
	v_pk_add_f32 v[8:9], v[14:15], v[8:9]
	v_mul_f32_e32 v15, v29, v28
	v_pk_add_f32 v[6:7], v[8:9], v[6:7]
	v_pk_add_f32 v[8:9], v[24:25], v[26:27]
	v_mul_f32_e32 v14, v15, v15
	v_pk_add_f32 v[6:7], v[6:7], v[8:9]
	v_mul_f32_e32 v9, v19, v0
	v_mul_f32_e32 v8, v9, v9
	v_pk_add_f32 v[8:9], v[8:9], v[14:15]
	v_lshlrev_b32_e32 v0, 16, v2
	v_pk_add_f32 v[6:7], v[6:7], v[8:9]
	v_mul_f32_e32 v8, v0, v0
	v_fmamk_f32 v8, v8, 0xbdd2d3e7, v129
	v_mul_f32_e32 v8, v8, v0
	v_exp_f32_e32 v8, v8
	v_and_b32_e32 v24, 0xffff0000, v5
	v_add_f32_e32 v8, 1.0, v8
	v_rcp_f32_e32 v8, v8
	s_nop 0
	v_mul_f32_e32 v9, v8, v0
	v_and_b32_e32 v0, 0xffff0000, v2
	v_mul_f32_e32 v2, v0, v0
	v_fmamk_f32 v2, v2, 0xbdd2d3e7, v129
	v_mul_f32_e32 v2, v2, v0
	v_exp_f32_e32 v2, v2
	v_mul_f32_e32 v8, v9, v9
	v_add_f32_e32 v2, 1.0, v2
	v_rcp_f32_e32 v2, v2
	s_nop 0
	v_mul_f32_e32 v15, v2, v0
	v_lshlrev_b32_e32 v0, 16, v3
	v_mul_f32_e32 v2, v0, v0
	v_fmamk_f32 v2, v2, 0xbdd2d3e7, v129
	v_mul_f32_e32 v2, v2, v0
	v_exp_f32_e32 v2, v2
	v_mul_f32_e32 v14, v15, v15
	v_add_f32_e32 v2, 1.0, v2
	v_rcp_f32_e32 v2, v2
	s_nop 0
	v_mul_f32_e32 v17, v2, v0
	v_and_b32_e32 v0, 0xffff0000, v3
	v_mul_f32_e32 v2, v0, v0
	v_fmamk_f32 v2, v2, 0xbdd2d3e7, v129
	v_mul_f32_e32 v2, v2, v0
	v_exp_f32_e32 v2, v2
	v_mul_f32_e32 v16, v17, v17
	v_add_f32_e32 v2, 1.0, v2
	v_rcp_f32_e32 v2, v2
	s_nop 0
	v_mul_f32_e32 v3, v2, v0
	v_lshlrev_b32_e32 v0, 16, v4
	v_mul_f32_e32 v19, v0, v0
	v_fmamk_f32 v19, v19, 0xbdd2d3e7, v129
	v_mul_f32_e32 v19, v19, v0
	v_exp_f32_e32 v19, v19
	v_mul_f32_e32 v2, v3, v3
	v_pk_add_f32 v[2:3], v[16:17], v[2:3]
	v_add_f32_e32 v19, 1.0, v19
	v_rcp_f32_e32 v19, v19
	s_nop 0
	v_mul_f32_e32 v21, v19, v0
	v_and_b32_e32 v0, 0xffff0000, v4
	v_mul_f32_e32 v4, v0, v0
	v_fmamk_f32 v4, v4, 0xbdd2d3e7, v129
	v_mul_f32_e32 v4, v4, v0
	v_exp_f32_e32 v4, v4
	v_mul_f32_e32 v20, v21, v21
	v_add_f32_e32 v4, 1.0, v4
	v_rcp_f32_e32 v4, v4
	s_nop 0
	v_mul_f32_e32 v23, v4, v0
	v_lshlrev_b32_e32 v0, 16, v5
	v_mul_f32_e32 v4, v0, v0
	v_fmamk_f32 v4, v4, 0xbdd2d3e7, v129
	v_mul_f32_e32 v4, v4, v0
	v_exp_f32_e32 v4, v4
	v_mul_f32_e32 v22, v23, v23
	v_add_f32_e32 v4, 1.0, v4
	v_rcp_f32_e32 v19, v4
	v_mul_f32_e32 v4, v24, v24
	v_fmamk_f32 v4, v4, 0xbdd2d3e7, v129
	v_mul_f32_e32 v4, v4, v24
	v_exp_f32_e32 v4, v4
	s_nop 0
	v_add_f32_e32 v4, 1.0, v4
	v_rcp_f32_e32 v25, v4
	v_pk_add_f32 v[4:5], v[8:9], v[14:15]
	s_nop 0
	v_pk_add_f32 v[4:5], v[6:7], v[4:5]
	v_mul_f32_e32 v7, v25, v24
	v_pk_add_f32 v[2:3], v[4:5], v[2:3]
	v_pk_add_f32 v[4:5], v[20:21], v[22:23]
	v_mul_f32_e32 v6, v7, v7
	v_pk_add_f32 v[2:3], v[2:3], v[4:5]
	v_mul_f32_e32 v5, v19, v0
	v_mul_f32_e32 v4, v5, v5
	v_pk_add_f32 v[4:5], v[4:5], v[6:7]
	s_nop 0
	v_pk_add_f32 v[14:15], v[2:3], v[4:5]
	s_cbranch_scc1 .LBB0_621
	v_readlane_b32 s0, v254, 51
	s_lshl_b32 s88, s0, 9
	v_readlane_b32 s40, v251, 6
	s_lshl_b64 s[6:7], s[88:89], 2
	v_readlane_b32 s52, v251, 18
	v_readlane_b32 s53, v251, 19
	s_add_u32 s1, s52, s6
	s_addc_u32 s2, s53, s7
	s_lshl_b32 s0, s10, 7
	s_and_b32 s0, s0, 0x180
	s_lshl_b32 s5, s0, 2
	s_add_u32 s16, s1, s5
	v_readlane_b32 s54, v251, 20
	s_addc_u32 s17, s2, 0
	v_readlane_b32 s55, v251, 21
	s_add_u32 s1, s54, s6
	s_addc_u32 s2, s55, s7
	s_add_u32 s20, s1, s5
	s_addc_u32 s21, s2, 0
	s_lshl_b32 s8, s0, 1
	s_mov_b32 s9, s89
	v_lshl_add_u64 v[2:3], v[10:11], 0, s[8:9]
	v_lshlrev_b32_e32 v0, 7, v18
	v_lshl_add_u64 v[22:23], v[2:3], 0, v[0:1]
	global_load_dwordx4 v[10:13], v[22:23], off offset:1024
	v_lshlrev_b32_e32 v20, 8, v18
	global_load_dwordx2 v[28:29], v20, s[16:17]
	global_load_dwordx2 v[36:37], v20, s[20:21]
	global_load_dwordx2 v[40:41], v20, s[16:17] offset:16
	global_load_dwordx2 v[42:43], v20, s[16:17] offset:32
	global_load_dwordx2 v[24:25], v20, s[16:17] offset:48
	global_load_dwordx2 v[44:45], v20, s[20:21] offset:16
	global_load_dwordx2 v[46:47], v20, s[20:21] offset:32
	global_load_dwordx2 v[26:27], v20, s[20:21] offset:48
	v_xor_b32_e32 v2, 1, v234
	v_cmp_lt_i32_e32 vcc, v2, v235
	s_mov_b32 s2, 0x3b000000
	v_lshlrev_b32_e32 v34, 6, v18
	v_cndmask_b32_e32 v2, v234, v2, vcc
	v_lshlrev_b32_e32 v80, 2, v2
	ds_bpermute_b32 v3, v80, v15
	ds_bpermute_b32 v2, v80, v14
	v_mul_u32_u24_e32 v4, 0x4400, v18
	v_lshlrev_b32_e32 v33, 1, v31
	s_mov_b32 s11, 0x800000
	v_add3_u32 v38, s15, v4, v33
	s_waitcnt lgkmcnt(0)
	v_pk_add_f32 v[2:3], v[14:15], v[2:3]
	v_or_b32_e32 v4, 1, v34
	v_pk_mul_f32 v[18:19], v[2:3], s[2:3] op_sel_hi:[1,0]
	v_mul_u32_u24_e32 v4, 0x110, v4
	v_fma_f32 v2, -v19, v19, v18
	v_max_f32_e32 v2, 0, v2
	v_add_f32_e32 v2, 0x358637bd, v2
	v_mul_f32_e32 v3, 0x4b800000, v2
	v_cmp_gt_f32_e32 vcc, s11, v2
	v_add3_u32 v35, s15, v4, v33
	v_or_b32_e32 v78, 7, v34
	v_cndmask_b32_e32 v2, v2, v3, vcc
	v_rsq_f32_e32 v18, v2
	global_load_dwordx4 v[14:17], v[22:23], off offset:1040
	global_load_dwordx4 v[2:5], v[22:23], off offset:1072
	global_load_dwordx4 v[6:9], v[22:23], off offset:1056
	v_or_b32_e32 v81, 10, v34
	v_or_b32_e32 v79, 11, v34
	v_mul_f32_e32 v39, 0x45800000, v18
	v_cndmask_b32_e32 v39, v18, v39, vcc
	v_readlane_b32 s41, v251, 7
	v_readlane_b32 s42, v251, 8
	v_readlane_b32 s43, v251, 9
	v_readlane_b32 s44, v251, 10
	v_readlane_b32 s45, v251, 11
	v_readlane_b32 s46, v251, 12
	v_readlane_b32 s47, v251, 13
	v_readlane_b32 s48, v251, 14
	v_readlane_b32 s49, v251, 15
	v_readlane_b32 s50, v251, 16
	v_readlane_b32 s51, v251, 17
	s_or_b32 s88, s0, s88
	v_readlane_b32 s40, v251, 22
	v_readlane_b32 s41, v251, 23
	v_mov_b32_e32 v21, v1
	v_mul_u32_u24_e32 v84, 0x110, v31
	v_add3_u32 v0, s15, v84, v0
	v_or_b32_e32 v101, 31, v34
	v_cmp_gt_u32_e32 vcc, v31, v34
	v_or_b32_e32 v57, 48, v34
	v_and_b32_e32 v32, 15, v50
	v_readlane_b32 s44, v251, 26
	v_readlane_b32 s45, v251, 27
	v_readlane_b32 s46, v251, 28
	v_readlane_b32 s47, v251, 29
	v_readlane_b32 s48, v251, 30
	v_readlane_b32 s49, v251, 31
	v_readlane_b32 s50, v251, 32
	v_readlane_b32 s51, v251, 33
	v_readlane_b32 s52, v251, 34
	v_readlane_b32 s53, v251, 35
	v_readlane_b32 s54, v251, 36
	v_readlane_b32 s55, v251, 37
	v_readlane_b32 s44, v251, 54
	v_readlane_b32 s50, v251, 60
	v_readlane_b32 s51, v251, 61
	s_add_u32 s6, s50, s8
	s_addc_u32 s7, s51, 0
	v_readlane_b32 s42, v251, 24
	v_readlane_b32 s43, v251, 25
	v_readlane_b32 s52, v251, 62
	v_readlane_b32 s53, v251, 63
	v_readlane_b32 s54, v252, 0
	v_readlane_b32 s55, v252, 1
	v_readlane_b32 s45, v251, 55
	s_waitcnt vmcnt(11)
	v_lshlrev_b32_e32 v48, 16, v11
	v_and_b32_e32 v11, 0xffff0000, v11
	v_mul_f32_e32 v54, v11, v11
	v_fmamk_f32 v54, v54, 0xbdd2d3e7, v129
	v_mul_f32_e32 v54, v54, v11
	v_lshlrev_b32_e32 v18, 16, v10
	v_and_b32_e32 v10, 0xffff0000, v10
	v_mul_f32_e32 v51, v18, v18
	v_mul_f32_e32 v52, v10, v10
	v_fmamk_f32 v51, v51, 0xbdd2d3e7, v129
	v_exp_f32_e32 v54, v54
	v_fmamk_f32 v52, v52, 0xbdd2d3e7, v129
	v_mul_f32_e32 v51, v51, v18
	v_mul_f32_e32 v52, v52, v10
	v_exp_f32_e32 v51, v51
	v_add_f32_e32 v54, 1.0, v54
	v_exp_f32_e32 v52, v52
	v_rcp_f32_e32 v54, v54
	v_lshlrev_b32_e32 v49, 16, v12
	v_mul_f32_e32 v55, v49, v49
	v_fmamk_f32 v55, v55, 0xbdd2d3e7, v129
	v_add_f32_e32 v51, 1.0, v51
	v_mul_f32_e32 v55, v55, v49
	v_add_f32_e32 v52, 1.0, v52
	v_rcp_f32_e32 v51, v51
	v_fma_f32 v11, v54, v11, -v19
	v_rcp_f32_e32 v52, v52
	v_mul_f32_e32 v59, v39, v11
	v_and_b32_e32 v11, 0xffff0000, v12
	v_mul_f32_e32 v12, v11, v11
	v_exp_f32_e32 v55, v55
	v_fmamk_f32 v12, v12, 0xbdd2d3e7, v129
	v_fma_f32 v18, v51, v18, -v19
	v_mul_f32_e32 v12, v12, v11
	v_fma_f32 v10, v52, v10, -v19
	v_mul_f32_e32 v18, v39, v18
	v_mul_f32_e32 v10, v39, v10
	s_waitcnt vmcnt(9)
	v_fma_f32 v18, v28, v18, v36
	v_lshlrev_b32_e32 v28, 16, v13
	v_add_f32_e32 v55, 1.0, v55
	v_fmac_f32_e32 v37, v29, v10
	v_exp_f32_e32 v12, v12
	v_mul_f32_e32 v29, v28, v28
	v_rcp_f32_e32 v55, v55
	v_fmamk_f32 v29, v29, 0xbdd2d3e7, v129
	v_mul_f32_e32 v29, v29, v28
	v_cvt_pk_bf16_f32 v10, v18, s0
	v_add_f32_e32 v12, 1.0, v12
	v_cvt_pk_bf16_f32 v18, v37, s0
	ds_write_b16 v38, v10 offset:34816
	ds_write_b16 v35, v18 offset:34816
	v_fma_f32 v10, v55, v49, -v19
	v_rcp_f32_e32 v12, v12
	v_exp_f32_e32 v29, v29
	v_mul_f32_e32 v10, v39, v10
	s_waitcnt vmcnt(5)
	v_fma_f32 v10, v40, v10, v44
	v_cvt_pk_bf16_f32 v10, v10, s0
	ds_write_b16 v35, v10 offset:35632
	v_fma_f32 v10, v12, v11, -v19
	v_add_f32_e32 v11, 1.0, v29
	v_rcp_f32_e32 v11, v11
	v_mul_f32_e32 v10, v39, v10
	v_fmac_f32_e32 v45, v10, v41
	v_cvt_pk_bf16_f32 v10, v45, s0
	ds_write_b16 v35, v10 offset:35904
	v_fma_f32 v10, v11, v28, -v19
	v_and_b32_e32 v11, 0xffff0000, v13
	v_mul_f32_e32 v12, v11, v11
	v_fmamk_f32 v12, v12, 0xbdd2d3e7, v129
	v_mul_f32_e32 v12, v12, v11
	v_exp_f32_e32 v12, v12
	s_waitcnt vmcnt(2)
	v_lshlrev_b32_e32 v13, 16, v14
	v_mul_f32_e32 v28, v13, v13
	v_fmamk_f32 v28, v28, 0xbdd2d3e7, v129
	v_add_f32_e32 v12, 1.0, v12
	v_rcp_f32_e32 v12, v12
	v_mul_f32_e32 v28, v28, v13
	v_fma_f32 v11, v12, v11, -v19
	v_exp_f32_e32 v28, v28
	v_mul_f32_e32 v44, v39, v11
	v_and_b32_e32 v11, 0xffff0000, v14
	v_mul_f32_e32 v12, v11, v11
	v_fmamk_f32 v12, v12, 0xbdd2d3e7, v129
	v_mul_f32_e32 v12, v12, v11
	v_mul_f32_e32 v45, v39, v10
	v_add_f32_e32 v10, 1.0, v28
	v_rcp_f32_e32 v10, v10
	v_exp_f32_e32 v12, v12
	v_lshlrev_b32_e32 v29, 16, v16
	v_fma_f32 v10, v10, v13, -v19
	v_lshlrev_b32_e32 v13, 16, v15
	v_add_f32_e32 v12, 1.0, v12
	v_mul_f32_e32 v14, v13, v13
	v_rcp_f32_e32 v12, v12
	v_fmamk_f32 v14, v14, 0xbdd2d3e7, v129
	v_mul_f32_e32 v10, v39, v10
	v_mul_f32_e32 v14, v14, v13
	v_fma_f32 v10, v42, v10, v46
	v_cvt_pk_bf16_f32 v10, v10, s0
	v_exp_f32_e32 v14, v14
	ds_write_b16 v35, v10 offset:36720
	v_fma_f32 v10, v12, v11, -v19
	v_mul_f32_e32 v10, v39, v10
	v_fmac_f32_e32 v47, v43, v10
	v_cvt_pk_bf16_f32 v10, v47, s0
	v_and_b32_e32 v15, 0xffff0000, v15
	v_add_f32_e32 v11, 1.0, v14
	ds_write_b16 v35, v10 offset:36992
	v_mul_f32_e32 v10, v15, v15
	v_rcp_f32_e32 v11, v11
	v_fmamk_f32 v10, v10, 0xbdd2d3e7, v129
	v_mul_f32_e32 v10, v10, v15
	v_fma_f32 v14, v11, v13, -v19
	v_exp_f32_e32 v28, v10
	global_load_dwordx2 v[10:11], v20, s[16:17] offset:64
	global_load_dwordx2 v[12:13], v20, s[20:21] offset:64
	v_mul_f32_e32 v37, v29, v29
	v_fmamk_f32 v37, v37, 0xbdd2d3e7, v129
	v_add_f32_e32 v28, 1.0, v28
	v_mul_f32_e32 v37, v37, v29
	v_rcp_f32_e32 v28, v28
	v_exp_f32_e32 v37, v37
	v_fma_f32 v15, v28, v15, -v19
	v_mul_f32_e32 v46, v39, v15
	v_and_b32_e32 v15, 0xffff0000, v16
	v_mul_f32_e32 v16, v15, v15
	v_mul_f32_e32 v47, v39, v14
	v_add_f32_e32 v14, 1.0, v37
	v_fmamk_f32 v16, v16, 0xbdd2d3e7, v129
	v_rcp_f32_e32 v14, v14
	v_mul_f32_e32 v16, v16, v15
	v_exp_f32_e32 v16, v16
	v_fma_f32 v14, v14, v29, -v19
	v_mul_f32_e32 v14, v39, v14
	v_fma_f32 v14, v24, v14, v26
	v_lshlrev_b32_e32 v24, 16, v17
	v_add_f32_e32 v16, 1.0, v16
	v_mul_f32_e32 v26, v24, v24
	v_rcp_f32_e32 v16, v16
	v_fmamk_f32 v26, v26, 0xbdd2d3e7, v129
	v_mul_f32_e32 v26, v26, v24
	v_cvt_pk_bf16_f32 v14, v14, s0
	v_exp_f32_e32 v26, v26
	ds_write_b16 v35, v14 offset:37808
	v_fma_f32 v14, v16, v15, -v19
	v_mul_f32_e32 v14, v39, v14
	v_fmac_f32_e32 v27, v14, v25
	v_cvt_pk_bf16_f32 v14, v27, s0
	v_and_b32_e32 v25, 0xffff0000, v17
	v_add_f32_e32 v15, 1.0, v26
	ds_write_b16 v35, v14 offset:38080
	v_mul_f32_e32 v14, v25, v25
	v_rcp_f32_e32 v15, v15
	v_fmamk_f32 v14, v14, 0xbdd2d3e7, v129
	v_mul_f32_e32 v14, v14, v25
	v_fma_f32 v24, v15, v24, -v19
	v_exp_f32_e32 v26, v14
	global_load_dwordx2 v[14:15], v20, s[16:17] offset:80
	global_load_dwordx2 v[16:17], v20, s[20:21] offset:80
	s_waitcnt vmcnt(4)
	v_lshlrev_b32_e32 v27, 16, v6
	v_mul_f32_e32 v28, v27, v27
	v_fmamk_f32 v28, v28, 0xbdd2d3e7, v129
	v_mul_f32_e32 v28, v28, v27
	v_exp_f32_e32 v28, v28
	v_mul_f32_e32 v55, v39, v24
	v_mul_f32_e32 v53, v48, v48
	v_fmamk_f32 v53, v53, 0xbdd2d3e7, v129
	v_add_f32_e32 v24, 1.0, v28
	v_rcp_f32_e32 v24, v24
	v_and_b32_e32 v6, 0xffff0000, v6
	v_mul_f32_e32 v53, v53, v48
	v_fma_f32 v24, v24, v27, -v19
	v_mul_f32_e32 v40, v39, v24
	v_mul_f32_e32 v24, v6, v6
	v_fmamk_f32 v24, v24, 0xbdd2d3e7, v129
	v_mul_f32_e32 v24, v24, v6
	v_exp_f32_e32 v53, v53
	v_exp_f32_e32 v41, v24
	v_add_f32_e32 v53, 1.0, v53
	v_add_f32_e32 v26, 1.0, v26
	v_rcp_f32_e32 v53, v53
	v_rcp_f32_e32 v26, v26
	s_waitcnt vmcnt(2)
	v_fma_f32 v10, v10, v40, v12
	v_lshlrev_b32_e32 v40, 16, v7
	v_add_f32_e32 v12, 1.0, v41
	v_mul_f32_e32 v41, v40, v40
	v_fmamk_f32 v41, v41, 0xbdd2d3e7, v129
	v_mul_f32_e32 v41, v41, v40
	v_fma_f32 v48, v53, v48, -v19
	v_fma_f32 v25, v26, v25, -v19
	v_mul_f32_e32 v65, v39, v48
	v_mul_f32_e32 v54, v39, v25
	global_load_dwordx2 v[24:25], v20, s[16:17] offset:96
	global_load_dwordx2 v[28:29], v20, s[16:17] offset:112
	global_load_dwordx2 v[26:27], v20, s[20:21] offset:96
	global_load_dwordx2 v[48:49], v20, s[20:21] offset:112
	v_exp_f32_e32 v41, v41
	v_rcp_f32_e32 v12, v12
	v_cvt_pk_bf16_f32 v10, v10, s0
	ds_write_b16 v35, v10 offset:38896
	v_add_f32_e32 v10, 1.0, v41
	v_fma_f32 v6, v12, v6, -v19
	v_rcp_f32_e32 v10, v10
	v_mul_f32_e32 v6, v39, v6
	v_fmac_f32_e32 v13, v11, v6
	v_cvt_pk_bf16_f32 v6, v13, s0
	v_and_b32_e32 v7, 0xffff0000, v7
	ds_write_b16 v35, v6 offset:39168
	v_fma_f32 v6, v10, v40, -v19
	v_mul_f32_e32 v10, v7, v7
	v_fmamk_f32 v10, v10, 0xbdd2d3e7, v129
	v_mul_f32_e32 v10, v10, v7
	v_exp_f32_e32 v10, v10
	v_lshlrev_b32_e32 v11, 16, v8
	v_mul_f32_e32 v12, v11, v11
	v_fmamk_f32 v12, v12, 0xbdd2d3e7, v129
	v_mul_f32_e32 v12, v12, v11
	v_add_f32_e32 v10, 1.0, v10
	v_rcp_f32_e32 v10, v10
	v_exp_f32_e32 v12, v12
	v_mul_f32_e32 v53, v39, v6
	v_fma_f32 v7, v10, v7, -v19
	v_mul_f32_e32 v52, v39, v7
	v_and_b32_e32 v7, 0xffff0000, v8
	v_add_f32_e32 v6, 1.0, v12
	v_mul_f32_e32 v8, v7, v7
	v_rcp_f32_e32 v6, v6
	v_fmamk_f32 v8, v8, 0xbdd2d3e7, v129
	v_mul_f32_e32 v8, v8, v7
	v_lshlrev_b32_e32 v10, 16, v9
	v_fma_f32 v6, v6, v11, -v19
	v_exp_f32_e32 v8, v8
	v_mul_f32_e32 v11, v10, v10
	v_fmamk_f32 v11, v11, 0xbdd2d3e7, v129
	v_mul_f32_e32 v11, v11, v10
	v_add_f32_e32 v8, 1.0, v8
	v_rcp_f32_e32 v8, v8
	v_exp_f32_e32 v11, v11
	v_mul_f32_e32 v6, v39, v6
	s_waitcnt vmcnt(4)
	v_fma_f32 v6, v14, v6, v16
	v_cvt_pk_bf16_f32 v6, v6, s0
	ds_write_b16 v35, v6 offset:39984
	v_fma_f32 v6, v8, v7, -v19
	v_add_f32_e32 v7, 1.0, v11
	v_rcp_f32_e32 v7, v7
	v_mul_f32_e32 v6, v39, v6
	v_fmac_f32_e32 v17, v6, v15
	v_cvt_pk_bf16_f32 v6, v17, s0
	ds_write_b16 v35, v6 offset:40256
	v_fma_f32 v6, v7, v10, -v19
	v_and_b32_e32 v7, 0xffff0000, v9
	v_lshlrev_b32_e32 v9, 16, v2
	v_mul_f32_e32 v10, v9, v9
	v_fmamk_f32 v10, v10, 0xbdd2d3e7, v129
	v_mul_f32_e32 v8, v7, v7
	v_mul_f32_e32 v10, v10, v9
	v_fmamk_f32 v8, v8, 0xbdd2d3e7, v129
	v_mul_f32_e32 v8, v8, v7
	v_exp_f32_e32 v10, v10
	v_exp_f32_e32 v8, v8
	v_mul_f32_e32 v58, v39, v6
	v_add_f32_e32 v6, 1.0, v10
	global_load_dwordx4 v[10:13], v[22:23], off offset:1104
	global_load_dwordx4 v[14:17], v[22:23], off offset:1088
	v_add_f32_e32 v8, 1.0, v8
	v_rcp_f32_e32 v8, v8
	v_and_b32_e32 v2, 0xffff0000, v2
	v_rcp_f32_e32 v6, v6
	v_or_b32_e32 v18, 4, v34
	v_fma_f32 v7, v8, v7, -v19
	v_mul_f32_e32 v56, v39, v7
	v_mul_f32_e32 v7, v2, v2
	v_fmamk_f32 v7, v7, 0xbdd2d3e7, v129
	v_mul_f32_e32 v7, v7, v2
	v_exp_f32_e32 v7, v7
	v_lshlrev_b32_e32 v8, 16, v3
	v_fma_f32 v6, v6, v9, -v19
	v_mul_f32_e32 v9, v8, v8
	v_add_f32_e32 v7, 1.0, v7
	v_rcp_f32_e32 v7, v7
	v_fmamk_f32 v9, v9, 0xbdd2d3e7, v129
	v_mul_f32_e32 v9, v9, v8
	v_fma_f32 v2, v7, v2, -v19
	v_mul_f32_e32 v6, v39, v6
	v_mul_f32_e32 v2, v39, v2
	s_waitcnt vmcnt(3)
	v_fma_f32 v6, v24, v6, v26
	v_exp_f32_e32 v9, v9
	v_fmac_f32_e32 v27, v25, v2
	v_cvt_pk_bf16_f32 v6, v6, s0
	v_cvt_pk_bf16_f32 v2, v27, s0
	ds_write_b16 v35, v6 offset:41072
	ds_write_b16 v35, v2 offset:41344
	global_load_dwordx2 v[24:25], v20, s[16:17] offset:128
	global_load_dwordx2 v[26:27], v20, s[20:21] offset:128
	v_add_f32_e32 v6, 1.0, v9
	v_rcp_f32_e32 v6, v6
	v_and_b32_e32 v3, 0xffff0000, v3
	v_lshlrev_b32_e32 v7, 16, v4
	v_or_b32_e32 v36, 8, v34
	v_fma_f32 v2, v6, v8, -v19
	v_mul_f32_e32 v6, v3, v3
	v_fmamk_f32 v6, v6, 0xbdd2d3e7, v129
	v_mul_f32_e32 v6, v6, v3
	v_exp_f32_e32 v6, v6
	v_mul_f32_e32 v8, v7, v7
	v_fmamk_f32 v8, v8, 0xbdd2d3e7, v129
	v_mul_f32_e32 v8, v8, v7
	v_add_f32_e32 v6, 1.0, v6
	v_rcp_f32_e32 v6, v6
	v_exp_f32_e32 v8, v8
	v_mul_f32_e32 v64, v39, v2
	v_fma_f32 v3, v6, v3, -v19
	v_mul_f32_e32 v63, v39, v3
	v_and_b32_e32 v3, 0xffff0000, v4
	v_add_f32_e32 v2, 1.0, v8
	v_mul_f32_e32 v4, v3, v3
	v_rcp_f32_e32 v2, v2
	v_fmamk_f32 v4, v4, 0xbdd2d3e7, v129
	v_mul_f32_e32 v4, v4, v3
	v_fma_f32 v2, v2, v7, -v19
	v_exp_f32_e32 v4, v4
	v_mul_f32_e32 v2, v39, v2
	s_waitcnt vmcnt(4)
	v_fma_f32 v2, v28, v2, v48
	v_cvt_pk_bf16_f32 v2, v2, s0
	ds_write_b16 v35, v2 offset:42160
	v_add_f32_e32 v2, 1.0, v4
	v_lshlrev_b32_e32 v4, 16, v5
	v_mul_f32_e32 v6, v4, v4
	v_fmamk_f32 v6, v6, 0xbdd2d3e7, v129
	v_rcp_f32_e32 v2, v2
	v_mul_f32_e32 v6, v6, v4
	v_exp_f32_e32 v6, v6
	v_fma_f32 v2, v2, v3, -v19
	v_mul_f32_e32 v2, v39, v2
	v_fmac_f32_e32 v49, v2, v29
	v_add_f32_e32 v2, 1.0, v6
	v_cvt_pk_bf16_f32 v6, v49, s0
	ds_write_b16 v35, v6 offset:42432
	global_load_dwordx2 v[60:61], v20, s[16:17] offset:144
	global_load_dwordx2 v[66:67], v20, s[20:21] offset:144
	v_and_b32_e32 v3, 0xffff0000, v5
	v_mul_f32_e32 v5, v3, v3
	v_fmamk_f32 v5, v5, 0xbdd2d3e7, v129
	v_mul_f32_e32 v5, v5, v3
	v_rcp_f32_e32 v2, v2
	v_exp_f32_e32 v5, v5
	s_waitcnt vmcnt(4)
	v_lshlrev_b32_e32 v28, 16, v14
	v_and_b32_e32 v14, 0xffff0000, v14
	v_fma_f32 v2, v2, v4, -v19
	v_add_f32_e32 v4, 1.0, v5
	v_mul_f32_e32 v5, v28, v28
	v_fmamk_f32 v5, v5, 0xbdd2d3e7, v129
	v_mul_f32_e32 v5, v5, v28
	v_rcp_f32_e32 v4, v4
	v_exp_f32_e32 v5, v5
	v_mul_f32_e32 v69, v39, v2
	v_fma_f32 v2, v4, v3, -v19
	v_mul_f32_e32 v68, v39, v2
	v_add_f32_e32 v2, 1.0, v5
	v_rcp_f32_e32 v29, v2
	global_load_dwordx4 v[2:5], v[22:23], off offset:1136
	global_load_dwordx4 v[6:9], v[22:23], off offset:1120
	v_or_b32_e32 v37, 12, v34
	v_or_b32_e32 v38, 16, v34
	v_fma_f32 v22, v29, v28, -v19
	v_mul_f32_e32 v48, v39, v22
	v_mul_f32_e32 v22, v14, v14
	v_fmamk_f32 v22, v22, 0xbdd2d3e7, v129
	v_mul_f32_e32 v22, v22, v14
	v_exp_f32_e32 v49, v22
	global_load_dwordx2 v[74:75], v20, s[16:17] offset:160
	global_load_dwordx2 v[22:23], v20, s[16:17] offset:176
	global_load_dwordx2 v[76:77], v20, s[20:21] offset:160
	global_load_dwordx2 v[28:29], v20, s[20:21] offset:176
	s_waitcnt vmcnt(8)
	v_fma_f32 v24, v24, v48, v26
	v_lshlrev_b32_e32 v48, 16, v15
	v_add_f32_e32 v26, 1.0, v49
	v_mul_f32_e32 v49, v48, v48
	v_fmamk_f32 v49, v49, 0xbdd2d3e7, v129
	v_mul_f32_e32 v49, v49, v48
	v_exp_f32_e32 v49, v49
	v_rcp_f32_e32 v26, v26
	v_cvt_pk_bf16_f32 v24, v24, s0
	ds_write_b16 v35, v24 offset:43248
	v_add_f32_e32 v24, 1.0, v49
	v_fma_f32 v14, v26, v14, -v19
	v_rcp_f32_e32 v24, v24
	v_mul_f32_e32 v14, v39, v14
	v_fmac_f32_e32 v27, v25, v14
	v_cvt_pk_bf16_f32 v14, v27, s0
	v_and_b32_e32 v15, 0xffff0000, v15
	ds_write_b16 v35, v14 offset:43520
	v_fma_f32 v14, v24, v48, -v19
	v_mul_f32_e32 v24, v15, v15
	v_fmamk_f32 v24, v24, 0xbdd2d3e7, v129
	v_mul_f32_e32 v24, v24, v15
	v_exp_f32_e32 v24, v24
	v_lshlrev_b32_e32 v25, 16, v16
	v_mul_f32_e32 v26, v25, v25
	v_fmamk_f32 v26, v26, 0xbdd2d3e7, v129
	v_mul_f32_e32 v26, v26, v25
	v_add_f32_e32 v24, 1.0, v24
	v_rcp_f32_e32 v24, v24
	v_exp_f32_e32 v26, v26
	v_mul_f32_e32 v73, v39, v14
	v_fma_f32 v15, v24, v15, -v19
	v_mul_f32_e32 v72, v39, v15
	v_and_b32_e32 v15, 0xffff0000, v16
	v_add_f32_e32 v14, 1.0, v26
	v_mul_f32_e32 v16, v15, v15
	v_rcp_f32_e32 v14, v14
	v_fmamk_f32 v16, v16, 0xbdd2d3e7, v129
	v_mul_f32_e32 v16, v16, v15
	v_lshlrev_b32_e32 v24, 16, v17
	v_fma_f32 v14, v14, v25, -v19
	v_exp_f32_e32 v16, v16
	v_mul_f32_e32 v25, v24, v24
	v_fmamk_f32 v25, v25, 0xbdd2d3e7, v129
	v_mul_f32_e32 v25, v25, v24
	v_add_f32_e32 v16, 1.0, v16
	v_rcp_f32_e32 v16, v16
	v_exp_f32_e32 v25, v25
	v_mul_f32_e32 v14, v39, v14
	s_waitcnt vmcnt(6)
	v_fma_f32 v14, v60, v14, v66
	v_cvt_pk_bf16_f32 v14, v14, s0
	ds_write_b16 v35, v14 offset:44336
	v_fma_f32 v14, v16, v15, -v19
	v_add_f32_e32 v15, 1.0, v25
	v_rcp_f32_e32 v15, v15
	v_mul_f32_e32 v14, v39, v14
	v_fmac_f32_e32 v67, v14, v61
	v_cvt_pk_bf16_f32 v14, v67, s0
	ds_write_b16 v35, v14 offset:44608
	v_fma_f32 v14, v15, v24, -v19
	v_and_b32_e32 v15, 0xffff0000, v17
	v_mul_f32_e32 v16, v15, v15
	v_fmamk_f32 v16, v16, 0xbdd2d3e7, v129
	v_mul_f32_e32 v16, v16, v15
	v_exp_f32_e32 v16, v16
	v_lshlrev_b32_e32 v17, 16, v10
	v_mul_f32_e32 v24, v17, v17
	v_fmamk_f32 v24, v24, 0xbdd2d3e7, v129
	v_mul_f32_e32 v24, v24, v17
	v_add_f32_e32 v16, 1.0, v16
	v_rcp_f32_e32 v16, v16
	v_exp_f32_e32 v24, v24
	v_and_b32_e32 v10, 0xffff0000, v10
	v_mul_f32_e32 v71, v39, v14
	v_fma_f32 v15, v16, v15, -v19
	v_add_f32_e32 v14, 1.0, v24
	v_mul_f32_e32 v70, v39, v15
	v_mul_f32_e32 v15, v10, v10
	v_rcp_f32_e32 v14, v14
	v_fmamk_f32 v15, v15, 0xbdd2d3e7, v129
	v_mul_f32_e32 v15, v15, v10
	v_fma_f32 v14, v14, v17, -v19
	v_exp_f32_e32 v15, v15
	v_mul_f32_e32 v14, v39, v14
	s_waitcnt vmcnt(1)
	v_fma_f32 v14, v74, v14, v76
	v_cvt_pk_bf16_f32 v14, v14, s0
	ds_write_b16 v35, v14 offset:45424
	v_add_f32_e32 v14, 1.0, v15
	v_lshlrev_b32_e32 v15, 16, v11
	v_rcp_f32_e32 v14, v14
	v_mul_f32_e32 v16, v15, v15
	v_fmamk_f32 v16, v16, 0xbdd2d3e7, v129
	v_mul_f32_e32 v16, v16, v15
	v_and_b32_e32 v11, 0xffff0000, v11
	v_fma_f32 v10, v14, v10, -v19
	v_mul_f32_e32 v14, v11, v11
	v_exp_f32_e32 v16, v16
	v_fmamk_f32 v14, v14, 0xbdd2d3e7, v129
	v_mul_f32_e32 v14, v14, v11
	v_mul_f32_e32 v10, v39, v10
	v_fmac_f32_e32 v77, v75, v10
	v_add_f32_e32 v10, 1.0, v16
	v_exp_f32_e32 v14, v14
	v_rcp_f32_e32 v10, v10
	v_cvt_pk_bf16_f32 v16, v77, s0
	ds_write_b16 v35, v16 offset:45696
	v_add_f32_e32 v14, 1.0, v14
	v_fma_f32 v10, v10, v15, -v19
	v_rcp_f32_e32 v14, v14
	v_lshlrev_b32_e32 v15, 16, v12
	v_mul_f32_e32 v16, v15, v15
	v_fmamk_f32 v16, v16, 0xbdd2d3e7, v129
	v_mul_f32_e32 v16, v16, v15
	v_mul_f32_e32 v67, v39, v10
	v_fma_f32 v10, v14, v11, -v19
	v_and_b32_e32 v11, 0xffff0000, v12
	v_mul_f32_e32 v12, v11, v11
	v_exp_f32_e32 v16, v16
	v_fmamk_f32 v12, v12, 0xbdd2d3e7, v129
	v_mul_f32_e32 v12, v12, v11
	v_mul_f32_e32 v66, v39, v10
	v_add_f32_e32 v10, 1.0, v16
	v_exp_f32_e32 v12, v12
	v_rcp_f32_e32 v10, v10
	v_or_b32_e32 v76, 2, v34
	v_lshlrev_b32_e32 v14, 2, v76
	v_add_f32_e32 v12, 1.0, v12
	v_fma_f32 v10, v10, v15, -v19
	v_rcp_f32_e32 v12, v12
	v_mul_f32_e32 v10, v39, v10
	s_waitcnt vmcnt(0)
	v_fma_f32 v10, v22, v10, v28
	v_cvt_pk_bf16_f32 v10, v10, s0
	ds_write_b16 v35, v10 offset:46512
	v_fma_f32 v10, v12, v11, -v19
	v_lshlrev_b32_e32 v11, 16, v13
	v_mul_f32_e32 v12, v11, v11
	v_fmamk_f32 v12, v12, 0xbdd2d3e7, v129
	v_mul_f32_e32 v12, v12, v11
	v_exp_f32_e32 v12, v12
	v_mul_f32_e32 v10, v39, v10
	v_fmac_f32_e32 v29, v10, v23
	v_cvt_pk_bf16_f32 v10, v29, s0
	global_load_dword v15, v14, s[16:17]
	s_nop 0
	global_load_dword v14, v14, s[20:21]
	ds_write_b16 v35, v10 offset:46784
	v_add_f32_e32 v10, 1.0, v12
	v_rcp_f32_e32 v10, v10
	v_or_b32_e32 v77, 3, v34
	v_lshlrev_b32_e32 v12, 2, v77
	global_load_dword v16, v12, s[16:17]
	global_load_dword v17, v12, s[20:21]
	v_fma_f32 v10, v10, v11, -v19
	v_and_b32_e32 v11, 0xffff0000, v13
	v_mul_f32_e32 v12, v11, v11
	v_fmamk_f32 v12, v12, 0xbdd2d3e7, v129
	v_mul_f32_e32 v12, v12, v11
	v_lshlrev_b32_e32 v13, 16, v6
	v_exp_f32_e32 v12, v12
	v_mul_f32_e32 v22, v13, v13
	v_fmamk_f32 v22, v22, 0xbdd2d3e7, v129
	v_mul_f32_e32 v22, v22, v13
	v_add_f32_e32 v12, 1.0, v12
	v_exp_f32_e32 v22, v22
	v_rcp_f32_e32 v12, v12
	v_mul_f32_e32 v75, v39, v10
	v_and_b32_e32 v6, 0xffff0000, v6
	v_add_f32_e32 v10, 1.0, v22
	v_fma_f32 v11, v12, v11, -v19
	v_rcp_f32_e32 v10, v10
	v_mul_f32_e32 v74, v39, v11
	v_mul_f32_e32 v11, v6, v6
	v_fmamk_f32 v11, v11, 0xbdd2d3e7, v129
	v_mul_f32_e32 v11, v11, v6
	v_fma_f32 v10, v10, v13, -v19
	v_exp_f32_e32 v22, v11
	v_mul_f32_e32 v82, v39, v10
	global_load_dwordx2 v[10:11], v20, s[16:17] offset:192
	global_load_dwordx2 v[12:13], v20, s[20:21] offset:192
	v_lshlrev_b32_e32 v23, 16, v7
	v_mul_f32_e32 v24, v23, v23
	v_and_b32_e32 v7, 0xffff0000, v7
	v_fmamk_f32 v24, v24, 0xbdd2d3e7, v129
	v_mul_f32_e32 v25, v7, v7
	v_mul_f32_e32 v24, v24, v23
	v_fmamk_f32 v25, v25, 0xbdd2d3e7, v129
	v_mul_f32_e32 v25, v25, v7
	v_add_f32_e32 v22, 1.0, v22
	v_rcp_f32_e32 v22, v22
	v_exp_f32_e32 v24, v24
	v_exp_f32_e32 v25, v25
	v_fma_f32 v6, v22, v6, -v19
	v_add_f32_e32 v22, 1.0, v24
	v_rcp_f32_e32 v22, v22
	v_add_f32_e32 v24, 1.0, v25
	v_rcp_f32_e32 v24, v24
	v_mul_f32_e32 v83, v39, v6
	v_fma_f32 v6, v22, v23, -v19
	v_mul_f32_e32 v62, v39, v6
	v_fma_f32 v6, v24, v7, -v19
	v_lshlrev_b32_e32 v91, 16, v8
	v_mul_f32_e32 v61, v39, v6
	v_or_b32_e32 v6, s88, v31
	v_lshlrev_b32_e32 v6, 7, v6
	v_mov_b32_e32 v7, v1
	v_lshl_add_u64 v[6:7], v[6:7], 2, s[40:41]
	v_lshl_add_u64 v[6:7], v[6:7], 0, v[20:21]
	v_and_b32_e32 v8, 0xffff0000, v8
	v_mul_f32_e32 v98, v8, v8
	v_fmamk_f32 v98, v98, 0xbdd2d3e7, v129
	v_mul_f32_e32 v98, v98, v8
	v_exp_f32_e32 v98, v98
	v_and_b32_e32 v99, 0xffff0000, v9
	v_and_b32_e32 v105, 0xffff0000, v5
	s_waitcnt vmcnt(4)
	v_fmac_f32_e32 v14, v15, v65
	v_mul_u32_u24_e32 v15, 0x110, v76
	v_cvt_pk_bf16_f32 v14, v14, s0
	v_add3_u32 v15, s15, v15, v33
	v_or_b32_e32 v65, 6, v34
	ds_write_b16 v15, v14 offset:34816
	v_lshlrev_b32_e32 v14, 2, v65
	global_load_dword v85, v14, s[16:17]
	global_load_dword v86, v14, s[20:21]
	s_waitcnt vmcnt(4)
	v_fmac_f32_e32 v17, v16, v59
	v_lshlrev_b32_e32 v14, 2, v78
	v_mul_u32_u24_e32 v15, 0x110, v77
	global_load_dword v87, v14, s[16:17]
	global_load_dword v88, v14, s[20:21]
	v_cvt_pk_bf16_f32 v14, v17, s0
	v_add3_u32 v15, s15, v15, v33
	ds_write_b16 v15, v14 offset:34816
	v_lshlrev_b32_e32 v14, 2, v81
	global_load_dwordx2 v[22:23], v20, s[16:17] offset:208
	global_load_dwordx2 v[24:25], v20, s[20:21] offset:208
	global_load_dword v89, v14, s[16:17]
	global_load_dword v90, v14, s[20:21]
	v_lshlrev_b32_e32 v14, 2, v79
	global_load_dword v92, v14, s[16:17]
	global_load_dword v93, v14, s[20:21]
	v_mul_f32_e32 v14, v91, v91
	v_fmamk_f32 v14, v14, 0xbdd2d3e7, v129
	v_mul_f32_e32 v14, v14, v91
	v_or_b32_e32 v59, 14, v34
	v_lshlrev_b32_e32 v15, 2, v59
	global_load_dword v94, v15, s[16:17]
	global_load_dword v95, v15, s[20:21]
	v_exp_f32_e32 v96, v14
	global_load_dwordx2 v[14:15], v20, s[16:17] offset:224
	global_load_dwordx2 v[16:17], v20, s[16:17] offset:240
	global_load_dwordx2 v[26:27], v20, s[20:21] offset:224
	s_nop 0
	global_load_dwordx2 v[20:21], v20, s[20:21] offset:240
	v_or_b32_e32 v40, 20, v34
	v_or_b32_e32 v41, 24, v34
	v_or_b32_e32 v42, 28, v34
	v_or_b32_e32 v43, 32, v34
	v_or_b32_e32 v48, 36, v34
	v_or_b32_e32 v49, 40, v34
	v_or_b32_e32 v51, 44, v34
	v_or_b32_e32 v60, 52, v34
	s_waitcnt vmcnt(16)
	v_fma_f32 v10, v10, v82, v12
	v_cvt_pk_bf16_f32 v12, v10, s0
	v_or_b32_e32 v10, 15, v34
	v_add_f32_e32 v82, 1.0, v96
	v_lshlrev_b32_e32 v96, 2, v10
	global_load_dword v97, v96, s[16:17]
	s_nop 0
	global_load_dword v96, v96, s[20:21]
	v_rcp_f32_e32 v82, v82
	ds_write_b16 v35, v12 offset:47600
	v_fmac_f32_e32 v13, v11, v83
	v_cvt_pk_bf16_f32 v11, v13, s0
	v_fma_f32 v12, v82, v91, -v19
	v_lshlrev_b32_e32 v91, 16, v9
	v_add_f32_e32 v82, 1.0, v98
	v_mul_f32_e32 v98, v91, v91
	v_fmamk_f32 v98, v98, 0xbdd2d3e7, v129
	v_mul_f32_e32 v98, v98, v91
	v_rcp_f32_e32 v82, v82
	v_exp_f32_e32 v98, v98
	v_mul_f32_e32 v12, v39, v12
	v_mul_u32_u24_e32 v13, 0x110, v81
	v_fma_f32 v8, v82, v8, -v19
	v_add_f32_e32 v82, 1.0, v98
	v_rcp_f32_e32 v82, v82
	v_mul_f32_e32 v100, v39, v8
	v_add3_u32 v13, s15, v13, v33
	v_mul_f32_e32 v9, v99, v99
	v_fma_f32 v8, v82, v91, -v19
	v_mul_u32_u24_e32 v82, 0x110, v65
	v_add3_u32 v82, s15, v82, v33
	v_fmamk_f32 v9, v9, 0xbdd2d3e7, v129
	v_mul_f32_e32 v9, v9, v99
	v_exp_f32_e32 v9, v9
	v_or_b32_e32 v91, 26, v34
	v_or_b32_e32 v29, 56, v34
	v_or_b32_e32 v28, 60, v34
	v_add_f32_e32 v9, 1.0, v9
	v_rcp_f32_e32 v98, v9
	v_mul_f32_e32 v9, v39, v8
	v_readlane_b32 s46, v251, 56
	v_readlane_b32 s47, v251, 57
	v_fma_f32 v8, v98, v99, -v19
	v_or_b32_e32 v98, 30, v34
	v_mul_f32_e32 v8, v39, v8
	v_readlane_b32 s48, v251, 58
	v_readlane_b32 s49, v251, 59
	s_waitcnt vmcnt(16)
	v_fmac_f32_e32 v86, v45, v85
	v_cvt_pk_bf16_f32 v45, v86, s0
	ds_write_b16 v82, v45 offset:34816
	v_mul_u32_u24_e32 v45, 0x110, v78
	s_waitcnt vmcnt(14)
	v_fmac_f32_e32 v88, v44, v87
	v_cvt_pk_bf16_f32 v44, v88, s0
	v_add3_u32 v45, s15, v45, v33
	ds_write_b16 v45, v44 offset:34816
	ds_write_b16 v35, v11 offset:47872
	s_waitcnt vmcnt(12)
	v_fma_f32 v11, v22, v12, v24
	s_waitcnt vmcnt(10)
	v_fmac_f32_e32 v90, v89, v47
	v_cvt_pk_bf16_f32 v12, v90, s0
	ds_write_b16 v13, v12 offset:34816
	s_waitcnt vmcnt(8)
	v_fmac_f32_e32 v93, v92, v46
	v_mul_u32_u24_e32 v13, 0x110, v79
	v_cvt_pk_bf16_f32 v12, v93, s0
	v_add3_u32 v13, s15, v13, v33
	v_cvt_pk_bf16_f32 v11, v11, s0
	ds_write_b16 v13, v12 offset:34816
	ds_write_b16 v35, v11 offset:48688
	v_lshlrev_b32_e32 v13, 16, v2
	v_mul_f32_e32 v22, v13, v13
	v_fmamk_f32 v22, v22, 0xbdd2d3e7, v129
	v_mul_f32_e32 v22, v22, v13
	v_exp_f32_e32 v22, v22
	v_fmac_f32_e32 v25, v100, v23
	v_cvt_pk_bf16_f32 v11, v25, s0
	s_waitcnt vmcnt(6)
	v_fmac_f32_e32 v95, v55, v94
	v_mul_u32_u24_e32 v12, 0x110, v59
	ds_write_b16 v35, v11 offset:48960
	v_cvt_pk_bf16_f32 v11, v95, s0
	v_add3_u32 v12, s15, v12, v33
	ds_write_b16 v12, v11 offset:34816
	v_add_f32_e32 v12, 1.0, v22
	v_rcp_f32_e32 v12, v12
	s_waitcnt vmcnt(0)
	v_fmac_f32_e32 v96, v54, v97
	v_mul_u32_u24_e32 v22, 0x110, v10
	v_cvt_pk_bf16_f32 v11, v96, s0
	v_add3_u32 v22, s15, v22, v33
	v_and_b32_e32 v2, 0xffff0000, v2
	ds_write_b16 v22, v11 offset:34816
	v_fma_f32 v11, v12, v13, -v19
	v_mul_f32_e32 v12, v2, v2
	v_lshlrev_b32_e32 v13, 16, v3
	v_fmamk_f32 v12, v12, 0xbdd2d3e7, v129
	v_mul_f32_e32 v22, v13, v13
	v_mul_f32_e32 v12, v12, v2
	v_fmamk_f32 v22, v22, 0xbdd2d3e7, v129
	v_mul_f32_e32 v22, v22, v13
	v_exp_f32_e32 v12, v12
	v_exp_f32_e32 v22, v22
	v_mul_f32_e32 v11, v39, v11
	v_add_f32_e32 v12, 1.0, v12
	v_fma_f32 v11, v14, v11, v26
	v_rcp_f32_e32 v12, v12
	v_add_f32_e32 v14, 1.0, v22
	v_rcp_f32_e32 v14, v14
	v_and_b32_e32 v3, 0xffff0000, v3
	v_fma_f32 v2, v12, v2, -v19
	v_mul_f32_e32 v12, v39, v2
	v_fma_f32 v2, v14, v13, -v19
	v_mul_f32_e32 v13, v3, v3
	v_fmamk_f32 v13, v13, 0xbdd2d3e7, v129
	v_mul_f32_e32 v13, v13, v3
	v_or_b32_e32 v86, 18, v34
	v_or_b32_e32 v87, 19, v34
	v_lshlrev_b32_e32 v14, 2, v86
	v_lshlrev_b32_e32 v22, 2, v87
	global_load_dword v26, v14, s[16:17]
	s_nop 0
	global_load_dword v14, v14, s[20:21]
	s_nop 0
	global_load_dword v54, v22, s[16:17]
	global_load_dword v55, v22, s[20:21]
	v_lshlrev_b32_e32 v22, 16, v4
	v_exp_f32_e32 v13, v13
	v_mul_f32_e32 v23, v22, v22
	v_fmamk_f32 v23, v23, 0xbdd2d3e7, v129
	v_mul_f32_e32 v23, v23, v22
	v_add_f32_e32 v13, 1.0, v13
	v_rcp_f32_e32 v13, v13
	v_exp_f32_e32 v23, v23
	v_or_b32_e32 v88, 22, v34
	v_lshlrev_b32_e32 v24, 2, v88
	v_fma_f32 v3, v13, v3, -v19
	v_add_f32_e32 v13, 1.0, v23
	global_load_dword v82, v24, s[16:17]
	global_load_dword v83, v24, s[20:21]
	v_or_b32_e32 v89, 23, v34
	v_rcp_f32_e32 v13, v13
	v_and_b32_e32 v4, 0xffff0000, v4
	v_lshlrev_b32_e32 v24, 2, v89
	v_mul_f32_e32 v23, v4, v4
	global_load_dword v84, v24, s[16:17]
	global_load_dword v85, v24, s[20:21]
	v_fmamk_f32 v23, v23, 0xbdd2d3e7, v129
	v_mul_f32_e32 v23, v23, v4
	v_fma_f32 v13, v13, v22, -v19
	v_lshlrev_b32_e32 v22, 2, v91
	global_load_dword v92, v22, s[16:17]
	global_load_dword v93, v22, s[20:21]
	v_or_b32_e32 v94, 27, v34
	v_exp_f32_e32 v23, v23
	v_lshlrev_b32_e32 v22, 2, v94
	global_load_dword v95, v22, s[16:17]
	global_load_dword v96, v22, s[20:21]
	v_lshlrev_b32_e32 v97, 16, v5
	v_lshlrev_b32_e32 v22, 2, v98
	global_load_dword v99, v22, s[16:17]
	global_load_dword v100, v22, s[20:21]
	v_mul_f32_e32 v22, 0x3d372713, v97
	v_mul_f32_e32 v90, v39, v13
	v_add_f32_e32 v13, 1.0, v23
	v_lshlrev_b32_e32 v23, 2, v101
	v_mul_f32_e32 v22, v22, v97
	global_load_dword v102, v23, s[16:17]
	global_load_dword v103, v23, s[20:21]
	v_fma_f32 v22, v22, v97, v97
	v_mul_f32_e32 v22, 0xbfcc422a, v22
	v_mul_f32_e32 v104, 0x3fb8aa3b, v22
	global_load_dwordx4 v[22:25], v[6:7], off offset:16
	global_load_dwordx4 v[44:47], v[6:7], off
	v_rcp_f32_e32 v13, v13
	v_exp_f32_e32 v104, v104
	v_mul_f32_e32 v5, v105, v105
	v_fmamk_f32 v5, v5, 0xbdd2d3e7, v129
	v_mul_f32_e32 v5, v5, v105
	v_fma_f32 v4, v13, v4, -v19
	v_add_f32_e32 v13, 1.0, v104
	v_rcp_f32_e32 v13, v13
	v_exp_f32_e32 v5, v5
	v_mul_f32_e32 v106, v39, v4
	v_cvt_pk_bf16_f32 v11, v11, s0
	v_fma_f32 v4, v13, v97, -v19
	v_add_f32_e32 v5, 1.0, v5
	v_rcp_f32_e32 v104, v5
	v_fmac_f32_e32 v27, v15, v12
	v_mul_f32_e32 v5, v39, v4
	v_fma_f32 v16, v16, v90, v20
	v_fma_f32 v4, v104, v105, -v19
	v_mul_u32_u24_e32 v19, 0x110, v88
	v_add3_u32 v19, s15, v19, v33
	v_cvt_pk_bf16_f32 v16, v16, s0
	v_fmac_f32_e32 v21, v106, v17
	v_mul_f32_e32 v2, v39, v2
	v_mul_f32_e32 v3, v39, v3
	v_mul_f32_e32 v4, v39, v4
	v_mul_u32_u24_e32 v17, 0x110, v91
	v_add3_u32 v17, s15, v17, v33
	v_readlane_b32 s56, v252, 2
	v_readlane_b32 s57, v252, 3
	v_readlane_b32 s58, v252, 4
	v_readlane_b32 s59, v252, 5
	s_waitcnt vmcnt(16)
	v_fmac_f32_e32 v14, v26, v53
	v_cvt_pk_bf16_f32 v13, v14, s0
	v_mul_u32_u24_e32 v14, 0x110, v86
	v_add3_u32 v14, s15, v14, v33
	ds_write_b16 v14, v13 offset:34816
	s_waitcnt vmcnt(14)
	v_fmac_f32_e32 v55, v54, v52
	v_mul_u32_u24_e32 v14, 0x110, v87
	v_cvt_pk_bf16_f32 v13, v55, s0
	v_add3_u32 v14, s15, v14, v33
	ds_write_b16 v14, v13 offset:34816
	ds_write_b16 v35, v11 offset:49776
	v_cvt_pk_bf16_f32 v11, v27, s0
	ds_write_b16 v35, v11 offset:50048
	global_load_dwordx4 v[12:15], v[6:7], off offset:48
	global_load_dwordx4 v[52:55], v[6:7], off offset:32
	s_waitcnt vmcnt(14)
	v_fmac_f32_e32 v83, v58, v82
	v_cvt_pk_bf16_f32 v11, v83, s0
	ds_write_b16 v19, v11 offset:34816
	v_mul_u32_u24_e32 v19, 0x110, v89
	v_add3_u32 v19, s15, v19, v33
	v_or_b32_e32 v58, 35, v34
	s_waitcnt vmcnt(12)
	v_fmac_f32_e32 v85, v56, v84
	v_cvt_pk_bf16_f32 v11, v85, s0
	v_or_b32_e32 v56, 34, v34
	ds_write_b16 v19, v11 offset:34816
	v_lshlrev_b32_e32 v11, 2, v56
	v_lshlrev_b32_e32 v19, 2, v58
	global_load_dword v39, v11, s[16:17]
	s_nop 0
	global_load_dword v11, v11, s[20:21]
	s_nop 0
	global_load_dword v90, v19, s[16:17]
	global_load_dword v97, v19, s[20:21]
	ds_write_b16 v35, v16 offset:50864
	v_cvt_pk_bf16_f32 v16, v21, s0
	s_waitcnt vmcnt(14)
	v_fmac_f32_e32 v93, v92, v64
	ds_write_b16 v35, v16 offset:51136
	v_cvt_pk_bf16_f32 v16, v93, s0
	ds_write_b16 v17, v16 offset:34816
	s_waitcnt vmcnt(12)
	v_fmac_f32_e32 v96, v95, v63
	v_mul_u32_u24_e32 v17, 0x110, v94
	v_cvt_pk_bf16_f32 v16, v96, s0
	v_add3_u32 v17, s15, v17, v33
	ds_write_b16 v17, v16 offset:34816
	s_waitcnt vmcnt(10)
	v_fmac_f32_e32 v100, v69, v99
	v_mul_u32_u24_e32 v17, 0x110, v98
	v_cvt_pk_bf16_f32 v16, v100, s0
	v_add3_u32 v17, s15, v17, v33
	ds_write_b16 v17, v16 offset:34816
	s_waitcnt vmcnt(8)
	v_fmac_f32_e32 v103, v68, v102
	v_mul_u32_u24_e32 v17, 0x110, v101
	v_cvt_pk_bf16_f32 v16, v103, s0
	v_add3_u32 v17, s15, v17, v33
	ds_write_b16 v17, v16 offset:34816
	s_waitcnt vmcnt(6)
	v_cndmask_b32_e32 v16, 0, v45, vcc
	v_cmp_le_u32_e32 vcc, v34, v31
	v_or_b32_e32 v35, 38, v34
	v_or_b32_e32 v68, 39, v34
	v_cndmask_b32_e32 v17, 0, v44, vcc
	v_cvt_pk_bf16_f32 v16, v17, v16
	v_lshlrev_b32_e32 v17, 2, v35
	global_load_dword v63, v17, s[16:17]
	global_load_dword v64, v17, s[20:21]
	v_lshlrev_b32_e32 v19, 2, v68
	global_load_dword v69, v19, s[16:17]
	global_load_dword v92, v19, s[20:21]
	v_cvt_pk_bf16_f32 v17, v46, v47
	v_cmp_le_u32_e32 vcc, v76, v31
	global_load_dwordx4 v[44:47], v[6:7], off offset:80
	global_load_dwordx4 v[82:85], v[6:7], off offset:64
	v_cndmask_b32_e32 v19, 0, v17, vcc
	v_lshrrev_b32_e32 v17, 16, v17
	v_cmp_le_u32_e32 vcc, v77, v31
	v_or_b32_e32 v77, 47, v34
	s_waitcnt vmcnt(8)
	v_fmac_f32_e32 v11, v39, v73
	v_cndmask_b32_e32 v17, 0, v17, vcc
	v_cmp_gt_u32_e32 vcc, v31, v18
	v_perm_b32 v17, v17, v19, s19
	v_cvt_pk_bf16_f32 v11, v11, s0
	v_cndmask_b32_e32 v19, 0, v23, vcc
	v_cmp_le_u32_e32 vcc, v18, v31
	s_waitcnt vmcnt(6)
	v_fmac_f32_e32 v97, v90, v72
	s_waitcnt vmcnt(4)
	v_fmac_f32_e32 v64, v71, v63
	v_cndmask_b32_e32 v18, 0, v22, vcc
	v_cvt_pk_bf16_f32 v18, v18, v19
	v_cvt_pk_bf16_f32 v19, v24, v25
	v_cmp_le_u32_e32 vcc, v65, v31
	s_waitcnt vmcnt(2)
	v_fmac_f32_e32 v92, v70, v69
	v_cndmask_b32_e32 v20, 0, v19, vcc
	v_lshrrev_b32_e32 v19, 16, v19
	v_cmp_le_u32_e32 vcc, v78, v31
	s_nop 1
	v_cndmask_b32_e32 v19, 0, v19, vcc
	v_perm_b32 v19, v19, v20, s19
	ds_write_b128 v0, v[16:19]
	global_load_dwordx4 v[20:23], v[6:7], off offset:112
	global_load_dwordx4 v[24:27], v[6:7], off offset:96
	v_cmp_gt_u32_e32 vcc, v31, v36
	s_nop 1
	v_cndmask_b32_e32 v16, 0, v53, vcc
	v_cmp_le_u32_e32 vcc, v36, v31
	s_nop 1
	v_cndmask_b32_e32 v17, 0, v52, vcc
	v_cvt_pk_bf16_f32 v16, v17, v16
	v_cvt_pk_bf16_f32 v17, v54, v55
	v_cmp_le_u32_e32 vcc, v81, v31
	v_or_b32_e32 v52, 42, v34
	v_or_b32_e32 v55, 43, v34
	v_cndmask_b32_e32 v18, 0, v17, vcc
	v_lshrrev_b32_e32 v17, 16, v17
	v_cmp_le_u32_e32 vcc, v79, v31
	v_lshlrev_b32_e32 v19, 2, v55
	v_and_or_b32 v81, v30, 64, v32
	v_cndmask_b32_e32 v17, 0, v17, vcc
	v_perm_b32 v17, v17, v18, s19
	v_mul_u32_u24_e32 v18, 0x110, v56
	v_add3_u32 v18, s15, v18, v33
	ds_write_b16 v18, v11 offset:34816
	v_lshlrev_b32_e32 v18, 2, v52
	global_load_dword v53, v18, s[16:17]
	global_load_dword v54, v18, s[20:21]
	v_mul_u32_u24_e32 v18, 0x110, v58
	v_cvt_pk_bf16_f32 v11, v97, s0
	v_add3_u32 v18, s15, v18, v33
	v_cmp_gt_u32_e32 vcc, v31, v37
	global_load_dword v65, v19, s[16:17]
	global_load_dword v72, v19, s[20:21]
	ds_write_b16 v18, v11 offset:34816
	v_cndmask_b32_e32 v11, 0, v13, vcc
	v_cmp_le_u32_e32 vcc, v37, v31
	s_waitcnt vmcnt(2)
	v_fmac_f32_e32 v54, v53, v67
	v_cndmask_b32_e32 v12, 0, v12, vcc
	v_cvt_pk_bf16_f32 v18, v12, v11
	v_cvt_pk_bf16_f32 v11, v14, v15
	v_cmp_le_u32_e32 vcc, v59, v31
	v_or_b32_e32 v59, 46, v34
	s_waitcnt vmcnt(0)
	v_fmac_f32_e32 v72, v65, v66
	v_cndmask_b32_e32 v12, 0, v11, vcc
	v_lshrrev_b32_e32 v11, 16, v11
	v_cmp_le_u32_e32 vcc, v10, v31
	s_nop 1
	v_cndmask_b32_e32 v10, 0, v11, vcc
	v_perm_b32 v19, v10, v12, s19
	v_lshlrev_b32_e32 v10, 2, v59
	global_load_dword v73, v10, s[16:17]
	global_load_dword v76, v10, s[20:21]
	ds_write_b128 v0, v[16:19] offset:16
	v_lshlrev_b32_e32 v10, 2, v77
	v_mul_u32_u24_e32 v11, 0x110, v35
	global_load_dword v78, v10, s[16:17]
	global_load_dword v79, v10, s[20:21]
	v_cvt_pk_bf16_f32 v10, v64, s0
	v_add3_u32 v11, s15, v11, v33
	ds_write_b16 v11, v10 offset:34816
	global_load_dwordx4 v[10:13], v[6:7], off offset:144
	global_load_dwordx4 v[14:17], v[6:7], off offset:128
	v_mul_u32_u24_e32 v19, 0x110, v68
	v_cvt_pk_bf16_f32 v18, v92, s0
	v_add3_u32 v19, s15, v19, v33
	v_cmp_gt_u32_e32 vcc, v31, v38
	ds_write_b16 v19, v18 offset:34816
	s_waitcnt vmcnt(4)
	v_fmac_f32_e32 v76, v75, v73
	v_cndmask_b32_e32 v18, 0, v83, vcc
	v_cmp_le_u32_e32 vcc, v38, v31
	s_waitcnt vmcnt(2)
	v_fmac_f32_e32 v79, v74, v78
	v_cndmask_b32_e32 v19, 0, v82, vcc
	v_cvt_pk_bf16_f32 v36, v19, v18
	v_cvt_pk_bf16_f32 v18, v84, v85
	v_cmp_le_u32_e32 vcc, v86, v31
	v_or_b32_e32 v82, s4, v81
	s_nop 0
	v_cndmask_b32_e32 v19, 0, v18, vcc
	v_lshrrev_b32_e32 v18, 16, v18
	v_cmp_le_u32_e32 vcc, v87, v31
	s_nop 1
	v_cndmask_b32_e32 v18, 0, v18, vcc
	v_cmp_gt_u32_e32 vcc, v31, v40
	v_perm_b32 v37, v18, v19, s19
	s_nop 0
	v_cndmask_b32_e32 v18, 0, v45, vcc
	v_cmp_le_u32_e32 vcc, v40, v31
	s_nop 1
	v_cndmask_b32_e32 v19, 0, v44, vcc
	v_cvt_pk_bf16_f32 v38, v19, v18
	v_cvt_pk_bf16_f32 v18, v46, v47
	v_cmp_le_u32_e32 vcc, v88, v31
	s_nop 1
	v_cndmask_b32_e32 v19, 0, v18, vcc
	v_lshrrev_b32_e32 v18, 16, v18
	v_cmp_le_u32_e32 vcc, v89, v31
	s_nop 1
	v_cndmask_b32_e32 v18, 0, v18, vcc
	v_cmp_gt_u32_e32 vcc, v31, v41
	v_perm_b32 v39, v18, v19, s19
	ds_write_b128 v0, v[36:39] offset:32
	v_cndmask_b32_e32 v18, 0, v25, vcc
	v_cmp_le_u32_e32 vcc, v41, v31
	v_mul_u32_u24_e32 v41, 0x110, v52
	v_add3_u32 v41, s15, v41, v33
	v_cndmask_b32_e32 v19, 0, v24, vcc
	v_cvt_pk_bf16_f32 v18, v19, v18
	v_cvt_pk_bf16_f32 v19, v26, v27
	global_load_dwordx4 v[24:27], v[6:7], off offset:176
	global_load_dwordx4 v[36:39], v[6:7], off offset:160
	v_cmp_le_u32_e32 vcc, v91, v31
	s_nop 1
	v_cndmask_b32_e32 v40, 0, v19, vcc
	v_lshrrev_b32_e32 v19, 16, v19
	v_cmp_le_u32_e32 vcc, v94, v31
	s_nop 1
	v_cndmask_b32_e32 v19, 0, v19, vcc
	v_cmp_gt_u32_e32 vcc, v31, v42
	v_perm_b32 v19, v19, v40, s19
	v_cvt_pk_bf16_f32 v40, v54, s0
	v_cndmask_b32_e32 v21, 0, v21, vcc
	v_cmp_le_u32_e32 vcc, v42, v31
	ds_write_b16 v41, v40 offset:34816
	v_mul_u32_u24_e32 v41, 0x110, v55
	v_cndmask_b32_e32 v20, 0, v20, vcc
	v_cvt_pk_bf16_f32 v20, v20, v21
	v_cvt_pk_bf16_f32 v21, v22, v23
	v_cmp_le_u32_e32 vcc, v98, v31
	v_cvt_pk_bf16_f32 v40, v72, s0
	v_add3_u32 v41, s15, v41, v33
	v_cndmask_b32_e32 v22, 0, v21, vcc
	v_lshrrev_b32_e32 v21, 16, v21
	v_cmp_le_u32_e32 vcc, v101, v31
	ds_write_b16 v41, v40 offset:34816
	v_mul_u32_u24_e32 v23, 0x110, v77
	v_cndmask_b32_e32 v21, 0, v21, vcc
	v_perm_b32 v21, v21, v22, s19
	ds_write_b128 v0, v[18:21] offset:48
	v_mul_u32_u24_e32 v19, 0x110, v59
	v_cvt_pk_bf16_f32 v18, v76, s0
	v_add3_u32 v19, s15, v19, v33
	v_cmp_gt_u32_e32 vcc, v31, v43
	ds_write_b16 v19, v18 offset:34816
	v_cvt_pk_bf16_f32 v22, v79, s0
	v_add3_u32 v23, s15, v23, v33
	s_waitcnt vmcnt(2)
	v_cndmask_b32_e32 v15, 0, v15, vcc
	v_cmp_le_u32_e32 vcc, v43, v31
	global_load_dwordx4 v[18:21], v[6:7], off offset:208
	global_load_dwordx4 v[44:47], v[6:7], off offset:192
	ds_write_b16 v23, v22 offset:34816
	v_cndmask_b32_e32 v14, 0, v14, vcc
	v_or_b32_e32 v23, 50, v34
	v_cvt_pk_bf16_f32 v14, v14, v15
	v_cvt_pk_bf16_f32 v15, v16, v17
	v_or_b32_e32 v22, 51, v34
	v_lshlrev_b32_e32 v17, 2, v23
	v_cmp_le_u32_e32 vcc, v56, v31
	global_load_dword v40, v17, s[16:17]
	global_load_dword v41, v17, s[20:21]
	v_lshlrev_b32_e32 v17, 2, v22
	v_cndmask_b32_e32 v16, 0, v15, vcc
	v_lshrrev_b32_e32 v15, 16, v15
	global_load_dword v42, v17, s[16:17]
	global_load_dword v43, v17, s[20:21]
	v_cmp_le_u32_e32 vcc, v58, v31
	s_waitcnt vmcnt(2)
	v_fmac_f32_e32 v41, v40, v62
	v_cndmask_b32_e32 v15, 0, v15, vcc
	v_cmp_gt_u32_e32 vcc, v31, v48
	v_perm_b32 v15, v15, v16, s19
	s_waitcnt vmcnt(0)
	v_fmac_f32_e32 v43, v42, v61
	v_cndmask_b32_e32 v11, 0, v11, vcc
	v_cmp_le_u32_e32 vcc, v48, v31
	v_or_b32_e32 v48, 54, v34
	s_nop 0
	v_cndmask_b32_e32 v10, 0, v10, vcc
	v_cvt_pk_bf16_f32 v16, v10, v11
	v_cvt_pk_bf16_f32 v10, v12, v13
	v_cmp_le_u32_e32 vcc, v35, v31
	v_or_b32_e32 v35, 55, v34
	s_nop 0
	v_cndmask_b32_e32 v11, 0, v10, vcc
	v_lshrrev_b32_e32 v10, 16, v10
	v_cmp_le_u32_e32 vcc, v68, v31
	s_nop 1
	v_cndmask_b32_e32 v10, 0, v10, vcc
	v_perm_b32 v17, v10, v11, s19
	v_lshlrev_b32_e32 v10, 2, v48
	global_load_dword v53, v10, s[16:17]
	global_load_dword v54, v10, s[20:21]
	v_lshlrev_b32_e32 v10, 2, v35
	global_load_dword v56, v10, s[16:17]
	global_load_dword v58, v10, s[20:21]
	v_cmp_gt_u32_e32 vcc, v31, v49
	ds_write_b128 v0, v[14:17] offset:64
	s_waitcnt vmcnt(2)
	v_fmac_f32_e32 v54, v9, v53
	v_cndmask_b32_e32 v10, 0, v37, vcc
	v_cmp_le_u32_e32 vcc, v49, v31
	v_or_b32_e32 v49, 59, v34
	v_cvt_pk_bf16_f32 v9, v54, s0
	v_cndmask_b32_e32 v11, 0, v36, vcc
	v_cvt_pk_bf16_f32 v10, v11, v10
	v_cvt_pk_bf16_f32 v11, v38, v39
	v_cmp_le_u32_e32 vcc, v52, v31
	global_load_dwordx4 v[14:17], v[6:7], off offset:240
	global_load_dwordx4 v[36:39], v[6:7], off offset:224
	v_cndmask_b32_e32 v12, 0, v11, vcc
	v_lshrrev_b32_e32 v11, 16, v11
	v_cmp_le_u32_e32 vcc, v55, v31
	v_or_b32_e32 v52, 58, v34
	s_waitcnt vmcnt(2)
	v_fmac_f32_e32 v58, v8, v56
	v_cndmask_b32_e32 v6, 0, v11, vcc
	v_perm_b32 v11, v6, v12, s19
	v_lshlrev_b32_e32 v6, 2, v52
	global_load_dword v55, v6, s[16:17]
	global_load_dword v63, v6, s[20:21]
	v_lshlrev_b32_e32 v6, 2, v49
	v_cmp_gt_u32_e32 vcc, v31, v51
	global_load_dword v64, v6, s[16:17]
	global_load_dword v65, v6, s[20:21]
	v_cndmask_b32_e32 v6, 0, v25, vcc
	v_cmp_le_u32_e32 vcc, v51, v31
	s_waitcnt vmcnt(2)
	v_fmac_f32_e32 v63, v55, v2
	v_cndmask_b32_e32 v7, 0, v24, vcc
	v_cvt_pk_bf16_f32 v12, v7, v6
	v_cvt_pk_bf16_f32 v6, v26, v27
	v_cmp_le_u32_e32 vcc, v59, v31
	v_mul_u32_u24_e32 v26, 0x110, v22
	v_cvt_pk_bf16_f32 v27, v41, s0
	v_cndmask_b32_e32 v7, 0, v6, vcc
	v_lshrrev_b32_e32 v6, 16, v6
	v_cmp_le_u32_e32 vcc, v77, v31
	v_add3_u32 v26, s15, v26, v33
	v_cvt_pk_bf16_f32 v2, v63, s0
	v_cndmask_b32_e32 v6, 0, v6, vcc
	v_perm_b32 v13, v6, v7, s19
	ds_write_b128 v0, v[10:13] offset:80
	v_or_b32_e32 v11, 62, v34
	v_or_b32_e32 v10, 63, v34
	v_lshlrev_b32_e32 v7, 2, v11
	global_load_dword v12, v7, s[16:17]
	global_load_dword v13, v7, s[20:21]
	v_lshlrev_b32_e32 v7, 2, v10
	global_load_dword v24, v7, s[16:17]
	global_load_dword v25, v7, s[20:21]
	v_cmp_gt_u32_e32 vcc, v31, v57
	s_waitcnt vmcnt(4)
	v_fmac_f32_e32 v65, v64, v3
	s_waitcnt vmcnt(2)
	v_fmac_f32_e32 v13, v5, v12
	v_cndmask_b32_e32 v6, 0, v45, vcc
	v_cmp_le_u32_e32 vcc, v57, v31
	v_cvt_pk_bf16_f32 v5, v13, s0
	s_waitcnt vmcnt(0)
	v_fmac_f32_e32 v25, v4, v24
	v_cndmask_b32_e32 v7, 0, v44, vcc
	v_cvt_pk_bf16_f32 v6, v7, v6
	v_mul_u32_u24_e32 v7, 0x110, v23
	v_add3_u32 v7, s15, v7, v33
	ds_write_b16 v7, v27 offset:34816
	v_cvt_pk_bf16_f32 v7, v43, s0
	ds_write_b16 v26, v7 offset:34816
	v_cvt_pk_bf16_f32 v7, v46, v47
	v_cmp_le_u32_e32 vcc, v23, v31
	s_nop 1
	v_cndmask_b32_e32 v23, 0, v7, vcc
	v_lshrrev_b32_e32 v7, 16, v7
	v_cmp_le_u32_e32 vcc, v22, v31
	s_nop 1
	v_cndmask_b32_e32 v7, 0, v7, vcc
	v_perm_b32 v7, v7, v23, s19
	v_cmp_gt_u32_e32 vcc, v31, v60
	ds_write_b64 v0, v[6:7] offset:96
	s_nop 0
	v_cndmask_b32_e32 v6, 0, v19, vcc
	v_cmp_le_u32_e32 vcc, v60, v31
	s_nop 1
	v_cndmask_b32_e32 v7, 0, v18, vcc
	v_cvt_pk_bf16_f32 v6, v7, v6
	v_mul_u32_u24_e32 v7, 0x110, v48
	v_add3_u32 v7, s15, v7, v33
	v_mul_u32_u24_e32 v18, 0x110, v35
	v_add3_u32 v18, s15, v18, v33
	ds_write_b16 v7, v9 offset:34816
	v_cvt_pk_bf16_f32 v7, v58, s0
	ds_write_b16 v18, v7 offset:34816
	v_cvt_pk_bf16_f32 v7, v20, v21
	v_cmp_le_u32_e32 vcc, v48, v31
	s_nop 1
	v_cndmask_b32_e32 v8, 0, v7, vcc
	v_lshrrev_b32_e32 v7, 16, v7
	v_cmp_le_u32_e32 vcc, v35, v31
	s_nop 1
	v_cndmask_b32_e32 v7, 0, v7, vcc
	v_perm_b32 v7, v7, v8, s19
	v_cmp_gt_u32_e32 vcc, v31, v29
	ds_write_b64 v0, v[6:7] offset:104
	v_mul_u32_u24_e32 v8, 0x110, v49
	v_cndmask_b32_e32 v6, 0, v37, vcc
	v_cmp_le_u32_e32 vcc, v29, v31
	v_add3_u32 v8, s15, v8, v33
	s_nop 0
	v_cndmask_b32_e32 v7, 0, v36, vcc
	v_cvt_pk_bf16_f32 v6, v7, v6
	v_mul_u32_u24_e32 v7, 0x110, v52
	v_add3_u32 v7, s15, v7, v33
	ds_write_b16 v7, v2 offset:34816
	v_cvt_pk_bf16_f32 v2, v65, s0
	ds_write_b16 v8, v2 offset:34816
	v_cvt_pk_bf16_f32 v2, v38, v39
	v_cmp_le_u32_e32 vcc, v52, v31
	s_nop 1
	v_cndmask_b32_e32 v3, 0, v2, vcc
	v_lshrrev_b32_e32 v2, 16, v2
	v_cmp_le_u32_e32 vcc, v49, v31
	s_nop 1
	v_cndmask_b32_e32 v2, 0, v2, vcc
	v_cmp_gt_u32_e32 vcc, v31, v28
	v_perm_b32 v7, v2, v3, s19
	ds_write_b64 v0, v[6:7] offset:112
	v_cndmask_b32_e32 v2, 0, v15, vcc
	v_cmp_le_u32_e32 vcc, v28, v31
	v_mul_u32_u24_e32 v6, 0x110, v10
	v_add3_u32 v6, s15, v6, v33
	v_cndmask_b32_e32 v3, 0, v14, vcc
	v_cvt_pk_bf16_f32 v2, v3, v2
	v_mul_u32_u24_e32 v3, 0x110, v11
	v_add3_u32 v3, s15, v3, v33
	ds_write_b16 v3, v5 offset:34816
	v_cvt_pk_bf16_f32 v3, v25, s0
	ds_write_b16 v6, v3 offset:34816
	v_cvt_pk_bf16_f32 v3, v16, v17
	v_cmp_le_u32_e32 vcc, v11, v31
	v_mul_u32_u24_e32 v7, 0x88, v81
	v_lshlrev_b32_e32 v81, 2, v81
	v_cndmask_b32_e32 v4, 0, v3, vcc
	v_lshrrev_b32_e32 v3, 16, v3
	v_cmp_le_u32_e32 vcc, v10, v31
	s_nop 1
	v_cndmask_b32_e32 v3, 0, v3, vcc
	v_perm_b32 v3, v3, v4, s19
	ds_write_b64 v0, v[2:3] offset:120
	v_bfe_u32 v0, v50, 4, 2
	v_and_b32_e32 v2, 0x4f, v50
	v_lshl_add_u32 v6, v0, 4, s15
	v_mul_u32_u24_e32 v2, 0x88, v2
	v_lshl_add_u32 v51, v2, 1, v6
	s_waitcnt lgkmcnt(0)
	s_barrier
	ds_read_b128 v[2:5], v51 offset:34816
	ds_read_b128 v[72:75], v51 offset:34880
	ds_read_b128 v[14:17], v51 offset:39168
	ds_read_b128 v[76:79], v51 offset:39232
	ds_read_b128 v[22:25], v51 offset:43520
	ds_read_b128 v[84:87], v51 offset:43584
	ds_read_b128 v[30:33], v51 offset:47872
	ds_read_b128 v[88:91], v51 offset:47936
	v_lshl_add_u32 v83, v7, 1, v6
	ds_read_b128 v[6:9], v83
	ds_read_b128 v[34:37], v83 offset:4352
	ds_read_b128 v[52:55], v83 offset:8704
	ds_read_b128 v[68:71], v83 offset:13056
	s_waitcnt lgkmcnt(3)
	v_mfma_f32_16x16x32_bf16 v[10:13], v[2:5], v[6:9], 0
	ds_read_b128 v[100:103], v51 offset:48000
	v_and_b32_e32 v50, 64, v50
	v_mfma_f32_16x16x32_bf16 v[18:21], v[14:17], v[6:9], 0
	v_mfma_f32_16x16x32_bf16 v[26:29], v[22:25], v[6:9], 0
	v_mfma_f32_16x16x32_bf16 v[6:9], v[30:33], v[6:9], 0
	s_waitcnt lgkmcnt(3)
	v_mfma_f32_16x16x32_bf16 v[38:41], v[2:5], v[34:37], 0
	v_mfma_f32_16x16x32_bf16 v[42:45], v[14:17], v[34:37], 0
	v_mfma_f32_16x16x32_bf16 v[46:49], v[22:25], v[34:37], 0
	v_mfma_f32_16x16x32_bf16 v[34:37], v[30:33], v[34:37], 0
	s_waitcnt lgkmcnt(2)
	v_mfma_f32_16x16x32_bf16 v[56:59], v[2:5], v[52:55], 0
	v_mfma_f32_16x16x32_bf16 v[60:63], v[14:17], v[52:55], 0
	v_mfma_f32_16x16x32_bf16 v[64:67], v[22:25], v[52:55], 0
	v_mfma_f32_16x16x32_bf16 v[52:55], v[30:33], v[52:55], 0
	s_waitcnt lgkmcnt(1)
	v_mfma_f32_16x16x32_bf16 v[2:5], v[2:5], v[68:71], 0
	v_mfma_f32_16x16x32_bf16 v[14:17], v[14:17], v[68:71], 0
	v_mfma_f32_16x16x32_bf16 v[22:25], v[22:25], v[68:71], 0
	v_mfma_f32_16x16x32_bf16 v[30:33], v[30:33], v[68:71], 0
	ds_read_b128 v[68:71], v83 offset:64
	s_waitcnt lgkmcnt(0)
	v_mfma_f32_16x16x32_bf16 v[10:13], v[72:75], v[68:71], v[10:13]
	v_mfma_f32_16x16x32_bf16 v[18:21], v[76:79], v[68:71], v[18:21]
	v_mfma_f32_16x16x32_bf16 v[26:29], v[84:87], v[68:71], v[26:29]
	v_mfma_f32_16x16x32_bf16 v[6:9], v[88:91], v[68:71], v[6:9]
	ds_read_b128 v[68:71], v83 offset:4416
	s_waitcnt lgkmcnt(0)
	v_mfma_f32_16x16x32_bf16 v[38:41], v[72:75], v[68:71], v[38:41]
	v_mfma_f32_16x16x32_bf16 v[42:45], v[76:79], v[68:71], v[42:45]
	v_mfma_f32_16x16x32_bf16 v[46:49], v[84:87], v[68:71], v[46:49]
	v_mfma_f32_16x16x32_bf16 v[34:37], v[88:91], v[68:71], v[34:37]
	ds_read_b128 v[68:71], v83 offset:8768
	s_waitcnt lgkmcnt(0)
	v_mfma_f32_16x16x32_bf16 v[92:95], v[76:79], v[68:71], v[60:63]
	s_nop 2
	ds_read_b128 v[60:63], v83 offset:13120
	v_mfma_f32_16x16x32_bf16 v[56:59], v[72:75], v[68:71], v[56:59]
	v_mfma_f32_16x16x32_bf16 v[96:99], v[84:87], v[68:71], v[64:67]
	v_mfma_f32_16x16x32_bf16 v[52:55], v[88:91], v[68:71], v[52:55]
	s_nop 1
	ds_read_b128 v[66:69], v51 offset:34944
	s_waitcnt lgkmcnt(1)
	v_mfma_f32_16x16x32_bf16 v[2:5], v[72:75], v[60:63], v[2:5]
	v_mfma_f32_16x16x32_bf16 v[70:73], v[88:91], v[60:63], v[30:33]
	s_nop 2
	ds_read_b128 v[30:33], v83 offset:128
	v_mfma_f32_16x16x32_bf16 v[14:17], v[76:79], v[60:63], v[14:17]
	s_waitcnt lgkmcnt(0)
	v_mfma_f32_16x16x32_bf16 v[74:77], v[66:69], v[30:33], v[10:13]
	s_nop 2
	ds_read_b128 v[10:13], v51 offset:39296
	v_mfma_f32_16x16x32_bf16 v[22:25], v[84:87], v[60:63], v[22:25]
	v_mfma_f32_16x16x32_bf16 v[104:107], v[100:103], v[30:33], v[6:9]
	s_nop 2
	ds_read_b128 v[6:9], v83 offset:4480
	s_waitcnt lgkmcnt(1)
	v_mfma_f32_16x16x32_bf16 v[84:87], v[10:13], v[30:33], v[18:21]
	s_nop 2
	ds_read_b128 v[18:21], v51 offset:43648
	s_waitcnt lgkmcnt(1)
	v_mfma_f32_16x16x32_bf16 v[108:111], v[66:69], v[6:9], v[38:41]
	v_mfma_f32_16x16x32_bf16 v[112:115], v[10:13], v[6:9], v[42:45]
	s_waitcnt lgkmcnt(0)
	v_mfma_f32_16x16x32_bf16 v[116:119], v[18:21], v[6:9], v[46:49]
	v_mfma_f32_16x16x32_bf16 v[62:65], v[100:103], v[6:9], v[34:37]
	ds_read_b128 v[6:9], v83 offset:8832
	s_waitcnt lgkmcnt(0)
	v_mfma_f32_16x16x32_bf16 v[42:45], v[100:103], v[6:9], v[52:55]
	s_nop 2
	ds_read_b128 v[52:55], v83 offset:13184
	v_mfma_f32_16x16x32_bf16 v[88:91], v[18:21], v[30:33], v[26:29]
	ds_read_b128 v[30:33], v51 offset:35008
	v_mfma_f32_16x16x32_bf16 v[46:49], v[18:21], v[6:9], v[96:99]
	s_waitcnt lgkmcnt(1)
	v_mfma_f32_16x16x32_bf16 v[26:29], v[66:69], v[52:55], v[2:5]
	v_mfma_f32_16x16x32_bf16 v[2:5], v[18:21], v[52:55], v[22:25]
	ds_read_b128 v[18:21], v51 offset:39360
	v_mfma_f32_16x16x32_bf16 v[38:41], v[66:69], v[6:9], v[56:59]
	v_mfma_f32_16x16x32_bf16 v[34:37], v[10:13], v[6:9], v[92:95]
	v_mfma_f32_16x16x32_bf16 v[6:9], v[10:13], v[52:55], v[14:17]
	v_mfma_f32_16x16x32_bf16 v[10:13], v[100:103], v[52:55], v[70:73]
	ds_read_b128 v[52:55], v83 offset:192
	ds_read_b128 v[22:25], v51 offset:43712
	ds_read_b128 v[14:17], v51 offset:48064
	v_lshlrev_b32_e32 v70, 3, v0
	v_lshlrev_b32_e32 v0, 1, v50
	v_lshl_add_u64 v[50:51], s[6:7], 0, v[0:1]
	v_mov_b32_e32 v71, v1
	s_waitcnt lgkmcnt(2)
	v_mfma_f32_16x16x32_bf16 v[92:95], v[30:33], v[52:55], v[74:77]
	ds_read_b128 v[100:103], v83 offset:4544
	s_nop 1
	v_lshl_add_u64 v[74:75], v[50:51], 0, v[70:71]
	v_mad_u64_u32 v[72:73], s[0:1], v82, s3, v[74:75]
	v_mfma_f32_16x16x32_bf16 v[96:99], v[18:21], v[52:55], v[84:87]
	s_lshl_b64 s[0:1], s[88:89], 2
	s_add_u32 s12, s42, s0
	s_addc_u32 s13, s43, s1
	s_waitcnt lgkmcnt(2)
	v_mfma_f32_16x16x32_bf16 v[86:89], v[22:25], v[52:55], v[88:91]
	global_load_dword v85, v81, s[12:13]
	v_or_b32_e32 v84, 16, v82
	v_mad_u64_u32 v[78:79], s[0:1], v84, s3, v[74:75]
	global_load_dwordx2 v[90:91], v[72:73], off
	s_waitcnt lgkmcnt(1)
	v_mfma_f32_16x16x32_bf16 v[66:69], v[14:17], v[52:55], v[104:107]
	s_cmpk_gt_u32 s10, 0xff
	s_waitcnt vmcnt(1)
	v_add_f32_e32 v87, v87, v85
	global_load_dwordx2 v[104:105], v[72:73], off offset:32
	s_waitcnt lgkmcnt(0)
	v_mfma_f32_16x16x32_bf16 v[58:61], v[30:33], v[100:103], v[108:111]
	global_load_dwordx2 v[106:107], v[72:73], off offset:64
	s_nop 1
	global_load_dwordx2 v[108:109], v[72:73], off offset:96
	s_waitcnt vmcnt(3)
	v_lshlrev_b32_e32 v72, 16, v90
	v_mul_f32_e32 v73, v72, v72
	v_and_b32_e32 v90, 0xffff0000, v90
	v_fmamk_f32 v73, v73, 0xbdd2d3e7, v129
	v_mul_f32_e32 v76, v90, v90
	v_mul_f32_e32 v73, v73, v72
	v_fmamk_f32 v76, v76, 0xbdd2d3e7, v129
	v_mul_f32_e32 v76, v76, v90
	v_exp_f32_e32 v73, v73
	v_exp_f32_e32 v110, v76
	v_add_f32_e32 v86, v86, v85
	v_add_f32_e32 v73, 1.0, v73
	v_rcp_f32_e32 v73, v73
	v_add_f32_e32 v110, 1.0, v110
	v_rcp_f32_e32 v110, v110
	v_add_f32_e32 v88, v88, v85
	v_mul_f32_e32 v72, v73, v72
	v_add_f32_e32 v73, v92, v85
	v_mul_f32_e32 v72, v72, v73
	v_mul_f32_e32 v73, v110, v90
	v_add_f32_e32 v90, v93, v85
	v_lshlrev_b32_e32 v92, 16, v91
	v_mul_f32_e32 v73, v73, v90
	v_mul_f32_e32 v90, v92, v92
	v_and_b32_e32 v91, 0xffff0000, v91
	v_fmamk_f32 v90, v90, 0xbdd2d3e7, v129
	v_mul_f32_e32 v93, v91, v91
	v_mul_f32_e32 v90, v90, v92
	v_fmamk_f32 v93, v93, 0xbdd2d3e7, v129
	v_mul_f32_e32 v93, v93, v91
	v_exp_f32_e32 v90, v90
	v_exp_f32_e32 v93, v93
	v_add_f32_e32 v89, v89, v85
	v_add_f32_e32 v90, 1.0, v90
	v_rcp_f32_e32 v110, v90
	v_cvt_pk_bf16_f32 v90, v72, v73
	v_add_f32_e32 v72, 1.0, v93
	v_rcp_f32_e32 v72, v72
	v_mul_f32_e32 v73, v110, v92
	v_add_f32_e32 v92, v94, v85
	v_mul_f32_e32 v73, v73, v92
	v_mul_f32_e32 v72, v72, v91
	v_add_f32_e32 v91, v95, v85
	v_mul_f32_e32 v72, v72, v91
	v_cvt_pk_bf16_f32 v91, v73, v72
	v_mov_b64_e32 v[72:73], s[50:51]
	v_mad_u64_u32 v[92:93], s[0:1], v82, s3, v[72:73]
	v_lshl_add_u64 v[92:93], v[92:93], 0, s[8:9]
	v_lshl_add_u64 v[92:93], v[92:93], 0, v[0:1]
	v_lshl_add_u64 v[92:93], v[92:93], 0, v[70:71]
	global_store_dwordx2 v[92:93], v[90:91], off
	v_add_f32_e32 v67, v67, v85
	v_add_f32_e32 v66, v66, v85
	global_load_dwordx2 v[76:77], v[78:79], off
	v_add_f32_e32 v68, v68, v85
	v_add_f32_e32 v69, v69, v85
	v_mfma_f32_16x16x32_bf16 v[54:57], v[18:21], v[100:103], v[112:115]
	s_waitcnt vmcnt(4)
	v_lshlrev_b32_e32 v94, 16, v104
	v_mul_f32_e32 v95, v94, v94
	v_and_b32_e32 v104, 0xffff0000, v104
	v_fmamk_f32 v95, v95, 0xbdd2d3e7, v129
	v_mul_f32_e32 v110, v104, v104
	v_mul_f32_e32 v95, v95, v94
	v_fmamk_f32 v110, v110, 0xbdd2d3e7, v129
	v_mul_f32_e32 v110, v110, v104
	v_exp_f32_e32 v95, v95
	v_exp_f32_e32 v110, v110
	v_mfma_f32_16x16x32_bf16 v[50:53], v[22:25], v[100:103], v[116:119]
	v_add_f32_e32 v95, 1.0, v95
	v_rcp_f32_e32 v95, v95
	v_add_f32_e32 v90, 1.0, v110
	v_rcp_f32_e32 v90, v90
	v_mfma_f32_16x16x32_bf16 v[62:65], v[14:17], v[100:103], v[62:65]
	v_mul_f32_e32 v91, v95, v94
	v_add_f32_e32 v94, v96, v85
	v_mul_f32_e32 v91, v91, v94
	v_mul_f32_e32 v90, v90, v104
	v_add_f32_e32 v94, v97, v85
	v_mul_f32_e32 v90, v90, v94
	v_lshlrev_b32_e32 v94, 16, v105
	v_mul_f32_e32 v95, v94, v94
	v_and_b32_e32 v96, 0xffff0000, v105
	v_fmamk_f32 v95, v95, 0xbdd2d3e7, v129
	v_mul_f32_e32 v97, v96, v96
	v_mul_f32_e32 v95, v95, v94
	v_fmamk_f32 v97, v97, 0xbdd2d3e7, v129
	v_mul_f32_e32 v97, v97, v96
	v_exp_f32_e32 v95, v95
	v_exp_f32_e32 v97, v97
	v_cvt_pk_bf16_f32 v90, v91, v90
	v_add_f32_e32 v95, 1.0, v95
	v_rcp_f32_e32 v95, v95
	v_add_f32_e32 v91, 1.0, v97
	v_rcp_f32_e32 v91, v91
	v_mul_f32_e32 v94, v95, v94
	v_add_f32_e32 v95, v98, v85
	v_mul_f32_e32 v94, v94, v95
	v_mul_f32_e32 v91, v91, v96
	v_add_f32_e32 v95, v99, v85
	v_mul_f32_e32 v91, v91, v95
	s_waitcnt vmcnt(3)
	v_and_b32_e32 v96, 0xffff0000, v106
	v_cvt_pk_bf16_f32 v91, v94, v91
	v_lshlrev_b32_e32 v94, 16, v106
	v_mul_f32_e32 v97, v96, v96
	v_mul_f32_e32 v95, v94, v94
	v_fmamk_f32 v97, v97, 0xbdd2d3e7, v129
	v_fmamk_f32 v95, v95, 0xbdd2d3e7, v129
	v_mul_f32_e32 v97, v97, v96
	v_mul_f32_e32 v95, v95, v94
	v_exp_f32_e32 v97, v97
	v_exp_f32_e32 v95, v95
	global_store_dwordx2 v[92:93], v[90:91], off offset:32
	v_add_f32_e32 v90, 1.0, v97
	v_add_f32_e32 v95, 1.0, v95
	v_rcp_f32_e32 v90, v90
	v_rcp_f32_e32 v95, v95
	v_mul_f32_e32 v90, v90, v96
	v_mul_f32_e32 v91, v95, v94
	v_mul_f32_e32 v87, v90, v87
	v_lshlrev_b32_e32 v90, 16, v107
	v_and_b32_e32 v94, 0xffff0000, v107
	v_mul_f32_e32 v86, v91, v86
	v_mul_f32_e32 v91, v90, v90
	v_mul_f32_e32 v95, v94, v94
	v_fmamk_f32 v91, v91, 0xbdd2d3e7, v129
	v_fmamk_f32 v95, v95, 0xbdd2d3e7, v129
	v_mul_f32_e32 v91, v91, v90
	v_mul_f32_e32 v95, v95, v94
	v_exp_f32_e32 v91, v91
	v_exp_f32_e32 v95, v95
	v_cvt_pk_bf16_f32 v86, v86, v87
	v_add_f32_e32 v91, 1.0, v91
	v_add_f32_e32 v87, 1.0, v95
	v_rcp_f32_e32 v91, v91
	v_rcp_f32_e32 v87, v87
	v_mul_f32_e32 v90, v91, v90
	v_mul_f32_e32 v87, v87, v94
	v_mul_f32_e32 v88, v90, v88
	v_mul_f32_e32 v87, v87, v89
	s_waitcnt vmcnt(3)
	v_and_b32_e32 v90, 0xffff0000, v108
	v_cvt_pk_bf16_f32 v87, v88, v87
	v_lshlrev_b32_e32 v88, 16, v108
	v_mul_f32_e32 v91, v90, v90
	v_mul_f32_e32 v89, v88, v88
	v_fmamk_f32 v91, v91, 0xbdd2d3e7, v129
	v_fmamk_f32 v89, v89, 0xbdd2d3e7, v129
	v_mul_f32_e32 v91, v91, v90
	v_mul_f32_e32 v89, v89, v88
	v_exp_f32_e32 v91, v91
	v_exp_f32_e32 v89, v89
	global_store_dwordx2 v[92:93], v[86:87], off offset:64
	v_add_f32_e32 v86, 1.0, v91
	v_add_f32_e32 v89, 1.0, v89
	v_rcp_f32_e32 v86, v86
	v_rcp_f32_e32 v89, v89
	v_mul_f32_e32 v86, v86, v90
	v_mul_f32_e32 v87, v89, v88
	v_mul_f32_e32 v67, v86, v67
	v_lshlrev_b32_e32 v86, 16, v109
	v_and_b32_e32 v88, 0xffff0000, v109
	v_mul_f32_e32 v66, v87, v66
	v_mul_f32_e32 v87, v86, v86
	v_mul_f32_e32 v89, v88, v88
	v_fmamk_f32 v87, v87, 0xbdd2d3e7, v129
	v_fmamk_f32 v89, v89, 0xbdd2d3e7, v129
	v_mul_f32_e32 v87, v87, v86
	v_mul_f32_e32 v89, v89, v88
	v_exp_f32_e32 v87, v87
	v_exp_f32_e32 v89, v89
	v_cvt_pk_bf16_f32 v66, v66, v67
	global_load_dwordx2 v[90:91], v[78:79], off offset:32
	v_add_f32_e32 v87, 1.0, v87
	v_add_f32_e32 v67, 1.0, v89
	v_rcp_f32_e32 v87, v87
	v_rcp_f32_e32 v67, v67
	v_mul_f32_e32 v86, v87, v86
	v_mul_f32_e32 v67, v67, v88
	v_mul_f32_e32 v68, v68, v86
	v_mul_f32_e32 v67, v69, v67
	v_cvt_pk_bf16_f32 v67, v68, v67
	global_store_dwordx2 v[92:93], v[66:67], off offset:96
	global_load_dword v85, v81, s[12:13] offset:64
	ds_read_b128 v[86:89], v83 offset:8896
	global_load_dwordx2 v[92:93], v[78:79], off offset:64
	global_load_dwordx2 v[94:95], v[78:79], off offset:96
	s_waitcnt vmcnt(7)
	v_lshlrev_b32_e32 v79, 16, v76
	v_and_b32_e32 v76, 0xffff0000, v76
	v_mul_f32_e32 v67, v76, v76
	v_mul_f32_e32 v66, v79, v79
	v_fmamk_f32 v67, v67, 0xbdd2d3e7, v129
	v_fmamk_f32 v66, v66, 0xbdd2d3e7, v129
	v_mul_f32_e32 v67, v67, v76
	v_mul_f32_e32 v66, v66, v79
	v_exp_f32_e32 v96, v67
	v_exp_f32_e32 v66, v66
	v_or_b32_e32 v78, 32, v82
	v_mad_u64_u32 v[68:69], s[0:1], v78, s3, v[74:75]
	v_add_f32_e32 v96, 1.0, v96
	v_add_f32_e32 v66, 1.0, v66
	v_rcp_f32_e32 v96, v96
	v_rcp_f32_e32 v97, v66
	global_load_dwordx2 v[66:67], v[68:69], off
	s_waitcnt lgkmcnt(0)
	v_mfma_f32_16x16x32_bf16 v[38:41], v[30:33], v[86:89], v[38:41]
	v_mul_f32_e32 v76, v96, v76
	v_mul_f32_e32 v79, v97, v79
	s_waitcnt vmcnt(3)
	v_add_f32_e32 v59, v59, v85
	v_add_f32_e32 v58, v58, v85
	v_mul_f32_e32 v59, v76, v59
	v_lshlrev_b32_e32 v76, 16, v77
	v_and_b32_e32 v77, 0xffff0000, v77
	v_mul_f32_e32 v58, v79, v58
	v_mul_f32_e32 v79, v76, v76
	v_mul_f32_e32 v96, v77, v77
	v_fmamk_f32 v79, v79, 0xbdd2d3e7, v129
	v_fmamk_f32 v96, v96, 0xbdd2d3e7, v129
	v_mul_f32_e32 v79, v79, v76
	v_mul_f32_e32 v96, v96, v77
	v_exp_f32_e32 v79, v79
	v_exp_f32_e32 v96, v96
	v_cvt_pk_bf16_f32 v58, v58, v59
	v_add_f32_e32 v60, v60, v85
	v_add_f32_e32 v79, 1.0, v79
	v_add_f32_e32 v59, 1.0, v96
	v_rcp_f32_e32 v79, v79
	v_rcp_f32_e32 v59, v59
	v_add_f32_e32 v61, v61, v85
	v_add_f32_e32 v55, v55, v85
	v_mul_f32_e32 v76, v79, v76
	v_mul_f32_e32 v59, v59, v77
	v_mul_f32_e32 v60, v76, v60
	v_mul_f32_e32 v59, v59, v61
	v_and_b32_e32 v79, 0xffff0000, v90
	v_cvt_pk_bf16_f32 v59, v60, v59
	v_mad_u64_u32 v[60:61], s[0:1], v84, s3, v[72:73]
	v_lshlrev_b32_e32 v76, 16, v90
	v_mul_f32_e32 v84, v79, v79
	v_mul_f32_e32 v77, v76, v76
	v_fmamk_f32 v84, v84, 0xbdd2d3e7, v129
	v_fmamk_f32 v77, v77, 0xbdd2d3e7, v129
	v_mul_f32_e32 v84, v84, v79
	v_mul_f32_e32 v77, v77, v76
	v_exp_f32_e32 v84, v84
	v_lshl_add_u64 v[60:61], v[60:61], 0, s[8:9]
	v_exp_f32_e32 v77, v77
	v_lshl_add_u64 v[60:61], v[60:61], 0, v[0:1]
	v_lshl_add_u64 v[60:61], v[60:61], 0, v[70:71]
	global_store_dwordx2 v[60:61], v[58:59], off
	v_add_f32_e32 v58, 1.0, v84
	v_add_f32_e32 v77, 1.0, v77
	v_rcp_f32_e32 v58, v58
	v_rcp_f32_e32 v77, v77
	v_add_f32_e32 v54, v54, v85
	v_add_f32_e32 v56, v56, v85
	v_mul_f32_e32 v58, v58, v79
	v_mul_f32_e32 v59, v77, v76
	v_mul_f32_e32 v55, v58, v55
	v_lshlrev_b32_e32 v58, 16, v91
	v_and_b32_e32 v76, 0xffff0000, v91
	v_mul_f32_e32 v54, v59, v54
	v_mul_f32_e32 v59, v58, v58
	v_mul_f32_e32 v77, v76, v76
	v_fmamk_f32 v59, v59, 0xbdd2d3e7, v129
	v_fmamk_f32 v77, v77, 0xbdd2d3e7, v129
	v_mul_f32_e32 v59, v59, v58
	v_mul_f32_e32 v77, v77, v76
	v_exp_f32_e32 v59, v59
	v_exp_f32_e32 v77, v77
	v_cvt_pk_bf16_f32 v54, v54, v55
	v_add_f32_e32 v57, v57, v85
	v_add_f32_e32 v59, 1.0, v59
	v_add_f32_e32 v55, 1.0, v77
	v_rcp_f32_e32 v59, v59
	v_rcp_f32_e32 v55, v55
	v_add_f32_e32 v51, v51, v85
	v_add_f32_e32 v50, v50, v85
	v_mul_f32_e32 v58, v59, v58
	v_mul_f32_e32 v55, v55, v76
	v_mul_f32_e32 v56, v58, v56
	v_mul_f32_e32 v55, v55, v57
	s_waitcnt vmcnt(3)
	v_and_b32_e32 v58, 0xffff0000, v92
	v_cvt_pk_bf16_f32 v55, v56, v55
	v_lshlrev_b32_e32 v56, 16, v92
	v_mul_f32_e32 v59, v58, v58
	v_mul_f32_e32 v57, v56, v56
	v_fmamk_f32 v59, v59, 0xbdd2d3e7, v129
	v_fmamk_f32 v57, v57, 0xbdd2d3e7, v129
	v_mul_f32_e32 v59, v59, v58
	v_mul_f32_e32 v57, v57, v56
	v_exp_f32_e32 v59, v59
	v_exp_f32_e32 v57, v57
	global_store_dwordx2 v[60:61], v[54:55], off offset:32
	v_add_f32_e32 v52, v52, v85
	v_add_f32_e32 v54, 1.0, v59
	v_add_f32_e32 v57, 1.0, v57
	v_rcp_f32_e32 v54, v54
	v_rcp_f32_e32 v57, v57
	v_add_f32_e32 v53, v53, v85
	v_mfma_f32_16x16x32_bf16 v[34:37], v[18:21], v[86:89], v[34:37]
	v_mul_f32_e32 v54, v54, v58
	v_mul_f32_e32 v55, v57, v56
	v_mul_f32_e32 v51, v54, v51
	v_lshlrev_b32_e32 v54, 16, v93
	v_and_b32_e32 v56, 0xffff0000, v93
	v_mul_f32_e32 v50, v55, v50
	v_mul_f32_e32 v55, v54, v54
	v_mul_f32_e32 v57, v56, v56
	v_fmamk_f32 v55, v55, 0xbdd2d3e7, v129
	v_fmamk_f32 v57, v57, 0xbdd2d3e7, v129
	v_mul_f32_e32 v55, v55, v54
	v_mul_f32_e32 v57, v57, v56
	v_exp_f32_e32 v55, v55
	v_exp_f32_e32 v57, v57
	v_cvt_pk_bf16_f32 v50, v50, v51
	v_mfma_f32_16x16x32_bf16 v[46:49], v[22:25], v[86:89], v[46:49]
	v_add_f32_e32 v55, 1.0, v55
	v_add_f32_e32 v51, 1.0, v57
	v_rcp_f32_e32 v55, v55
	v_rcp_f32_e32 v51, v51
	v_mfma_f32_16x16x32_bf16 v[42:45], v[14:17], v[86:89], v[42:45]
	v_or_b32_e32 v57, 48, v82
	v_mul_f32_e32 v54, v55, v54
	v_mul_f32_e32 v51, v51, v56
	v_mul_f32_e32 v52, v54, v52
	v_mul_f32_e32 v51, v51, v53
	v_cvt_pk_bf16_f32 v51, v52, v51
	s_waitcnt vmcnt(3)
	v_lshlrev_b32_e32 v52, 16, v94
	v_mul_f32_e32 v53, v52, v52
	v_and_b32_e32 v54, 0xffff0000, v94
	v_fmamk_f32 v53, v53, 0xbdd2d3e7, v129
	v_mul_f32_e32 v55, v54, v54
	v_mul_f32_e32 v53, v53, v52
	v_fmamk_f32 v55, v55, 0xbdd2d3e7, v129
	v_mul_f32_e32 v55, v55, v54
	v_exp_f32_e32 v53, v53
	v_exp_f32_e32 v55, v55
	global_store_dwordx2 v[60:61], v[50:51], off offset:64
	v_add_f32_e32 v53, 1.0, v53
	v_rcp_f32_e32 v53, v53
	v_add_f32_e32 v50, 1.0, v55
	v_rcp_f32_e32 v50, v50
	v_mul_f32_e32 v51, v53, v52
	v_add_f32_e32 v52, v62, v85
	v_mul_f32_e32 v51, v51, v52
	v_mul_f32_e32 v50, v50, v54
	v_add_f32_e32 v52, v63, v85
	v_mul_f32_e32 v50, v50, v52
	v_lshlrev_b32_e32 v52, 16, v95
	v_mul_f32_e32 v53, v52, v52
	v_and_b32_e32 v54, 0xffff0000, v95
	v_fmamk_f32 v53, v53, 0xbdd2d3e7, v129
	v_mul_f32_e32 v55, v54, v54
	v_mul_f32_e32 v53, v53, v52
	v_fmamk_f32 v55, v55, 0xbdd2d3e7, v129
	v_mul_f32_e32 v55, v55, v54
	v_exp_f32_e32 v53, v53
	v_exp_f32_e32 v55, v55
	v_cvt_pk_bf16_f32 v50, v51, v50
	v_add_f32_e32 v53, 1.0, v53
	v_rcp_f32_e32 v53, v53
	v_add_f32_e32 v51, 1.0, v55
	v_rcp_f32_e32 v51, v51
	v_mul_f32_e32 v52, v53, v52
	v_add_f32_e32 v53, v64, v85
	v_mul_f32_e32 v52, v52, v53
	v_mul_f32_e32 v51, v51, v54
	v_add_f32_e32 v53, v65, v85
	v_mul_f32_e32 v51, v51, v53
	v_cvt_pk_bf16_f32 v51, v52, v51
	global_store_dwordx2 v[60:61], v[50:51], off offset:96
	global_load_dword v56, v81, s[12:13] offset:128
	global_load_dwordx2 v[54:55], v[68:69], off offset:32
	ds_read_b128 v[50:53], v83 offset:13248
	global_load_dwordx2 v[58:59], v[68:69], off offset:64
	global_load_dwordx2 v[60:61], v[68:69], off offset:96
	s_waitcnt vmcnt(8)
	v_lshlrev_b32_e32 v62, 16, v66
	s_waitcnt lgkmcnt(0)
	v_mfma_f32_16x16x32_bf16 v[26:29], v[30:33], v[50:53], v[26:29]
	v_mul_f32_e32 v30, v62, v62
	v_and_b32_e32 v63, 0xffff0000, v66
	v_fmamk_f32 v30, v30, 0xbdd2d3e7, v129
	v_mul_f32_e32 v31, v63, v63
	v_mul_f32_e32 v30, v30, v62
	v_fmamk_f32 v31, v31, 0xbdd2d3e7, v129
	v_mul_f32_e32 v31, v31, v63
	v_exp_f32_e32 v30, v30
	v_exp_f32_e32 v64, v31
	v_mad_u64_u32 v[32:33], s[0:1], v57, s3, v[74:75]
	v_add_f32_e32 v30, 1.0, v30
	v_rcp_f32_e32 v65, v30
	v_add_f32_e32 v64, 1.0, v64
	v_rcp_f32_e32 v64, v64
	global_load_dwordx2 v[30:31], v[32:33], off
	v_mul_f32_e32 v62, v65, v62
	v_mfma_f32_16x16x32_bf16 v[6:9], v[18:21], v[50:53], v[6:9]
	global_load_dwordx2 v[18:19], v[32:33], off offset:32
	s_waitcnt vmcnt(5)
	v_add_f32_e32 v38, v38, v56
	v_mul_f32_e32 v38, v62, v38
	v_mul_f32_e32 v62, v64, v63
	v_add_f32_e32 v39, v39, v56
	v_mul_f32_e32 v39, v62, v39
	v_lshlrev_b32_e32 v62, 16, v67
	v_mul_f32_e32 v63, v62, v62
	v_fmamk_f32 v63, v63, 0xbdd2d3e7, v129
	v_and_b32_e32 v64, 0xffff0000, v67
	v_mul_f32_e32 v63, v63, v62
	v_mul_f32_e32 v65, v64, v64
	v_fmamk_f32 v65, v65, 0xbdd2d3e7, v129
	v_mul_f32_e32 v65, v65, v64
	v_exp_f32_e32 v63, v63
	v_exp_f32_e32 v65, v65
	v_add_f32_e32 v63, 1.0, v63
	v_rcp_f32_e32 v63, v63
	v_cvt_pk_bf16_f32 v38, v38, v39
	v_add_f32_e32 v39, 1.0, v65
	v_rcp_f32_e32 v39, v39
	v_mul_f32_e32 v62, v63, v62
	v_add_f32_e32 v40, v40, v56
	v_mul_f32_e32 v40, v62, v40
	s_waitcnt vmcnt(4)
	v_lshlrev_b32_e32 v62, 16, v54
	v_and_b32_e32 v54, 0xffff0000, v54
	v_mul_f32_e32 v39, v39, v64
	v_mul_f32_e32 v64, v54, v54
	v_mul_f32_e32 v63, v62, v62
	v_fmamk_f32 v64, v64, 0xbdd2d3e7, v129
	v_fmamk_f32 v63, v63, 0xbdd2d3e7, v129
	v_mul_f32_e32 v64, v64, v54
	v_add_f32_e32 v41, v41, v56
	v_mul_f32_e32 v63, v63, v62
	v_mul_f32_e32 v39, v39, v41
	v_cvt_pk_bf16_f32 v39, v40, v39
	v_mad_u64_u32 v[40:41], s[0:1], v78, s3, v[72:73]
	v_exp_f32_e32 v64, v64
	v_lshl_add_u64 v[40:41], v[40:41], 0, s[8:9]
	v_exp_f32_e32 v63, v63
	v_lshl_add_u64 v[40:41], v[40:41], 0, v[0:1]
	v_lshl_add_u64 v[40:41], v[40:41], 0, v[70:71]
	global_store_dwordx2 v[40:41], v[38:39], off
	v_add_f32_e32 v38, 1.0, v64
	v_add_f32_e32 v63, 1.0, v63
	v_rcp_f32_e32 v38, v38
	v_rcp_f32_e32 v63, v63
	v_add_f32_e32 v35, v35, v56
	v_add_f32_e32 v34, v34, v56
	v_mul_f32_e32 v38, v38, v54
	v_mul_f32_e32 v39, v63, v62
	v_mul_f32_e32 v35, v38, v35
	v_lshlrev_b32_e32 v38, 16, v55
	v_and_b32_e32 v54, 0xffff0000, v55
	v_mul_f32_e32 v34, v39, v34
	v_mul_f32_e32 v39, v38, v38
	v_mul_f32_e32 v55, v54, v54
	v_fmamk_f32 v39, v39, 0xbdd2d3e7, v129
	v_fmamk_f32 v55, v55, 0xbdd2d3e7, v129
	v_mul_f32_e32 v39, v39, v38
	v_mul_f32_e32 v55, v55, v54
	v_exp_f32_e32 v39, v39
	v_exp_f32_e32 v55, v55
	v_cvt_pk_bf16_f32 v34, v34, v35
	v_add_f32_e32 v36, v36, v56
	v_add_f32_e32 v39, 1.0, v39
	v_add_f32_e32 v35, 1.0, v55
	v_rcp_f32_e32 v39, v39
	v_rcp_f32_e32 v35, v35
	v_add_f32_e32 v37, v37, v56
	v_mfma_f32_16x16x32_bf16 v[2:5], v[22:25], v[50:53], v[2:5]
	v_mul_f32_e32 v38, v39, v38
	v_mul_f32_e32 v35, v35, v54
	v_mul_f32_e32 v36, v38, v36
	v_mul_f32_e32 v35, v35, v37
	v_cvt_pk_bf16_f32 v35, v36, v35
	s_waitcnt vmcnt(4)
	v_lshlrev_b32_e32 v36, 16, v58
	v_mul_f32_e32 v37, v36, v36
	v_and_b32_e32 v38, 0xffff0000, v58
	v_fmamk_f32 v37, v37, 0xbdd2d3e7, v129
	v_mul_f32_e32 v39, v38, v38
	v_mul_f32_e32 v37, v37, v36
	v_fmamk_f32 v39, v39, 0xbdd2d3e7, v129
	v_mul_f32_e32 v39, v39, v38
	v_exp_f32_e32 v37, v37
	v_exp_f32_e32 v39, v39
	global_store_dwordx2 v[40:41], v[34:35], off offset:32
	v_add_f32_e32 v37, 1.0, v37
	v_rcp_f32_e32 v37, v37
	v_add_f32_e32 v34, 1.0, v39
	v_rcp_f32_e32 v34, v34
	s_waitcnt vmcnt(3)
	v_lshlrev_b32_e32 v24, 16, v30
	v_mul_f32_e32 v35, v37, v36
	v_add_f32_e32 v36, v46, v56
	v_mul_f32_e32 v35, v35, v36
	v_mul_f32_e32 v34, v34, v38
	v_add_f32_e32 v36, v47, v56
	v_mul_f32_e32 v34, v34, v36
	v_lshlrev_b32_e32 v36, 16, v59
	v_mul_f32_e32 v37, v36, v36
	v_and_b32_e32 v38, 0xffff0000, v59
	v_fmamk_f32 v37, v37, 0xbdd2d3e7, v129
	v_mul_f32_e32 v39, v38, v38
	v_mul_f32_e32 v37, v37, v36
	v_fmamk_f32 v39, v39, 0xbdd2d3e7, v129
	v_mul_f32_e32 v39, v39, v38
	v_exp_f32_e32 v37, v37
	v_exp_f32_e32 v39, v39
	v_cvt_pk_bf16_f32 v34, v35, v34
	v_add_f32_e32 v37, 1.0, v37
	v_rcp_f32_e32 v37, v37
	v_add_f32_e32 v35, 1.0, v39
	v_rcp_f32_e32 v35, v35
	v_mul_f32_e32 v25, 0x3d372713, v24
	v_mul_f32_e32 v36, v37, v36
	v_add_f32_e32 v37, v48, v56
	v_mul_f32_e32 v36, v36, v37
	v_mul_f32_e32 v35, v35, v38
	v_add_f32_e32 v37, v49, v56
	v_mul_f32_e32 v35, v35, v37
	v_cvt_pk_bf16_f32 v35, v36, v35
	v_lshlrev_b32_e32 v36, 16, v60
	v_mul_f32_e32 v37, v36, v36
	v_and_b32_e32 v38, 0xffff0000, v60
	v_fmamk_f32 v37, v37, 0xbdd2d3e7, v129
	v_mul_f32_e32 v39, v38, v38
	v_mul_f32_e32 v37, v37, v36
	v_fmamk_f32 v39, v39, 0xbdd2d3e7, v129
	v_mul_f32_e32 v39, v39, v38
	v_exp_f32_e32 v37, v37
	v_exp_f32_e32 v39, v39
	global_store_dwordx2 v[40:41], v[34:35], off offset:64
	v_add_f32_e32 v37, 1.0, v37
	v_rcp_f32_e32 v37, v37
	v_add_f32_e32 v34, 1.0, v39
	v_rcp_f32_e32 v34, v34
	v_and_b32_e32 v30, 0xffff0000, v30
	v_mul_f32_e32 v35, v37, v36
	v_add_f32_e32 v36, v42, v56
	v_mul_f32_e32 v35, v35, v36
	v_mul_f32_e32 v34, v34, v38
	v_add_f32_e32 v36, v43, v56
	v_mul_f32_e32 v34, v34, v36
	v_lshlrev_b32_e32 v36, 16, v61
	v_mul_f32_e32 v37, v36, v36
	v_and_b32_e32 v38, 0xffff0000, v61
	v_fmamk_f32 v37, v37, 0xbdd2d3e7, v129
	v_mul_f32_e32 v39, v38, v38
	v_mul_f32_e32 v37, v37, v36
	v_fmamk_f32 v39, v39, 0xbdd2d3e7, v129
	v_mul_f32_e32 v39, v39, v38
	v_exp_f32_e32 v37, v37
	v_exp_f32_e32 v39, v39
	v_cvt_pk_bf16_f32 v34, v35, v34
	v_add_f32_e32 v37, 1.0, v37
	v_rcp_f32_e32 v37, v37
	v_add_f32_e32 v35, 1.0, v39
	v_rcp_f32_e32 v35, v35
	v_mul_f32_e32 v25, v25, v24
	v_mul_f32_e32 v36, v37, v36
	v_add_f32_e32 v37, v44, v56
	v_mul_f32_e32 v36, v36, v37
	v_mul_f32_e32 v35, v35, v38
	v_add_f32_e32 v37, v45, v56
	v_mul_f32_e32 v35, v35, v37
	v_cvt_pk_bf16_f32 v35, v36, v35
	global_store_dwordx2 v[40:41], v[34:35], off offset:96
	global_load_dword v34, v81, s[12:13] offset:192
	s_nop 0
	global_load_dwordx2 v[20:21], v[32:33], off offset:64
	global_load_dwordx2 v[22:23], v[32:33], off offset:96
	v_mul_f32_e32 v32, v30, v30
	v_fma_f32 v25, v25, v24, v24
	v_fmamk_f32 v32, v32, 0xbdd2d3e7, v129
	v_mul_f32_e32 v25, 0xbfcc422a, v25
	v_mul_f32_e32 v32, v32, v30
	v_mul_f32_e32 v25, 0x3fb8aa3b, v25
	v_exp_f32_e32 v25, v25
	v_exp_f32_e32 v32, v32
	v_mfma_f32_16x16x32_bf16 v[10:13], v[14:17], v[50:53], v[10:13]
	v_add_f32_e32 v25, 1.0, v25
	v_rcp_f32_e32 v25, v25
	v_add_f32_e32 v14, 1.0, v32
	v_rcp_f32_e32 v14, v14
	v_mul_f32_e32 v15, v25, v24
	v_and_b32_e32 v24, 0xffff0000, v31
	v_mul_f32_e32 v14, v14, v30
	v_mul_f32_e32 v25, v24, v24
	v_fmamk_f32 v25, v25, 0xbdd2d3e7, v129
	v_mul_f32_e32 v25, v25, v24
	v_exp_f32_e32 v25, v25
	s_waitcnt vmcnt(2)
	v_add_f32_e32 v16, v26, v34
	v_mul_f32_e32 v15, v15, v16
	v_add_f32_e32 v16, v27, v34
	v_mul_f32_e32 v14, v14, v16
	v_lshlrev_b32_e32 v16, 16, v31
	v_mul_f32_e32 v17, v16, v16
	v_fmamk_f32 v17, v17, 0xbdd2d3e7, v129
	v_mul_f32_e32 v17, v17, v16
	v_exp_f32_e32 v17, v17
	v_cvt_pk_bf16_f32 v14, v15, v14
	v_add_f32_e32 v15, 1.0, v25
	v_rcp_f32_e32 v15, v15
	v_add_f32_e32 v17, 1.0, v17
	v_rcp_f32_e32 v17, v17
	v_add_f32_e32 v6, v6, v34
	v_mul_f32_e32 v15, v15, v24
	v_add_f32_e32 v7, v7, v34
	v_mul_f32_e32 v16, v17, v16
	v_add_f32_e32 v17, v28, v34
	v_mul_f32_e32 v16, v16, v17
	v_add_f32_e32 v17, v29, v34
	v_mul_f32_e32 v15, v15, v17
	v_cvt_pk_bf16_f32 v15, v16, v15
	v_mad_u64_u32 v[16:17], s[0:1], v57, s3, v[72:73]
	v_lshl_add_u64 v[16:17], v[16:17], 0, s[8:9]
	v_lshl_add_u64 v[16:17], v[16:17], 0, v[0:1]
	v_lshlrev_b32_e32 v0, 16, v18
	v_mul_f32_e32 v24, v0, v0
	v_and_b32_e32 v18, 0xffff0000, v18
	v_fmamk_f32 v24, v24, 0xbdd2d3e7, v129
	v_mul_f32_e32 v25, v18, v18
	v_mul_f32_e32 v24, v24, v0
	v_fmamk_f32 v25, v25, 0xbdd2d3e7, v129
	v_mul_f32_e32 v25, v25, v18
	v_exp_f32_e32 v24, v24
	v_exp_f32_e32 v25, v25
	v_lshl_add_u64 v[16:17], v[16:17], 0, v[70:71]
	v_add_f32_e32 v24, 1.0, v24
	v_rcp_f32_e32 v24, v24
	global_store_dwordx2 v[16:17], v[14:15], off
	v_add_f32_e32 v14, 1.0, v25
	v_rcp_f32_e32 v14, v14
	v_mul_f32_e32 v0, v24, v0
	v_mul_f32_e32 v0, v0, v6
	v_and_b32_e32 v15, 0xffff0000, v19
	v_mul_f32_e32 v6, v14, v18
	v_mul_f32_e32 v6, v6, v7
	v_lshlrev_b32_e32 v7, 16, v19
	v_mul_f32_e32 v14, v7, v7
	v_fmamk_f32 v14, v14, 0xbdd2d3e7, v129
	v_mul_f32_e32 v18, v15, v15
	v_mul_f32_e32 v14, v14, v7
	v_fmamk_f32 v18, v18, 0xbdd2d3e7, v129
	v_mul_f32_e32 v18, v18, v15
	v_exp_f32_e32 v14, v14
	v_exp_f32_e32 v18, v18
	v_cvt_pk_bf16_f32 v6, v0, v6
	v_add_f32_e32 v14, 1.0, v14
	v_rcp_f32_e32 v14, v14
	v_add_f32_e32 v0, 1.0, v18
	v_rcp_f32_e32 v0, v0
	v_add_f32_e32 v8, v8, v34
	v_mul_f32_e32 v7, v14, v7
	v_mul_f32_e32 v7, v7, v8
	v_mul_f32_e32 v0, v0, v15
	v_add_f32_e32 v8, v9, v34
	v_mul_f32_e32 v0, v0, v8
	v_cvt_pk_bf16_f32 v7, v7, v0
	s_waitcnt vmcnt(2)
	v_lshlrev_b32_e32 v0, 16, v20
	v_mul_f32_e32 v8, v0, v0
	v_and_b32_e32 v9, 0xffff0000, v20
	v_fmamk_f32 v8, v8, 0xbdd2d3e7, v129
	v_mul_f32_e32 v14, v9, v9
	v_mul_f32_e32 v8, v8, v0
	v_fmamk_f32 v14, v14, 0xbdd2d3e7, v129
	v_mul_f32_e32 v14, v14, v9
	v_exp_f32_e32 v8, v8
	v_exp_f32_e32 v14, v14
	global_store_dwordx2 v[16:17], v[6:7], off offset:32
	v_add_f32_e32 v8, 1.0, v8
	v_rcp_f32_e32 v8, v8
	v_add_f32_e32 v6, 1.0, v14
	v_rcp_f32_e32 v6, v6
	v_add_f32_e32 v2, v2, v34
	v_mul_f32_e32 v0, v8, v0
	v_mul_f32_e32 v0, v0, v2
	v_mul_f32_e32 v2, v6, v9
	v_add_f32_e32 v3, v3, v34
	v_mul_f32_e32 v2, v2, v3
	v_lshlrev_b32_e32 v3, 16, v21
	v_mul_f32_e32 v6, v3, v3
	v_and_b32_e32 v7, 0xffff0000, v21
	v_fmamk_f32 v6, v6, 0xbdd2d3e7, v129
	v_mul_f32_e32 v8, v7, v7
	v_mul_f32_e32 v6, v6, v3
	v_fmamk_f32 v8, v8, 0xbdd2d3e7, v129
	v_mul_f32_e32 v8, v8, v7
	v_exp_f32_e32 v6, v6
	v_exp_f32_e32 v8, v8
	v_cvt_pk_bf16_f32 v2, v0, v2
	v_add_f32_e32 v6, 1.0, v6
	v_rcp_f32_e32 v6, v6
	v_add_f32_e32 v0, 1.0, v8
	v_rcp_f32_e32 v0, v0
	v_add_f32_e32 v4, v4, v34
	v_mul_f32_e32 v3, v6, v3
	v_mul_f32_e32 v3, v3, v4
	v_mul_f32_e32 v0, v0, v7
	v_add_f32_e32 v4, v5, v34
	v_mul_f32_e32 v0, v0, v4
	v_cvt_pk_bf16_f32 v3, v3, v0
	s_waitcnt vmcnt(2)
	v_lshlrev_b32_e32 v0, 16, v22
	v_mul_f32_e32 v4, v0, v0
	v_and_b32_e32 v5, 0xffff0000, v22
	v_fmamk_f32 v4, v4, 0xbdd2d3e7, v129
	v_mul_f32_e32 v6, v5, v5
	v_mul_f32_e32 v4, v4, v0
	v_fmamk_f32 v6, v6, 0xbdd2d3e7, v129
	v_mul_f32_e32 v6, v6, v5
	v_exp_f32_e32 v4, v4
	v_exp_f32_e32 v6, v6
	global_store_dwordx2 v[16:17], v[2:3], off offset:64
	v_add_f32_e32 v4, 1.0, v4
	v_rcp_f32_e32 v4, v4
	v_add_f32_e32 v2, 1.0, v6
	v_rcp_f32_e32 v2, v2
	v_add_f32_e32 v3, v10, v34
	v_mul_f32_e32 v0, v4, v0
	v_mul_f32_e32 v0, v0, v3
	v_mul_f32_e32 v2, v2, v5
	v_add_f32_e32 v3, v11, v34
	v_mul_f32_e32 v2, v2, v3
	v_lshlrev_b32_e32 v3, 16, v23
	v_mul_f32_e32 v4, v3, v3
	v_and_b32_e32 v5, 0xffff0000, v23
	v_fmamk_f32 v4, v4, 0xbdd2d3e7, v129
	v_mul_f32_e32 v6, v5, v5
	v_mul_f32_e32 v4, v4, v3
	v_fmamk_f32 v6, v6, 0xbdd2d3e7, v129
	v_mul_f32_e32 v6, v6, v5
	v_exp_f32_e32 v4, v4
	v_exp_f32_e32 v6, v6
	v_cvt_pk_bf16_f32 v2, v0, v2
	v_add_f32_e32 v4, 1.0, v4
	v_rcp_f32_e32 v4, v4
	v_add_f32_e32 v0, 1.0, v6
	v_rcp_f32_e32 v0, v0
	v_mul_f32_e32 v3, v4, v3
	v_add_f32_e32 v4, v12, v34
	v_mul_f32_e32 v3, v3, v4
	v_mul_f32_e32 v0, v0, v5
	v_add_f32_e32 v4, v13, v34
	v_mul_f32_e32 v0, v0, v4
	v_cvt_pk_bf16_f32 v3, v3, v0
	global_store_dwordx2 v[16:17], v[2:3], off offset:96
	s_barrier
	s_cbranch_scc0 .LBB0_626
	s_and_b32 s0, s10, 3
	s_lshl_b32 s1, s10, 5
	v_mov_b32_e32 v38, v194
	v_cvt_f32_ubyte0_e32 v0, s0
	s_and_b32 s1, s1, 0x7fffff80
	v_sub_f32_e32 v37, 0xc0a00000, v0
	v_bfe_u32 v36, v38, 1, 7
	s_mov_b32 s2, 0xc2fc0000
	v_cmp_gt_f32_e32 vcc, s2, v37
	v_or_b32_e32 v0, s1, v36
	v_mov_b64_e32 v[2:3], s[50:51]
	s_and_b64 s[4:5], vcc, exec
	v_mad_u64_u32 v[34:35], s[4:5], v0, s3, v[2:3]
	v_and_b32_e32 v40, 1, v38
	s_cselect_b32 s2, 0xffffffc0, 0
	s_lshl_b32 s4, s0, 8
	s_mov_b32 s5, s89
	v_lshl_add_u64 v[2:3], v[34:35], 0, s[4:5]
	v_lshlrev_b32_e32 v4, 7, v40
	v_mov_b32_e32 v5, v1
	v_lshl_add_u64 v[2:3], v[2:3], 0, v[4:5]
	global_load_dwordx4 v[30:33], v[2:3], off offset:3072
	global_load_dwordx4 v[26:29], v[2:3], off offset:3088
	global_load_dwordx4 v[22:25], v[2:3], off offset:3104
	global_load_dwordx4 v[18:21], v[2:3], off offset:3120
	global_load_dwordx4 v[14:17], v[2:3], off offset:3136
	global_load_dwordx4 v[10:13], v[2:3], off offset:3152
	global_load_dwordx4 v[6:9], v[2:3], off offset:3168
	s_nop 0
	global_load_dwordx4 v[2:5], v[2:3], off offset:3184
	s_mov_b32 s1, s89
	s_lshl_b32 s0, s0, 7
	v_lshlrev_b32_e32 v0, 6, v40
	v_mul_u32_u24_e32 v41, 0x2200, v40
	v_cndmask_b32_e32 v42, 0, v248, vcc
	v_lshl_add_u64 v[34:35], v[34:35], 0, s[0:1]
	v_lshlrev_b32_e32 v36, 1, v36
	v_lshlrev_b32_e32 v41, 1, v41
	v_add_f32_e32 v37, v37, v42
	v_lshl_add_u64 v[42:43], v[34:35], 0, v[0:1]
	v_add3_u32 v44, s15, v41, v36
	v_add3_u32 v41, s15, v36, v41
	v_exp_f32_e32 v45, v37
	global_load_dwordx4 v[34:37], v[42:43], off offset:2560
	v_lshrrev_b32_e32 v39, 1, v38
	v_and_b32_e32 v55, 0x60, v39
	v_ldexp_f32 v0, v45, s2
	v_sub_f32_e32 v0, 1.0, v0
	v_cmp_gt_f32_e32 vcc, s11, v0
	s_and_b64 s[0:1], vcc, exec
	s_cselect_b32 s0, 32, 0
	v_ldexp_f32 v0, v0, s0
	v_log_f32_e32 v0, v0
	s_mov_b32 s0, 0x3f317217
	v_bfe_u32 v54, v38, 4, 2
	s_mov_b32 s11, s89
	s_mul_i32 s2, s10, 3
	s_movk_i32 s39, 0xd80
	s_mov_b32 s69, 0x800000
	s_waitcnt vmcnt(8)
	ds_write_b16 v44, v30
	ds_write_b16_d16_hi v41, v30 offset:272
	ds_write_b16 v44, v31 offset:544
	ds_write_b16_d16_hi v41, v31 offset:816
	ds_write_b16 v44, v32 offset:1088
	ds_write_b16_d16_hi v41, v32 offset:1360
	ds_write_b16 v44, v33 offset:1632
	ds_write_b16_d16_hi v41, v33 offset:1904
	s_waitcnt vmcnt(7)
	ds_write_b16 v44, v26 offset:2176
	ds_write_b16_d16_hi v41, v26 offset:2448
	ds_write_b16 v44, v27 offset:2720
	ds_write_b16_d16_hi v41, v27 offset:2992
	ds_write_b16 v44, v28 offset:3264
	ds_write_b16_d16_hi v41, v28 offset:3536
	ds_write_b16 v44, v29 offset:3808
	ds_write_b16_d16_hi v41, v29 offset:4080
	s_waitcnt vmcnt(6)
	ds_write_b16 v44, v22 offset:4352
	ds_write_b16_d16_hi v41, v22 offset:4624
	ds_write_b16 v44, v23 offset:4896
	ds_write_b16_d16_hi v41, v23 offset:5168
	ds_write_b16 v44, v24 offset:5440
	ds_write_b16_d16_hi v41, v24 offset:5712
	ds_write_b16 v44, v25 offset:5984
	ds_write_b16_d16_hi v41, v25 offset:6256
	s_waitcnt vmcnt(5)
	ds_write_b16 v44, v18 offset:6528
	ds_write_b16_d16_hi v41, v18 offset:6800
	ds_write_b16 v44, v19 offset:7072
	ds_write_b16_d16_hi v41, v19 offset:7344
	ds_write_b16 v44, v20 offset:7616
	ds_write_b16_d16_hi v41, v20 offset:7888
	ds_write_b16 v44, v21 offset:8160
	ds_write_b16_d16_hi v41, v21 offset:8432
	s_waitcnt vmcnt(4)
	ds_write_b16 v44, v14 offset:8704
	ds_write_b16_d16_hi v41, v14 offset:8976
	ds_write_b16 v44, v15 offset:9248
	ds_write_b16_d16_hi v41, v15 offset:9520
	ds_write_b16 v44, v16 offset:9792
	ds_write_b16_d16_hi v41, v16 offset:10064
	ds_write_b16 v44, v17 offset:10336
	ds_write_b16_d16_hi v41, v17 offset:10608
	s_waitcnt vmcnt(3)
	ds_write_b16 v44, v10 offset:10880
	ds_write_b16_d16_hi v41, v10 offset:11152
	ds_write_b16 v44, v11 offset:11424
	ds_write_b16_d16_hi v41, v11 offset:11696
	ds_write_b16 v44, v12 offset:11968
	ds_write_b16_d16_hi v41, v12 offset:12240
	ds_write_b16 v44, v13 offset:12512
	ds_write_b16_d16_hi v41, v13 offset:12784
	s_waitcnt vmcnt(2)
	ds_write_b16 v44, v6 offset:13056
	ds_write_b16_d16_hi v41, v6 offset:13328
	ds_write_b16 v44, v7 offset:13600
	ds_write_b16_d16_hi v41, v7 offset:13872
	global_load_dwordx4 v[10:13], v[42:43], off offset:2576
	ds_write_b16 v44, v8 offset:14144
	ds_write_b16_d16_hi v41, v8 offset:14416
	ds_write_b16 v44, v9 offset:14688
	ds_write_b16_d16_hi v41, v9 offset:14960
	s_waitcnt vmcnt(2)
	ds_write_b16 v44, v2 offset:15232
	ds_write_b16_d16_hi v41, v2 offset:15504
	ds_write_b16 v44, v3 offset:15776
	ds_write_b16_d16_hi v41, v3 offset:16048
	ds_write_b16 v44, v4 offset:16320
	ds_write_b16_d16_hi v41, v4 offset:16592
	global_load_dwordx4 v[6:9], v[42:43], off offset:2592
	v_mul_f32_e32 v2, 0x3f317217, v0
	v_fma_f32 v2, v0, s0, -v2
	v_fmac_f32_e32 v2, 0x3377d1cf, v0
	s_mov_b32 s0, 0x7f800000
	v_fmac_f32_e32 v2, 0x3f317217, v0
	v_cmp_lt_f32_e64 s[0:1], |v0|, s0
	ds_write_b16 v44, v5 offset:16864
	ds_write_b16_d16_hi v41, v5 offset:17136
	v_cndmask_b32_e64 v0, v0, v2, s[0:1]
	v_cndmask_b32_e32 v2, 0, v231, vcc
	s_movk_i32 s0, 0x7f
	v_sub_f32_e32 v0, v0, v2
	v_bitop3_b32 v2, v39, s0, v39 bitop3:0xc
	v_cvt_f32_ubyte0_e32 v2, v2
	v_mul_f32_e32 v2, v0, v2
	v_mul_f32_e32 v0, 0x3fb8aa3b, v2
	s_mov_b32 s0, 0x3fb8aa3b
	v_fma_f32 v3, v2, s0, -v0
	v_rndne_f32_e32 v4, v0
	v_fmac_f32_e32 v3, 0x32a5705f, v2
	v_sub_f32_e32 v0, v0, v4
	v_add_f32_e32 v0, v0, v3
	v_exp_f32_e32 v3, v0
	v_cvt_i32_f32_e32 v4, v4
	s_mov_b32 s0, 0xc2ce8ed0
	v_cmp_ngt_f32_e32 vcc, s0, v2
	s_mov_b32 s0, 0x42b17218
	v_ldexp_f32 v3, v3, v4
	v_cndmask_b32_e32 v3, 0, v3, vcc
	v_cmp_nlt_f32_e32 vcc, s0, v2
	s_waitcnt vmcnt(2)
	v_lshlrev_b32_e32 v15, 16, v34
	v_and_b32_e32 v0, 15, v38
	v_cndmask_b32_e32 v2, v195, v3, vcc
	v_mul_f32_e32 v14, 0x3e000000, v2
	global_load_dwordx4 v[2:5], v[42:43], off offset:2608
	v_mul_f32_e32 v15, v14, v15
	v_cvt_pk_bf16_f32 v15, v15, s0
	s_movk_i32 s0, 0xde00
	v_mad_i32_i24 v16, v40, s0, v44
	ds_write_b16 v16, v15 offset:34816
	v_and_b32_e32 v15, 0xffff0000, v34
	v_mul_f32_e32 v15, v14, v15
	v_cvt_pk_bf16_f32 v15, v15, s0
	v_mad_i32_i24 v17, v40, s0, v41
	ds_write_b16 v17, v15 offset:35088
	v_lshlrev_b32_e32 v15, 16, v35
	v_mul_f32_e32 v15, v14, v15
	v_cvt_pk_bf16_f32 v15, v15, s0
	ds_write_b16 v16, v15 offset:35360
	v_and_b32_e32 v15, 0xffff0000, v35
	v_mul_f32_e32 v15, v14, v15
	v_cvt_pk_bf16_f32 v15, v15, s0
	ds_write_b16 v17, v15 offset:35632
	v_lshlrev_b32_e32 v15, 16, v36
	v_mul_f32_e32 v15, v14, v15
	v_cvt_pk_bf16_f32 v15, v15, s0
	ds_write_b16 v16, v15 offset:35904
	v_and_b32_e32 v15, 0xffff0000, v36
	v_mul_f32_e32 v15, v14, v15
	v_cvt_pk_bf16_f32 v15, v15, s0
	ds_write_b16 v17, v15 offset:36176
	v_lshlrev_b32_e32 v15, 16, v37
	v_mul_f32_e32 v15, v14, v15
	v_cvt_pk_bf16_f32 v15, v15, s0
	ds_write_b16 v16, v15 offset:36448
	v_and_b32_e32 v15, 0xffff0000, v37
	v_mul_f32_e32 v15, v14, v15
	v_cvt_pk_bf16_f32 v15, v15, s0
	ds_write_b16 v17, v15 offset:36720
	s_waitcnt vmcnt(2)
	v_lshlrev_b32_e32 v15, 16, v10
	v_and_b32_e32 v10, 0xffff0000, v10
	v_mul_f32_e32 v10, v14, v10
	v_cvt_pk_bf16_f32 v10, v10, s0
	ds_write_b16 v17, v10 offset:37264
	v_lshlrev_b32_e32 v10, 16, v11
	v_mul_f32_e32 v10, v14, v10
	v_cvt_pk_bf16_f32 v10, v10, s0
	ds_write_b16 v16, v10 offset:37536
	v_and_b32_e32 v10, 0xffff0000, v11
	v_mul_f32_e32 v10, v14, v10
	v_cvt_pk_bf16_f32 v10, v10, s0
	ds_write_b16 v17, v10 offset:37808
	v_lshlrev_b32_e32 v10, 16, v12
	v_mul_f32_e32 v10, v14, v10
	v_cvt_pk_bf16_f32 v10, v10, s0
	ds_write_b16 v16, v10 offset:38080
	v_and_b32_e32 v10, 0xffff0000, v12
	v_mul_f32_e32 v10, v14, v10
	v_cvt_pk_bf16_f32 v10, v10, s0
	ds_write_b16 v17, v10 offset:38352
	v_lshlrev_b32_e32 v10, 16, v13
	v_mul_f32_e32 v10, v14, v10
	v_cvt_pk_bf16_f32 v10, v10, s0
	ds_write_b16 v16, v10 offset:38624
	v_and_b32_e32 v10, 0xffff0000, v13
	v_mul_f32_e32 v10, v14, v10
	v_cvt_pk_bf16_f32 v10, v10, s0
	ds_write_b16 v17, v10 offset:38896
	s_waitcnt vmcnt(1)
	v_lshlrev_b32_e32 v10, 16, v6
	v_and_b32_e32 v6, 0xffff0000, v6
	v_mul_f32_e32 v6, v14, v6
	v_cvt_pk_bf16_f32 v6, v6, s0
	ds_write_b16 v17, v6 offset:39440
	v_lshlrev_b32_e32 v6, 16, v7
	v_mul_f32_e32 v6, v14, v6
	v_cvt_pk_bf16_f32 v6, v6, s0
	ds_write_b16 v16, v6 offset:39712
	v_and_b32_e32 v6, 0xffff0000, v7
	v_mul_f32_e32 v6, v14, v6
	v_cvt_pk_bf16_f32 v6, v6, s0
	ds_write_b16 v17, v6 offset:39984
	v_lshlrev_b32_e32 v6, 16, v8
	v_mul_f32_e32 v6, v14, v6
	v_cvt_pk_bf16_f32 v6, v6, s0
	ds_write_b16 v16, v6 offset:40256
	v_and_b32_e32 v6, 0xffff0000, v8
	v_mul_f32_e32 v6, v14, v6
	v_cvt_pk_bf16_f32 v6, v6, s0
	ds_write_b16 v17, v6 offset:40528
	v_lshlrev_b32_e32 v6, 16, v9
	v_mul_f32_e32 v6, v14, v6
	v_cvt_pk_bf16_f32 v6, v6, s0
	ds_write_b16 v16, v6 offset:40800
	v_and_b32_e32 v6, 0xffff0000, v9
	v_mul_f32_e32 v6, v14, v6
	v_cvt_pk_bf16_f32 v6, v6, s0
	ds_write_b16 v17, v6 offset:41072
	s_waitcnt vmcnt(0)
	v_lshlrev_b32_e32 v6, 16, v2
	v_and_b32_e32 v2, 0xffff0000, v2
	v_mul_f32_e32 v2, v14, v2
	v_cvt_pk_bf16_f32 v2, v2, s0
	ds_write_b16 v17, v2 offset:41616
	v_lshlrev_b32_e32 v2, 16, v3
	v_mul_f32_e32 v2, v14, v2
	v_cvt_pk_bf16_f32 v2, v2, s0
	ds_write_b16 v16, v2 offset:41888
	v_and_b32_e32 v2, 0xffff0000, v3
	v_mul_f32_e32 v2, v14, v2
	v_cvt_pk_bf16_f32 v2, v2, s0
	ds_write_b16 v17, v2 offset:42160
	v_lshlrev_b32_e32 v2, 16, v4
	v_mul_f32_e32 v2, v14, v2
	v_cvt_pk_bf16_f32 v2, v2, s0
	ds_write_b16 v16, v2 offset:42432
	v_and_b32_e32 v2, 0xffff0000, v4
	v_mul_f32_e32 v2, v14, v2
	v_cvt_pk_bf16_f32 v2, v2, s0
	ds_write_b16 v17, v2 offset:42704
	v_lshlrev_b32_e32 v2, 16, v5
	v_mul_f32_e32 v2, v14, v2
	v_cvt_pk_bf16_f32 v2, v2, s0
	ds_write_b16 v16, v2 offset:42976
	v_and_b32_e32 v2, 0xffff0000, v5
	v_mul_f32_e32 v2, v14, v2
	v_mul_f32_e32 v6, v14, v6
	v_cvt_pk_bf16_f32 v2, v2, s0
	v_cvt_pk_bf16_f32 v6, v6, s0
	ds_write_b16 v17, v2 offset:43248
	v_or_b32_e32 v2, v55, v0
	v_mul_f32_e32 v15, v14, v15
	v_mul_f32_e32 v10, v14, v10
	ds_write_b16 v16, v6 offset:41344
	v_lshl_add_u32 v6, v54, 4, s15
	v_mul_u32_u24_e32 v2, 0x88, v2
	v_mul_u32_u24_e32 v7, 0x88, v0
	v_cvt_pk_bf16_f32 v15, v15, s0
	v_cvt_pk_bf16_f32 v10, v10, s0
	v_lshl_add_u32 v56, v2, 1, v6
	v_lshl_add_u32 v57, v7, 1, v6
	ds_write_b16 v16, v15 offset:36992
	ds_write_b16 v16, v10 offset:39168
	s_waitcnt lgkmcnt(0)
	s_barrier
	ds_read_b128 v[2:5], v56
	ds_read_b128 v[38:41], v56 offset:64
	ds_read_b128 v[6:9], v57 offset:34816
	ds_read_b128 v[34:37], v56 offset:4352
	ds_read_b128 v[14:17], v57 offset:39168
	ds_read_b128 v[22:25], v57 offset:43520
	ds_read_b128 v[30:33], v57 offset:47872
	ds_read_b128 v[46:49], v57 offset:43584
	s_waitcnt lgkmcnt(5)
	v_mfma_f32_16x16x32_bf16 v[10:13], v[2:5], v[6:9], 0
	ds_read_b128 v[42:45], v57 offset:39232
	ds_read_b128 v[50:53], v57 offset:47936
	s_lshl_b64 s[0:1], s[10:11], 15
	s_waitcnt lgkmcnt(5)
	v_mfma_f32_16x16x32_bf16 v[18:21], v[2:5], v[14:17], 0
	s_add_u32 s0, s24, s0
	s_addc_u32 s1, s25, s1
	s_add_i32 s9, s2, 0xfffffd80
	s_waitcnt lgkmcnt(4)
	v_mfma_f32_16x16x32_bf16 v[26:29], v[2:5], v[22:25], 0
	s_waitcnt lgkmcnt(3)
	v_mfma_f32_16x16x32_bf16 v[2:5], v[2:5], v[30:33], 0
	v_mfma_f32_16x16x32_bf16 v[6:9], v[34:37], v[6:9], 0
	v_mfma_f32_16x16x32_bf16 v[14:17], v[34:37], v[14:17], 0
	v_mfma_f32_16x16x32_bf16 v[22:25], v[34:37], v[22:25], 0
	v_mfma_f32_16x16x32_bf16 v[30:33], v[34:37], v[30:33], 0
	ds_read_b128 v[34:37], v57 offset:34880
	s_waitcnt lgkmcnt(0)
	v_mfma_f32_16x16x32_bf16 v[10:13], v[38:41], v[34:37], v[10:13]
	v_mfma_f32_16x16x32_bf16 v[18:21], v[38:41], v[42:45], v[18:21]
	v_mfma_f32_16x16x32_bf16 v[26:29], v[38:41], v[46:49], v[26:29]
	v_mfma_f32_16x16x32_bf16 v[2:5], v[38:41], v[50:53], v[2:5]
	ds_read_b128 v[38:41], v56 offset:4416
	s_waitcnt lgkmcnt(0)
	v_mfma_f32_16x16x32_bf16 v[6:9], v[38:41], v[34:37], v[6:9]
	ds_read_b128 v[34:37], v56 offset:128
	v_mfma_f32_16x16x32_bf16 v[14:17], v[38:41], v[42:45], v[14:17]
	ds_read_b128 v[42:45], v57 offset:39296
	v_mfma_f32_16x16x32_bf16 v[22:25], v[38:41], v[46:49], v[22:25]
	ds_read_b128 v[46:49], v57 offset:43648
	v_mfma_f32_16x16x32_bf16 v[30:33], v[38:41], v[50:53], v[30:33]
	ds_read_b128 v[38:41], v57 offset:34944
	ds_read_b128 v[50:53], v57 offset:48000
	s_waitcnt lgkmcnt(1)
	v_mfma_f32_16x16x32_bf16 v[10:13], v[34:37], v[38:41], v[10:13]
	v_mfma_f32_16x16x32_bf16 v[18:21], v[34:37], v[42:45], v[18:21]
	v_mfma_f32_16x16x32_bf16 v[26:29], v[34:37], v[46:49], v[26:29]
	s_waitcnt lgkmcnt(0)
	v_mfma_f32_16x16x32_bf16 v[2:5], v[34:37], v[50:53], v[2:5]
	ds_read_b128 v[34:37], v56 offset:4480
	s_waitcnt lgkmcnt(0)
	v_mfma_f32_16x16x32_bf16 v[6:9], v[34:37], v[38:41], v[6:9]
	ds_read_b128 v[38:41], v56 offset:192
	v_mfma_f32_16x16x32_bf16 v[14:17], v[34:37], v[42:45], v[14:17]
	ds_read_b128 v[42:45], v57 offset:39360
	v_mfma_f32_16x16x32_bf16 v[22:25], v[34:37], v[46:49], v[22:25]
	ds_read_b128 v[46:49], v57 offset:43712
	v_mfma_f32_16x16x32_bf16 v[30:33], v[34:37], v[50:53], v[30:33]
	ds_read_b128 v[34:37], v57 offset:35008
	ds_read_b128 v[50:53], v57 offset:48064
	s_waitcnt lgkmcnt(1)
	v_mfma_f32_16x16x32_bf16 v[10:13], v[38:41], v[34:37], v[10:13]
	v_mfma_f32_16x16x32_bf16 v[18:21], v[38:41], v[42:45], v[18:21]
	v_mfma_f32_16x16x32_bf16 v[26:29], v[38:41], v[46:49], v[26:29]
	s_waitcnt lgkmcnt(0)
	v_mfma_f32_16x16x32_bf16 v[2:5], v[38:41], v[50:53], v[2:5]
	ds_read_b128 v[38:41], v56 offset:4544
	s_waitcnt lgkmcnt(0)
	v_mfma_f32_16x16x32_bf16 v[6:9], v[38:41], v[34:37], v[6:9]
	v_lshlrev_b32_e32 v37, 6, v55
	v_lshl_or_b32 v37, v54, 8, v37
	v_or_b32_e32 v34, 16, v0
	v_mfma_f32_16x16x32_bf16 v[14:17], v[38:41], v[42:45], v[14:17]
	v_or_b32_e32 v35, 32, v0
	v_or_b32_e32 v36, 48, v0
	v_mfma_f32_16x16x32_bf16 v[22:25], v[38:41], v[46:49], v[22:25]
	v_mfma_f32_16x16x32_bf16 v[30:33], v[38:41], v[50:53], v[30:33]
	v_or_b32_e32 v38, v37, v0
	v_lshlrev_b32_e32 v38, 2, v38
	global_store_dword v38, v10, s[0:1]
	global_store_dword v38, v11, s[0:1] offset:256
	global_store_dword v38, v12, s[0:1] offset:512
	global_store_dword v38, v13, s[0:1] offset:768
	global_store_dword v38, v18, s[0:1] offset:64
	v_or_b32_e32 v10, v37, v34
	v_lshlrev_b32_e32 v10, 2, v10
	global_store_dword v10, v19, s[0:1] offset:256
	global_store_dword v10, v20, s[0:1] offset:512
	global_store_dword v10, v21, s[0:1] offset:768
	global_store_dword v38, v26, s[0:1] offset:128
	v_or_b32_e32 v10, v37, v35
	v_lshlrev_b32_e32 v10, 2, v10
	global_store_dword v10, v27, s[0:1] offset:256
	global_store_dword v10, v28, s[0:1] offset:512
	global_store_dword v10, v29, s[0:1] offset:768
	global_store_dword v38, v2, s[0:1] offset:192
	v_or_b32_e32 v2, v37, v36
	v_lshlrev_b32_e32 v2, 2, v2
	global_store_dword v2, v3, s[0:1] offset:256
	global_store_dword v2, v4, s[0:1] offset:512
	global_store_dword v2, v5, s[0:1] offset:768
	v_or_b32_e32 v2, 0x400, v37
	v_or_b32_e32 v3, v2, v0
	v_lshlrev_b32_e32 v3, 2, v3
	global_store_dword v3, v6, s[0:1]
	v_or_b32_e32 v3, 0x440, v37
	v_or_b32_e32 v4, v3, v0
	v_lshlrev_b32_e32 v4, 2, v4
	global_store_dword v4, v7, s[0:1]
	v_or_b32_e32 v4, 0x480, v37
	v_or_b32_e32 v5, v4, v0
	v_lshlrev_b32_e32 v5, 2, v5
	global_store_dword v5, v8, s[0:1]
	v_or_b32_e32 v5, 0x4c0, v37
	v_or_b32_e32 v0, v5, v0
	v_lshlrev_b32_e32 v0, 2, v0
	global_store_dword v0, v9, s[0:1]
	v_or_b32_e32 v0, v2, v34
	v_lshlrev_b32_e32 v0, 2, v0
	global_store_dword v0, v14, s[0:1]
	v_or_b32_e32 v0, v3, v34
	v_lshlrev_b32_e32 v0, 2, v0
	global_store_dword v0, v15, s[0:1]
	v_or_b32_e32 v0, v4, v34
	v_lshlrev_b32_e32 v0, 2, v0
	global_store_dword v0, v16, s[0:1]
	v_or_b32_e32 v0, v5, v34
	v_lshlrev_b32_e32 v0, 2, v0
	global_store_dword v0, v17, s[0:1]
	v_or_b32_e32 v0, v2, v35
	v_lshlrev_b32_e32 v0, 2, v0
	global_store_dword v0, v22, s[0:1]
	v_or_b32_e32 v0, v3, v35
	v_lshlrev_b32_e32 v0, 2, v0
	global_store_dword v0, v23, s[0:1]
	v_or_b32_e32 v0, v4, v35
	v_lshlrev_b32_e32 v0, 2, v0
	global_store_dword v0, v24, s[0:1]
	v_or_b32_e32 v0, v5, v35
	v_lshlrev_b32_e32 v0, 2, v0
	global_store_dword v0, v25, s[0:1]
	v_or_b32_e32 v0, v2, v36
	v_lshlrev_b32_e32 v0, 2, v0
	global_store_dword v0, v30, s[0:1]
	v_or_b32_e32 v0, v3, v36
	v_lshlrev_b32_e32 v0, 2, v0
	global_store_dword v0, v31, s[0:1]
	v_or_b32_e32 v0, v4, v36
	v_lshlrev_b32_e32 v0, 2, v0
	global_store_dword v0, v32, s[0:1]
	v_or_b32_e32 v0, v5, v36
	v_lshlrev_b32_e32 v0, 2, v0
	global_store_dword v0, v33, s[0:1]
	s_lshl_b32 s0, s9, 6
	s_and_b32 s11, s0, 0x3fc0
	v_mov_b32_e32 v0, v194
	s_cmpk_lt_u32 s9, 0x200
	s_barrier
	s_cselect_b64 s[0:1], -1, 0
	s_and_b64 s[4:5], s[0:1], exec
	v_bfe_u32 v12, v0, 2, 6
	v_lshlrev_b32_e32 v0, 4, v0
	s_cselect_b32 s4, s39, 0xe80
	s_lshr_b32 s5, s9, 2
	v_and_b32_e32 v10, 48, v0
	v_or_b32_e32 v0, s11, v12
	s_and_b32 s9, s5, 64
	v_mul_u32_u24_e32 v0, 0xf80, v0
	s_or_b32 s4, s4, s9
	v_lshlrev_b32_e32 v0, 1, v0
	v_lshl_add_u64 v[2:3], s[50:51], 0, v[0:1]
	s_lshl_b32 s4, s4, 1
	s_mov_b32 s5, s89
	v_lshl_add_u64 v[2:3], v[2:3], 0, s[4:5]
	v_lshlrev_b32_e32 v0, 1, v10
	v_lshl_add_u64 v[6:7], v[2:3], 0, v[0:1]
	global_load_dwordx4 v[2:5], v[6:7], off
	s_nop 0
	global_load_dwordx4 v[6:9], v[6:7], off offset:16
	v_mul_u32_u24_e32 v10, 0x48, v10
	v_lshlrev_b32_e32 v10, 1, v10
	v_lshlrev_b32_e32 v11, 1, v12
	v_add3_u32 v13, s15, v10, v11
	v_add3_u32 v10, s15, v11, v10
	s_and_b64 s[0:1], s[0:1], exec
	s_cselect_b32 s1, s53, s55
	s_cselect_b32 s0, s52, s54
	s_waitcnt vmcnt(1)
	ds_write_b16 v13, v2
	ds_write_b16_d16_hi v10, v2 offset:144
	ds_write_b16 v13, v3 offset:288
	ds_write_b16_d16_hi v10, v3 offset:432
	ds_write_b16 v13, v4 offset:576
	ds_write_b16_d16_hi v10, v4 offset:720
	ds_write_b16 v13, v5 offset:864
	ds_write_b16_d16_hi v10, v5 offset:1008
	s_waitcnt vmcnt(0)
	ds_write_b16 v13, v6 offset:1152
	ds_write_b16_d16_hi v10, v6 offset:1296
	ds_write_b16 v13, v7 offset:1440
	ds_write_b16_d16_hi v10, v7 offset:1584
	ds_write_b16 v13, v8 offset:1728
	ds_write_b16_d16_hi v10, v8 offset:1872
	ds_write_b16 v13, v9 offset:2016
	ds_write_b16_d16_hi v10, v9 offset:2160
	v_or_b32_e32 v2, s9, v12
	v_lshlrev_b32_e32 v2, 15, v2
	v_mov_b32_e32 v3, v1
	v_lshl_add_u64 v[10:11], s[0:1], 0, v[2:3]
	v_mul_u32_u24_e32 v2, 0x90, v12
	v_add3_u32 v6, s15, v2, v0
	s_waitcnt lgkmcnt(0)
	s_barrier
	ds_read_b128 v[2:5], v6
	ds_read_b128 v[6:9], v6 offset:16
	s_lshl_b32 s0, s11, 1
	s_mov_b32 s1, s89
	s_add_i32 s9, s2, 0xfffffd81
	v_lshl_add_u64 v[10:11], v[10:11], 0, s[0:1]
	s_lshl_b32 s0, s9, 6
	s_and_b32 s11, s0, 0x3fc0
	v_lshl_add_u64 v[10:11], v[10:11], 0, v[0:1]
	v_mov_b32_e32 v0, v194
	s_cmpk_lt_u32 s9, 0x200
	s_waitcnt lgkmcnt(1)
	global_store_dwordx4 v[10:11], v[2:5], off
	s_waitcnt lgkmcnt(0)
	global_store_dwordx4 v[10:11], v[6:9], off offset:16
	s_barrier
	s_cselect_b64 s[0:1], -1, 0
	s_and_b64 s[4:5], s[0:1], exec
	v_bfe_u32 v12, v0, 2, 6
	v_lshlrev_b32_e32 v0, 4, v0
	s_cselect_b32 s4, s39, 0xe80
	s_lshr_b32 s5, s9, 2
	v_and_b32_e32 v10, 48, v0
	v_or_b32_e32 v0, s11, v12
	s_and_b32 s9, s5, 64
	v_mul_u32_u24_e32 v0, 0xf80, v0
	s_or_b32 s4, s4, s9
	v_lshlrev_b32_e32 v0, 1, v0
	v_lshl_add_u64 v[2:3], s[50:51], 0, v[0:1]
	s_lshl_b32 s4, s4, 1
	s_mov_b32 s5, s89
	v_lshl_add_u64 v[2:3], v[2:3], 0, s[4:5]
	v_lshlrev_b32_e32 v0, 1, v10
	v_lshl_add_u64 v[6:7], v[2:3], 0, v[0:1]
	global_load_dwordx4 v[2:5], v[6:7], off
	s_nop 0
	global_load_dwordx4 v[6:9], v[6:7], off offset:16
	v_mul_u32_u24_e32 v10, 0x48, v10
	v_lshlrev_b32_e32 v10, 1, v10
	v_lshlrev_b32_e32 v11, 1, v12
	v_add3_u32 v13, s15, v10, v11
	v_add3_u32 v10, s15, v11, v10
	s_and_b64 s[0:1], s[0:1], exec
	s_cselect_b32 s1, s53, s55
	s_cselect_b32 s0, s52, s54
	s_addk_i32 s2, 0xfd82
	s_waitcnt vmcnt(1)
	ds_write_b16 v13, v2
	ds_write_b16_d16_hi v10, v2 offset:144
	ds_write_b16 v13, v3 offset:288
	ds_write_b16_d16_hi v10, v3 offset:432
	ds_write_b16 v13, v4 offset:576
	ds_write_b16_d16_hi v10, v4 offset:720
	ds_write_b16 v13, v5 offset:864
	ds_write_b16_d16_hi v10, v5 offset:1008
	s_waitcnt vmcnt(0)
	ds_write_b16 v13, v6 offset:1152
	ds_write_b16_d16_hi v10, v6 offset:1296
	ds_write_b16 v13, v7 offset:1440
	ds_write_b16_d16_hi v10, v7 offset:1584
	ds_write_b16 v13, v8 offset:1728
	ds_write_b16_d16_hi v10, v8 offset:1872
	ds_write_b16 v13, v9 offset:2016
	ds_write_b16_d16_hi v10, v9 offset:2160
	v_or_b32_e32 v2, s9, v12
	v_lshlrev_b32_e32 v2, 15, v2
	v_mov_b32_e32 v3, v1
	v_lshl_add_u64 v[10:11], s[0:1], 0, v[2:3]
	v_mul_u32_u24_e32 v2, 0x90, v12
	v_add3_u32 v6, s15, v2, v0
	s_waitcnt lgkmcnt(0)
	s_barrier
	ds_read_b128 v[2:5], v6
	ds_read_b128 v[6:9], v6 offset:16
	s_lshl_b32 s0, s11, 1
	s_mov_b32 s1, s89
	v_lshl_add_u64 v[10:11], v[10:11], 0, s[0:1]
	s_lshl_b32 s0, s2, 6
	s_and_b32 s9, s0, 0x3fc0
	v_lshl_add_u64 v[10:11], v[10:11], 0, v[0:1]
	v_mov_b32_e32 v0, v194
	s_cmpk_lt_u32 s2, 0x200
	s_waitcnt lgkmcnt(1)
	global_store_dwordx4 v[10:11], v[2:5], off
	s_waitcnt lgkmcnt(0)
	global_store_dwordx4 v[10:11], v[6:9], off offset:16
	s_barrier
	s_cselect_b64 s[0:1], -1, 0
	s_and_b64 s[4:5], s[0:1], exec
	v_bfe_u32 v12, v0, 2, 6
	v_lshlrev_b32_e32 v0, 4, v0
	s_cselect_b32 s4, s39, 0xe80
	s_lshr_b32 s2, s2, 2
	v_and_b32_e32 v10, 48, v0
	v_or_b32_e32 v0, s9, v12
	s_and_b32 s2, s2, 64
	v_mul_u32_u24_e32 v0, 0xf80, v0
	s_or_b32 s4, s4, s2
	v_lshlrev_b32_e32 v0, 1, v0
	v_lshl_add_u64 v[2:3], s[50:51], 0, v[0:1]
	s_lshl_b32 s4, s4, 1
	s_mov_b32 s5, s89
	v_lshl_add_u64 v[2:3], v[2:3], 0, s[4:5]
	v_lshlrev_b32_e32 v0, 1, v10
	v_lshl_add_u64 v[6:7], v[2:3], 0, v[0:1]
	global_load_dwordx4 v[2:5], v[6:7], off
	s_nop 0
	global_load_dwordx4 v[6:9], v[6:7], off offset:16
	v_mul_u32_u24_e32 v10, 0x48, v10
	v_lshlrev_b32_e32 v10, 1, v10
	v_lshlrev_b32_e32 v11, 1, v12
	v_add3_u32 v13, s15, v10, v11
	v_add3_u32 v10, s15, v11, v10
	s_and_b64 s[0:1], s[0:1], exec
	s_cselect_b32 s1, s53, s55
	s_cselect_b32 s0, s52, s54
	s_mov_b64 s[4:5], 0
	s_waitcnt vmcnt(1)
	ds_write_b16 v13, v2
	ds_write_b16_d16_hi v10, v2 offset:144
	ds_write_b16 v13, v3 offset:288
	ds_write_b16_d16_hi v10, v3 offset:432
	ds_write_b16 v13, v4 offset:576
	ds_write_b16_d16_hi v10, v4 offset:720
	ds_write_b16 v13, v5 offset:864
	ds_write_b16_d16_hi v10, v5 offset:1008
	s_waitcnt vmcnt(0)
	ds_write_b16 v13, v6 offset:1152
	ds_write_b16_d16_hi v10, v6 offset:1296
	ds_write_b16 v13, v7 offset:1440
	ds_write_b16_d16_hi v10, v7 offset:1584
	ds_write_b16 v13, v8 offset:1728
	ds_write_b16_d16_hi v10, v8 offset:1872
	ds_write_b16 v13, v9 offset:2016
	ds_write_b16_d16_hi v10, v9 offset:2160
	v_or_b32_e32 v2, s2, v12
	v_lshlrev_b32_e32 v2, 15, v2
	v_mov_b32_e32 v3, v1
	v_lshl_add_u64 v[10:11], s[0:1], 0, v[2:3]
	v_mul_u32_u24_e32 v2, 0x90, v12
	v_add3_u32 v6, s15, v2, v0
	s_waitcnt lgkmcnt(0)
	s_barrier
	ds_read_b128 v[2:5], v6
	ds_read_b128 v[6:9], v6 offset:16
	s_lshl_b32 s0, s9, 1
	s_mov_b32 s1, s89
	v_lshl_add_u64 v[10:11], v[10:11], 0, s[0:1]
	v_lshl_add_u64 v[10:11], v[10:11], 0, v[0:1]
	s_mov_b64 s[0:1], 0
	s_cmpk_lt_u32 s10, 0x180
	s_waitcnt lgkmcnt(1)
	global_store_dwordx4 v[10:11], v[2:5], off
	s_waitcnt lgkmcnt(0)
	global_store_dwordx4 v[10:11], v[6:9], off offset:16
	s_barrier
	s_cbranch_scc0 .LBB0_627
	s_lshl_b32 s2, s10, 6
	v_mov_b32_e32 v0, v194
	s_and_b32 s2, s2, 0x3fc0
	s_xor_b32 s2, s2, 0x2000
	v_bfe_u32 v12, v0, 2, 6
	v_lshlrev_b32_e32 v0, 4, v0
	v_and_b32_e32 v10, 48, v0
	v_or_b32_e32 v0, s2, v12
	v_mul_u32_u24_e32 v0, 0xf80, v0
	v_readlane_b32 s40, v251, 54
	v_lshlrev_b32_e32 v0, 1, v0
	v_readlane_b32 s46, v251, 60
	v_readlane_b32 s47, v251, 61
	s_mov_b64 s[4:5], 0x1d80
	v_lshlrev_b32_e32 v11, 1, v12
	v_lshl_add_u64 v[2:3], s[46:47], 0, v[0:1]
	v_lshlrev_b32_e32 v0, 1, v10
	v_lshl_add_u64 v[2:3], v[2:3], 0, v[0:1]
	v_lshl_add_u64 v[6:7], v[2:3], 0, s[4:5]
	v_add_co_u32_e32 v2, vcc, s68, v2
	v_mul_u32_u24_e32 v10, 0x48, v10
	s_nop 0
	v_addc_co_u32_e32 v3, vcc, 0, v3, vcc
	global_load_dwordx4 v[2:5], v[2:3], off offset:3456
	s_nop 0
	global_load_dwordx4 v[6:9], v[6:7], off offset:16
	v_lshlrev_b32_e32 v10, 1, v10
	v_add3_u32 v13, s15, v10, v11
	v_add3_u32 v10, s15, v11, v10
	v_readlane_b32 s50, v252, 0
	v_readlane_b32 s51, v252, 1
	s_lshl_b32 s4, s2, 1
	s_mov_b32 s5, s89
	v_readlane_b32 s41, v251, 55
	v_readlane_b32 s42, v251, 56
	v_readlane_b32 s43, v251, 57
	v_readlane_b32 s44, v251, 58
	v_readlane_b32 s45, v251, 59
	v_readlane_b32 s48, v251, 62
	v_readlane_b32 s49, v251, 63
	v_readlane_b32 s52, v252, 2
	v_readlane_b32 s53, v252, 3
	v_readlane_b32 s54, v252, 4
	v_readlane_b32 s55, v252, 5
	s_waitcnt vmcnt(1)
	ds_write_b16 v13, v2
	ds_write_b16_d16_hi v10, v2 offset:144
	ds_write_b16 v13, v3 offset:288
	ds_write_b16_d16_hi v10, v3 offset:432
	ds_write_b16 v13, v4 offset:576
	ds_write_b16_d16_hi v10, v4 offset:720
	ds_write_b16 v13, v5 offset:864
	ds_write_b16_d16_hi v10, v5 offset:1008
	s_waitcnt vmcnt(0)
	ds_write_b16 v13, v6 offset:1152
	ds_write_b16_d16_hi v10, v6 offset:1296
	ds_write_b16 v13, v7 offset:1440
	ds_write_b16_d16_hi v10, v7 offset:1584
	ds_write_b16 v13, v8 offset:1728
	ds_write_b16_d16_hi v10, v8 offset:1872
	ds_write_b16 v13, v9 offset:2016
	ds_write_b16_d16_hi v10, v9 offset:2160
	v_lshlrev_b32_e32 v2, 15, v12
	v_mov_b32_e32 v3, v1
	v_lshl_add_u64 v[2:3], s[50:51], 0, v[2:3]
	v_lshl_add_u64 v[2:3], v[2:3], 0, s[4:5]
	v_lshl_add_u64 v[2:3], v[2:3], 0, v[0:1]
	v_mul_u32_u24_e32 v4, 0x90, v12
	s_mov_b64 s[4:5], 0x200000
	v_add3_u32 v0, s15, v4, v0
	v_add_co_u32_e32 v12, vcc, 0x200000, v2
	s_waitcnt lgkmcnt(0)
	s_barrier
	v_lshl_add_u64 v[10:11], v[2:3], 0, s[4:5]
	v_addc_co_u32_e32 v13, vcc, 0, v3, vcc
	ds_read_b128 v[2:5], v0
	ds_read_b128 v[6:9], v0 offset:16
	s_waitcnt lgkmcnt(1)
	global_store_dwordx4 v[12:13], v[2:5], off
	s_waitcnt lgkmcnt(0)
	global_store_dwordx4 v[10:11], v[6:9], off offset:16
	s_barrier
	s_mov_b64 s[4:5], -1
	s_branch .LBB0_627

.LBB0_629:
	v_lshl_add_u64 v[14:15], v[12:13], 0, s[0:1]
	global_load_dwordx4 v[2:5], v[14:15], off offset:1072
	global_load_dwordx4 v[6:9], v[14:15], off offset:1056
	global_load_dwordx4 v[20:23], v[14:15], off offset:1040
	global_load_dwordx4 v[24:27], v[14:15], off offset:1024
	s_add_u32 s0, s0, 0x80
	s_addc_u32 s1, s1, 0
	s_cmpk_lg_i32 s0, 0x200
	s_waitcnt vmcnt(0)
	v_lshlrev_b32_e32 v0, 16, v24
	v_mul_f32_e32 v17, v0, v0
	v_fmamk_f32 v17, v17, 0xbdd2d3e7, v129
	v_mul_f32_e32 v17, v17, v0
	v_exp_f32_e32 v17, v17
	v_and_b32_e32 v40, 0xffff0000, v27
	v_add_f32_e32 v17, 1.0, v17
	v_rcp_f32_e32 v17, v17
	s_nop 0
	v_mul_f32_e32 v29, v17, v0
	v_and_b32_e32 v0, 0xffff0000, v24
	v_mul_f32_e32 v17, v0, v0
	v_fmamk_f32 v17, v17, 0xbdd2d3e7, v129
	v_mul_f32_e32 v17, v17, v0
	v_exp_f32_e32 v17, v17
	v_mul_f32_e32 v28, v29, v29
	v_add_f32_e32 v17, 1.0, v17
	v_rcp_f32_e32 v17, v17
	s_nop 0
	v_mul_f32_e32 v33, v17, v0
	v_lshlrev_b32_e32 v0, 16, v25
	v_mul_f32_e32 v17, v0, v0
	v_fmamk_f32 v17, v17, 0xbdd2d3e7, v129
	v_mul_f32_e32 v17, v17, v0
	v_exp_f32_e32 v17, v17
	v_mul_f32_e32 v32, v33, v33
	v_add_f32_e32 v17, 1.0, v17
	v_rcp_f32_e32 v17, v17
	s_nop 0
	v_mul_f32_e32 v35, v17, v0
	v_and_b32_e32 v0, 0xffff0000, v25
	v_mul_f32_e32 v17, v0, v0
	v_fmamk_f32 v17, v17, 0xbdd2d3e7, v129
	v_mul_f32_e32 v17, v17, v0
	v_exp_f32_e32 v17, v17
	v_mul_f32_e32 v34, v35, v35
	v_add_f32_e32 v17, 1.0, v17
	v_rcp_f32_e32 v17, v17
	s_nop 0
	v_mul_f32_e32 v25, v17, v0
	v_lshlrev_b32_e32 v0, 16, v26
	v_mul_f32_e32 v17, v0, v0
	v_fmamk_f32 v17, v17, 0xbdd2d3e7, v129
	v_mul_f32_e32 v17, v17, v0
	v_exp_f32_e32 v17, v17
	v_mul_f32_e32 v24, v25, v25
	v_pk_add_f32 v[24:25], v[34:35], v[24:25]
	v_add_f32_e32 v17, 1.0, v17
	v_rcp_f32_e32 v17, v17
	s_nop 0
	v_mul_f32_e32 v37, v17, v0
	v_and_b32_e32 v0, 0xffff0000, v26
	v_mul_f32_e32 v17, v0, v0
	v_fmamk_f32 v17, v17, 0xbdd2d3e7, v129
	v_mul_f32_e32 v17, v17, v0
	v_exp_f32_e32 v17, v17
	v_mul_f32_e32 v26, v40, v40
	v_fmamk_f32 v26, v26, 0xbdd2d3e7, v129
	v_mul_f32_e32 v26, v26, v40
	v_add_f32_e32 v17, 1.0, v17
	v_rcp_f32_e32 v17, v17
	v_exp_f32_e32 v26, v26
	v_mul_f32_e32 v39, v17, v0
	v_lshlrev_b32_e32 v0, 16, v27
	v_mul_f32_e32 v17, v0, v0
	v_fmamk_f32 v17, v17, 0xbdd2d3e7, v129
	v_mul_f32_e32 v17, v17, v0
	v_exp_f32_e32 v17, v17
	v_add_f32_e32 v26, 1.0, v26
	v_rcp_f32_e32 v41, v26
	v_pk_add_f32 v[26:27], v[28:29], v[32:33]
	v_add_f32_e32 v17, 1.0, v17
	v_rcp_f32_e32 v17, v17
	v_mul_f32_e32 v36, v37, v37
	v_mul_f32_e32 v38, v39, v39
	v_pk_add_f32 v[18:19], v[18:19], v[26:27]
	v_mul_f32_e32 v27, v41, v40
	v_pk_add_f32 v[18:19], v[18:19], v[24:25]
	v_pk_add_f32 v[24:25], v[36:37], v[38:39]
	v_mul_f32_e32 v26, v27, v27
	v_pk_add_f32 v[18:19], v[18:19], v[24:25]
	v_mul_f32_e32 v25, v17, v0
	v_lshlrev_b32_e32 v0, 16, v20
	v_mul_f32_e32 v17, v0, v0
	v_fmamk_f32 v17, v17, 0xbdd2d3e7, v129
	v_mul_f32_e32 v17, v17, v0
	v_exp_f32_e32 v17, v17
	v_mul_f32_e32 v24, v25, v25
	v_pk_add_f32 v[24:25], v[24:25], v[26:27]
	v_and_b32_e32 v36, 0xffff0000, v23
	v_add_f32_e32 v17, 1.0, v17
	v_rcp_f32_e32 v17, v17
	v_pk_add_f32 v[18:19], v[18:19], v[24:25]
	v_mul_f32_e32 v25, v17, v0
	v_and_b32_e32 v0, 0xffff0000, v20
	v_mul_f32_e32 v17, v0, v0
	v_fmamk_f32 v17, v17, 0xbdd2d3e7, v129
	v_mul_f32_e32 v17, v17, v0
	v_exp_f32_e32 v17, v17
	v_mul_f32_e32 v24, v25, v25
	v_add_f32_e32 v17, 1.0, v17
	v_rcp_f32_e32 v17, v17
	s_nop 0
	v_mul_f32_e32 v27, v17, v0
	v_lshlrev_b32_e32 v0, 16, v21
	v_mul_f32_e32 v17, v0, v0
	v_fmamk_f32 v17, v17, 0xbdd2d3e7, v129
	v_mul_f32_e32 v17, v17, v0
	v_exp_f32_e32 v17, v17
	v_mul_f32_e32 v26, v27, v27
	v_add_f32_e32 v17, 1.0, v17
	v_rcp_f32_e32 v17, v17
	s_nop 0
	v_mul_f32_e32 v29, v17, v0
	v_and_b32_e32 v0, 0xffff0000, v21
	v_mul_f32_e32 v17, v0, v0
	v_fmamk_f32 v17, v17, 0xbdd2d3e7, v129
	v_mul_f32_e32 v17, v17, v0
	v_exp_f32_e32 v17, v17
	v_mul_f32_e32 v28, v29, v29
	v_add_f32_e32 v17, 1.0, v17
	v_rcp_f32_e32 v17, v17
	s_nop 0
	v_mul_f32_e32 v21, v17, v0
	v_lshlrev_b32_e32 v0, 16, v22
	v_mul_f32_e32 v17, v0, v0
	v_fmamk_f32 v17, v17, 0xbdd2d3e7, v129
	v_mul_f32_e32 v17, v17, v0
	v_exp_f32_e32 v17, v17
	v_mul_f32_e32 v20, v21, v21
	v_pk_add_f32 v[20:21], v[28:29], v[20:21]
	v_add_f32_e32 v17, 1.0, v17
	v_rcp_f32_e32 v17, v17
	s_nop 0
	v_mul_f32_e32 v33, v17, v0
	v_and_b32_e32 v0, 0xffff0000, v22
	v_mul_f32_e32 v17, v0, v0
	v_fmamk_f32 v17, v17, 0xbdd2d3e7, v129
	v_mul_f32_e32 v17, v17, v0
	v_exp_f32_e32 v17, v17
	v_mul_f32_e32 v22, v36, v36
	v_fmamk_f32 v22, v22, 0xbdd2d3e7, v129
	v_mul_f32_e32 v22, v22, v36
	v_add_f32_e32 v17, 1.0, v17
	v_rcp_f32_e32 v17, v17
	v_exp_f32_e32 v22, v22
	v_mul_f32_e32 v35, v17, v0
	v_lshlrev_b32_e32 v0, 16, v23
	v_mul_f32_e32 v17, v0, v0
	v_fmamk_f32 v17, v17, 0xbdd2d3e7, v129
	v_mul_f32_e32 v17, v17, v0
	v_exp_f32_e32 v17, v17
	v_add_f32_e32 v22, 1.0, v22
	v_rcp_f32_e32 v37, v22
	v_pk_add_f32 v[22:23], v[24:25], v[26:27]
	v_add_f32_e32 v17, 1.0, v17
	v_rcp_f32_e32 v17, v17
	v_mul_f32_e32 v32, v33, v33
	v_mul_f32_e32 v34, v35, v35
	v_pk_add_f32 v[18:19], v[18:19], v[22:23]
	v_mul_f32_e32 v23, v37, v36
	v_pk_add_f32 v[18:19], v[18:19], v[20:21]
	v_pk_add_f32 v[20:21], v[32:33], v[34:35]
	v_mul_f32_e32 v22, v23, v23
	v_pk_add_f32 v[18:19], v[18:19], v[20:21]
	v_mul_f32_e32 v21, v17, v0
	v_lshlrev_b32_e32 v0, 16, v6
	v_mul_f32_e32 v17, v0, v0
	v_fmamk_f32 v17, v17, 0xbdd2d3e7, v129
	v_mul_f32_e32 v17, v17, v0
	v_exp_f32_e32 v17, v17
	v_mul_f32_e32 v20, v21, v21
	v_pk_add_f32 v[20:21], v[20:21], v[22:23]
	v_and_b32_e32 v32, 0xffff0000, v9
	v_add_f32_e32 v17, 1.0, v17
	v_rcp_f32_e32 v17, v17
	v_pk_add_f32 v[18:19], v[18:19], v[20:21]
	v_mul_f32_e32 v21, v17, v0
	v_and_b32_e32 v0, 0xffff0000, v6
	v_mul_f32_e32 v6, v0, v0
	v_fmamk_f32 v6, v6, 0xbdd2d3e7, v129
	v_mul_f32_e32 v6, v6, v0
	v_exp_f32_e32 v6, v6
	v_mul_f32_e32 v20, v21, v21
	v_add_f32_e32 v6, 1.0, v6
	v_rcp_f32_e32 v6, v6
	s_nop 0
	v_mul_f32_e32 v23, v6, v0
	v_lshlrev_b32_e32 v0, 16, v7
	v_mul_f32_e32 v6, v0, v0
	v_fmamk_f32 v6, v6, 0xbdd2d3e7, v129
	v_mul_f32_e32 v6, v6, v0
	v_exp_f32_e32 v6, v6
	v_mul_f32_e32 v22, v23, v23
	v_add_f32_e32 v6, 1.0, v6
	v_rcp_f32_e32 v6, v6
	s_nop 0
	v_mul_f32_e32 v25, v6, v0
	v_and_b32_e32 v0, 0xffff0000, v7
	v_mul_f32_e32 v6, v0, v0
	v_fmamk_f32 v6, v6, 0xbdd2d3e7, v129
	v_mul_f32_e32 v6, v6, v0
	v_exp_f32_e32 v6, v6
	v_mul_f32_e32 v24, v25, v25
	v_add_f32_e32 v6, 1.0, v6
	v_rcp_f32_e32 v6, v6
	s_nop 0
	v_mul_f32_e32 v7, v6, v0
	v_lshlrev_b32_e32 v0, 16, v8
	v_mul_f32_e32 v17, v0, v0
	v_fmamk_f32 v17, v17, 0xbdd2d3e7, v129
	v_mul_f32_e32 v17, v17, v0
	v_exp_f32_e32 v17, v17
	v_mul_f32_e32 v6, v7, v7
	v_pk_add_f32 v[6:7], v[24:25], v[6:7]
	v_add_f32_e32 v17, 1.0, v17
	v_rcp_f32_e32 v17, v17
	s_nop 0
	v_mul_f32_e32 v27, v17, v0
	v_and_b32_e32 v0, 0xffff0000, v8
	v_mul_f32_e32 v8, v0, v0
	v_fmamk_f32 v8, v8, 0xbdd2d3e7, v129
	v_mul_f32_e32 v8, v8, v0
	v_exp_f32_e32 v8, v8
	v_mul_f32_e32 v26, v27, v27
	v_add_f32_e32 v8, 1.0, v8
	v_rcp_f32_e32 v8, v8
	s_nop 0
	v_mul_f32_e32 v29, v8, v0
	v_lshlrev_b32_e32 v0, 16, v9
	v_mul_f32_e32 v8, v0, v0
	v_fmamk_f32 v8, v8, 0xbdd2d3e7, v129
	v_mul_f32_e32 v8, v8, v0
	v_exp_f32_e32 v8, v8
	v_mul_f32_e32 v28, v29, v29
	v_add_f32_e32 v8, 1.0, v8
	v_rcp_f32_e32 v17, v8
	v_mul_f32_e32 v8, v32, v32
	v_fmamk_f32 v8, v8, 0xbdd2d3e7, v129
	v_mul_f32_e32 v8, v8, v32
	v_exp_f32_e32 v8, v8
	s_nop 0
	v_add_f32_e32 v8, 1.0, v8
	v_rcp_f32_e32 v33, v8
	v_pk_add_f32 v[8:9], v[20:21], v[22:23]
	s_nop 0
	v_pk_add_f32 v[8:9], v[18:19], v[8:9]
	v_mul_f32_e32 v19, v33, v32
	v_pk_add_f32 v[6:7], v[8:9], v[6:7]
	v_pk_add_f32 v[8:9], v[26:27], v[28:29]
	v_mul_f32_e32 v18, v19, v19
	v_pk_add_f32 v[6:7], v[6:7], v[8:9]
	v_mul_f32_e32 v9, v17, v0
	v_mul_f32_e32 v8, v9, v9
	v_pk_add_f32 v[8:9], v[8:9], v[18:19]
	v_lshlrev_b32_e32 v0, 16, v2
	v_pk_add_f32 v[6:7], v[6:7], v[8:9]
	v_mul_f32_e32 v8, v0, v0
	v_fmamk_f32 v8, v8, 0xbdd2d3e7, v129
	v_mul_f32_e32 v8, v8, v0
	v_exp_f32_e32 v8, v8
	v_and_b32_e32 v26, 0xffff0000, v5
	v_add_f32_e32 v8, 1.0, v8
	v_rcp_f32_e32 v8, v8
	s_nop 0
	v_mul_f32_e32 v9, v8, v0
	v_and_b32_e32 v0, 0xffff0000, v2
	v_mul_f32_e32 v2, v0, v0
	v_fmamk_f32 v2, v2, 0xbdd2d3e7, v129
	v_mul_f32_e32 v2, v2, v0
	v_exp_f32_e32 v2, v2
	v_mul_f32_e32 v8, v9, v9
	v_add_f32_e32 v2, 1.0, v2
	v_rcp_f32_e32 v2, v2
	s_nop 0
	v_mul_f32_e32 v19, v2, v0
	v_lshlrev_b32_e32 v0, 16, v3
	v_mul_f32_e32 v2, v0, v0
	v_fmamk_f32 v2, v2, 0xbdd2d3e7, v129
	v_mul_f32_e32 v2, v2, v0
	v_exp_f32_e32 v2, v2
	v_mul_f32_e32 v18, v19, v19
	v_add_f32_e32 v2, 1.0, v2
	v_rcp_f32_e32 v2, v2
	s_nop 0
	v_mul_f32_e32 v21, v2, v0
	v_and_b32_e32 v0, 0xffff0000, v3
	v_mul_f32_e32 v2, v0, v0
	v_fmamk_f32 v2, v2, 0xbdd2d3e7, v129
	v_mul_f32_e32 v2, v2, v0
	v_exp_f32_e32 v2, v2
	v_mul_f32_e32 v20, v21, v21
	v_add_f32_e32 v2, 1.0, v2
	v_rcp_f32_e32 v2, v2
	s_nop 0
	v_mul_f32_e32 v3, v2, v0
	v_lshlrev_b32_e32 v0, 16, v4
	v_mul_f32_e32 v17, v0, v0
	v_fmamk_f32 v17, v17, 0xbdd2d3e7, v129
	v_mul_f32_e32 v17, v17, v0
	v_exp_f32_e32 v17, v17
	v_mul_f32_e32 v2, v3, v3
	v_pk_add_f32 v[2:3], v[20:21], v[2:3]
	v_add_f32_e32 v17, 1.0, v17
	v_rcp_f32_e32 v17, v17
	s_nop 0
	v_mul_f32_e32 v23, v17, v0
	v_and_b32_e32 v0, 0xffff0000, v4
	v_mul_f32_e32 v4, v0, v0
	v_fmamk_f32 v4, v4, 0xbdd2d3e7, v129
	v_mul_f32_e32 v4, v4, v0
	v_exp_f32_e32 v4, v4
	v_mul_f32_e32 v22, v23, v23
	v_add_f32_e32 v4, 1.0, v4
	v_rcp_f32_e32 v4, v4
	s_nop 0
	v_mul_f32_e32 v25, v4, v0
	v_lshlrev_b32_e32 v0, 16, v5
	v_mul_f32_e32 v4, v0, v0
	v_fmamk_f32 v4, v4, 0xbdd2d3e7, v129
	v_mul_f32_e32 v4, v4, v0
	v_exp_f32_e32 v4, v4
	v_mul_f32_e32 v24, v25, v25
	v_add_f32_e32 v4, 1.0, v4
	v_rcp_f32_e32 v17, v4
	v_mul_f32_e32 v4, v26, v26
	v_fmamk_f32 v4, v4, 0xbdd2d3e7, v129
	v_mul_f32_e32 v4, v4, v26
	v_exp_f32_e32 v4, v4
	s_nop 0
	v_add_f32_e32 v4, 1.0, v4
	v_rcp_f32_e32 v27, v4
	v_pk_add_f32 v[4:5], v[8:9], v[18:19]
	s_nop 0
	v_pk_add_f32 v[4:5], v[6:7], v[4:5]
	v_mul_f32_e32 v7, v27, v26
	v_pk_add_f32 v[2:3], v[4:5], v[2:3]
	v_pk_add_f32 v[4:5], v[22:23], v[24:25]
	v_mul_f32_e32 v6, v7, v7
	v_pk_add_f32 v[2:3], v[2:3], v[4:5]
	v_mul_f32_e32 v5, v17, v0
	v_mul_f32_e32 v4, v5, v5
	v_pk_add_f32 v[4:5], v[4:5], v[6:7]
	s_nop 0
	v_pk_add_f32 v[26:27], v[2:3], v[4:5]
	global_load_dwordx4 v[2:5], v[14:15], off offset:1136
	global_load_dwordx4 v[6:9], v[14:15], off offset:1120
	global_load_dwordx4 v[18:21], v[14:15], off offset:1104
	global_load_dwordx4 v[22:25], v[14:15], off offset:1088
	s_waitcnt vmcnt(0)
	v_lshlrev_b32_e32 v0, 16, v22
	v_mul_f32_e32 v14, v0, v0
	v_fmamk_f32 v14, v14, 0xbdd2d3e7, v129
	v_mul_f32_e32 v14, v14, v0
	v_exp_f32_e32 v14, v14
	s_nop 0
	v_add_f32_e32 v14, 1.0, v14
	v_rcp_f32_e32 v14, v14
	s_nop 0
	v_mul_f32_e32 v15, v14, v0
	v_and_b32_e32 v0, 0xffff0000, v22
	v_mul_f32_e32 v14, v0, v0
	v_fmamk_f32 v14, v14, 0xbdd2d3e7, v129
	v_mul_f32_e32 v14, v14, v0
	v_exp_f32_e32 v14, v14
	s_nop 0
	v_add_f32_e32 v14, 1.0, v14
	v_rcp_f32_e32 v14, v14
	s_nop 0
	v_mul_f32_e32 v29, v14, v0
	v_lshlrev_b32_e32 v0, 16, v23
	v_mul_f32_e32 v17, v0, v0
	v_fmamk_f32 v17, v17, 0xbdd2d3e7, v129
	v_mul_f32_e32 v17, v17, v0
	v_exp_f32_e32 v17, v17
	v_mul_f32_e32 v14, v15, v15
	v_mul_f32_e32 v28, v29, v29
	v_pk_add_f32 v[14:15], v[14:15], v[28:29]
	v_add_f32_e32 v17, 1.0, v17
	v_rcp_f32_e32 v17, v17
	v_pk_add_f32 v[14:15], v[26:27], v[14:15]
	v_mul_f32_e32 v33, v17, v0
	v_and_b32_e32 v0, 0xffff0000, v23
	v_mul_f32_e32 v17, v0, v0
	v_fmamk_f32 v17, v17, 0xbdd2d3e7, v129
	v_mul_f32_e32 v17, v17, v0
	v_exp_f32_e32 v17, v17
	v_mul_f32_e32 v32, v33, v33
	v_add_f32_e32 v17, 1.0, v17
	v_rcp_f32_e32 v17, v17
	s_nop 0
	v_mul_f32_e32 v23, v17, v0
	v_lshlrev_b32_e32 v0, 16, v24
	v_mul_f32_e32 v17, v0, v0
	v_fmamk_f32 v17, v17, 0xbdd2d3e7, v129
	v_mul_f32_e32 v17, v17, v0
	v_exp_f32_e32 v17, v17
	v_mul_f32_e32 v22, v23, v23
	v_pk_add_f32 v[22:23], v[32:33], v[22:23]
	v_add_f32_e32 v17, 1.0, v17
	v_rcp_f32_e32 v17, v17
	v_pk_add_f32 v[14:15], v[14:15], v[22:23]
	v_mul_f32_e32 v35, v17, v0
	v_and_b32_e32 v0, 0xffff0000, v24
	v_mul_f32_e32 v17, v0, v0
	v_fmamk_f32 v17, v17, 0xbdd2d3e7, v129
	v_mul_f32_e32 v17, v17, v0
	v_exp_f32_e32 v17, v17
	v_and_b32_e32 v24, 0xffff0000, v25
	v_mul_f32_e32 v34, v35, v35
	v_add_f32_e32 v17, 1.0, v17
	v_rcp_f32_e32 v17, v17
	s_nop 0
	v_mul_f32_e32 v37, v17, v0
	v_lshlrev_b32_e32 v0, 16, v25
	v_mul_f32_e32 v17, v0, v0
	v_fmamk_f32 v17, v17, 0xbdd2d3e7, v129
	v_mul_f32_e32 v17, v17, v0
	v_exp_f32_e32 v17, v17
	v_mul_f32_e32 v36, v37, v37
	v_mul_f32_e32 v25, v24, v24
	v_fmamk_f32 v25, v25, 0xbdd2d3e7, v129
	v_add_f32_e32 v17, 1.0, v17
	v_rcp_f32_e32 v17, v17
	v_pk_add_f32 v[22:23], v[34:35], v[36:37]
	v_mul_f32_e32 v25, v25, v24
	v_pk_add_f32 v[14:15], v[14:15], v[22:23]
	v_mul_f32_e32 v23, v17, v0
	v_lshlrev_b32_e32 v0, 16, v18
	v_mul_f32_e32 v17, v0, v0
	v_fmamk_f32 v17, v17, 0xbdd2d3e7, v129
	v_exp_f32_e32 v25, v25
	v_mul_f32_e32 v17, v17, v0
	v_exp_f32_e32 v17, v17
	v_add_f32_e32 v25, 1.0, v25
	v_rcp_f32_e32 v25, v25
	v_mul_f32_e32 v22, v23, v23
	v_add_f32_e32 v17, 1.0, v17
	v_rcp_f32_e32 v17, v17
	v_mul_f32_e32 v25, v25, v24
	v_mul_f32_e32 v24, v25, v25
	v_pk_add_f32 v[22:23], v[22:23], v[24:25]
	v_and_b32_e32 v34, 0xffff0000, v21
	v_pk_add_f32 v[14:15], v[14:15], v[22:23]
	v_mul_f32_e32 v23, v17, v0
	v_and_b32_e32 v0, 0xffff0000, v18
	v_mul_f32_e32 v17, v0, v0
	v_fmamk_f32 v17, v17, 0xbdd2d3e7, v129
	v_mul_f32_e32 v17, v17, v0
	v_exp_f32_e32 v17, v17
	v_mul_f32_e32 v22, v23, v23
	v_add_f32_e32 v17, 1.0, v17
	v_rcp_f32_e32 v17, v17
	s_nop 0
	v_mul_f32_e32 v25, v17, v0
	v_lshlrev_b32_e32 v0, 16, v19
	v_mul_f32_e32 v17, v0, v0
	v_fmamk_f32 v17, v17, 0xbdd2d3e7, v129
	v_mul_f32_e32 v17, v17, v0
	v_exp_f32_e32 v17, v17
	v_mul_f32_e32 v24, v25, v25
	v_add_f32_e32 v17, 1.0, v17
	v_rcp_f32_e32 v17, v17
	s_nop 0
	v_mul_f32_e32 v27, v17, v0
	v_and_b32_e32 v0, 0xffff0000, v19
	v_mul_f32_e32 v17, v0, v0
	v_fmamk_f32 v17, v17, 0xbdd2d3e7, v129
	v_mul_f32_e32 v17, v17, v0
	v_exp_f32_e32 v17, v17
	v_mul_f32_e32 v26, v27, v27
	v_add_f32_e32 v17, 1.0, v17
	v_rcp_f32_e32 v17, v17
	s_nop 0
	v_mul_f32_e32 v19, v17, v0
	v_lshlrev_b32_e32 v0, 16, v20
	v_mul_f32_e32 v17, v0, v0
	v_fmamk_f32 v17, v17, 0xbdd2d3e7, v129
	v_mul_f32_e32 v17, v17, v0
	v_exp_f32_e32 v17, v17
	v_mul_f32_e32 v18, v19, v19
	v_pk_add_f32 v[18:19], v[26:27], v[18:19]
	v_add_f32_e32 v17, 1.0, v17
	v_rcp_f32_e32 v17, v17
	s_nop 0
	v_mul_f32_e32 v29, v17, v0
	v_and_b32_e32 v0, 0xffff0000, v20
	v_mul_f32_e32 v17, v0, v0
	v_fmamk_f32 v17, v17, 0xbdd2d3e7, v129
	v_mul_f32_e32 v17, v17, v0
	v_exp_f32_e32 v17, v17
	v_mul_f32_e32 v20, v34, v34
	v_fmamk_f32 v20, v20, 0xbdd2d3e7, v129
	v_mul_f32_e32 v20, v20, v34
	v_add_f32_e32 v17, 1.0, v17
	v_rcp_f32_e32 v17, v17
	v_exp_f32_e32 v20, v20
	v_mul_f32_e32 v33, v17, v0
	v_lshlrev_b32_e32 v0, 16, v21
	v_mul_f32_e32 v17, v0, v0
	v_fmamk_f32 v17, v17, 0xbdd2d3e7, v129
	v_mul_f32_e32 v17, v17, v0
	v_exp_f32_e32 v17, v17
	v_add_f32_e32 v20, 1.0, v20
	v_rcp_f32_e32 v35, v20
	v_pk_add_f32 v[20:21], v[22:23], v[24:25]
	v_add_f32_e32 v17, 1.0, v17
	v_rcp_f32_e32 v17, v17
	v_mul_f32_e32 v28, v29, v29
	v_mul_f32_e32 v32, v33, v33
	v_pk_add_f32 v[14:15], v[14:15], v[20:21]
	v_mul_f32_e32 v21, v35, v34
	v_pk_add_f32 v[14:15], v[14:15], v[18:19]
	v_pk_add_f32 v[18:19], v[28:29], v[32:33]
	v_mul_f32_e32 v20, v21, v21
	v_pk_add_f32 v[14:15], v[14:15], v[18:19]
	v_mul_f32_e32 v19, v17, v0
	v_lshlrev_b32_e32 v0, 16, v6
	v_mul_f32_e32 v17, v0, v0
	v_fmamk_f32 v17, v17, 0xbdd2d3e7, v129
	v_mul_f32_e32 v17, v17, v0
	v_exp_f32_e32 v17, v17
	v_mul_f32_e32 v18, v19, v19
	v_pk_add_f32 v[18:19], v[18:19], v[20:21]
	v_and_b32_e32 v28, 0xffff0000, v9
	v_add_f32_e32 v17, 1.0, v17
	v_rcp_f32_e32 v17, v17
	v_pk_add_f32 v[14:15], v[14:15], v[18:19]
	v_mul_f32_e32 v19, v17, v0
	v_and_b32_e32 v0, 0xffff0000, v6
	v_mul_f32_e32 v6, v0, v0
	v_fmamk_f32 v6, v6, 0xbdd2d3e7, v129
	v_mul_f32_e32 v6, v6, v0
	v_exp_f32_e32 v6, v6
	v_mul_f32_e32 v18, v19, v19
	v_add_f32_e32 v6, 1.0, v6
	v_rcp_f32_e32 v6, v6
	s_nop 0
	v_mul_f32_e32 v21, v6, v0
	v_lshlrev_b32_e32 v0, 16, v7
	v_mul_f32_e32 v6, v0, v0
	v_fmamk_f32 v6, v6, 0xbdd2d3e7, v129
	v_mul_f32_e32 v6, v6, v0
	v_exp_f32_e32 v6, v6
	v_mul_f32_e32 v20, v21, v21
	v_add_f32_e32 v6, 1.0, v6
	v_rcp_f32_e32 v6, v6
	s_nop 0
	v_mul_f32_e32 v23, v6, v0
	v_and_b32_e32 v0, 0xffff0000, v7
	v_mul_f32_e32 v6, v0, v0
	v_fmamk_f32 v6, v6, 0xbdd2d3e7, v129
	v_mul_f32_e32 v6, v6, v0
	v_exp_f32_e32 v6, v6
	v_mul_f32_e32 v22, v23, v23
	v_add_f32_e32 v6, 1.0, v6
	v_rcp_f32_e32 v6, v6
	s_nop 0
	v_mul_f32_e32 v7, v6, v0
	v_lshlrev_b32_e32 v0, 16, v8
	v_mul_f32_e32 v17, v0, v0
	v_fmamk_f32 v17, v17, 0xbdd2d3e7, v129
	v_mul_f32_e32 v17, v17, v0
	v_exp_f32_e32 v17, v17
	v_mul_f32_e32 v6, v7, v7
	v_pk_add_f32 v[6:7], v[22:23], v[6:7]
	v_add_f32_e32 v17, 1.0, v17
	v_rcp_f32_e32 v17, v17
	s_nop 0
	v_mul_f32_e32 v25, v17, v0
	v_and_b32_e32 v0, 0xffff0000, v8
	v_mul_f32_e32 v8, v0, v0
	v_fmamk_f32 v8, v8, 0xbdd2d3e7, v129
	v_mul_f32_e32 v8, v8, v0
	v_exp_f32_e32 v8, v8
	v_mul_f32_e32 v24, v25, v25
	v_add_f32_e32 v8, 1.0, v8
	v_rcp_f32_e32 v8, v8
	s_nop 0
	v_mul_f32_e32 v27, v8, v0
	v_lshlrev_b32_e32 v0, 16, v9
	v_mul_f32_e32 v8, v0, v0
	v_fmamk_f32 v8, v8, 0xbdd2d3e7, v129
	v_mul_f32_e32 v8, v8, v0
	v_exp_f32_e32 v8, v8
	v_mul_f32_e32 v26, v27, v27
	v_add_f32_e32 v8, 1.0, v8
	v_rcp_f32_e32 v17, v8
	v_mul_f32_e32 v8, v28, v28
	v_fmamk_f32 v8, v8, 0xbdd2d3e7, v129
	v_mul_f32_e32 v8, v8, v28
	v_exp_f32_e32 v8, v8
	s_nop 0
	v_add_f32_e32 v8, 1.0, v8
	v_rcp_f32_e32 v29, v8
	v_pk_add_f32 v[8:9], v[18:19], v[20:21]
	s_nop 0
	v_pk_add_f32 v[8:9], v[14:15], v[8:9]
	v_mul_f32_e32 v15, v29, v28
	v_pk_add_f32 v[6:7], v[8:9], v[6:7]
	v_pk_add_f32 v[8:9], v[24:25], v[26:27]
	v_mul_f32_e32 v14, v15, v15
	v_pk_add_f32 v[6:7], v[6:7], v[8:9]
	v_mul_f32_e32 v9, v17, v0
	v_mul_f32_e32 v8, v9, v9
	v_pk_add_f32 v[8:9], v[8:9], v[14:15]
	v_lshlrev_b32_e32 v0, 16, v2
	v_pk_add_f32 v[6:7], v[6:7], v[8:9]
	v_mul_f32_e32 v8, v0, v0
	v_fmamk_f32 v8, v8, 0xbdd2d3e7, v129
	v_mul_f32_e32 v8, v8, v0
	v_exp_f32_e32 v8, v8
	v_and_b32_e32 v24, 0xffff0000, v5
	v_add_f32_e32 v8, 1.0, v8
	v_rcp_f32_e32 v8, v8
	s_nop 0
	v_mul_f32_e32 v9, v8, v0
	v_and_b32_e32 v0, 0xffff0000, v2
	v_mul_f32_e32 v2, v0, v0
	v_fmamk_f32 v2, v2, 0xbdd2d3e7, v129
	v_mul_f32_e32 v2, v2, v0
	v_exp_f32_e32 v2, v2
	v_mul_f32_e32 v8, v9, v9
	v_add_f32_e32 v2, 1.0, v2
	v_rcp_f32_e32 v2, v2
	s_nop 0
	v_mul_f32_e32 v15, v2, v0
	v_lshlrev_b32_e32 v0, 16, v3
	v_mul_f32_e32 v2, v0, v0
	v_fmamk_f32 v2, v2, 0xbdd2d3e7, v129
	v_mul_f32_e32 v2, v2, v0
	v_exp_f32_e32 v2, v2
	v_mul_f32_e32 v14, v15, v15
	v_add_f32_e32 v2, 1.0, v2
	v_rcp_f32_e32 v2, v2
	s_nop 0
	v_mul_f32_e32 v19, v2, v0
	v_and_b32_e32 v0, 0xffff0000, v3
	v_mul_f32_e32 v2, v0, v0
	v_fmamk_f32 v2, v2, 0xbdd2d3e7, v129
	v_mul_f32_e32 v2, v2, v0
	v_exp_f32_e32 v2, v2
	v_mul_f32_e32 v18, v19, v19
	v_add_f32_e32 v2, 1.0, v2
	v_rcp_f32_e32 v2, v2
	s_nop 0
	v_mul_f32_e32 v3, v2, v0
	v_lshlrev_b32_e32 v0, 16, v4
	v_mul_f32_e32 v17, v0, v0
	v_fmamk_f32 v17, v17, 0xbdd2d3e7, v129
	v_mul_f32_e32 v17, v17, v0
	v_exp_f32_e32 v17, v17
	v_mul_f32_e32 v2, v3, v3
	v_pk_add_f32 v[2:3], v[18:19], v[2:3]
	v_add_f32_e32 v17, 1.0, v17
	v_rcp_f32_e32 v17, v17
	s_nop 0
	v_mul_f32_e32 v21, v17, v0
	v_and_b32_e32 v0, 0xffff0000, v4
	v_mul_f32_e32 v4, v0, v0
	v_fmamk_f32 v4, v4, 0xbdd2d3e7, v129
	v_mul_f32_e32 v4, v4, v0
	v_exp_f32_e32 v4, v4
	v_mul_f32_e32 v20, v21, v21
	v_add_f32_e32 v4, 1.0, v4
	v_rcp_f32_e32 v4, v4
	s_nop 0
	v_mul_f32_e32 v23, v4, v0
	v_lshlrev_b32_e32 v0, 16, v5
	v_mul_f32_e32 v4, v0, v0
	v_fmamk_f32 v4, v4, 0xbdd2d3e7, v129
	v_mul_f32_e32 v4, v4, v0
	v_exp_f32_e32 v4, v4
	v_mul_f32_e32 v22, v23, v23
	v_add_f32_e32 v4, 1.0, v4
	v_rcp_f32_e32 v17, v4
	v_mul_f32_e32 v4, v24, v24
	v_fmamk_f32 v4, v4, 0xbdd2d3e7, v129
	v_mul_f32_e32 v4, v4, v24
	v_exp_f32_e32 v4, v4
	s_nop 0
	v_add_f32_e32 v4, 1.0, v4
	v_rcp_f32_e32 v25, v4
	v_pk_add_f32 v[4:5], v[8:9], v[14:15]
	s_nop 0
	v_pk_add_f32 v[4:5], v[6:7], v[4:5]
	v_mul_f32_e32 v7, v25, v24
	v_pk_add_f32 v[2:3], v[4:5], v[2:3]
	v_pk_add_f32 v[4:5], v[20:21], v[22:23]
	v_mul_f32_e32 v6, v7, v7
	v_pk_add_f32 v[2:3], v[2:3], v[4:5]
	v_mul_f32_e32 v5, v17, v0
	v_mul_f32_e32 v4, v5, v5
	v_pk_add_f32 v[4:5], v[4:5], v[6:7]
	s_nop 0
	v_pk_add_f32 v[18:19], v[2:3], v[4:5]
	s_cbranch_scc1 .LBB0_629
	s_mov_b32 s9, s89
	v_lshl_add_u64 v[2:3], v[10:11], 0, s[8:9]
	v_lshlrev_b32_e32 v0, 7, v16
	v_lshl_add_u64 v[22:23], v[2:3], 0, v[0:1]
	global_load_dwordx4 v[10:13], v[22:23], off offset:1024
	v_lshlrev_b32_e32 v20, 8, v16
	global_load_dwordx2 v[28:29], v20, s[16:17]
	global_load_dwordx2 v[36:37], v20, s[20:21]
	global_load_dwordx2 v[40:41], v20, s[16:17] offset:16
	global_load_dwordx2 v[42:43], v20, s[16:17] offset:32
	global_load_dwordx2 v[24:25], v20, s[16:17] offset:48
	global_load_dwordx2 v[44:45], v20, s[20:21] offset:16
	global_load_dwordx2 v[46:47], v20, s[20:21] offset:32
	global_load_dwordx2 v[26:27], v20, s[20:21] offset:48
	v_lshlrev_b32_e32 v34, 6, v16
	v_mul_u32_u24_e32 v4, 0x4400, v16
	global_load_dwordx4 v[14:17], v[22:23], off offset:1040
	ds_bpermute_b32 v3, v80, v19
	ds_bpermute_b32 v2, v80, v18
	s_mov_b32 s0, 0x3b000000
	v_lshlrev_b32_e32 v33, 1, v31
	v_add3_u32 v38, s15, v4, v33
	v_or_b32_e32 v4, 1, v34
	s_waitcnt lgkmcnt(0)
	v_pk_add_f32 v[2:3], v[18:19], v[2:3]
	v_mul_u32_u24_e32 v39, 0x110, v4
	v_pk_mul_f32 v[18:19], v[2:3], s[0:1] op_sel_hi:[1,0]
	v_or_b32_e32 v78, 7, v34
	v_fma_f32 v2, -v19, v19, v18
	v_max_f32_e32 v2, 0, v2
	v_add_f32_e32 v2, 0x358637bd, v2
	v_mul_f32_e32 v3, 0x4b800000, v2
	v_cmp_gt_f32_e32 vcc, s69, v2
	v_add3_u32 v18, s15, v39, v33
	v_or_b32_e32 v80, 10, v34
	v_cndmask_b32_e32 v2, v2, v3, vcc
	v_rsq_f32_e32 v48, v2
	global_load_dwordx4 v[2:5], v[22:23], off offset:1072
	global_load_dwordx4 v[6:9], v[22:23], off offset:1056
	v_or_b32_e32 v79, 11, v34
	v_readlane_b32 s40, v251, 22
	v_mul_f32_e32 v39, 0x45800000, v48
	v_cndmask_b32_e32 v39, v48, v39, vcc
	v_readlane_b32 s41, v251, 23
	v_mov_b32_e32 v21, v1
	v_mul_u32_u24_e32 v83, 0x110, v31
	v_add3_u32 v0, s15, v83, v0
	v_or_b32_e32 v100, 31, v34
	v_cmp_gt_u32_e32 vcc, v31, v34
	v_or_b32_e32 v35, 4, v34
	v_and_b32_e32 v32, 15, v50
	v_readlane_b32 s42, v251, 24
	v_readlane_b32 s43, v251, 25
	v_readlane_b32 s44, v251, 26
	v_readlane_b32 s45, v251, 27
	v_readlane_b32 s46, v251, 28
	v_readlane_b32 s47, v251, 29
	v_readlane_b32 s48, v251, 30
	v_readlane_b32 s49, v251, 31
	v_readlane_b32 s50, v251, 32
	v_readlane_b32 s51, v251, 33
	v_readlane_b32 s52, v251, 34
	v_readlane_b32 s53, v251, 35
	v_readlane_b32 s54, v251, 36
	v_readlane_b32 s55, v251, 37
	s_mov_b32 s2, 0x1f000
	s_waitcnt vmcnt(11)
	v_lshlrev_b32_e32 v48, 16, v10
	v_and_b32_e32 v10, 0xffff0000, v10
	v_lshlrev_b32_e32 v49, 16, v11
	v_and_b32_e32 v11, 0xffff0000, v11
	v_mul_f32_e32 v52, v48, v48
	v_mul_f32_e32 v53, v10, v10
	v_mul_f32_e32 v55, v11, v11
	v_fmamk_f32 v52, v52, 0xbdd2d3e7, v129
	v_fmamk_f32 v53, v53, 0xbdd2d3e7, v129
	v_fmamk_f32 v55, v55, 0xbdd2d3e7, v129
	v_mul_f32_e32 v52, v52, v48
	v_mul_f32_e32 v53, v53, v10
	v_mul_f32_e32 v55, v55, v11
	v_exp_f32_e32 v52, v52
	v_exp_f32_e32 v53, v53
	v_exp_f32_e32 v55, v55
	v_lshlrev_b32_e32 v51, 16, v12
	v_add_f32_e32 v52, 1.0, v52
	v_add_f32_e32 v53, 1.0, v53
	v_add_f32_e32 v55, 1.0, v55
	v_rcp_f32_e32 v52, v52
	v_mul_f32_e32 v56, v51, v51
	v_rcp_f32_e32 v53, v53
	v_rcp_f32_e32 v55, v55
	v_fmamk_f32 v56, v56, 0xbdd2d3e7, v129
	v_mul_f32_e32 v56, v56, v51
	v_fma_f32 v48, v52, v48, -v19
	v_and_b32_e32 v12, 0xffff0000, v12
	v_fma_f32 v10, v53, v10, -v19
	v_fma_f32 v11, v55, v11, -v19
	v_mul_f32_e32 v48, v39, v48
	v_mul_f32_e32 v57, 0x3d372713, v12
	v_exp_f32_e32 v56, v56
	v_mul_f32_e32 v10, v39, v10
	v_mul_f32_e32 v59, v39, v11
	s_waitcnt vmcnt(9)
	v_fma_f32 v11, v28, v48, v36
	v_mul_f32_e32 v57, v57, v12
	v_fmac_f32_e32 v37, v29, v10
	v_cvt_pk_bf16_f32 v10, v11, s0
	v_cvt_pk_bf16_f32 v11, v37, s0
	ds_write_b16 v38, v10 offset:34816
	ds_write_b16 v18, v11 offset:34816
	v_fma_f32 v10, v57, v12, v12
	v_mul_f32_e32 v10, 0xbfcc422a, v10
	v_lshlrev_b32_e32 v28, 16, v13
	v_add_f32_e32 v56, 1.0, v56
	v_mul_f32_e32 v10, 0x3fb8aa3b, v10
	v_mul_f32_e32 v29, v28, v28
	v_rcp_f32_e32 v56, v56
	v_exp_f32_e32 v10, v10
	v_fmamk_f32 v29, v29, 0xbdd2d3e7, v129
	v_mul_f32_e32 v29, v29, v28
	v_fma_f32 v51, v56, v51, -v19
	v_add_f32_e32 v10, 1.0, v10
	v_exp_f32_e32 v29, v29
	v_mul_f32_e32 v11, v39, v51
	v_rcp_f32_e32 v10, v10
	s_waitcnt vmcnt(5)
	v_fma_f32 v11, v40, v11, v44
	v_cvt_pk_bf16_f32 v11, v11, s0
	ds_write_b16 v18, v11 offset:35632
	v_add_f32_e32 v11, 1.0, v29
	v_fma_f32 v10, v10, v12, -v19
	v_rcp_f32_e32 v11, v11
	v_mul_f32_e32 v10, v39, v10
	v_fmac_f32_e32 v45, v10, v41
	v_cvt_pk_bf16_f32 v10, v45, s0
	ds_write_b16 v18, v10 offset:35904
	v_fma_f32 v10, v11, v28, -v19
	v_and_b32_e32 v11, 0xffff0000, v13
	v_mul_f32_e32 v12, v11, v11
	v_fmamk_f32 v12, v12, 0xbdd2d3e7, v129
	v_mul_f32_e32 v12, v12, v11
	v_exp_f32_e32 v12, v12
	s_waitcnt vmcnt(2)
	v_lshlrev_b32_e32 v13, 16, v14
	v_mul_f32_e32 v28, v13, v13
	v_fmamk_f32 v28, v28, 0xbdd2d3e7, v129
	v_add_f32_e32 v12, 1.0, v12
	v_rcp_f32_e32 v12, v12
	v_mul_f32_e32 v28, v28, v13
	v_fma_f32 v11, v12, v11, -v19
	v_exp_f32_e32 v28, v28
	v_mul_f32_e32 v44, v39, v11
	v_and_b32_e32 v11, 0xffff0000, v14
	v_mul_f32_e32 v12, v11, v11
	v_fmamk_f32 v12, v12, 0xbdd2d3e7, v129
	v_mul_f32_e32 v12, v12, v11
	v_mul_f32_e32 v45, v39, v10
	v_add_f32_e32 v10, 1.0, v28
	v_rcp_f32_e32 v10, v10
	v_exp_f32_e32 v12, v12
	v_lshlrev_b32_e32 v29, 16, v16
	v_fma_f32 v10, v10, v13, -v19
	v_lshlrev_b32_e32 v13, 16, v15
	v_add_f32_e32 v12, 1.0, v12
	v_mul_f32_e32 v14, v13, v13
	v_rcp_f32_e32 v12, v12
	v_fmamk_f32 v14, v14, 0xbdd2d3e7, v129
	v_mul_f32_e32 v10, v39, v10
	v_mul_f32_e32 v14, v14, v13
	v_fma_f32 v10, v42, v10, v46
	v_cvt_pk_bf16_f32 v10, v10, s0
	v_exp_f32_e32 v14, v14
	ds_write_b16 v18, v10 offset:36720
	v_fma_f32 v10, v12, v11, -v19
	v_mul_f32_e32 v10, v39, v10
	v_fmac_f32_e32 v47, v43, v10
	v_cvt_pk_bf16_f32 v10, v47, s0
	v_and_b32_e32 v15, 0xffff0000, v15
	v_add_f32_e32 v11, 1.0, v14
	ds_write_b16 v18, v10 offset:36992
	v_mul_f32_e32 v10, v15, v15
	v_rcp_f32_e32 v11, v11
	v_fmamk_f32 v10, v10, 0xbdd2d3e7, v129
	v_mul_f32_e32 v10, v10, v15
	v_fma_f32 v14, v11, v13, -v19
	v_exp_f32_e32 v28, v10
	global_load_dwordx2 v[10:11], v20, s[16:17] offset:64
	global_load_dwordx2 v[12:13], v20, s[20:21] offset:64
	v_mul_f32_e32 v37, v29, v29
	v_fmamk_f32 v37, v37, 0xbdd2d3e7, v129
	v_add_f32_e32 v28, 1.0, v28
	v_mul_f32_e32 v37, v37, v29
	v_rcp_f32_e32 v28, v28
	v_exp_f32_e32 v37, v37
	v_fma_f32 v15, v28, v15, -v19
	v_mul_f32_e32 v46, v39, v15
	v_and_b32_e32 v15, 0xffff0000, v16
	v_mul_f32_e32 v16, v15, v15
	v_mul_f32_e32 v47, v39, v14
	v_add_f32_e32 v14, 1.0, v37
	v_fmamk_f32 v16, v16, 0xbdd2d3e7, v129
	v_rcp_f32_e32 v14, v14
	v_mul_f32_e32 v16, v16, v15
	v_exp_f32_e32 v16, v16
	v_fma_f32 v14, v14, v29, -v19
	v_mul_f32_e32 v14, v39, v14
	v_fma_f32 v14, v24, v14, v26
	v_lshlrev_b32_e32 v24, 16, v17
	v_add_f32_e32 v16, 1.0, v16
	v_mul_f32_e32 v26, v24, v24
	v_rcp_f32_e32 v16, v16
	v_fmamk_f32 v26, v26, 0xbdd2d3e7, v129
	v_mul_f32_e32 v26, v26, v24
	v_cvt_pk_bf16_f32 v14, v14, s0
	v_exp_f32_e32 v26, v26
	ds_write_b16 v18, v14 offset:37808
	v_fma_f32 v14, v16, v15, -v19
	v_mul_f32_e32 v14, v39, v14
	v_fmac_f32_e32 v27, v14, v25
	v_cvt_pk_bf16_f32 v14, v27, s0
	v_and_b32_e32 v25, 0xffff0000, v17
	v_add_f32_e32 v15, 1.0, v26
	ds_write_b16 v18, v14 offset:38080
	v_mul_f32_e32 v14, v25, v25
	v_rcp_f32_e32 v15, v15
	v_fmamk_f32 v14, v14, 0xbdd2d3e7, v129
	v_mul_f32_e32 v14, v14, v25
	v_fma_f32 v24, v15, v24, -v19
	v_exp_f32_e32 v26, v14
	global_load_dwordx2 v[14:15], v20, s[16:17] offset:80
	global_load_dwordx2 v[16:17], v20, s[20:21] offset:80
	s_waitcnt vmcnt(4)
	v_lshlrev_b32_e32 v27, 16, v6
	v_mul_f32_e32 v28, v27, v27
	v_fmamk_f32 v28, v28, 0xbdd2d3e7, v129
	v_mul_f32_e32 v28, v28, v27
	v_exp_f32_e32 v28, v28
	v_mul_f32_e32 v55, v39, v24
	v_mul_f32_e32 v54, v49, v49
	v_fmamk_f32 v54, v54, 0xbdd2d3e7, v129
	v_add_f32_e32 v24, 1.0, v28
	v_rcp_f32_e32 v24, v24
	v_and_b32_e32 v6, 0xffff0000, v6
	v_mul_f32_e32 v54, v54, v49
	v_fma_f32 v24, v24, v27, -v19
	v_mul_f32_e32 v40, v39, v24
	v_mul_f32_e32 v24, v6, v6
	v_fmamk_f32 v24, v24, 0xbdd2d3e7, v129
	v_mul_f32_e32 v24, v24, v6
	v_exp_f32_e32 v54, v54
	v_exp_f32_e32 v41, v24
	v_add_f32_e32 v54, 1.0, v54
	v_add_f32_e32 v26, 1.0, v26
	v_rcp_f32_e32 v54, v54
	v_rcp_f32_e32 v26, v26
	s_waitcnt vmcnt(2)
	v_fma_f32 v10, v10, v40, v12
	v_lshlrev_b32_e32 v40, 16, v7
	v_add_f32_e32 v12, 1.0, v41
	v_mul_f32_e32 v41, v40, v40
	v_fmamk_f32 v41, v41, 0xbdd2d3e7, v129
	v_mul_f32_e32 v41, v41, v40
	v_fma_f32 v49, v54, v49, -v19
	v_fma_f32 v25, v26, v25, -v19
	v_mul_f32_e32 v65, v39, v49
	v_mul_f32_e32 v54, v39, v25
	global_load_dwordx2 v[24:25], v20, s[16:17] offset:96
	global_load_dwordx2 v[28:29], v20, s[16:17] offset:112
	global_load_dwordx2 v[26:27], v20, s[20:21] offset:96
	global_load_dwordx2 v[48:49], v20, s[20:21] offset:112
	v_exp_f32_e32 v41, v41
	v_rcp_f32_e32 v12, v12
	v_cvt_pk_bf16_f32 v10, v10, s0
	ds_write_b16 v18, v10 offset:38896
	v_add_f32_e32 v10, 1.0, v41
	v_fma_f32 v6, v12, v6, -v19
	v_rcp_f32_e32 v10, v10
	v_mul_f32_e32 v6, v39, v6
	v_fmac_f32_e32 v13, v11, v6
	v_cvt_pk_bf16_f32 v6, v13, s0
	v_and_b32_e32 v7, 0xffff0000, v7
	ds_write_b16 v18, v6 offset:39168
	v_fma_f32 v6, v10, v40, -v19
	v_mul_f32_e32 v10, v7, v7
	v_fmamk_f32 v10, v10, 0xbdd2d3e7, v129
	v_mul_f32_e32 v10, v10, v7
	v_exp_f32_e32 v10, v10
	v_lshlrev_b32_e32 v11, 16, v8
	v_mul_f32_e32 v12, v11, v11
	v_fmamk_f32 v12, v12, 0xbdd2d3e7, v129
	v_mul_f32_e32 v12, v12, v11
	v_add_f32_e32 v10, 1.0, v10
	v_rcp_f32_e32 v10, v10
	v_exp_f32_e32 v12, v12
	v_mul_f32_e32 v53, v39, v6
	v_fma_f32 v7, v10, v7, -v19
	v_mul_f32_e32 v52, v39, v7
	v_and_b32_e32 v7, 0xffff0000, v8
	v_add_f32_e32 v6, 1.0, v12
	v_mul_f32_e32 v8, v7, v7
	v_rcp_f32_e32 v6, v6
	v_fmamk_f32 v8, v8, 0xbdd2d3e7, v129
	v_mul_f32_e32 v8, v8, v7
	v_lshlrev_b32_e32 v10, 16, v9
	v_fma_f32 v6, v6, v11, -v19
	v_exp_f32_e32 v8, v8
	v_mul_f32_e32 v11, v10, v10
	v_fmamk_f32 v11, v11, 0xbdd2d3e7, v129
	v_mul_f32_e32 v11, v11, v10
	v_add_f32_e32 v8, 1.0, v8
	v_rcp_f32_e32 v8, v8
	v_exp_f32_e32 v11, v11
	v_mul_f32_e32 v6, v39, v6
	s_waitcnt vmcnt(4)
	v_fma_f32 v6, v14, v6, v16
	v_cvt_pk_bf16_f32 v6, v6, s0
	ds_write_b16 v18, v6 offset:39984
	v_fma_f32 v6, v8, v7, -v19
	v_add_f32_e32 v7, 1.0, v11
	v_rcp_f32_e32 v7, v7
	v_mul_f32_e32 v6, v39, v6
	v_fmac_f32_e32 v17, v6, v15
	v_cvt_pk_bf16_f32 v6, v17, s0
	ds_write_b16 v18, v6 offset:40256
	v_fma_f32 v6, v7, v10, -v19
	v_and_b32_e32 v7, 0xffff0000, v9
	v_lshlrev_b32_e32 v9, 16, v2
	v_mul_f32_e32 v10, v9, v9
	v_fmamk_f32 v10, v10, 0xbdd2d3e7, v129
	v_mul_f32_e32 v8, v7, v7
	v_mul_f32_e32 v10, v10, v9
	v_fmamk_f32 v8, v8, 0xbdd2d3e7, v129
	v_mul_f32_e32 v8, v8, v7
	v_exp_f32_e32 v10, v10
	v_exp_f32_e32 v8, v8
	v_mul_f32_e32 v58, v39, v6
	v_add_f32_e32 v6, 1.0, v10
	global_load_dwordx4 v[10:13], v[22:23], off offset:1104
	global_load_dwordx4 v[14:17], v[22:23], off offset:1088
	v_add_f32_e32 v8, 1.0, v8
	v_rcp_f32_e32 v8, v8
	v_and_b32_e32 v2, 0xffff0000, v2
	v_rcp_f32_e32 v6, v6
	v_or_b32_e32 v36, 8, v34
	v_fma_f32 v7, v8, v7, -v19
	v_mul_f32_e32 v56, v39, v7
	v_mul_f32_e32 v7, v2, v2
	v_fmamk_f32 v7, v7, 0xbdd2d3e7, v129
	v_mul_f32_e32 v7, v7, v2
	v_exp_f32_e32 v7, v7
	v_lshlrev_b32_e32 v8, 16, v3
	v_fma_f32 v6, v6, v9, -v19
	v_mul_f32_e32 v9, v8, v8
	v_add_f32_e32 v7, 1.0, v7
	v_rcp_f32_e32 v7, v7
	v_fmamk_f32 v9, v9, 0xbdd2d3e7, v129
	v_mul_f32_e32 v9, v9, v8
	v_fma_f32 v2, v7, v2, -v19
	v_mul_f32_e32 v6, v39, v6
	v_mul_f32_e32 v2, v39, v2
	s_waitcnt vmcnt(3)
	v_fma_f32 v6, v24, v6, v26
	v_exp_f32_e32 v9, v9
	v_fmac_f32_e32 v27, v25, v2
	v_cvt_pk_bf16_f32 v6, v6, s0
	v_cvt_pk_bf16_f32 v2, v27, s0
	ds_write_b16 v18, v6 offset:41072
	ds_write_b16 v18, v2 offset:41344
	global_load_dwordx2 v[24:25], v20, s[16:17] offset:128
	global_load_dwordx2 v[26:27], v20, s[20:21] offset:128
	v_add_f32_e32 v6, 1.0, v9
	v_rcp_f32_e32 v6, v6
	v_and_b32_e32 v3, 0xffff0000, v3
	v_lshlrev_b32_e32 v7, 16, v4
	v_or_b32_e32 v37, 12, v34
	v_fma_f32 v2, v6, v8, -v19
	v_mul_f32_e32 v6, v3, v3
	v_fmamk_f32 v6, v6, 0xbdd2d3e7, v129
	v_mul_f32_e32 v6, v6, v3
	v_exp_f32_e32 v6, v6
	v_mul_f32_e32 v8, v7, v7
	v_fmamk_f32 v8, v8, 0xbdd2d3e7, v129
	v_mul_f32_e32 v8, v8, v7
	v_add_f32_e32 v6, 1.0, v6
	v_rcp_f32_e32 v6, v6
	v_exp_f32_e32 v8, v8
	v_mul_f32_e32 v64, v39, v2
	v_fma_f32 v3, v6, v3, -v19
	v_mul_f32_e32 v63, v39, v3
	v_and_b32_e32 v3, 0xffff0000, v4
	v_add_f32_e32 v2, 1.0, v8
	v_mul_f32_e32 v4, v3, v3
	v_rcp_f32_e32 v2, v2
	v_fmamk_f32 v4, v4, 0xbdd2d3e7, v129
	v_mul_f32_e32 v4, v4, v3
	v_fma_f32 v2, v2, v7, -v19
	v_exp_f32_e32 v4, v4
	v_mul_f32_e32 v2, v39, v2
	s_waitcnt vmcnt(4)
	v_fma_f32 v2, v28, v2, v48
	v_cvt_pk_bf16_f32 v2, v2, s0
	ds_write_b16 v18, v2 offset:42160
	v_add_f32_e32 v2, 1.0, v4
	v_lshlrev_b32_e32 v4, 16, v5
	v_mul_f32_e32 v6, v4, v4
	v_fmamk_f32 v6, v6, 0xbdd2d3e7, v129
	v_rcp_f32_e32 v2, v2
	v_mul_f32_e32 v6, v6, v4
	v_exp_f32_e32 v6, v6
	v_fma_f32 v2, v2, v3, -v19
	v_mul_f32_e32 v2, v39, v2
	v_fmac_f32_e32 v49, v2, v29
	v_add_f32_e32 v2, 1.0, v6
	v_cvt_pk_bf16_f32 v6, v49, s0
	ds_write_b16 v18, v6 offset:42432
	global_load_dwordx2 v[60:61], v20, s[16:17] offset:144
	global_load_dwordx2 v[66:67], v20, s[20:21] offset:144
	v_and_b32_e32 v3, 0xffff0000, v5
	v_mul_f32_e32 v5, v3, v3
	v_fmamk_f32 v5, v5, 0xbdd2d3e7, v129
	v_mul_f32_e32 v5, v5, v3
	v_rcp_f32_e32 v2, v2
	v_exp_f32_e32 v5, v5
	s_waitcnt vmcnt(4)
	v_lshlrev_b32_e32 v28, 16, v14
	v_and_b32_e32 v14, 0xffff0000, v14
	v_fma_f32 v2, v2, v4, -v19
	v_add_f32_e32 v4, 1.0, v5
	v_mul_f32_e32 v5, v28, v28
	v_fmamk_f32 v5, v5, 0xbdd2d3e7, v129
	v_mul_f32_e32 v5, v5, v28
	v_rcp_f32_e32 v4, v4
	v_exp_f32_e32 v5, v5
	v_mul_f32_e32 v69, v39, v2
	v_fma_f32 v2, v4, v3, -v19
	v_mul_f32_e32 v68, v39, v2
	v_add_f32_e32 v2, 1.0, v5
	v_rcp_f32_e32 v29, v2
	global_load_dwordx4 v[2:5], v[22:23], off offset:1136
	global_load_dwordx4 v[6:9], v[22:23], off offset:1120
	v_or_b32_e32 v38, 16, v34
	v_or_b32_e32 v40, 20, v34
	v_fma_f32 v22, v29, v28, -v19
	v_mul_f32_e32 v48, v39, v22
	v_mul_f32_e32 v22, v14, v14
	v_fmamk_f32 v22, v22, 0xbdd2d3e7, v129
	v_mul_f32_e32 v22, v22, v14
	v_exp_f32_e32 v49, v22
	global_load_dwordx2 v[74:75], v20, s[16:17] offset:160
	global_load_dwordx2 v[22:23], v20, s[16:17] offset:176
	global_load_dwordx2 v[76:77], v20, s[20:21] offset:160
	global_load_dwordx2 v[28:29], v20, s[20:21] offset:176
	s_waitcnt vmcnt(8)
	v_fma_f32 v24, v24, v48, v26
	v_lshlrev_b32_e32 v48, 16, v15
	v_add_f32_e32 v26, 1.0, v49
	v_mul_f32_e32 v49, v48, v48
	v_fmamk_f32 v49, v49, 0xbdd2d3e7, v129
	v_mul_f32_e32 v49, v49, v48
	v_exp_f32_e32 v49, v49
	v_rcp_f32_e32 v26, v26
	v_cvt_pk_bf16_f32 v24, v24, s0
	ds_write_b16 v18, v24 offset:43248
	v_add_f32_e32 v24, 1.0, v49
	v_fma_f32 v14, v26, v14, -v19
	v_rcp_f32_e32 v24, v24
	v_mul_f32_e32 v14, v39, v14
	v_fmac_f32_e32 v27, v25, v14
	v_cvt_pk_bf16_f32 v14, v27, s0
	v_and_b32_e32 v15, 0xffff0000, v15
	ds_write_b16 v18, v14 offset:43520
	v_fma_f32 v14, v24, v48, -v19
	v_mul_f32_e32 v24, v15, v15
	v_fmamk_f32 v24, v24, 0xbdd2d3e7, v129
	v_mul_f32_e32 v24, v24, v15
	v_exp_f32_e32 v24, v24
	v_lshlrev_b32_e32 v25, 16, v16
	v_mul_f32_e32 v26, v25, v25
	v_fmamk_f32 v26, v26, 0xbdd2d3e7, v129
	v_mul_f32_e32 v26, v26, v25
	v_add_f32_e32 v24, 1.0, v24
	v_rcp_f32_e32 v24, v24
	v_exp_f32_e32 v26, v26
	v_mul_f32_e32 v73, v39, v14
	v_fma_f32 v15, v24, v15, -v19
	v_mul_f32_e32 v72, v39, v15
	v_and_b32_e32 v15, 0xffff0000, v16
	v_add_f32_e32 v14, 1.0, v26
	v_mul_f32_e32 v16, v15, v15
	v_rcp_f32_e32 v14, v14
	v_fmamk_f32 v16, v16, 0xbdd2d3e7, v129
	v_mul_f32_e32 v16, v16, v15
	v_lshlrev_b32_e32 v24, 16, v17
	v_fma_f32 v14, v14, v25, -v19
	v_exp_f32_e32 v16, v16
	v_mul_f32_e32 v25, v24, v24
	v_fmamk_f32 v25, v25, 0xbdd2d3e7, v129
	v_mul_f32_e32 v25, v25, v24
	v_add_f32_e32 v16, 1.0, v16
	v_rcp_f32_e32 v16, v16
	v_exp_f32_e32 v25, v25
	v_mul_f32_e32 v14, v39, v14
	s_waitcnt vmcnt(6)
	v_fma_f32 v14, v60, v14, v66
	v_cvt_pk_bf16_f32 v14, v14, s0
	ds_write_b16 v18, v14 offset:44336
	v_fma_f32 v14, v16, v15, -v19
	v_add_f32_e32 v15, 1.0, v25
	v_rcp_f32_e32 v15, v15
	v_mul_f32_e32 v14, v39, v14
	v_fmac_f32_e32 v67, v14, v61
	v_cvt_pk_bf16_f32 v14, v67, s0
	ds_write_b16 v18, v14 offset:44608
	v_fma_f32 v14, v15, v24, -v19
	v_and_b32_e32 v15, 0xffff0000, v17
	v_mul_f32_e32 v16, v15, v15
	v_fmamk_f32 v16, v16, 0xbdd2d3e7, v129
	v_mul_f32_e32 v16, v16, v15
	v_exp_f32_e32 v16, v16
	v_lshlrev_b32_e32 v17, 16, v10
	v_mul_f32_e32 v24, v17, v17
	v_fmamk_f32 v24, v24, 0xbdd2d3e7, v129
	v_mul_f32_e32 v24, v24, v17
	v_add_f32_e32 v16, 1.0, v16
	v_rcp_f32_e32 v16, v16
	v_exp_f32_e32 v24, v24
	v_and_b32_e32 v10, 0xffff0000, v10
	v_mul_f32_e32 v71, v39, v14
	v_fma_f32 v15, v16, v15, -v19
	v_add_f32_e32 v14, 1.0, v24
	v_mul_f32_e32 v70, v39, v15
	v_mul_f32_e32 v15, v10, v10
	v_rcp_f32_e32 v14, v14
	v_fmamk_f32 v15, v15, 0xbdd2d3e7, v129
	v_mul_f32_e32 v15, v15, v10
	v_fma_f32 v14, v14, v17, -v19
	v_exp_f32_e32 v15, v15
	v_mul_f32_e32 v14, v39, v14
	s_waitcnt vmcnt(1)
	v_fma_f32 v14, v74, v14, v76
	v_cvt_pk_bf16_f32 v14, v14, s0
	ds_write_b16 v18, v14 offset:45424
	v_add_f32_e32 v14, 1.0, v15
	v_lshlrev_b32_e32 v15, 16, v11
	v_rcp_f32_e32 v14, v14
	v_mul_f32_e32 v16, v15, v15
	v_fmamk_f32 v16, v16, 0xbdd2d3e7, v129
	v_mul_f32_e32 v16, v16, v15
	v_and_b32_e32 v11, 0xffff0000, v11
	v_fma_f32 v10, v14, v10, -v19
	v_mul_f32_e32 v14, v11, v11
	v_exp_f32_e32 v16, v16
	v_fmamk_f32 v14, v14, 0xbdd2d3e7, v129
	v_mul_f32_e32 v14, v14, v11
	v_mul_f32_e32 v10, v39, v10
	v_fmac_f32_e32 v77, v75, v10
	v_add_f32_e32 v10, 1.0, v16
	v_exp_f32_e32 v14, v14
	v_rcp_f32_e32 v10, v10
	v_cvt_pk_bf16_f32 v16, v77, s0
	ds_write_b16 v18, v16 offset:45696
	v_add_f32_e32 v14, 1.0, v14
	v_fma_f32 v10, v10, v15, -v19
	v_rcp_f32_e32 v14, v14
	v_lshlrev_b32_e32 v15, 16, v12
	v_mul_f32_e32 v16, v15, v15
	v_fmamk_f32 v16, v16, 0xbdd2d3e7, v129
	v_mul_f32_e32 v16, v16, v15
	v_mul_f32_e32 v67, v39, v10
	v_fma_f32 v10, v14, v11, -v19
	v_and_b32_e32 v11, 0xffff0000, v12
	v_mul_f32_e32 v12, v11, v11
	v_exp_f32_e32 v16, v16
	v_fmamk_f32 v12, v12, 0xbdd2d3e7, v129
	v_mul_f32_e32 v12, v12, v11
	v_mul_f32_e32 v66, v39, v10
	v_add_f32_e32 v10, 1.0, v16
	v_exp_f32_e32 v12, v12
	v_rcp_f32_e32 v10, v10
	v_or_b32_e32 v76, 2, v34
	v_or_b32_e32 v77, 3, v34
	v_add_f32_e32 v12, 1.0, v12
	v_fma_f32 v10, v10, v15, -v19
	v_rcp_f32_e32 v12, v12
	v_mul_f32_e32 v10, v39, v10
	s_waitcnt vmcnt(0)
	v_fma_f32 v10, v22, v10, v28
	v_cvt_pk_bf16_f32 v10, v10, s0
	ds_write_b16 v18, v10 offset:46512
	v_fma_f32 v10, v12, v11, -v19
	v_lshlrev_b32_e32 v11, 16, v13
	v_mul_f32_e32 v12, v11, v11
	v_fmamk_f32 v12, v12, 0xbdd2d3e7, v129
	v_mul_f32_e32 v12, v12, v11
	v_exp_f32_e32 v12, v12
	v_mul_f32_e32 v10, v39, v10
	v_fmac_f32_e32 v29, v10, v23
	v_lshlrev_b32_e32 v14, 2, v76
	v_add_f32_e32 v12, 1.0, v12
	v_rcp_f32_e32 v12, v12
	v_cvt_pk_bf16_f32 v10, v29, s0
	v_lshlrev_b32_e32 v16, 2, v77
	global_load_dword v15, v14, s[16:17]
	s_nop 0
	global_load_dword v14, v14, s[20:21]
	s_nop 0
	global_load_dword v17, v16, s[16:17]
	s_nop 0
	global_load_dword v16, v16, s[20:21]
	ds_write_b16 v18, v10 offset:46784
	v_fma_f32 v10, v12, v11, -v19
	v_and_b32_e32 v11, 0xffff0000, v13
	v_lshlrev_b32_e32 v13, 16, v6
	v_mul_f32_e32 v22, v13, v13
	v_fmamk_f32 v22, v22, 0xbdd2d3e7, v129
	v_mul_f32_e32 v22, v22, v13
	v_mul_f32_e32 v12, v11, v11
	v_fmamk_f32 v12, v12, 0xbdd2d3e7, v129
	v_exp_f32_e32 v22, v22
	v_mul_f32_e32 v12, v12, v11
	v_exp_f32_e32 v12, v12
	v_mul_f32_e32 v75, v39, v10
	v_add_f32_e32 v10, 1.0, v22
	v_rcp_f32_e32 v10, v10
	v_add_f32_e32 v12, 1.0, v12
	v_and_b32_e32 v6, 0xffff0000, v6
	v_rcp_f32_e32 v12, v12
	v_fma_f32 v22, v10, v13, -v19
	v_mul_f32_e32 v10, v6, v6
	v_fmamk_f32 v10, v10, 0xbdd2d3e7, v129
	v_mul_f32_e32 v10, v10, v6
	v_fma_f32 v11, v12, v11, -v19
	v_mul_f32_e32 v74, v39, v11
	v_exp_f32_e32 v23, v10
	global_load_dwordx2 v[10:11], v20, s[16:17] offset:192
	global_load_dwordx2 v[12:13], v20, s[20:21] offset:192
	v_mul_f32_e32 v81, v39, v22
	v_lshlrev_b32_e32 v90, 16, v8
	v_add_f32_e32 v22, 1.0, v23
	v_lshlrev_b32_e32 v23, 16, v7
	v_mul_f32_e32 v24, v23, v23
	v_and_b32_e32 v7, 0xffff0000, v7
	v_fmamk_f32 v24, v24, 0xbdd2d3e7, v129
	v_mul_f32_e32 v25, v7, v7
	v_mul_f32_e32 v24, v24, v23
	v_fmamk_f32 v25, v25, 0xbdd2d3e7, v129
	v_mul_f32_e32 v25, v25, v7
	v_rcp_f32_e32 v22, v22
	v_exp_f32_e32 v24, v24
	v_exp_f32_e32 v25, v25
	v_fma_f32 v6, v22, v6, -v19
	v_add_f32_e32 v22, 1.0, v24
	v_rcp_f32_e32 v22, v22
	v_add_f32_e32 v24, 1.0, v25
	v_rcp_f32_e32 v24, v24
	v_mul_f32_e32 v82, v39, v6
	v_fma_f32 v6, v22, v23, -v19
	v_mul_f32_e32 v62, v39, v6
	v_fma_f32 v6, v24, v7, -v19
	v_mul_f32_e32 v61, v39, v6
	v_or_b32_e32 v6, s88, v31
	v_lshlrev_b32_e32 v6, 7, v6
	v_mov_b32_e32 v7, v1
	v_lshl_add_u64 v[6:7], v[6:7], 2, s[40:41]
	v_lshl_add_u64 v[6:7], v[6:7], 0, v[20:21]
	v_and_b32_e32 v8, 0xffff0000, v8
	v_mul_f32_e32 v97, v8, v8
	v_fmamk_f32 v97, v97, 0xbdd2d3e7, v129
	v_mul_f32_e32 v97, v97, v8
	v_exp_f32_e32 v97, v97
	v_and_b32_e32 v98, 0xffff0000, v9
	v_and_b32_e32 v104, 0xffff0000, v5
	v_or_b32_e32 v41, 24, v34
	v_or_b32_e32 v42, 28, v34
	v_or_b32_e32 v43, 32, v34
	v_or_b32_e32 v48, 36, v34
	s_waitcnt vmcnt(4)
	v_fmac_f32_e32 v14, v15, v65
	v_mul_u32_u24_e32 v15, 0x110, v76
	v_cvt_pk_bf16_f32 v14, v14, s0
	v_add3_u32 v15, s15, v15, v33
	v_or_b32_e32 v65, 6, v34
	ds_write_b16 v15, v14 offset:34816
	v_lshlrev_b32_e32 v14, 2, v65
	global_load_dword v84, v14, s[16:17]
	global_load_dword v85, v14, s[20:21]
	s_waitcnt vmcnt(4)
	v_fmac_f32_e32 v16, v17, v59
	v_lshlrev_b32_e32 v14, 2, v78
	v_mul_u32_u24_e32 v15, 0x110, v77
	global_load_dword v86, v14, s[16:17]
	global_load_dword v87, v14, s[20:21]
	v_cvt_pk_bf16_f32 v14, v16, s0
	v_add3_u32 v15, s15, v15, v33
	ds_write_b16 v15, v14 offset:34816
	v_lshlrev_b32_e32 v14, 2, v80
	global_load_dwordx2 v[22:23], v20, s[16:17] offset:208
	global_load_dwordx2 v[24:25], v20, s[20:21] offset:208
	global_load_dword v88, v14, s[16:17]
	global_load_dword v89, v14, s[20:21]
	v_lshlrev_b32_e32 v14, 2, v79
	global_load_dword v91, v14, s[16:17]
	global_load_dword v92, v14, s[20:21]
	v_mul_f32_e32 v14, v90, v90
	v_fmamk_f32 v14, v14, 0xbdd2d3e7, v129
	v_mul_f32_e32 v14, v14, v90
	v_or_b32_e32 v59, 14, v34
	v_lshlrev_b32_e32 v15, 2, v59
	global_load_dword v93, v15, s[16:17]
	global_load_dword v94, v15, s[20:21]
	v_exp_f32_e32 v95, v14
	global_load_dwordx2 v[14:15], v20, s[16:17] offset:224
	global_load_dwordx2 v[16:17], v20, s[16:17] offset:240
	global_load_dwordx2 v[26:27], v20, s[20:21] offset:224
	s_nop 0
	global_load_dwordx2 v[20:21], v20, s[20:21] offset:240
	v_or_b32_e32 v49, 40, v34
	v_or_b32_e32 v51, 44, v34
	v_or_b32_e32 v57, 48, v34
	s_waitcnt vmcnt(16)
	v_fma_f32 v10, v10, v81, v12
	v_cvt_pk_bf16_f32 v12, v10, s0
	v_or_b32_e32 v10, 15, v34
	v_add_f32_e32 v81, 1.0, v95
	v_lshlrev_b32_e32 v95, 2, v10
	global_load_dword v96, v95, s[16:17]
	s_nop 0
	global_load_dword v95, v95, s[20:21]
	v_rcp_f32_e32 v81, v81
	ds_write_b16 v18, v12 offset:47600
	v_fmac_f32_e32 v13, v11, v82
	v_cvt_pk_bf16_f32 v11, v13, s0
	v_fma_f32 v12, v81, v90, -v19
	v_lshlrev_b32_e32 v90, 16, v9
	v_add_f32_e32 v81, 1.0, v97
	v_mul_f32_e32 v97, v90, v90
	v_fmamk_f32 v97, v97, 0xbdd2d3e7, v129
	v_mul_f32_e32 v97, v97, v90
	v_rcp_f32_e32 v81, v81
	v_exp_f32_e32 v97, v97
	v_mul_f32_e32 v12, v39, v12
	v_mul_u32_u24_e32 v13, 0x110, v80
	v_fma_f32 v8, v81, v8, -v19
	v_add_f32_e32 v81, 1.0, v97
	v_rcp_f32_e32 v81, v81
	v_mul_f32_e32 v99, v39, v8
	v_add3_u32 v13, s15, v13, v33
	v_mul_f32_e32 v9, v98, v98
	v_fma_f32 v8, v81, v90, -v19
	v_mul_u32_u24_e32 v81, 0x110, v65
	v_add3_u32 v81, s15, v81, v33
	v_fmamk_f32 v9, v9, 0xbdd2d3e7, v129
	v_mul_f32_e32 v9, v9, v98
	v_exp_f32_e32 v9, v9
	v_or_b32_e32 v90, 26, v34
	v_or_b32_e32 v60, 52, v34
	v_or_b32_e32 v29, 56, v34
	v_add_f32_e32 v9, 1.0, v9
	v_rcp_f32_e32 v97, v9
	v_mul_f32_e32 v9, v39, v8
	v_or_b32_e32 v28, 60, v34
	v_readlane_b32 s40, v251, 54
	v_fma_f32 v8, v97, v98, -v19
	v_or_b32_e32 v97, 30, v34
	v_mul_f32_e32 v8, v39, v8
	v_readlane_b32 s46, v251, 60
	v_readlane_b32 s47, v251, 61
	v_readlane_b32 s48, v251, 62
	v_readlane_b32 s49, v251, 63
	v_readlane_b32 s41, v251, 55
	v_readlane_b32 s42, v251, 56
	v_readlane_b32 s43, v251, 57
	s_waitcnt vmcnt(16)
	v_fmac_f32_e32 v85, v45, v84
	v_cvt_pk_bf16_f32 v45, v85, s0
	ds_write_b16 v81, v45 offset:34816
	v_mul_u32_u24_e32 v45, 0x110, v78
	s_waitcnt vmcnt(14)
	v_fmac_f32_e32 v87, v44, v86
	v_cvt_pk_bf16_f32 v44, v87, s0
	v_add3_u32 v45, s15, v45, v33
	ds_write_b16 v45, v44 offset:34816
	ds_write_b16 v18, v11 offset:47872
	s_waitcnt vmcnt(12)
	v_fma_f32 v11, v22, v12, v24
	s_waitcnt vmcnt(10)
	v_fmac_f32_e32 v89, v88, v47
	v_cvt_pk_bf16_f32 v12, v89, s0
	ds_write_b16 v13, v12 offset:34816
	s_waitcnt vmcnt(8)
	v_fmac_f32_e32 v92, v91, v46
	v_mul_u32_u24_e32 v13, 0x110, v79
	v_cvt_pk_bf16_f32 v12, v92, s0
	v_add3_u32 v13, s15, v13, v33
	v_cvt_pk_bf16_f32 v11, v11, s0
	ds_write_b16 v13, v12 offset:34816
	ds_write_b16 v18, v11 offset:48688
	v_lshlrev_b32_e32 v13, 16, v2
	v_mul_f32_e32 v22, v13, v13
	v_fmamk_f32 v22, v22, 0xbdd2d3e7, v129
	v_mul_f32_e32 v22, v22, v13
	v_exp_f32_e32 v22, v22
	v_fmac_f32_e32 v25, v99, v23
	v_cvt_pk_bf16_f32 v11, v25, s0
	s_waitcnt vmcnt(6)
	v_fmac_f32_e32 v94, v55, v93
	v_mul_u32_u24_e32 v12, 0x110, v59
	ds_write_b16 v18, v11 offset:48960
	v_cvt_pk_bf16_f32 v11, v94, s0
	v_add3_u32 v12, s15, v12, v33
	ds_write_b16 v12, v11 offset:34816
	v_add_f32_e32 v12, 1.0, v22
	v_rcp_f32_e32 v12, v12
	s_waitcnt vmcnt(0)
	v_fmac_f32_e32 v95, v54, v96
	v_mul_u32_u24_e32 v22, 0x110, v10
	v_cvt_pk_bf16_f32 v11, v95, s0
	v_add3_u32 v22, s15, v22, v33
	v_and_b32_e32 v2, 0xffff0000, v2
	ds_write_b16 v22, v11 offset:34816
	v_fma_f32 v11, v12, v13, -v19
	v_mul_f32_e32 v12, v2, v2
	v_lshlrev_b32_e32 v13, 16, v3
	v_fmamk_f32 v12, v12, 0xbdd2d3e7, v129
	v_mul_f32_e32 v22, v13, v13
	v_mul_f32_e32 v12, v12, v2
	v_fmamk_f32 v22, v22, 0xbdd2d3e7, v129
	v_mul_f32_e32 v22, v22, v13
	v_exp_f32_e32 v12, v12
	v_exp_f32_e32 v22, v22
	v_mul_f32_e32 v11, v39, v11
	v_add_f32_e32 v12, 1.0, v12
	v_fma_f32 v11, v14, v11, v26
	v_rcp_f32_e32 v12, v12
	v_add_f32_e32 v14, 1.0, v22
	v_rcp_f32_e32 v14, v14
	v_and_b32_e32 v3, 0xffff0000, v3
	v_fma_f32 v2, v12, v2, -v19
	v_mul_f32_e32 v12, v39, v2
	v_fma_f32 v2, v14, v13, -v19
	v_mul_f32_e32 v13, v3, v3
	v_fmamk_f32 v13, v13, 0xbdd2d3e7, v129
	v_mul_f32_e32 v13, v13, v3
	v_or_b32_e32 v81, 18, v34
	v_or_b32_e32 v86, 19, v34
	v_lshlrev_b32_e32 v14, 2, v81
	v_lshlrev_b32_e32 v22, 2, v86
	global_load_dword v26, v14, s[16:17]
	s_nop 0
	global_load_dword v14, v14, s[20:21]
	s_nop 0
	global_load_dword v54, v22, s[16:17]
	global_load_dword v55, v22, s[20:21]
	v_lshlrev_b32_e32 v22, 16, v4
	v_exp_f32_e32 v13, v13
	v_mul_f32_e32 v23, v22, v22
	v_fmamk_f32 v23, v23, 0xbdd2d3e7, v129
	v_mul_f32_e32 v23, v23, v22
	v_add_f32_e32 v13, 1.0, v13
	v_rcp_f32_e32 v13, v13
	v_exp_f32_e32 v23, v23
	v_or_b32_e32 v87, 22, v34
	v_lshlrev_b32_e32 v24, 2, v87
	v_fma_f32 v3, v13, v3, -v19
	v_add_f32_e32 v13, 1.0, v23
	global_load_dword v82, v24, s[16:17]
	global_load_dword v83, v24, s[20:21]
	v_or_b32_e32 v88, 23, v34
	v_rcp_f32_e32 v13, v13
	v_and_b32_e32 v4, 0xffff0000, v4
	v_lshlrev_b32_e32 v24, 2, v88
	v_mul_f32_e32 v23, v4, v4
	global_load_dword v84, v24, s[16:17]
	global_load_dword v85, v24, s[20:21]
	v_fmamk_f32 v23, v23, 0xbdd2d3e7, v129
	v_mul_f32_e32 v23, v23, v4
	v_fma_f32 v13, v13, v22, -v19
	v_lshlrev_b32_e32 v22, 2, v90
	global_load_dword v91, v22, s[16:17]
	global_load_dword v92, v22, s[20:21]
	v_or_b32_e32 v93, 27, v34
	v_exp_f32_e32 v23, v23
	v_lshlrev_b32_e32 v22, 2, v93
	global_load_dword v94, v22, s[16:17]
	global_load_dword v95, v22, s[20:21]
	v_lshlrev_b32_e32 v96, 16, v5
	v_lshlrev_b32_e32 v22, 2, v97
	global_load_dword v98, v22, s[16:17]
	global_load_dword v99, v22, s[20:21]
	v_mul_f32_e32 v22, 0x3d372713, v96
	v_mul_f32_e32 v89, v39, v13
	v_add_f32_e32 v13, 1.0, v23
	v_lshlrev_b32_e32 v23, 2, v100
	v_mul_f32_e32 v22, v22, v96
	global_load_dword v101, v23, s[16:17]
	global_load_dword v102, v23, s[20:21]
	v_fma_f32 v22, v22, v96, v96
	v_mul_f32_e32 v22, 0xbfcc422a, v22
	v_mul_f32_e32 v103, 0x3fb8aa3b, v22
	global_load_dwordx4 v[22:25], v[6:7], off offset:16
	global_load_dwordx4 v[44:47], v[6:7], off
	v_rcp_f32_e32 v13, v13
	v_exp_f32_e32 v103, v103
	v_mul_f32_e32 v5, v104, v104
	v_fmamk_f32 v5, v5, 0xbdd2d3e7, v129
	v_mul_f32_e32 v5, v5, v104
	v_fma_f32 v4, v13, v4, -v19
	v_add_f32_e32 v13, 1.0, v103
	v_rcp_f32_e32 v13, v13
	v_exp_f32_e32 v5, v5
	v_mul_f32_e32 v105, v39, v4
	v_cvt_pk_bf16_f32 v11, v11, s0
	v_fma_f32 v4, v13, v96, -v19
	v_add_f32_e32 v5, 1.0, v5
	v_rcp_f32_e32 v103, v5
	v_fmac_f32_e32 v27, v15, v12
	v_mul_f32_e32 v5, v39, v4
	v_fma_f32 v16, v16, v89, v20
	v_fma_f32 v4, v103, v104, -v19
	v_mul_u32_u24_e32 v19, 0x110, v87
	v_add3_u32 v19, s15, v19, v33
	v_cvt_pk_bf16_f32 v16, v16, s0
	v_fmac_f32_e32 v21, v105, v17
	v_mul_f32_e32 v2, v39, v2
	v_mul_f32_e32 v3, v39, v3
	v_mul_f32_e32 v4, v39, v4
	v_mul_u32_u24_e32 v17, 0x110, v90
	v_add3_u32 v17, s15, v17, v33
	v_readlane_b32 s44, v251, 58
	v_readlane_b32 s45, v251, 59
	v_readlane_b32 s50, v252, 0
	v_readlane_b32 s51, v252, 1
	s_waitcnt vmcnt(16)
	v_fmac_f32_e32 v14, v26, v53
	v_cvt_pk_bf16_f32 v13, v14, s0
	v_mul_u32_u24_e32 v14, 0x110, v81
	v_add3_u32 v14, s15, v14, v33
	ds_write_b16 v14, v13 offset:34816
	s_waitcnt vmcnt(14)
	v_fmac_f32_e32 v55, v54, v52
	v_mul_u32_u24_e32 v14, 0x110, v86
	v_cvt_pk_bf16_f32 v13, v55, s0
	v_add3_u32 v14, s15, v14, v33
	ds_write_b16 v14, v13 offset:34816
	ds_write_b16 v18, v11 offset:49776
	v_cvt_pk_bf16_f32 v11, v27, s0
	ds_write_b16 v18, v11 offset:50048
	global_load_dwordx4 v[12:15], v[6:7], off offset:48
	global_load_dwordx4 v[52:55], v[6:7], off offset:32
	v_readlane_b32 s52, v252, 2
	v_readlane_b32 s53, v252, 3
	v_readlane_b32 s54, v252, 4
	s_waitcnt vmcnt(14)
	v_fmac_f32_e32 v83, v58, v82
	v_cvt_pk_bf16_f32 v11, v83, s0
	ds_write_b16 v19, v11 offset:34816
	v_mul_u32_u24_e32 v19, 0x110, v88
	v_add3_u32 v19, s15, v19, v33
	v_or_b32_e32 v58, 35, v34
	s_waitcnt vmcnt(12)
	v_fmac_f32_e32 v85, v56, v84
	v_cvt_pk_bf16_f32 v11, v85, s0
	v_or_b32_e32 v56, 34, v34
	ds_write_b16 v19, v11 offset:34816
	v_lshlrev_b32_e32 v11, 2, v56
	v_lshlrev_b32_e32 v19, 2, v58
	global_load_dword v39, v11, s[16:17]
	s_nop 0
	global_load_dword v11, v11, s[20:21]
	s_nop 0
	global_load_dword v89, v19, s[16:17]
	global_load_dword v96, v19, s[20:21]
	ds_write_b16 v18, v16 offset:50864
	v_cvt_pk_bf16_f32 v16, v21, s0
	s_waitcnt vmcnt(14)
	v_fmac_f32_e32 v92, v91, v64
	ds_write_b16 v18, v16 offset:51136
	v_cvt_pk_bf16_f32 v16, v92, s0
	ds_write_b16 v17, v16 offset:34816
	s_waitcnt vmcnt(12)
	v_fmac_f32_e32 v95, v94, v63
	v_mul_u32_u24_e32 v17, 0x110, v93
	v_cvt_pk_bf16_f32 v16, v95, s0
	v_add3_u32 v17, s15, v17, v33
	ds_write_b16 v17, v16 offset:34816
	s_waitcnt vmcnt(10)
	v_fmac_f32_e32 v99, v69, v98
	v_mul_u32_u24_e32 v17, 0x110, v97
	v_cvt_pk_bf16_f32 v16, v99, s0
	v_add3_u32 v17, s15, v17, v33
	ds_write_b16 v17, v16 offset:34816
	s_waitcnt vmcnt(8)
	v_fmac_f32_e32 v102, v68, v101
	v_mul_u32_u24_e32 v17, 0x110, v100
	v_cvt_pk_bf16_f32 v16, v102, s0
	v_add3_u32 v17, s15, v17, v33
	ds_write_b16 v17, v16 offset:34816
	s_waitcnt vmcnt(6)
	v_cndmask_b32_e32 v16, 0, v45, vcc
	v_cmp_le_u32_e32 vcc, v34, v31
	v_or_b32_e32 v63, 38, v34
	v_or_b32_e32 v69, 39, v34
	v_cndmask_b32_e32 v17, 0, v44, vcc
	v_cvt_pk_bf16_f32 v16, v17, v16
	v_lshlrev_b32_e32 v17, 2, v63
	global_load_dword v64, v17, s[16:17]
	global_load_dword v68, v17, s[20:21]
	v_lshlrev_b32_e32 v18, 2, v69
	global_load_dword v91, v18, s[16:17]
	global_load_dword v92, v18, s[20:21]
	v_cvt_pk_bf16_f32 v17, v46, v47
	v_cmp_le_u32_e32 vcc, v76, v31
	global_load_dwordx4 v[44:47], v[6:7], off offset:80
	global_load_dwordx4 v[82:85], v[6:7], off offset:64
	v_cndmask_b32_e32 v18, 0, v17, vcc
	v_lshrrev_b32_e32 v17, 16, v17
	v_cmp_le_u32_e32 vcc, v77, v31
	v_or_b32_e32 v76, 47, v34
	v_readlane_b32 s55, v252, 5
	v_cndmask_b32_e32 v17, 0, v17, vcc
	v_cmp_gt_u32_e32 vcc, v31, v35
	v_perm_b32 v17, v17, v18, s19
	s_waitcnt vmcnt(8)
	v_fmac_f32_e32 v11, v39, v73
	v_cndmask_b32_e32 v18, 0, v23, vcc
	v_cmp_le_u32_e32 vcc, v35, v31
	v_cvt_pk_bf16_f32 v11, v11, s0
	v_or_b32_e32 v35, 42, v34
	v_cndmask_b32_e32 v19, 0, v22, vcc
	v_cvt_pk_bf16_f32 v18, v19, v18
	v_cvt_pk_bf16_f32 v19, v24, v25
	v_cmp_le_u32_e32 vcc, v65, v31
	s_waitcnt vmcnt(6)
	v_fmac_f32_e32 v96, v89, v72
	s_waitcnt vmcnt(4)
	v_fmac_f32_e32 v68, v71, v64
	v_cndmask_b32_e32 v20, 0, v19, vcc
	v_lshrrev_b32_e32 v19, 16, v19
	v_cmp_le_u32_e32 vcc, v78, v31
	s_waitcnt vmcnt(2)
	v_fmac_f32_e32 v92, v70, v91
	v_cndmask_b32_e32 v19, 0, v19, vcc
	v_perm_b32 v19, v19, v20, s19
	ds_write_b128 v0, v[16:19]
	global_load_dwordx4 v[20:23], v[6:7], off offset:112
	global_load_dwordx4 v[24:27], v[6:7], off offset:96
	v_cmp_gt_u32_e32 vcc, v31, v36
	s_nop 1
	v_cndmask_b32_e32 v16, 0, v53, vcc
	v_cmp_le_u32_e32 vcc, v36, v31
	s_nop 1
	v_cndmask_b32_e32 v17, 0, v52, vcc
	v_cvt_pk_bf16_f32 v16, v17, v16
	v_cvt_pk_bf16_f32 v17, v54, v55
	v_cmp_le_u32_e32 vcc, v80, v31
	v_or_b32_e32 v54, 43, v34
	v_lshlrev_b32_e32 v19, 2, v54
	v_cndmask_b32_e32 v18, 0, v17, vcc
	v_lshrrev_b32_e32 v17, 16, v17
	v_cmp_le_u32_e32 vcc, v79, v31
	s_nop 1
	v_cndmask_b32_e32 v17, 0, v17, vcc
	v_perm_b32 v17, v17, v18, s19
	v_mul_u32_u24_e32 v18, 0x110, v56
	v_add3_u32 v18, s15, v18, v33
	ds_write_b16 v18, v11 offset:34816
	v_lshlrev_b32_e32 v18, 2, v35
	global_load_dword v52, v18, s[16:17]
	global_load_dword v53, v18, s[20:21]
	v_mul_u32_u24_e32 v18, 0x110, v58
	v_cvt_pk_bf16_f32 v11, v96, s0
	v_add3_u32 v18, s15, v18, v33
	v_cmp_gt_u32_e32 vcc, v31, v37
	global_load_dword v55, v19, s[16:17]
	global_load_dword v65, v19, s[20:21]
	ds_write_b16 v18, v11 offset:34816
	v_cndmask_b32_e32 v11, 0, v13, vcc
	v_cmp_le_u32_e32 vcc, v37, v31
	s_waitcnt vmcnt(2)
	v_fmac_f32_e32 v53, v52, v67
	v_cndmask_b32_e32 v12, 0, v12, vcc
	v_cvt_pk_bf16_f32 v18, v12, v11
	v_cvt_pk_bf16_f32 v11, v14, v15
	v_cmp_le_u32_e32 vcc, v59, v31
	v_or_b32_e32 v59, 46, v34
	s_waitcnt vmcnt(0)
	v_fmac_f32_e32 v65, v55, v66
	v_cndmask_b32_e32 v12, 0, v11, vcc
	v_lshrrev_b32_e32 v11, 16, v11
	v_cmp_le_u32_e32 vcc, v10, v31
	v_or_b32_e32 v52, 54, v34
	s_nop 0
	v_cndmask_b32_e32 v10, 0, v11, vcc
	v_perm_b32 v19, v10, v12, s19
	v_lshlrev_b32_e32 v10, 2, v59
	global_load_dword v72, v10, s[16:17]
	global_load_dword v73, v10, s[20:21]
	ds_write_b128 v0, v[16:19] offset:16
	v_lshlrev_b32_e32 v10, 2, v76
	v_mul_u32_u24_e32 v11, 0x110, v63
	global_load_dword v77, v10, s[16:17]
	global_load_dword v78, v10, s[20:21]
	v_cvt_pk_bf16_f32 v10, v68, s0
	v_add3_u32 v11, s15, v11, v33
	ds_write_b16 v11, v10 offset:34816
	global_load_dwordx4 v[10:13], v[6:7], off offset:144
	global_load_dwordx4 v[14:17], v[6:7], off offset:128
	v_mul_u32_u24_e32 v19, 0x110, v69
	v_cvt_pk_bf16_f32 v18, v92, s0
	v_add3_u32 v19, s15, v19, v33
	v_cmp_gt_u32_e32 vcc, v31, v38
	ds_write_b16 v19, v18 offset:34816
	s_waitcnt vmcnt(4)
	v_fmac_f32_e32 v73, v75, v72
	v_cndmask_b32_e32 v18, 0, v83, vcc
	v_cmp_le_u32_e32 vcc, v38, v31
	s_waitcnt vmcnt(2)
	v_fmac_f32_e32 v78, v74, v77
	v_cndmask_b32_e32 v19, 0, v82, vcc
	v_cvt_pk_bf16_f32 v36, v19, v18
	v_cvt_pk_bf16_f32 v18, v84, v85
	v_cmp_le_u32_e32 vcc, v81, v31
	s_nop 1
	v_cndmask_b32_e32 v19, 0, v18, vcc
	v_lshrrev_b32_e32 v18, 16, v18
	v_cmp_le_u32_e32 vcc, v86, v31
	s_nop 1
	v_cndmask_b32_e32 v18, 0, v18, vcc
	v_cmp_gt_u32_e32 vcc, v31, v40
	v_perm_b32 v37, v18, v19, s19
	s_nop 0
	v_cndmask_b32_e32 v18, 0, v45, vcc
	v_cmp_le_u32_e32 vcc, v40, v31
	s_nop 1
	v_cndmask_b32_e32 v19, 0, v44, vcc
	v_cvt_pk_bf16_f32 v38, v19, v18
	v_cvt_pk_bf16_f32 v18, v46, v47
	v_cmp_le_u32_e32 vcc, v87, v31
	s_nop 1
	v_cndmask_b32_e32 v19, 0, v18, vcc
	v_lshrrev_b32_e32 v18, 16, v18
	v_cmp_le_u32_e32 vcc, v88, v31
	s_nop 1
	v_cndmask_b32_e32 v18, 0, v18, vcc
	v_cmp_gt_u32_e32 vcc, v31, v41
	v_perm_b32 v39, v18, v19, s19
	ds_write_b128 v0, v[36:39] offset:32
	v_cndmask_b32_e32 v18, 0, v25, vcc
	v_cmp_le_u32_e32 vcc, v41, v31
	v_mul_u32_u24_e32 v41, 0x110, v35
	v_add3_u32 v41, s15, v41, v33
	v_cndmask_b32_e32 v19, 0, v24, vcc
	v_cvt_pk_bf16_f32 v18, v19, v18
	v_cvt_pk_bf16_f32 v19, v26, v27
	global_load_dwordx4 v[24:27], v[6:7], off offset:176
	global_load_dwordx4 v[36:39], v[6:7], off offset:160
	v_cmp_le_u32_e32 vcc, v90, v31
	s_nop 1
	v_cndmask_b32_e32 v40, 0, v19, vcc
	v_lshrrev_b32_e32 v19, 16, v19
	v_cmp_le_u32_e32 vcc, v93, v31
	s_nop 1
	v_cndmask_b32_e32 v19, 0, v19, vcc
	v_cmp_gt_u32_e32 vcc, v31, v42
	v_perm_b32 v19, v19, v40, s19
	v_cvt_pk_bf16_f32 v40, v53, s0
	v_cndmask_b32_e32 v21, 0, v21, vcc
	v_cmp_le_u32_e32 vcc, v42, v31
	ds_write_b16 v41, v40 offset:34816
	v_mul_u32_u24_e32 v41, 0x110, v54
	v_cndmask_b32_e32 v20, 0, v20, vcc
	v_cvt_pk_bf16_f32 v20, v20, v21
	v_cvt_pk_bf16_f32 v21, v22, v23
	v_cmp_le_u32_e32 vcc, v97, v31
	v_cvt_pk_bf16_f32 v40, v65, s0
	v_add3_u32 v41, s15, v41, v33
	v_cndmask_b32_e32 v22, 0, v21, vcc
	v_lshrrev_b32_e32 v21, 16, v21
	v_cmp_le_u32_e32 vcc, v100, v31
	ds_write_b16 v41, v40 offset:34816
	v_mul_u32_u24_e32 v23, 0x110, v76
	v_cndmask_b32_e32 v21, 0, v21, vcc
	v_perm_b32 v21, v21, v22, s19
	ds_write_b128 v0, v[18:21] offset:48
	v_mul_u32_u24_e32 v19, 0x110, v59
	v_cvt_pk_bf16_f32 v18, v73, s0
	v_add3_u32 v19, s15, v19, v33
	v_cmp_gt_u32_e32 vcc, v31, v43
	ds_write_b16 v19, v18 offset:34816
	v_cvt_pk_bf16_f32 v22, v78, s0
	v_add3_u32 v23, s15, v23, v33
	s_waitcnt vmcnt(2)
	v_cndmask_b32_e32 v15, 0, v15, vcc
	v_cmp_le_u32_e32 vcc, v43, v31
	global_load_dwordx4 v[18:21], v[6:7], off offset:208
	global_load_dwordx4 v[44:47], v[6:7], off offset:192
	ds_write_b16 v23, v22 offset:34816
	v_cndmask_b32_e32 v14, 0, v14, vcc
	v_or_b32_e32 v23, 50, v34
	v_cvt_pk_bf16_f32 v14, v14, v15
	v_cvt_pk_bf16_f32 v15, v16, v17
	v_or_b32_e32 v22, 51, v34
	v_lshlrev_b32_e32 v17, 2, v23
	v_cmp_le_u32_e32 vcc, v56, v31
	global_load_dword v40, v17, s[16:17]
	global_load_dword v41, v17, s[20:21]
	v_lshlrev_b32_e32 v17, 2, v22
	v_cndmask_b32_e32 v16, 0, v15, vcc
	v_lshrrev_b32_e32 v15, 16, v15
	global_load_dword v42, v17, s[16:17]
	global_load_dword v43, v17, s[20:21]
	v_cmp_le_u32_e32 vcc, v58, v31
	s_waitcnt vmcnt(2)
	v_fmac_f32_e32 v41, v40, v62
	v_cndmask_b32_e32 v15, 0, v15, vcc
	v_cmp_gt_u32_e32 vcc, v31, v48
	v_perm_b32 v15, v15, v16, s19
	s_waitcnt vmcnt(0)
	v_fmac_f32_e32 v43, v42, v61
	v_cndmask_b32_e32 v11, 0, v11, vcc
	v_cmp_le_u32_e32 vcc, v48, v31
	v_or_b32_e32 v48, 55, v34
	s_nop 0
	v_cndmask_b32_e32 v10, 0, v10, vcc
	v_cvt_pk_bf16_f32 v16, v10, v11
	v_cvt_pk_bf16_f32 v10, v12, v13
	v_cmp_le_u32_e32 vcc, v63, v31
	s_nop 1
	v_cndmask_b32_e32 v11, 0, v10, vcc
	v_lshrrev_b32_e32 v10, 16, v10
	v_cmp_le_u32_e32 vcc, v69, v31
	s_nop 1
	v_cndmask_b32_e32 v10, 0, v10, vcc
	v_perm_b32 v17, v10, v11, s19
	v_lshlrev_b32_e32 v10, 2, v52
	global_load_dword v53, v10, s[16:17]
	global_load_dword v55, v10, s[20:21]
	v_lshlrev_b32_e32 v10, 2, v48
	global_load_dword v56, v10, s[16:17]
	global_load_dword v58, v10, s[20:21]
	v_cmp_gt_u32_e32 vcc, v31, v49
	ds_write_b128 v0, v[14:17] offset:64
	s_waitcnt vmcnt(2)
	v_fmac_f32_e32 v55, v9, v53
	v_cndmask_b32_e32 v10, 0, v37, vcc
	v_cmp_le_u32_e32 vcc, v49, v31
	v_or_b32_e32 v49, 58, v34
	v_cvt_pk_bf16_f32 v9, v55, s0
	v_cndmask_b32_e32 v11, 0, v36, vcc
	v_cvt_pk_bf16_f32 v10, v11, v10
	v_cvt_pk_bf16_f32 v11, v38, v39
	v_cmp_le_u32_e32 vcc, v35, v31
	global_load_dwordx4 v[14:17], v[6:7], off offset:240
	global_load_dwordx4 v[36:39], v[6:7], off offset:224
	v_cndmask_b32_e32 v12, 0, v11, vcc
	v_lshrrev_b32_e32 v11, 16, v11
	v_cmp_le_u32_e32 vcc, v54, v31
	v_or_b32_e32 v35, 59, v34
	s_waitcnt vmcnt(2)
	v_fmac_f32_e32 v58, v8, v56
	v_cndmask_b32_e32 v6, 0, v11, vcc
	v_perm_b32 v11, v6, v12, s19
	v_lshlrev_b32_e32 v6, 2, v49
	global_load_dword v54, v6, s[16:17]
	global_load_dword v63, v6, s[20:21]
	v_lshlrev_b32_e32 v6, 2, v35
	v_cmp_gt_u32_e32 vcc, v31, v51
	global_load_dword v64, v6, s[16:17]
	global_load_dword v65, v6, s[20:21]
	v_cndmask_b32_e32 v6, 0, v25, vcc
	v_cmp_le_u32_e32 vcc, v51, v31
	s_waitcnt vmcnt(2)
	v_fmac_f32_e32 v63, v54, v2
	v_cndmask_b32_e32 v7, 0, v24, vcc
	v_cvt_pk_bf16_f32 v12, v7, v6
	v_cvt_pk_bf16_f32 v6, v26, v27
	v_cmp_le_u32_e32 vcc, v59, v31
	v_mul_u32_u24_e32 v26, 0x110, v22
	v_cvt_pk_bf16_f32 v27, v41, s0
	v_cndmask_b32_e32 v7, 0, v6, vcc
	v_lshrrev_b32_e32 v6, 16, v6
	v_cmp_le_u32_e32 vcc, v76, v31
	v_add3_u32 v26, s15, v26, v33
	v_cvt_pk_bf16_f32 v2, v63, s0
	v_cndmask_b32_e32 v6, 0, v6, vcc
	v_perm_b32 v13, v6, v7, s19
	ds_write_b128 v0, v[10:13] offset:80
	v_or_b32_e32 v11, 62, v34
	v_or_b32_e32 v10, 63, v34
	v_lshlrev_b32_e32 v7, 2, v11
	global_load_dword v12, v7, s[16:17]
	global_load_dword v13, v7, s[20:21]
	v_lshlrev_b32_e32 v7, 2, v10
	global_load_dword v24, v7, s[16:17]
	global_load_dword v25, v7, s[20:21]
	v_cmp_gt_u32_e32 vcc, v31, v57
	s_waitcnt vmcnt(4)
	v_fmac_f32_e32 v65, v64, v3
	v_and_or_b32 v76, v30, 64, v32
	v_cndmask_b32_e32 v6, 0, v45, vcc
	v_cmp_le_u32_e32 vcc, v57, v31
	s_waitcnt vmcnt(2)
	v_fmac_f32_e32 v13, v5, v12
	v_cndmask_b32_e32 v7, 0, v44, vcc
	v_cvt_pk_bf16_f32 v6, v7, v6
	v_mul_u32_u24_e32 v7, 0x110, v23
	v_add3_u32 v7, s15, v7, v33
	ds_write_b16 v7, v27 offset:34816
	v_cvt_pk_bf16_f32 v7, v43, s0
	ds_write_b16 v26, v7 offset:34816
	v_cvt_pk_bf16_f32 v7, v46, v47
	v_cmp_le_u32_e32 vcc, v23, v31
	v_cvt_pk_bf16_f32 v5, v13, s0
	s_waitcnt vmcnt(0)
	v_fmac_f32_e32 v25, v4, v24
	v_cndmask_b32_e32 v23, 0, v7, vcc
	v_lshrrev_b32_e32 v7, 16, v7
	v_cmp_le_u32_e32 vcc, v22, v31
	s_nop 1
	v_cndmask_b32_e32 v7, 0, v7, vcc
	v_perm_b32 v7, v7, v23, s19
	v_cmp_gt_u32_e32 vcc, v31, v60
	ds_write_b64 v0, v[6:7] offset:96
	s_nop 0
	v_cndmask_b32_e32 v6, 0, v19, vcc
	v_cmp_le_u32_e32 vcc, v60, v31
	s_nop 1
	v_cndmask_b32_e32 v7, 0, v18, vcc
	v_cvt_pk_bf16_f32 v6, v7, v6
	v_mul_u32_u24_e32 v7, 0x110, v52
	v_add3_u32 v7, s15, v7, v33
	v_mul_u32_u24_e32 v18, 0x110, v48
	v_add3_u32 v18, s15, v18, v33
	ds_write_b16 v7, v9 offset:34816
	v_cvt_pk_bf16_f32 v7, v58, s0
	ds_write_b16 v18, v7 offset:34816
	v_cvt_pk_bf16_f32 v7, v20, v21
	v_cmp_le_u32_e32 vcc, v52, v31
	s_nop 1
	v_cndmask_b32_e32 v8, 0, v7, vcc
	v_lshrrev_b32_e32 v7, 16, v7
	v_cmp_le_u32_e32 vcc, v48, v31
	s_nop 1
	v_cndmask_b32_e32 v7, 0, v7, vcc
	v_perm_b32 v7, v7, v8, s19
	v_cmp_gt_u32_e32 vcc, v31, v29
	ds_write_b64 v0, v[6:7] offset:104
	v_mul_u32_u24_e32 v8, 0x110, v35
	v_cndmask_b32_e32 v6, 0, v37, vcc
	v_cmp_le_u32_e32 vcc, v29, v31
	v_add3_u32 v8, s15, v8, v33
	s_nop 0
	v_cndmask_b32_e32 v7, 0, v36, vcc
	v_cvt_pk_bf16_f32 v6, v7, v6
	v_mul_u32_u24_e32 v7, 0x110, v49
	v_add3_u32 v7, s15, v7, v33
	ds_write_b16 v7, v2 offset:34816
	v_cvt_pk_bf16_f32 v2, v65, s0
	ds_write_b16 v8, v2 offset:34816
	v_cvt_pk_bf16_f32 v2, v38, v39
	v_cmp_le_u32_e32 vcc, v49, v31
	s_nop 1
	v_cndmask_b32_e32 v3, 0, v2, vcc
	v_lshrrev_b32_e32 v2, 16, v2
	v_cmp_le_u32_e32 vcc, v35, v31
	s_nop 1
	v_cndmask_b32_e32 v2, 0, v2, vcc
	v_cmp_gt_u32_e32 vcc, v31, v28
	v_perm_b32 v7, v2, v3, s19
	ds_write_b64 v0, v[6:7] offset:112
	v_cndmask_b32_e32 v2, 0, v15, vcc
	v_cmp_le_u32_e32 vcc, v28, v31
	v_mul_u32_u24_e32 v6, 0x110, v10
	v_add3_u32 v6, s15, v6, v33
	v_cndmask_b32_e32 v3, 0, v14, vcc
	v_cvt_pk_bf16_f32 v2, v3, v2
	v_mul_u32_u24_e32 v3, 0x110, v11
	v_add3_u32 v3, s15, v3, v33
	ds_write_b16 v3, v5 offset:34816
	v_cvt_pk_bf16_f32 v3, v25, s0
	ds_write_b16 v6, v3 offset:34816
	v_cvt_pk_bf16_f32 v3, v16, v17
	v_cmp_le_u32_e32 vcc, v11, v31
	v_mul_u32_u24_e32 v7, 0x88, v76
	s_mov_b64 s[0:1], 0x1f000
	v_cndmask_b32_e32 v4, 0, v3, vcc
	v_lshrrev_b32_e32 v3, 16, v3
	v_cmp_le_u32_e32 vcc, v10, v31
	s_nop 1
	v_cndmask_b32_e32 v3, 0, v3, vcc
	v_perm_b32 v3, v3, v4, s19
	ds_write_b64 v0, v[2:3] offset:120
	v_bfe_u32 v0, v50, 4, 2
	v_and_b32_e32 v2, 0x4f, v50
	v_lshl_add_u32 v6, v0, 4, s15
	v_mul_u32_u24_e32 v2, 0x88, v2
	v_lshl_add_u32 v51, v2, 1, v6
	s_waitcnt lgkmcnt(0)
	s_barrier
	ds_read_b128 v[2:5], v51 offset:34816
	ds_read_b128 v[72:75], v51 offset:34880
	ds_read_b128 v[14:17], v51 offset:39168
	ds_read_b128 v[78:81], v51 offset:39232
	ds_read_b128 v[22:25], v51 offset:43520
	ds_read_b128 v[82:85], v51 offset:43584
	ds_read_b128 v[30:33], v51 offset:47872
	ds_read_b128 v[86:89], v51 offset:47936
	v_lshl_add_u32 v77, v7, 1, v6
	ds_read_b128 v[6:9], v77
	ds_read_b128 v[34:37], v77 offset:4352
	ds_read_b128 v[52:55], v77 offset:8704
	ds_read_b128 v[68:71], v77 offset:13056
	s_waitcnt lgkmcnt(3)
	v_mfma_f32_16x16x32_bf16 v[10:13], v[2:5], v[6:9], 0
	ds_read_b128 v[98:101], v51 offset:48000
	v_mfma_f32_16x16x32_bf16 v[18:21], v[14:17], v[6:9], 0
	v_mfma_f32_16x16x32_bf16 v[26:29], v[22:25], v[6:9], 0
	v_mfma_f32_16x16x32_bf16 v[6:9], v[30:33], v[6:9], 0
	s_waitcnt lgkmcnt(3)
	v_mfma_f32_16x16x32_bf16 v[38:41], v[2:5], v[34:37], 0
	v_mfma_f32_16x16x32_bf16 v[42:45], v[14:17], v[34:37], 0
	v_mfma_f32_16x16x32_bf16 v[46:49], v[22:25], v[34:37], 0
	v_mfma_f32_16x16x32_bf16 v[34:37], v[30:33], v[34:37], 0
	s_waitcnt lgkmcnt(2)
	v_mfma_f32_16x16x32_bf16 v[56:59], v[2:5], v[52:55], 0
	v_mfma_f32_16x16x32_bf16 v[60:63], v[14:17], v[52:55], 0
	v_mfma_f32_16x16x32_bf16 v[64:67], v[22:25], v[52:55], 0
	v_mfma_f32_16x16x32_bf16 v[52:55], v[30:33], v[52:55], 0
	s_waitcnt lgkmcnt(1)
	v_mfma_f32_16x16x32_bf16 v[2:5], v[2:5], v[68:71], 0
	v_mfma_f32_16x16x32_bf16 v[14:17], v[14:17], v[68:71], 0
	v_mfma_f32_16x16x32_bf16 v[22:25], v[22:25], v[68:71], 0
	v_mfma_f32_16x16x32_bf16 v[30:33], v[30:33], v[68:71], 0
	ds_read_b128 v[68:71], v77 offset:64
	s_waitcnt lgkmcnt(0)
	v_mfma_f32_16x16x32_bf16 v[10:13], v[72:75], v[68:71], v[10:13]
	v_mfma_f32_16x16x32_bf16 v[18:21], v[78:81], v[68:71], v[18:21]
	v_mfma_f32_16x16x32_bf16 v[26:29], v[82:85], v[68:71], v[26:29]
	v_mfma_f32_16x16x32_bf16 v[6:9], v[86:89], v[68:71], v[6:9]
	ds_read_b128 v[68:71], v77 offset:4416
	s_waitcnt lgkmcnt(0)
	v_mfma_f32_16x16x32_bf16 v[38:41], v[72:75], v[68:71], v[38:41]
	v_mfma_f32_16x16x32_bf16 v[42:45], v[78:81], v[68:71], v[42:45]
	v_mfma_f32_16x16x32_bf16 v[46:49], v[82:85], v[68:71], v[46:49]
	v_mfma_f32_16x16x32_bf16 v[34:37], v[86:89], v[68:71], v[34:37]
	ds_read_b128 v[68:71], v77 offset:8768
	s_waitcnt lgkmcnt(0)
	v_mfma_f32_16x16x32_bf16 v[90:93], v[78:81], v[68:71], v[60:63]
	s_nop 2
	ds_read_b128 v[60:63], v77 offset:13120
	v_mfma_f32_16x16x32_bf16 v[56:59], v[72:75], v[68:71], v[56:59]
	v_mfma_f32_16x16x32_bf16 v[94:97], v[82:85], v[68:71], v[64:67]
	v_mfma_f32_16x16x32_bf16 v[52:55], v[86:89], v[68:71], v[52:55]
	s_nop 1
	ds_read_b128 v[66:69], v51 offset:34944
	s_waitcnt lgkmcnt(1)
	v_mfma_f32_16x16x32_bf16 v[2:5], v[72:75], v[60:63], v[2:5]
	v_mfma_f32_16x16x32_bf16 v[70:73], v[86:89], v[60:63], v[30:33]
	s_nop 2
	ds_read_b128 v[30:33], v77 offset:128
	v_mfma_f32_16x16x32_bf16 v[14:17], v[78:81], v[60:63], v[14:17]
	s_waitcnt lgkmcnt(0)
	v_mfma_f32_16x16x32_bf16 v[78:81], v[66:69], v[30:33], v[10:13]
	s_nop 2
	ds_read_b128 v[10:13], v51 offset:39296
	v_mfma_f32_16x16x32_bf16 v[22:25], v[82:85], v[60:63], v[22:25]
	v_mfma_f32_16x16x32_bf16 v[102:105], v[98:101], v[30:33], v[6:9]
	s_nop 2
	ds_read_b128 v[6:9], v77 offset:4480
	s_waitcnt lgkmcnt(1)
	v_mfma_f32_16x16x32_bf16 v[82:85], v[10:13], v[30:33], v[18:21]
	s_nop 2
	ds_read_b128 v[18:21], v51 offset:43648
	s_waitcnt lgkmcnt(1)
	v_mfma_f32_16x16x32_bf16 v[106:109], v[66:69], v[6:9], v[38:41]
	v_mfma_f32_16x16x32_bf16 v[110:113], v[10:13], v[6:9], v[42:45]
	s_waitcnt lgkmcnt(0)
	v_mfma_f32_16x16x32_bf16 v[114:117], v[18:21], v[6:9], v[46:49]
	v_mfma_f32_16x16x32_bf16 v[62:65], v[98:101], v[6:9], v[34:37]
	ds_read_b128 v[6:9], v77 offset:8832
	s_waitcnt lgkmcnt(0)
	v_mfma_f32_16x16x32_bf16 v[42:45], v[98:101], v[6:9], v[52:55]
	s_nop 2
	ds_read_b128 v[52:55], v77 offset:13184
	v_mfma_f32_16x16x32_bf16 v[86:89], v[18:21], v[30:33], v[26:29]
	ds_read_b128 v[30:33], v51 offset:35008
	s_waitcnt lgkmcnt(1)
	v_mfma_f32_16x16x32_bf16 v[26:29], v[66:69], v[52:55], v[2:5]
	v_mfma_f32_16x16x32_bf16 v[2:5], v[18:21], v[52:55], v[22:25]
	s_nop 2
	v_and_b32_e32 v22, 64, v50
	v_mfma_f32_16x16x32_bf16 v[38:41], v[66:69], v[6:9], v[56:59]
	v_lshlrev_b32_e32 v66, 3, v0
	v_lshlrev_b32_e32 v0, 1, v22
	v_or_b32_e32 v24, s4, v76
	v_lshl_add_u64 v[22:23], s[6:7], 0, v[0:1]
	v_mov_b32_e32 v67, v1
	v_mfma_f32_16x16x32_bf16 v[34:37], v[10:13], v[6:9], v[90:93]
	v_lshl_add_u64 v[22:23], v[22:23], 0, v[66:67]
	v_lshlrev_b32_e32 v76, 2, v76
	s_mov_b32 s4, 0x3e000
	v_mfma_f32_16x16x32_bf16 v[46:49], v[18:21], v[6:9], v[94:97]
	v_mfma_f32_16x16x32_bf16 v[6:9], v[10:13], v[52:55], v[14:17]
	v_mfma_f32_16x16x32_bf16 v[10:13], v[98:101], v[52:55], v[70:73]
	ds_read_b128 v[52:55], v77 offset:192
	s_nop 0
	ds_read_b128 v[14:17], v51 offset:39360
	ds_read_b128 v[18:21], v51 offset:43712
	v_mul_u32_u24_e32 v72, 0x1f00, v24
	v_mov_b32_e32 v73, v1
	v_lshl_add_u64 v[68:69], v[22:23], 0, v[72:73]
	global_load_dwordx2 v[98:99], v[68:69], off
	global_load_dwordx2 v[100:101], v[68:69], off offset:32
	ds_read_b128 v[94:97], v77 offset:4544
	s_waitcnt lgkmcnt(0)
	v_mfma_f32_16x16x32_bf16 v[58:61], v[30:33], v[94:97], v[106:109]
	s_nop 2
	global_load_dword v106, v76, s[12:13]
	ds_read_b128 v[22:25], v51 offset:48064
	v_lshl_add_u64 v[72:73], s[46:47], 0, v[72:73]
	s_waitcnt lgkmcnt(0)
	v_mfma_f32_16x16x32_bf16 v[90:93], v[22:25], v[52:55], v[102:105]
	s_nop 2
	global_load_dwordx2 v[102:103], v[68:69], off offset:64
	global_load_dwordx2 v[104:105], v[68:69], off offset:96
	v_lshl_add_u64 v[72:73], v[72:73], 0, s[8:9]
	v_lshl_add_u64 v[72:73], v[72:73], 0, v[0:1]
	v_mfma_f32_16x16x32_bf16 v[78:81], v[30:33], v[52:55], v[78:81]
	v_lshl_add_u64 v[66:67], v[72:73], 0, v[66:67]
	v_add_co_u32_e32 v70, vcc, s2, v68
	v_mfma_f32_16x16x32_bf16 v[82:85], v[14:17], v[52:55], v[82:85]
	s_nop 0
	v_addc_co_u32_e32 v71, vcc, 0, v69, vcc
	s_waitcnt vmcnt(4)
	v_lshlrev_b32_e32 v107, 16, v98
	v_and_b32_e32 v98, 0xffff0000, v98
	v_mul_f32_e32 v75, v98, v98
	v_mul_f32_e32 v74, v107, v107
	v_fmamk_f32 v75, v75, 0xbdd2d3e7, v129
	v_fmamk_f32 v74, v74, 0xbdd2d3e7, v129
	v_mul_f32_e32 v75, v75, v98
	v_mul_f32_e32 v74, v74, v107
	v_exp_f32_e32 v108, v75
	v_exp_f32_e32 v74, v74
	s_waitcnt vmcnt(2)
	v_add_f32_e32 v79, v79, v106
	v_add_f32_e32 v78, v78, v106
	v_add_f32_e32 v108, 1.0, v108
	v_add_f32_e32 v74, 1.0, v74
	v_rcp_f32_e32 v108, v108
	v_rcp_f32_e32 v109, v74
	v_add_f32_e32 v80, v80, v106
	v_add_f32_e32 v81, v81, v106
	v_mul_f32_e32 v98, v108, v98
	v_mul_f32_e32 v107, v109, v107
	v_mul_f32_e32 v79, v98, v79
	v_lshlrev_b32_e32 v98, 16, v99
	v_and_b32_e32 v99, 0xffff0000, v99
	v_mul_f32_e32 v78, v107, v78
	v_mul_f32_e32 v107, v98, v98
	v_mul_f32_e32 v108, v99, v99
	v_fmamk_f32 v107, v107, 0xbdd2d3e7, v129
	v_fmamk_f32 v108, v108, 0xbdd2d3e7, v129
	v_mul_f32_e32 v107, v107, v98
	v_mul_f32_e32 v108, v108, v99
	v_exp_f32_e32 v107, v107
	v_exp_f32_e32 v108, v108
	v_cvt_pk_bf16_f32 v78, v78, v79
	v_lshlrev_b32_e32 v0, 16, v100
	v_add_f32_e32 v107, 1.0, v107
	v_add_f32_e32 v79, 1.0, v108
	v_rcp_f32_e32 v107, v107
	v_rcp_f32_e32 v79, v79
	v_mul_f32_e32 v72, v0, v0
	v_and_b32_e32 v73, 0xffff0000, v100
	v_mul_f32_e32 v98, v107, v98
	v_mul_f32_e32 v79, v79, v99
	v_mul_f32_e32 v80, v98, v80
	v_mul_f32_e32 v79, v79, v81
	v_cvt_pk_bf16_f32 v79, v80, v79
	v_fmamk_f32 v72, v72, 0xbdd2d3e7, v129
	v_mul_f32_e32 v80, v73, v73
	v_mul_f32_e32 v72, v72, v0
	v_fmamk_f32 v80, v80, 0xbdd2d3e7, v129
	v_mul_f32_e32 v80, v80, v73
	v_exp_f32_e32 v72, v72
	v_exp_f32_e32 v80, v80
	global_store_dwordx2 v[66:67], v[78:79], off
	v_add_f32_e32 v72, 1.0, v72
	v_rcp_f32_e32 v72, v72
	v_add_f32_e32 v78, 1.0, v80
	v_rcp_f32_e32 v78, v78
	v_and_b32_e32 v79, 0xffff0000, v101
	v_mul_f32_e32 v0, v72, v0
	v_add_f32_e32 v72, v82, v106
	v_mul_f32_e32 v0, v0, v72
	v_mul_f32_e32 v72, v78, v73
	v_add_f32_e32 v73, v83, v106
	v_mul_f32_e32 v72, v72, v73
	v_lshlrev_b32_e32 v73, 16, v101
	v_mul_f32_e32 v78, v73, v73
	v_fmamk_f32 v78, v78, 0xbdd2d3e7, v129
	v_mul_f32_e32 v80, v79, v79
	v_mul_f32_e32 v78, v78, v73
	v_fmamk_f32 v80, v80, 0xbdd2d3e7, v129
	v_mul_f32_e32 v80, v80, v79
	v_exp_f32_e32 v78, v78
	v_exp_f32_e32 v80, v80
	v_cvt_pk_bf16_f32 v72, v0, v72
	v_add_f32_e32 v78, 1.0, v78
	v_rcp_f32_e32 v78, v78
	v_add_f32_e32 v0, 1.0, v80
	v_rcp_f32_e32 v0, v0
	v_mfma_f32_16x16x32_bf16 v[86:89], v[18:21], v[52:55], v[86:89]
	v_mul_f32_e32 v73, v78, v73
	v_add_f32_e32 v78, v84, v106
	v_mul_f32_e32 v73, v73, v78
	v_mul_f32_e32 v0, v0, v79
	v_add_f32_e32 v78, v85, v106
	v_mul_f32_e32 v0, v0, v78
	v_cvt_pk_bf16_f32 v73, v73, v0
	s_waitcnt vmcnt(2)
	v_lshlrev_b32_e32 v0, 16, v102
	v_mul_f32_e32 v78, v0, v0
	v_and_b32_e32 v79, 0xffff0000, v102
	v_fmamk_f32 v78, v78, 0xbdd2d3e7, v129
	v_mul_f32_e32 v80, v79, v79
	v_mul_f32_e32 v78, v78, v0
	v_fmamk_f32 v80, v80, 0xbdd2d3e7, v129
	v_mul_f32_e32 v80, v80, v79
	v_exp_f32_e32 v78, v78
	v_exp_f32_e32 v80, v80
	global_store_dwordx2 v[66:67], v[72:73], off offset:32
	v_add_f32_e32 v78, 1.0, v78
	v_rcp_f32_e32 v78, v78
	v_add_f32_e32 v72, 1.0, v80
	v_rcp_f32_e32 v72, v72
	v_add_f32_e32 v73, v86, v106
	v_mul_f32_e32 v0, v78, v0
	v_mul_f32_e32 v0, v0, v73
	v_mul_f32_e32 v72, v72, v79
	v_add_f32_e32 v73, v87, v106
	v_mul_f32_e32 v72, v72, v73
	v_lshlrev_b32_e32 v73, 16, v103
	v_mul_f32_e32 v78, v73, v73
	v_and_b32_e32 v79, 0xffff0000, v103
	v_fmamk_f32 v78, v78, 0xbdd2d3e7, v129
	v_mul_f32_e32 v80, v79, v79
	v_mul_f32_e32 v78, v78, v73
	v_fmamk_f32 v80, v80, 0xbdd2d3e7, v129
	v_mul_f32_e32 v80, v80, v79
	v_exp_f32_e32 v78, v78
	v_exp_f32_e32 v80, v80
	v_cvt_pk_bf16_f32 v72, v0, v72
	v_add_f32_e32 v78, 1.0, v78
	v_rcp_f32_e32 v78, v78
	v_add_f32_e32 v0, 1.0, v80
	v_rcp_f32_e32 v0, v0
	global_load_dwordx2 v[74:75], v[70:71], off
	global_load_dwordx2 v[82:83], v[70:71], off offset:32
	v_mul_f32_e32 v73, v78, v73
	v_add_f32_e32 v78, v88, v106
	v_mul_f32_e32 v73, v73, v78
	v_mul_f32_e32 v0, v0, v79
	v_add_f32_e32 v78, v89, v106
	v_mul_f32_e32 v0, v0, v78
	v_cvt_pk_bf16_f32 v73, v73, v0
	s_waitcnt vmcnt(4)
	v_lshlrev_b32_e32 v0, 16, v104
	v_mul_f32_e32 v78, v0, v0
	v_and_b32_e32 v79, 0xffff0000, v104
	v_fmamk_f32 v78, v78, 0xbdd2d3e7, v129
	v_mul_f32_e32 v80, v79, v79
	v_mul_f32_e32 v78, v78, v0
	v_fmamk_f32 v80, v80, 0xbdd2d3e7, v129
	v_mul_f32_e32 v80, v80, v79
	v_exp_f32_e32 v78, v78
	v_exp_f32_e32 v80, v80
	global_store_dwordx2 v[66:67], v[72:73], off offset:64
	v_add_f32_e32 v78, 1.0, v78
	v_rcp_f32_e32 v78, v78
	v_add_f32_e32 v72, 1.0, v80
	v_rcp_f32_e32 v72, v72
	v_add_f32_e32 v73, v90, v106
	v_mul_f32_e32 v0, v78, v0
	v_mul_f32_e32 v0, v0, v73
	v_mul_f32_e32 v72, v72, v79
	v_add_f32_e32 v73, v91, v106
	v_mul_f32_e32 v72, v72, v73
	v_lshlrev_b32_e32 v73, 16, v105
	v_mul_f32_e32 v78, v73, v73
	v_and_b32_e32 v79, 0xffff0000, v105
	v_fmamk_f32 v78, v78, 0xbdd2d3e7, v129
	v_mul_f32_e32 v80, v79, v79
	v_mul_f32_e32 v78, v78, v73
	v_fmamk_f32 v80, v80, 0xbdd2d3e7, v129
	v_mul_f32_e32 v80, v80, v79
	v_exp_f32_e32 v78, v78
	v_exp_f32_e32 v80, v80
	v_cvt_pk_bf16_f32 v72, v0, v72
	v_add_f32_e32 v78, 1.0, v78
	v_rcp_f32_e32 v78, v78
	v_add_f32_e32 v0, 1.0, v80
	v_rcp_f32_e32 v0, v0
	v_mfma_f32_16x16x32_bf16 v[54:57], v[14:17], v[94:97], v[110:113]
	v_mul_f32_e32 v73, v78, v73
	v_add_f32_e32 v78, v92, v106
	v_mul_f32_e32 v73, v78, v73
	v_mul_f32_e32 v0, v0, v79
	v_add_f32_e32 v78, v93, v106
	v_mul_f32_e32 v0, v78, v0
	v_cvt_pk_bf16_f32 v73, v73, v0
	global_store_dwordx2 v[66:67], v[72:73], off offset:96
	global_load_dword v0, v76, s[12:13] offset:64
	ds_read_b128 v[78:81], v77 offset:8896
	global_load_dwordx2 v[84:85], v[70:71], off offset:64
	global_load_dwordx2 v[86:87], v[70:71], off offset:96
	v_add_co_u32_e32 v72, vcc, s4, v68
	v_mfma_f32_16x16x32_bf16 v[50:53], v[18:21], v[94:97], v[114:117]
	s_nop 0
	v_addc_co_u32_e32 v73, vcc, 0, v69, vcc
	s_waitcnt vmcnt(6)
	v_lshlrev_b32_e32 v88, 16, v74
	v_and_b32_e32 v74, 0xffff0000, v74
	v_mul_f32_e32 v71, v74, v74
	v_mul_f32_e32 v70, v88, v88
	v_fmamk_f32 v71, v71, 0xbdd2d3e7, v129
	v_fmamk_f32 v70, v70, 0xbdd2d3e7, v129
	v_mul_f32_e32 v71, v71, v74
	v_mul_f32_e32 v70, v70, v88
	v_exp_f32_e32 v89, v71
	v_exp_f32_e32 v70, v70
	v_mfma_f32_16x16x32_bf16 v[62:65], v[22:25], v[94:97], v[62:65]
	v_add_f32_e32 v89, 1.0, v89
	v_add_f32_e32 v70, 1.0, v70
	v_rcp_f32_e32 v89, v89
	v_rcp_f32_e32 v90, v70
	global_load_dwordx2 v[70:71], v[72:73], off
	s_waitcnt lgkmcnt(0)
	v_mfma_f32_16x16x32_bf16 v[38:41], v[30:33], v[78:81], v[38:41]
	v_mul_f32_e32 v74, v89, v74
	v_mul_f32_e32 v88, v90, v88
	s_waitcnt vmcnt(3)
	v_add_f32_e32 v59, v59, v0
	v_add_f32_e32 v58, v58, v0
	v_mul_f32_e32 v59, v74, v59
	v_lshlrev_b32_e32 v74, 16, v75
	v_mul_f32_e32 v58, v88, v58
	v_mul_f32_e32 v88, v74, v74
	v_fmamk_f32 v88, v88, 0xbdd2d3e7, v129
	v_mul_f32_e32 v88, v88, v74
	v_exp_f32_e32 v88, v88
	v_and_b32_e32 v75, 0xffff0000, v75
	v_mul_f32_e32 v89, v75, v75
	v_fmamk_f32 v89, v89, 0xbdd2d3e7, v129
	v_mul_f32_e32 v89, v89, v75
	v_add_f32_e32 v88, 1.0, v88
	v_rcp_f32_e32 v88, v88
	v_exp_f32_e32 v89, v89
	v_cvt_pk_bf16_f32 v58, v58, v59
	v_mul_f32_e32 v74, v88, v74
	v_lshlrev_b32_e32 v88, 16, v82
	v_and_b32_e32 v82, 0xffff0000, v82
	v_mul_f32_e32 v90, v82, v82
	v_add_f32_e32 v59, 1.0, v89
	v_mul_f32_e32 v89, v88, v88
	v_fmamk_f32 v90, v90, 0xbdd2d3e7, v129
	v_rcp_f32_e32 v59, v59
	v_fmamk_f32 v89, v89, 0xbdd2d3e7, v129
	v_mul_f32_e32 v90, v90, v82
	v_mul_f32_e32 v89, v89, v88
	v_exp_f32_e32 v90, v90
	v_add_f32_e32 v60, v60, v0
	v_mul_f32_e32 v59, v59, v75
	v_add_f32_e32 v61, v61, v0
	v_exp_f32_e32 v89, v89
	v_mul_f32_e32 v60, v74, v60
	v_mul_f32_e32 v59, v59, v61
	v_add_co_u32_e32 v74, vcc, s2, v66
	v_cvt_pk_bf16_f32 v59, v60, v59
	s_nop 0
	v_addc_co_u32_e32 v75, vcc, 0, v67, vcc
	global_store_dwordx2 v[74:75], v[58:59], off
	v_add_f32_e32 v58, 1.0, v90
	v_add_f32_e32 v89, 1.0, v89
	v_rcp_f32_e32 v58, v58
	v_rcp_f32_e32 v89, v89
	v_add_f32_e32 v55, v55, v0
	v_add_f32_e32 v54, v54, v0
	v_mul_f32_e32 v58, v58, v82
	v_mul_f32_e32 v59, v89, v88
	v_mul_f32_e32 v55, v58, v55
	v_lshlrev_b32_e32 v58, 16, v83
	v_and_b32_e32 v74, 0xffff0000, v83
	v_mul_f32_e32 v54, v59, v54
	v_mul_f32_e32 v59, v58, v58
	v_mul_f32_e32 v75, v74, v74
	v_fmamk_f32 v59, v59, 0xbdd2d3e7, v129
	v_fmamk_f32 v75, v75, 0xbdd2d3e7, v129
	v_mul_f32_e32 v59, v59, v58
	v_mul_f32_e32 v75, v75, v74
	v_exp_f32_e32 v59, v59
	v_exp_f32_e32 v75, v75
	v_cvt_pk_bf16_f32 v54, v54, v55
	v_add_f32_e32 v56, v56, v0
	v_add_f32_e32 v59, 1.0, v59
	v_add_f32_e32 v55, 1.0, v75
	v_rcp_f32_e32 v59, v59
	v_rcp_f32_e32 v55, v55
	v_add_f32_e32 v57, v57, v0
	v_lshl_add_u64 v[60:61], v[66:67], 0, s[0:1]
	v_mul_f32_e32 v58, v59, v58
	v_mul_f32_e32 v55, v55, v74
	v_mul_f32_e32 v56, v58, v56
	v_mul_f32_e32 v55, v55, v57
	s_waitcnt vmcnt(3)
	v_and_b32_e32 v58, 0xffff0000, v84
	v_cvt_pk_bf16_f32 v55, v56, v55
	v_lshlrev_b32_e32 v56, 16, v84
	v_mul_f32_e32 v59, v58, v58
	v_mul_f32_e32 v57, v56, v56
	v_fmamk_f32 v59, v59, 0xbdd2d3e7, v129
	v_fmamk_f32 v57, v57, 0xbdd2d3e7, v129
	v_mul_f32_e32 v59, v59, v58
	v_mul_f32_e32 v57, v57, v56
	v_exp_f32_e32 v59, v59
	v_exp_f32_e32 v57, v57
	global_store_dwordx2 v[60:61], v[54:55], off offset:32
	v_add_f32_e32 v51, v51, v0
	v_add_f32_e32 v54, 1.0, v59
	v_add_f32_e32 v57, 1.0, v57
	v_rcp_f32_e32 v54, v54
	v_rcp_f32_e32 v57, v57
	v_add_f32_e32 v50, v50, v0
	v_add_f32_e32 v52, v52, v0
	v_mul_f32_e32 v54, v54, v58
	v_mul_f32_e32 v55, v57, v56
	v_mul_f32_e32 v51, v54, v51
	v_lshlrev_b32_e32 v54, 16, v85
	v_and_b32_e32 v56, 0xffff0000, v85
	v_mul_f32_e32 v50, v55, v50
	v_mul_f32_e32 v55, v54, v54
	v_mul_f32_e32 v57, v56, v56
	v_fmamk_f32 v55, v55, 0xbdd2d3e7, v129
	v_fmamk_f32 v57, v57, 0xbdd2d3e7, v129
	v_mul_f32_e32 v55, v55, v54
	v_mul_f32_e32 v57, v57, v56
	v_exp_f32_e32 v55, v55
	v_exp_f32_e32 v57, v57
	v_cvt_pk_bf16_f32 v50, v50, v51
	v_add_f32_e32 v53, v53, v0
	v_add_f32_e32 v55, 1.0, v55
	v_add_f32_e32 v51, 1.0, v57
	v_rcp_f32_e32 v55, v55
	v_rcp_f32_e32 v51, v51
	s_mov_b32 s2, 0x5d000
	v_mfma_f32_16x16x32_bf16 v[34:37], v[14:17], v[78:81], v[34:37]
	v_mul_f32_e32 v54, v55, v54
	v_mul_f32_e32 v51, v51, v56
	v_mul_f32_e32 v52, v54, v52
	v_mul_f32_e32 v51, v51, v53
	v_cvt_pk_bf16_f32 v51, v52, v51
	s_waitcnt vmcnt(3)
	v_lshlrev_b32_e32 v52, 16, v86
	v_mul_f32_e32 v53, v52, v52
	v_and_b32_e32 v54, 0xffff0000, v86
	v_fmamk_f32 v53, v53, 0xbdd2d3e7, v129
	v_mul_f32_e32 v55, v54, v54
	v_mul_f32_e32 v53, v53, v52
	v_fmamk_f32 v55, v55, 0xbdd2d3e7, v129
	v_mul_f32_e32 v55, v55, v54
	v_exp_f32_e32 v53, v53
	v_exp_f32_e32 v55, v55
	global_store_dwordx2 v[60:61], v[50:51], off offset:64
	v_add_f32_e32 v53, 1.0, v53
	v_rcp_f32_e32 v53, v53
	v_add_f32_e32 v50, 1.0, v55
	v_rcp_f32_e32 v50, v50
	s_mov_b64 s[0:1], 0x3e000
	v_mul_f32_e32 v51, v53, v52
	v_add_f32_e32 v52, v62, v0
	v_mul_f32_e32 v51, v51, v52
	v_mul_f32_e32 v50, v50, v54
	v_add_f32_e32 v52, v63, v0
	v_mul_f32_e32 v50, v50, v52
	v_lshlrev_b32_e32 v52, 16, v87
	v_and_b32_e32 v54, 0xffff0000, v87
	v_mul_f32_e32 v53, v52, v52
	v_mul_f32_e32 v55, v54, v54
	v_fmamk_f32 v53, v53, 0xbdd2d3e7, v129
	v_fmamk_f32 v55, v55, 0xbdd2d3e7, v129
	v_mul_f32_e32 v53, v53, v52
	v_mul_f32_e32 v55, v55, v54
	v_exp_f32_e32 v53, v53
	v_exp_f32_e32 v55, v55
	v_cvt_pk_bf16_f32 v50, v51, v50
	v_mfma_f32_16x16x32_bf16 v[46:49], v[18:21], v[78:81], v[46:49]
	v_add_f32_e32 v53, 1.0, v53
	v_add_f32_e32 v51, 1.0, v55
	v_rcp_f32_e32 v53, v53
	v_rcp_f32_e32 v51, v51
	v_mfma_f32_16x16x32_bf16 v[42:45], v[22:25], v[78:81], v[42:45]
	v_mul_f32_e32 v52, v53, v52
	v_add_f32_e32 v53, v64, v0
	v_mul_f32_e32 v51, v51, v54
	v_add_f32_e32 v0, v65, v0
	v_mul_f32_e32 v52, v52, v53
	v_mul_f32_e32 v0, v51, v0
	v_cvt_pk_bf16_f32 v51, v52, v0
	global_store_dwordx2 v[60:61], v[50:51], off offset:96
	global_load_dword v0, v76, s[12:13] offset:128
	global_load_dwordx2 v[54:55], v[72:73], off offset:32
	ds_read_b128 v[50:53], v77 offset:13248
	global_load_dwordx2 v[56:57], v[72:73], off offset:64
	global_load_dwordx2 v[58:59], v[72:73], off offset:96
	s_waitcnt vmcnt(8)
	v_lshlrev_b32_e32 v60, 16, v70
	s_waitcnt lgkmcnt(0)
	v_mfma_f32_16x16x32_bf16 v[26:29], v[30:33], v[50:53], v[26:29]
	v_mul_f32_e32 v30, v60, v60
	v_and_b32_e32 v61, 0xffff0000, v70
	v_fmamk_f32 v30, v30, 0xbdd2d3e7, v129
	v_mul_f32_e32 v31, v61, v61
	v_mul_f32_e32 v30, v30, v60
	v_fmamk_f32 v31, v31, 0xbdd2d3e7, v129
	v_mul_f32_e32 v31, v31, v61
	v_exp_f32_e32 v30, v30
	v_exp_f32_e32 v62, v31
	v_add_co_u32_e32 v32, vcc, s2, v68
	v_add_f32_e32 v30, 1.0, v30
	v_rcp_f32_e32 v63, v30
	v_add_f32_e32 v62, 1.0, v62
	v_rcp_f32_e32 v62, v62
	v_addc_co_u32_e32 v33, vcc, 0, v69, vcc
	v_mul_f32_e32 v60, v63, v60
	global_load_dwordx2 v[30:31], v[32:33], off
	v_mfma_f32_16x16x32_bf16 v[6:9], v[14:17], v[50:53], v[6:9]
	global_load_dwordx2 v[14:15], v[32:33], off offset:32
	s_waitcnt vmcnt(5)
	v_add_f32_e32 v38, v38, v0
	v_mul_f32_e32 v38, v60, v38
	v_mul_f32_e32 v60, v62, v61
	v_and_b32_e32 v62, 0xffff0000, v71
	v_mul_f32_e32 v63, v62, v62
	v_fmamk_f32 v63, v63, 0xbdd2d3e7, v129
	v_mul_f32_e32 v63, v63, v62
	v_add_f32_e32 v39, v39, v0
	v_exp_f32_e32 v63, v63
	v_mul_f32_e32 v39, v60, v39
	v_lshlrev_b32_e32 v60, 16, v71
	v_mul_f32_e32 v61, v60, v60
	v_fmamk_f32 v61, v61, 0xbdd2d3e7, v129
	v_mul_f32_e32 v61, v61, v60
	v_cvt_pk_bf16_f32 v38, v38, v39
	v_add_f32_e32 v39, 1.0, v63
	v_rcp_f32_e32 v39, v39
	v_exp_f32_e32 v61, v61
	v_add_f32_e32 v40, v40, v0
	v_mul_f32_e32 v39, v39, v62
	s_waitcnt vmcnt(4)
	v_lshlrev_b32_e32 v62, 16, v54
	v_and_b32_e32 v54, 0xffff0000, v54
	v_mul_f32_e32 v64, v54, v54
	v_add_f32_e32 v61, 1.0, v61
	v_mul_f32_e32 v63, v62, v62
	v_fmamk_f32 v64, v64, 0xbdd2d3e7, v129
	v_rcp_f32_e32 v61, v61
	v_fmamk_f32 v63, v63, 0xbdd2d3e7, v129
	v_mul_f32_e32 v64, v64, v54
	v_mul_f32_e32 v63, v63, v62
	v_exp_f32_e32 v64, v64
	v_mul_f32_e32 v60, v61, v60
	v_add_f32_e32 v41, v41, v0
	v_exp_f32_e32 v63, v63
	v_mul_f32_e32 v40, v60, v40
	v_mul_f32_e32 v39, v39, v41
	v_add_co_u32_e32 v60, vcc, s4, v66
	v_cvt_pk_bf16_f32 v39, v40, v39
	s_nop 0
	v_addc_co_u32_e32 v61, vcc, 0, v67, vcc
	global_store_dwordx2 v[60:61], v[38:39], off
	v_add_f32_e32 v38, 1.0, v64
	v_add_f32_e32 v63, 1.0, v63
	v_rcp_f32_e32 v38, v38
	v_rcp_f32_e32 v63, v63
	v_add_f32_e32 v35, v35, v0
	v_add_f32_e32 v34, v34, v0
	v_mul_f32_e32 v38, v38, v54
	v_mul_f32_e32 v39, v63, v62
	v_mul_f32_e32 v35, v38, v35
	v_lshlrev_b32_e32 v38, 16, v55
	v_and_b32_e32 v54, 0xffff0000, v55
	v_mul_f32_e32 v34, v39, v34
	v_mul_f32_e32 v39, v38, v38
	v_mul_f32_e32 v55, v54, v54
	v_fmamk_f32 v39, v39, 0xbdd2d3e7, v129
	v_fmamk_f32 v55, v55, 0xbdd2d3e7, v129
	v_mul_f32_e32 v39, v39, v38
	v_mul_f32_e32 v55, v55, v54
	v_exp_f32_e32 v39, v39
	v_exp_f32_e32 v55, v55
	v_cvt_pk_bf16_f32 v34, v34, v35
	v_add_f32_e32 v36, v36, v0
	v_add_f32_e32 v39, 1.0, v39
	v_add_f32_e32 v35, 1.0, v55
	v_rcp_f32_e32 v39, v39
	v_rcp_f32_e32 v35, v35
	v_add_f32_e32 v37, v37, v0
	v_lshl_add_u64 v[40:41], v[66:67], 0, s[0:1]
	v_mul_f32_e32 v38, v39, v38
	v_mul_f32_e32 v35, v35, v54
	v_mul_f32_e32 v36, v38, v36
	v_mul_f32_e32 v35, v35, v37
	v_cvt_pk_bf16_f32 v35, v36, v35
	s_waitcnt vmcnt(4)
	v_lshlrev_b32_e32 v36, 16, v56
	v_mul_f32_e32 v37, v36, v36
	v_and_b32_e32 v38, 0xffff0000, v56
	v_fmamk_f32 v37, v37, 0xbdd2d3e7, v129
	v_mul_f32_e32 v39, v38, v38
	v_mul_f32_e32 v37, v37, v36
	v_fmamk_f32 v39, v39, 0xbdd2d3e7, v129
	v_mul_f32_e32 v39, v39, v38
	v_exp_f32_e32 v37, v37
	v_exp_f32_e32 v39, v39
	global_store_dwordx2 v[40:41], v[34:35], off offset:32
	v_add_f32_e32 v37, 1.0, v37
	v_rcp_f32_e32 v37, v37
	v_add_f32_e32 v34, 1.0, v39
	v_rcp_f32_e32 v34, v34
	v_mfma_f32_16x16x32_bf16 v[2:5], v[18:21], v[50:53], v[2:5]
	v_mul_f32_e32 v35, v37, v36
	v_add_f32_e32 v36, v46, v0
	v_mul_f32_e32 v35, v35, v36
	v_mul_f32_e32 v34, v34, v38
	v_add_f32_e32 v36, v47, v0
	v_mul_f32_e32 v34, v34, v36
	v_lshlrev_b32_e32 v36, 16, v57
	v_mul_f32_e32 v37, v36, v36
	v_and_b32_e32 v38, 0xffff0000, v57
	v_fmamk_f32 v37, v37, 0xbdd2d3e7, v129
	v_mul_f32_e32 v39, v38, v38
	v_mul_f32_e32 v37, v37, v36
	v_fmamk_f32 v39, v39, 0xbdd2d3e7, v129
	v_mul_f32_e32 v39, v39, v38
	v_exp_f32_e32 v37, v37
	v_exp_f32_e32 v39, v39
	v_cvt_pk_bf16_f32 v34, v35, v34
	v_add_f32_e32 v37, 1.0, v37
	v_rcp_f32_e32 v37, v37
	v_add_f32_e32 v35, 1.0, v39
	v_rcp_f32_e32 v35, v35
	s_waitcnt vmcnt(3)
	v_lshlrev_b32_e32 v20, 16, v30
	v_mul_f32_e32 v36, v37, v36
	v_add_f32_e32 v37, v48, v0
	v_mul_f32_e32 v36, v36, v37
	v_mul_f32_e32 v35, v35, v38
	v_add_f32_e32 v37, v49, v0
	v_mul_f32_e32 v35, v35, v37
	v_cvt_pk_bf16_f32 v35, v36, v35
	v_lshlrev_b32_e32 v36, 16, v58
	v_mul_f32_e32 v37, v36, v36
	v_and_b32_e32 v38, 0xffff0000, v58
	v_fmamk_f32 v37, v37, 0xbdd2d3e7, v129
	v_mul_f32_e32 v39, v38, v38
	v_mul_f32_e32 v37, v37, v36
	v_fmamk_f32 v39, v39, 0xbdd2d3e7, v129
	v_mul_f32_e32 v39, v39, v38
	v_exp_f32_e32 v37, v37
	v_exp_f32_e32 v39, v39
	global_store_dwordx2 v[40:41], v[34:35], off offset:64
	v_add_f32_e32 v37, 1.0, v37
	v_rcp_f32_e32 v37, v37
	v_add_f32_e32 v34, 1.0, v39
	v_rcp_f32_e32 v34, v34
	v_mul_f32_e32 v21, v20, v20
	v_mul_f32_e32 v35, v37, v36
	v_add_f32_e32 v36, v42, v0
	v_mul_f32_e32 v35, v35, v36
	v_mul_f32_e32 v34, v34, v38
	v_add_f32_e32 v36, v43, v0
	v_mul_f32_e32 v34, v34, v36
	v_lshlrev_b32_e32 v36, 16, v59
	v_and_b32_e32 v38, 0xffff0000, v59
	v_mul_f32_e32 v37, v36, v36
	v_mul_f32_e32 v39, v38, v38
	v_fmamk_f32 v37, v37, 0xbdd2d3e7, v129
	v_fmamk_f32 v39, v39, 0xbdd2d3e7, v129
	v_mul_f32_e32 v37, v37, v36
	v_mul_f32_e32 v39, v39, v38
	v_exp_f32_e32 v37, v37
	v_exp_f32_e32 v39, v39
	v_cvt_pk_bf16_f32 v34, v35, v34
	v_and_b32_e32 v30, 0xffff0000, v30
	v_add_f32_e32 v37, 1.0, v37
	v_add_f32_e32 v35, 1.0, v39
	v_rcp_f32_e32 v37, v37
	v_rcp_f32_e32 v35, v35
	v_fmamk_f32 v21, v21, 0xbdd2d3e7, v129
	v_mul_f32_e32 v21, v21, v20
	v_mul_f32_e32 v36, v37, v36
	v_add_f32_e32 v37, v44, v0
	v_mul_f32_e32 v35, v35, v38
	v_add_f32_e32 v0, v45, v0
	v_mul_f32_e32 v36, v36, v37
	v_mul_f32_e32 v0, v35, v0
	v_cvt_pk_bf16_f32 v35, v36, v0
	global_store_dwordx2 v[40:41], v[34:35], off offset:96
	global_load_dword v0, v76, s[12:13] offset:192
	global_load_dwordx2 v[16:17], v[32:33], off offset:64
	global_load_dwordx2 v[18:19], v[32:33], off offset:96
	v_mul_f32_e32 v32, v30, v30
	v_fmamk_f32 v32, v32, 0xbdd2d3e7, v129
	v_mul_f32_e32 v32, v32, v30
	v_exp_f32_e32 v21, v21
	v_exp_f32_e32 v32, v32
	v_mfma_f32_16x16x32_bf16 v[10:13], v[22:25], v[50:53], v[10:13]
	v_add_f32_e32 v21, 1.0, v21
	v_rcp_f32_e32 v21, v21
	v_add_f32_e32 v22, 1.0, v32
	v_rcp_f32_e32 v22, v22
	v_and_b32_e32 v24, 0xffff0000, v31
	v_mul_f32_e32 v20, v21, v20
	v_mul_f32_e32 v25, v24, v24
	v_fmamk_f32 v25, v25, 0xbdd2d3e7, v129
	v_mul_f32_e32 v25, v25, v24
	v_exp_f32_e32 v25, v25
	s_mov_b64 s[0:1], 0x5d000
	s_waitcnt vmcnt(2)
	v_add_f32_e32 v21, v26, v0
	v_mul_f32_e32 v20, v20, v21
	v_mul_f32_e32 v21, v22, v30
	v_add_f32_e32 v22, v27, v0
	v_mul_f32_e32 v21, v21, v22
	v_lshlrev_b32_e32 v22, 16, v31
	v_mul_f32_e32 v23, v22, v22
	v_fmamk_f32 v23, v23, 0xbdd2d3e7, v129
	v_mul_f32_e32 v23, v23, v22
	v_exp_f32_e32 v23, v23
	v_lshlrev_b32_e32 v26, 16, v14
	v_and_b32_e32 v14, 0xffff0000, v14
	v_cvt_pk_bf16_f32 v20, v20, v21
	v_add_f32_e32 v23, 1.0, v23
	v_rcp_f32_e32 v23, v23
	v_add_f32_e32 v21, 1.0, v25
	v_mul_f32_e32 v27, v26, v26
	v_rcp_f32_e32 v21, v21
	v_mul_f32_e32 v22, v23, v22
	v_add_f32_e32 v23, v28, v0
	v_mul_f32_e32 v28, v14, v14
	v_fmamk_f32 v28, v28, 0xbdd2d3e7, v129
	v_fmamk_f32 v27, v27, 0xbdd2d3e7, v129
	v_mul_f32_e32 v28, v28, v14
	v_mul_f32_e32 v27, v27, v26
	v_exp_f32_e32 v28, v28
	v_mul_f32_e32 v22, v22, v23
	v_mul_f32_e32 v21, v21, v24
	v_add_f32_e32 v23, v29, v0
	v_exp_f32_e32 v27, v27
	v_mul_f32_e32 v21, v21, v23
	v_add_co_u32_e32 v24, vcc, s2, v66
	v_cvt_pk_bf16_f32 v21, v22, v21
	s_nop 0
	v_addc_co_u32_e32 v25, vcc, 0, v67, vcc
	global_store_dwordx2 v[24:25], v[20:21], off
	v_add_f32_e32 v20, 1.0, v28
	v_add_f32_e32 v27, 1.0, v27
	v_rcp_f32_e32 v20, v20
	v_rcp_f32_e32 v27, v27
	v_add_f32_e32 v7, v7, v0
	v_add_f32_e32 v6, v6, v0
	v_mul_f32_e32 v14, v20, v14
	v_mul_f32_e32 v21, v27, v26
	v_mul_f32_e32 v7, v14, v7
	v_lshlrev_b32_e32 v14, 16, v15
	v_and_b32_e32 v15, 0xffff0000, v15
	v_mul_f32_e32 v6, v21, v6
	v_mul_f32_e32 v20, v14, v14
	v_mul_f32_e32 v21, v15, v15
	v_fmamk_f32 v20, v20, 0xbdd2d3e7, v129
	v_fmamk_f32 v21, v21, 0xbdd2d3e7, v129
	v_mul_f32_e32 v20, v20, v14
	v_mul_f32_e32 v21, v21, v15
	v_exp_f32_e32 v20, v20
	v_exp_f32_e32 v21, v21
	v_cvt_pk_bf16_f32 v6, v6, v7
	v_add_f32_e32 v8, v8, v0
	v_add_f32_e32 v20, 1.0, v20
	v_add_f32_e32 v7, 1.0, v21
	v_rcp_f32_e32 v20, v20
	v_rcp_f32_e32 v7, v7
	v_add_f32_e32 v9, v9, v0
	v_lshl_add_u64 v[22:23], v[66:67], 0, s[0:1]
	v_mul_f32_e32 v14, v20, v14
	v_mul_f32_e32 v7, v7, v15
	v_mul_f32_e32 v8, v14, v8
	v_mul_f32_e32 v7, v7, v9
	s_waitcnt vmcnt(2)
	v_and_b32_e32 v14, 0xffff0000, v16
	v_cvt_pk_bf16_f32 v7, v8, v7
	v_lshlrev_b32_e32 v8, 16, v16
	v_mul_f32_e32 v15, v14, v14
	v_mul_f32_e32 v9, v8, v8
	v_fmamk_f32 v15, v15, 0xbdd2d3e7, v129
	v_fmamk_f32 v9, v9, 0xbdd2d3e7, v129
	v_mul_f32_e32 v15, v15, v14
	v_mul_f32_e32 v9, v9, v8
	v_exp_f32_e32 v15, v15
	v_exp_f32_e32 v9, v9
	global_store_dwordx2 v[22:23], v[6:7], off offset:32
	v_add_f32_e32 v3, v3, v0
	v_add_f32_e32 v6, 1.0, v15
	v_add_f32_e32 v9, 1.0, v9
	v_rcp_f32_e32 v6, v6
	v_rcp_f32_e32 v9, v9
	v_add_f32_e32 v2, v2, v0
	v_add_f32_e32 v4, v4, v0
	v_mul_f32_e32 v6, v6, v14
	v_mul_f32_e32 v7, v9, v8
	v_mul_f32_e32 v3, v6, v3
	v_lshlrev_b32_e32 v6, 16, v17
	v_and_b32_e32 v8, 0xffff0000, v17
	v_mul_f32_e32 v2, v7, v2
	v_mul_f32_e32 v7, v6, v6
	v_mul_f32_e32 v9, v8, v8
	v_fmamk_f32 v7, v7, 0xbdd2d3e7, v129
	v_fmamk_f32 v9, v9, 0xbdd2d3e7, v129
	v_mul_f32_e32 v7, v7, v6
	v_mul_f32_e32 v9, v9, v8
	v_exp_f32_e32 v7, v7
	v_exp_f32_e32 v9, v9
	v_cvt_pk_bf16_f32 v2, v2, v3
	v_add_f32_e32 v5, v5, v0
	v_add_f32_e32 v7, 1.0, v7
	v_add_f32_e32 v3, 1.0, v9
	v_rcp_f32_e32 v7, v7
	v_rcp_f32_e32 v3, v3
	s_lshl_b32 s0, s38, 6
	s_and_b32 s2, s0, 0x3fc0
	v_mul_f32_e32 v6, v7, v6
	v_mul_f32_e32 v3, v3, v8
	v_mul_f32_e32 v4, v6, v4
	v_mul_f32_e32 v3, v3, v5
	v_cvt_pk_bf16_f32 v3, v4, v3
	s_waitcnt vmcnt(2)
	v_lshlrev_b32_e32 v4, 16, v18
	v_mul_f32_e32 v5, v4, v4
	v_and_b32_e32 v6, 0xffff0000, v18
	v_fmamk_f32 v5, v5, 0xbdd2d3e7, v129
	v_mul_f32_e32 v7, v6, v6
	v_mul_f32_e32 v5, v5, v4
	v_fmamk_f32 v7, v7, 0xbdd2d3e7, v129
	v_mul_f32_e32 v7, v7, v6
	v_exp_f32_e32 v5, v5
	v_exp_f32_e32 v7, v7
	global_store_dwordx2 v[22:23], v[2:3], off offset:64
	v_add_f32_e32 v5, 1.0, v5
	v_rcp_f32_e32 v5, v5
	v_add_f32_e32 v2, 1.0, v7
	v_rcp_f32_e32 v2, v2
	s_lshr_b32 s0, s38, 2
	v_mul_f32_e32 v3, v5, v4
	v_add_f32_e32 v4, v10, v0
	v_mul_f32_e32 v3, v3, v4
	v_mul_f32_e32 v2, v2, v6
	v_add_f32_e32 v4, v11, v0
	v_mul_f32_e32 v2, v2, v4
	v_lshlrev_b32_e32 v4, 16, v19
	v_and_b32_e32 v6, 0xffff0000, v19
	v_mul_f32_e32 v5, v4, v4
	v_mul_f32_e32 v7, v6, v6
	v_fmamk_f32 v5, v5, 0xbdd2d3e7, v129
	v_fmamk_f32 v7, v7, 0xbdd2d3e7, v129
	v_mul_f32_e32 v5, v5, v4
	v_mul_f32_e32 v7, v7, v6
	v_exp_f32_e32 v5, v5
	v_exp_f32_e32 v7, v7
	v_cvt_pk_bf16_f32 v2, v3, v2
	s_and_b32 s4, s0, 64
	v_add_f32_e32 v5, 1.0, v5
	v_add_f32_e32 v3, 1.0, v7
	v_rcp_f32_e32 v5, v5
	v_rcp_f32_e32 v3, v3
	s_lshl_b32 s88, s4, 1
	s_mov_b64 s[0:1], 0x1b00
	v_mul_f32_e32 v4, v5, v4
	v_add_f32_e32 v5, v12, v0
	v_mul_f32_e32 v3, v3, v6
	v_add_f32_e32 v0, v13, v0
	v_mul_f32_e32 v4, v4, v5
	v_mul_f32_e32 v0, v3, v0
	v_cvt_pk_bf16_f32 v3, v4, v0
	v_mov_b32_e32 v0, v194
	global_store_dwordx2 v[22:23], v[2:3], off offset:96
	s_barrier
	s_nop 0
	v_bfe_u32 v12, v0, 2, 6
	v_lshlrev_b32_e32 v0, 4, v0
	v_and_b32_e32 v10, 48, v0
	v_or_b32_e32 v0, s2, v12
	v_mul_u32_u24_e32 v0, 0xf80, v0
	v_lshlrev_b32_e32 v0, 1, v0
	v_lshl_add_u64 v[2:3], s[46:47], 0, v[0:1]
	v_lshl_add_u64 v[2:3], v[2:3], 0, s[88:89]
	v_lshlrev_b32_e32 v0, 1, v10
	v_lshl_add_u64 v[6:7], v[2:3], 0, v[0:1]
	v_add_co_u32_e32 v2, vcc, s68, v6
	v_mul_u32_u24_e32 v10, 0x48, v10
	s_nop 0
	v_addc_co_u32_e32 v3, vcc, 0, v7, vcc
	global_load_dwordx4 v[2:5], v[2:3], off offset:2816
	v_lshl_add_u64 v[6:7], v[6:7], 0, s[0:1]
	global_load_dwordx4 v[6:9], v[6:7], off offset:16
	v_lshlrev_b32_e32 v10, 1, v10
	v_lshlrev_b32_e32 v11, 1, v12
	v_add3_u32 v13, s15, v10, v11
	v_add3_u32 v10, s15, v11, v10
	s_lshl_b32 s88, s2, 1
	s_waitcnt vmcnt(1)
	ds_write_b16 v13, v2
	ds_write_b16_d16_hi v10, v2 offset:144
	ds_write_b16 v13, v3 offset:288
	ds_write_b16_d16_hi v10, v3 offset:432
	ds_write_b16 v13, v4 offset:576
	ds_write_b16_d16_hi v10, v4 offset:720
	ds_write_b16 v13, v5 offset:864
	ds_write_b16_d16_hi v10, v5 offset:1008
	s_waitcnt vmcnt(0)
	ds_write_b16 v13, v6 offset:1152
	ds_write_b16_d16_hi v10, v6 offset:1296
	ds_write_b16 v13, v7 offset:1440
	ds_write_b16_d16_hi v10, v7 offset:1584
	ds_write_b16 v13, v8 offset:1728
	ds_write_b16_d16_hi v10, v8 offset:1872
	ds_write_b16 v13, v9 offset:2016
	ds_write_b16_d16_hi v10, v9 offset:2160
	v_or_b32_e32 v2, s4, v12
	v_lshlrev_b32_e32 v2, 15, v2
	v_mov_b32_e32 v3, v1
	v_lshl_add_u64 v[10:11], s[48:49], 0, v[2:3]
	v_mul_u32_u24_e32 v2, 0x90, v12
	v_add3_u32 v6, s15, v2, v0
	s_waitcnt lgkmcnt(0)
	s_barrier
	ds_read_b128 v[2:5], v6
	ds_read_b128 v[6:9], v6 offset:16
	v_lshl_add_u64 v[10:11], v[10:11], 0, s[88:89]
	v_lshl_add_u64 v[10:11], v[10:11], 0, v[0:1]
	s_mov_b64 s[4:5], -1
	s_waitcnt lgkmcnt(1)
	global_store_dwordx4 v[10:11], v[2:5], off
	s_waitcnt lgkmcnt(0)
	global_store_dwordx4 v[10:11], v[6:9], off offset:16
	s_barrier
